# speedup vs baseline: 1.0014x; 1.0014x over previous
; #define STAGE(P, BASE, LD, br, kt) do { const char* _gp = (const char*)((BASE) + (long)((br) * (LD) + (kt) * BK)); \
;     __builtin_amdgcn_global_load_lds((const unsigned*)(_gp + vo_##BASE##0), (unsigned*)((char*)(P) + tidx * 16), 16, 0, 0); \
;     __builtin_amdgcn_global_load_lds((const unsigned*)(_gp + vo_##BASE##1), (unsigned*)((char*)(P) + tidx * 16 + 8192), 16, 0, 0); } while (0)
; #define LDA(dst, b, h) for (int m = 0; m < 4; ++m) for (int k = 0; k < 2; ++k) \
;     dst[m][k] = *reinterpret_cast<const bf16x8*>((char*)SA(b, h) + lds_byte(wr * 64 + m * 16 + fr, k * 32 + fq * 8))
; #define LDB(dst, b, h) for (int n = 0; n < 2; ++n) for (int k = 0; k < 2; ++k) \
;     dst[n][k] = *reinterpret_cast<const bf16x8*>((char*)SB(b, h) + lds_byte(wc * 32 + n * 16 + fr, k * 32 + fq * 8))
; #define MMA(ai, bj, At, Bt_) do { __builtin_amdgcn_s_setprio(1); \
;     for (int m = 0; m < 4; ++m) for (int n = 0; n < 2; ++n) for (int k = 0; k < 2; ++k) \
;       acc[ai][bj][m][n] = __builtin_amdgcn_mfma_f32_16x16x32_bf16(At[m][k], Bt_[n][k], acc[ai][bj][m][n], 0, 0, 0); \
;     __builtin_amdgcn_s_setprio(0); } while (0)
; #define WAIT_V(n) asm volatile("s_waitcnt vmcnt(" #n ")" ::: "memory")
; #define WAIT_L(n) asm volatile("s_waitcnt lgkmcnt(" #n ")" ::: "memory")
; #define BAR __builtin_amdgcn_s_barrier()
; #define SCHED __builtin_amdgcn_sched_barrier(0)
; __device__ __forceinline__ void gemm_main(acc_t& acc, const u16* A, int lda, const u16* Bt, int ldb, int nt, const int tidx) {
;     ...
;     for (int t = 0; t < nt - 2; t += 2) {
;         LDB(B0, 0, 0); SCHED; LDA(At, 0, 0); STAGE(SA(1, 1), A, lda, HALF, t + 1);
;         WAIT_L(8); BAR; WAIT_L(0); MMA(0, 0, At, B0); BAR; SCHED;
;         LDB(B1, 0, 1); STAGE(SB(0, 0), Bt, ldb, 0, t + 2);
;         BAR; WAIT_L(0); MMA(0, 1, At, B1); BAR;
;         LDA(At, 0, 1); STAGE(SA(0, 0), A, lda, 0, t + 2);
;         BAR; WAIT_L(0); MMA(1, 0, At, B0); BAR; SCHED;
;         STAGE(SB(0, 1), Bt, ldb, HALF, t + 2);
;         WAIT_V(6); BAR; MMA(1, 1, At, B1); BAR;
.LBB0_347:
	v_add_u32_e32 v170, v143, v132
	ds_read_b128 v[158:161], v170
	ds_read_b128 v[162:165], v170 offset:1024
	ds_read_b128 v[166:169], v170 offset:2048
	ds_read_b128 v[170:173], v170 offset:3072
	s_add_i32 s24, s10, 0x40040
	s_ashr_i32 s25, s24, 31
	s_lshl_b64 s[24:25], s[24:25], 1
	s_add_u32 s24, s6, s24
	v_add_u32_e32 v218, 0xc000, v135
	s_addc_u32 s25, s7, s25
	v_readfirstlane_b32 s11, v218
	v_add_u32_e32 v218, 0xe000, v135
	v_add_u32_e32 v192, v144, v141
	v_add_u32_e32 v193, v142, v140
	v_add_u32_e32 v234, v142, v138
	v_add_u32_e32 v235, v142, v139
	v_lshl_add_u64 v[190:191], s[24:25], 0, v[0:1]
	s_mov_b32 m0, s11
	v_readfirstlane_b32 s11, v218
	ds_read_b128 v[174:177], v192
	ds_read_b128 v[178:181], v192 offset:1024
	ds_read_b128 v[194:197], v193
	ds_read_b128 v[198:201], v193 offset:1024
	ds_read_b128 v[202:205], v234
	ds_read_b128 v[206:209], v234 offset:1024
	ds_read_b128 v[210:213], v235
	ds_read_b128 v[214:217], v235 offset:1024
	global_load_lds_dwordx4 v[190:191], off
	v_lshl_add_u64 v[190:191], s[24:25], 0, v[130:131]
	s_mov_b32 m0, s11
	s_nop 0
	global_load_lds_dwordx4 v[190:191], off
	s_waitcnt lgkmcnt(8)
	s_barrier
	s_waitcnt lgkmcnt(0)
	s_setprio 1
	v_mfma_f32_16x16x32_bf16 v[126:129], v[174:177], v[158:161], v[126:129]
	v_mfma_f32_16x16x32_bf16 v[122:125], v[174:177], v[166:169], v[122:125]
	v_mfma_f32_16x16x32_bf16 v[118:121], v[194:197], v[158:161], v[118:121]
	v_mfma_f32_16x16x32_bf16 v[114:117], v[194:197], v[166:169], v[114:117]
	v_mfma_f32_16x16x32_bf16 v[110:113], v[202:205], v[158:161], v[110:113]
	v_mfma_f32_16x16x32_bf16 v[106:109], v[202:205], v[166:169], v[106:109]
	v_mfma_f32_16x16x32_bf16 v[102:105], v[210:213], v[158:161], v[102:105]
	v_mfma_f32_16x16x32_bf16 v[98:101], v[210:213], v[166:169], v[98:101]
	v_mfma_f32_16x16x32_bf16 v[126:129], v[178:181], v[162:165], v[126:129]
	v_mfma_f32_16x16x32_bf16 v[122:125], v[178:181], v[170:173], v[122:125]
	v_mfma_f32_16x16x32_bf16 v[118:121], v[198:201], v[162:165], v[118:121]
	v_mfma_f32_16x16x32_bf16 v[114:117], v[198:201], v[170:173], v[114:117]
	v_mfma_f32_16x16x32_bf16 v[110:113], v[206:209], v[162:165], v[110:113]
	v_mfma_f32_16x16x32_bf16 v[106:109], v[206:209], v[170:173], v[106:109]
	v_mfma_f32_16x16x32_bf16 v[102:105], v[214:217], v[162:165], v[102:105]
	v_mfma_f32_16x16x32_bf16 v[98:101], v[214:217], v[170:173], v[98:101]
	s_setprio 0
	s_barrier
	s_add_i32 s72, s10, 0x80
	s_add_i32 s23, s23, 2
	s_lshl_b64 s[24:25], s[72:73], 1
	s_add_u32 s26, s8, s24
	v_add_u32_e32 v190, v137, v132
	s_addc_u32 s27, s9, s25
	v_readfirstlane_b32 s11, v145
	ds_read_b128 v[218:221], v190
	ds_read_b128 v[222:225], v190 offset:1024
	ds_read_b128 v[226:229], v190 offset:2048
	ds_read_b128 v[230:233], v190 offset:3072
	v_lshl_add_u64 v[190:191], s[26:27], 0, v[0:1]
	s_mov_b32 m0, s11
	v_readfirstlane_b32 s11, v146
	global_load_lds_dwordx4 v[190:191], off
	v_lshl_add_u64 v[190:191], s[26:27], 0, v[130:131]
	s_mov_b32 m0, s11
	s_nop 0
	global_load_lds_dwordx4 v[190:191], off
	s_barrier
	s_waitcnt lgkmcnt(0)
	s_setprio 1
	v_mfma_f32_16x16x32_bf16 v[94:97], v[174:177], v[218:221], v[94:97]
	v_mfma_f32_16x16x32_bf16 v[90:93], v[174:177], v[226:229], v[90:93]
	v_mfma_f32_16x16x32_bf16 v[86:89], v[194:197], v[218:221], v[86:89]
	v_mfma_f32_16x16x32_bf16 v[82:85], v[194:197], v[226:229], v[82:85]
	v_mfma_f32_16x16x32_bf16 v[78:81], v[202:205], v[218:221], v[78:81]
	v_mfma_f32_16x16x32_bf16 v[74:77], v[202:205], v[226:229], v[74:77]
	v_mfma_f32_16x16x32_bf16 v[70:73], v[210:213], v[218:221], v[70:73]
	v_mfma_f32_16x16x32_bf16 v[66:69], v[210:213], v[226:229], v[66:69]
	v_mfma_f32_16x16x32_bf16 v[94:97], v[178:181], v[222:225], v[94:97]
	v_mfma_f32_16x16x32_bf16 v[90:93], v[178:181], v[230:233], v[90:93]
	v_mfma_f32_16x16x32_bf16 v[86:89], v[198:201], v[222:225], v[86:89]
	v_mfma_f32_16x16x32_bf16 v[82:85], v[198:201], v[230:233], v[82:85]
	v_mfma_f32_16x16x32_bf16 v[78:81], v[206:209], v[222:225], v[78:81]
	v_mfma_f32_16x16x32_bf16 v[74:77], v[206:209], v[230:233], v[74:77]
	v_mfma_f32_16x16x32_bf16 v[70:73], v[214:217], v[222:225], v[70:73]
	v_mfma_f32_16x16x32_bf16 v[66:69], v[214:217], v[230:233], v[66:69]
	s_setprio 0
	s_add_u32 s24, s6, s24
	s_addc_u32 s25, s7, s25
	v_readfirstlane_b32 s11, v135
	v_lshl_add_u64 v[190:191], s[24:25], 0, v[0:1]
	s_mov_b32 m0, s11
	v_readfirstlane_b32 s11, v147
	s_barrier
	ds_read_b128 v[174:177], v192 offset:16384
	ds_read_b128 v[178:181], v192 offset:17408
	ds_read_b128 v[194:197], v193 offset:16384
	ds_read_b128 v[198:201], v193 offset:17408
	ds_read_b128 v[202:205], v234 offset:16384
	ds_read_b128 v[206:209], v234 offset:17408
	ds_read_b128 v[210:213], v235 offset:16384
	ds_read_b128 v[214:217], v235 offset:17408
	global_load_lds_dwordx4 v[190:191], off
	v_lshl_add_u64 v[190:191], s[24:25], 0, v[130:131]
	s_mov_b32 m0, s11
	s_nop 0
	global_load_lds_dwordx4 v[190:191], off
	s_barrier
	s_waitcnt lgkmcnt(0)
	s_setprio 1
	v_mfma_f32_16x16x32_bf16 v[62:65], v[174:177], v[158:161], v[62:65]
	v_mfma_f32_16x16x32_bf16 v[58:61], v[174:177], v[166:169], v[58:61]
	v_mfma_f32_16x16x32_bf16 v[54:57], v[194:197], v[158:161], v[54:57]
	v_mfma_f32_16x16x32_bf16 v[50:53], v[194:197], v[166:169], v[50:53]
	v_mfma_f32_16x16x32_bf16 v[46:49], v[202:205], v[158:161], v[46:49]
	v_mfma_f32_16x16x32_bf16 v[42:45], v[202:205], v[166:169], v[42:45]
	v_mfma_f32_16x16x32_bf16 v[38:41], v[210:213], v[158:161], v[38:41]
	v_mfma_f32_16x16x32_bf16 v[34:37], v[210:213], v[166:169], v[34:37]
	v_mfma_f32_16x16x32_bf16 v[62:65], v[178:181], v[162:165], v[62:65]
	v_mfma_f32_16x16x32_bf16 v[58:61], v[178:181], v[170:173], v[58:61]
	v_mfma_f32_16x16x32_bf16 v[54:57], v[198:201], v[162:165], v[54:57]
	v_mfma_f32_16x16x32_bf16 v[50:53], v[198:201], v[170:173], v[50:53]
	v_mfma_f32_16x16x32_bf16 v[46:49], v[206:209], v[162:165], v[46:49]
	v_mfma_f32_16x16x32_bf16 v[42:45], v[206:209], v[170:173], v[42:45]
	v_mfma_f32_16x16x32_bf16 v[38:41], v[214:217], v[162:165], v[38:41]
	v_mfma_f32_16x16x32_bf16 v[34:37], v[214:217], v[170:173], v[34:37]
	s_setprio 0
	s_barrier
; #define STAGE(P, BASE, LD, br, kt) do { const char* _gp = (const char*)((BASE) + (long)((br) * (LD) + (kt) * BK)); \
;     __builtin_amdgcn_global_load_lds((const unsigned*)(_gp + vo_##BASE##0), (unsigned*)((char*)(P) + tidx * 16), 16, 0, 0); \
;     __builtin_amdgcn_global_load_lds((const unsigned*)(_gp + vo_##BASE##1), (unsigned*)((char*)(P) + tidx * 16 + 8192), 16, 0, 0); } while (0)
; #define LDA(dst, b, h) for (int m = 0; m < 4; ++m) for (int k = 0; k < 2; ++k) \
;     dst[m][k] = *reinterpret_cast<const bf16x8*>((char*)SA(b, h) + lds_byte(wr * 64 + m * 16 + fr, k * 32 + fq * 8))
; #define LDB(dst, b, h) for (int n = 0; n < 2; ++n) for (int k = 0; k < 2; ++k) \
;     dst[n][k] = *reinterpret_cast<const bf16x8*>((char*)SB(b, h) + lds_byte(wc * 32 + n * 16 + fr, k * 32 + fq * 8))
; #define MMA(ai, bj, At, Bt_) do { __builtin_amdgcn_s_setprio(1); \
;     for (int m = 0; m < 4; ++m) for (int n = 0; n < 2; ++n) for (int k = 0; k < 2; ++k) \
;       acc[ai][bj][m][n] = __builtin_amdgcn_mfma_f32_16x16x32_bf16(At[m][k], Bt_[n][k], acc[ai][bj][m][n], 0, 0, 0); \
;     __builtin_amdgcn_s_setprio(0); } while (0)
; #define WAIT_V(n) asm volatile("s_waitcnt vmcnt(" #n ")" ::: "memory")
; #define WAIT_L(n) asm volatile("s_waitcnt lgkmcnt(" #n ")" ::: "memory")
; #define BAR __builtin_amdgcn_s_barrier()
; #define SCHED __builtin_amdgcn_sched_barrier(0)
; __device__ __forceinline__ void gemm_main(acc_t& acc, const u16* A, int lda, const u16* Bt, int ldb, int nt, const int tidx) {
;     ...
;         LDB(B1, 0, 1); STAGE(SB(0, 0), Bt, ldb, 0, t + 2);
;         BAR; WAIT_L(0); MMA(0, 1, At, B1); BAR;
;         LDA(At, 0, 1); STAGE(SA(0, 0), A, lda, 0, t + 2);
;         BAR; WAIT_L(0); MMA(1, 0, At, B0); BAR; SCHED;
;         STAGE(SB(0, 1), Bt, ldb, HALF, t + 2);
;         WAIT_V(6); BAR; MMA(1, 1, At, B1); BAR;
;         LDB(B0, 1, 0); SCHED; LDA(At, 1, 0); STAGE(SA(0, 1), A, lda, HALF, t + 2);
;         WAIT_L(8); BAR; WAIT_L(0); MMA(0, 0, At, B0); BAR; SCHED;
;         LDB(B1, 1, 1); STAGE(SB(1, 0), Bt, ldb, 0, t + 3);
;         BAR; WAIT_L(0); MMA(0, 1, At, B1); BAR;
;         LDA(At, 1, 1); STAGE(SA(1, 0), A, lda, 0, t + 3);
;         BAR; WAIT_L(0); MMA(1, 0, At, B0); BAR; SCHED;
;         STAGE(SB(1, 1), Bt, ldb, HALF, t + 3);
;         WAIT_V(6); BAR; MMA(1, 1, At, B1); BAR;
	s_add_i32 s24, s10, 0x40080
	s_mov_b32 s25, s73
	s_lshl_b64 s[24:25], s[24:25], 1
	s_add_u32 s26, s8, s24
	s_addc_u32 s27, s9, s25
	v_readfirstlane_b32 s11, v148
	v_lshl_add_u64 v[158:159], s[26:27], 0, v[0:1]
	s_mov_b32 m0, s11
	v_readfirstlane_b32 s11, v149
	global_load_lds_dwordx4 v[158:159], off
	v_lshl_add_u64 v[158:159], s[26:27], 0, v[130:131]
	s_mov_b32 m0, s11
	s_nop 0
	global_load_lds_dwordx4 v[158:159], off
	s_waitcnt vmcnt(6)
	s_barrier
	s_setprio 1
	v_mfma_f32_16x16x32_bf16 v[30:33], v[174:177], v[218:221], v[30:33]
	v_mfma_f32_16x16x32_bf16 v[26:29], v[174:177], v[226:229], v[26:29]
	v_mfma_f32_16x16x32_bf16 v[22:25], v[194:197], v[218:221], v[22:25]
	v_mfma_f32_16x16x32_bf16 v[18:21], v[194:197], v[226:229], v[18:21]
	v_mfma_f32_16x16x32_bf16 v[14:17], v[202:205], v[218:221], v[14:17]
	v_mfma_f32_16x16x32_bf16 v[10:13], v[202:205], v[226:229], v[10:13]
	v_mfma_f32_16x16x32_bf16 v[6:9], v[210:213], v[218:221], v[6:9]
	v_mfma_f32_16x16x32_bf16 v[2:5], v[210:213], v[226:229], v[2:5]
	v_mfma_f32_16x16x32_bf16 v[30:33], v[178:181], v[222:225], v[30:33]
	v_mfma_f32_16x16x32_bf16 v[26:29], v[178:181], v[230:233], v[26:29]
	v_mfma_f32_16x16x32_bf16 v[22:25], v[198:201], v[222:225], v[22:25]
	v_mfma_f32_16x16x32_bf16 v[18:21], v[198:201], v[230:233], v[18:21]
	v_mfma_f32_16x16x32_bf16 v[14:17], v[206:209], v[222:225], v[14:17]
	v_mfma_f32_16x16x32_bf16 v[10:13], v[206:209], v[230:233], v[10:13]
	v_mfma_f32_16x16x32_bf16 v[6:9], v[214:217], v[222:225], v[6:9]
	v_mfma_f32_16x16x32_bf16 v[2:5], v[214:217], v[230:233], v[2:5]
	s_setprio 0
	v_add_u32_e32 v170, v134, v132
	s_barrier
	ds_read_b128 v[158:161], v170
	ds_read_b128 v[162:165], v170 offset:1024
	ds_read_b128 v[166:169], v170 offset:2048
	ds_read_b128 v[170:173], v170 offset:3072
	s_add_u32 s24, s6, s24
	s_addc_u32 s25, s7, s25
	v_readfirstlane_b32 s11, v150
	v_lshl_add_u64 v[190:191], s[24:25], 0, v[0:1]
	s_mov_b32 m0, s11
	v_readfirstlane_b32 s11, v151
	ds_read_b128 v[174:177], v192 offset:32768
	ds_read_b128 v[178:181], v192 offset:33792
	ds_read_b128 v[194:197], v193 offset:32768
	ds_read_b128 v[198:201], v193 offset:33792
	ds_read_b128 v[202:205], v234 offset:32768
	ds_read_b128 v[206:209], v234 offset:33792
	ds_read_b128 v[210:213], v235 offset:32768
	ds_read_b128 v[214:217], v235 offset:33792
	global_load_lds_dwordx4 v[190:191], off
	v_lshl_add_u64 v[190:191], s[24:25], 0, v[130:131]
	s_mov_b32 m0, s11
	s_nop 0
	global_load_lds_dwordx4 v[190:191], off
	s_waitcnt lgkmcnt(8)
	s_barrier
	s_waitcnt lgkmcnt(0)
	s_setprio 1
	v_mfma_f32_16x16x32_bf16 v[126:129], v[174:177], v[158:161], v[126:129]
	v_mfma_f32_16x16x32_bf16 v[122:125], v[174:177], v[166:169], v[122:125]
	v_mfma_f32_16x16x32_bf16 v[118:121], v[194:197], v[158:161], v[118:121]
	v_mfma_f32_16x16x32_bf16 v[114:117], v[194:197], v[166:169], v[114:117]
	v_mfma_f32_16x16x32_bf16 v[110:113], v[202:205], v[158:161], v[110:113]
	v_mfma_f32_16x16x32_bf16 v[106:109], v[202:205], v[166:169], v[106:109]
	v_mfma_f32_16x16x32_bf16 v[102:105], v[210:213], v[158:161], v[102:105]
	v_mfma_f32_16x16x32_bf16 v[98:101], v[210:213], v[166:169], v[98:101]
	v_mfma_f32_16x16x32_bf16 v[126:129], v[178:181], v[162:165], v[126:129]
	v_mfma_f32_16x16x32_bf16 v[122:125], v[178:181], v[170:173], v[122:125]
	v_mfma_f32_16x16x32_bf16 v[118:121], v[198:201], v[162:165], v[118:121]
	v_mfma_f32_16x16x32_bf16 v[114:117], v[198:201], v[170:173], v[114:117]
	v_mfma_f32_16x16x32_bf16 v[110:113], v[206:209], v[162:165], v[110:113]
	v_mfma_f32_16x16x32_bf16 v[106:109], v[206:209], v[170:173], v[106:109]
	v_mfma_f32_16x16x32_bf16 v[102:105], v[214:217], v[162:165], v[102:105]
	v_mfma_f32_16x16x32_bf16 v[98:101], v[214:217], v[170:173], v[98:101]
	s_setprio 0
	s_barrier
	s_ashr_i32 s11, s10, 31
	s_lshl_b64 s[24:25], s[10:11], 1
	s_add_u32 s26, s8, s24
	v_add_u32_e32 v190, v133, v132
	s_addc_u32 s27, s9, s25
	ds_read_b128 v[218:221], v190
	ds_read_b128 v[222:225], v190 offset:1024
	ds_read_b128 v[226:229], v190 offset:2048
	ds_read_b128 v[230:233], v190 offset:3072
	v_lshl_add_u64 v[190:191], s[26:27], 0, v[0:1]
	v_readfirstlane_b32 s11, v152
	v_lshl_add_u64 v[190:191], v[190:191], 0, s[0:1]
	s_mov_b32 m0, s11
	v_readfirstlane_b32 s11, v153
	global_load_lds_dwordx4 v[190:191], off
	v_lshl_add_u64 v[190:191], s[26:27], 0, v[130:131]
	v_lshl_add_u64 v[190:191], v[190:191], 0, s[0:1]
	s_mov_b32 m0, s11
	s_nop 0
	global_load_lds_dwordx4 v[190:191], off
	s_barrier
	s_waitcnt lgkmcnt(0)
	s_setprio 1
	v_mfma_f32_16x16x32_bf16 v[94:97], v[174:177], v[218:221], v[94:97]
	v_mfma_f32_16x16x32_bf16 v[90:93], v[174:177], v[226:229], v[90:93]
	v_mfma_f32_16x16x32_bf16 v[86:89], v[194:197], v[218:221], v[86:89]
	v_mfma_f32_16x16x32_bf16 v[82:85], v[194:197], v[226:229], v[82:85]
	v_mfma_f32_16x16x32_bf16 v[78:81], v[202:205], v[218:221], v[78:81]
	v_mfma_f32_16x16x32_bf16 v[74:77], v[202:205], v[226:229], v[74:77]
	v_mfma_f32_16x16x32_bf16 v[70:73], v[210:213], v[218:221], v[70:73]
	v_mfma_f32_16x16x32_bf16 v[66:69], v[210:213], v[226:229], v[66:69]
	v_mfma_f32_16x16x32_bf16 v[94:97], v[178:181], v[222:225], v[94:97]
	v_mfma_f32_16x16x32_bf16 v[90:93], v[178:181], v[230:233], v[90:93]
	v_mfma_f32_16x16x32_bf16 v[86:89], v[198:201], v[222:225], v[86:89]
	v_mfma_f32_16x16x32_bf16 v[82:85], v[198:201], v[230:233], v[82:85]
	v_mfma_f32_16x16x32_bf16 v[78:81], v[206:209], v[222:225], v[78:81]
	v_mfma_f32_16x16x32_bf16 v[74:77], v[206:209], v[230:233], v[74:77]
	v_mfma_f32_16x16x32_bf16 v[70:73], v[214:217], v[222:225], v[70:73]
	v_mfma_f32_16x16x32_bf16 v[66:69], v[214:217], v[230:233], v[66:69]
	s_setprio 0
	s_add_u32 s24, s6, s24
	s_addc_u32 s25, s7, s25
	v_lshl_add_u64 v[190:191], s[24:25], 0, v[0:1]
	v_readfirstlane_b32 s11, v154
	v_lshl_add_u64 v[190:191], v[190:191], 0, s[0:1]
	s_mov_b32 m0, s11
	s_barrier
; #define STAGE(P, BASE, LD, br, kt) do { const char* _gp = (const char*)((BASE) + (long)((br) * (LD) + (kt) * BK)); \
;     __builtin_amdgcn_global_load_lds((const unsigned*)(_gp + vo_##BASE##0), (unsigned*)((char*)(P) + tidx * 16), 16, 0, 0); \
;     __builtin_amdgcn_global_load_lds((const unsigned*)(_gp + vo_##BASE##1), (unsigned*)((char*)(P) + tidx * 16 + 8192), 16, 0, 0); } while (0)
; #define LDA(dst, b, h) for (int m = 0; m < 4; ++m) for (int k = 0; k < 2; ++k) \
;     dst[m][k] = *reinterpret_cast<const bf16x8*>((char*)SA(b, h) + lds_byte(wr * 64 + m * 16 + fr, k * 32 + fq * 8))
; #define LDB(dst, b, h) for (int n = 0; n < 2; ++n) for (int k = 0; k < 2; ++k) \
;     dst[n][k] = *reinterpret_cast<const bf16x8*>((char*)SB(b, h) + lds_byte(wc * 32 + n * 16 + fr, k * 32 + fq * 8))
; #define MMA(ai, bj, At, Bt_) do { __builtin_amdgcn_s_setprio(1); \
;     for (int m = 0; m < 4; ++m) for (int n = 0; n < 2; ++n) for (int k = 0; k < 2; ++k) \
;       acc[ai][bj][m][n] = __builtin_amdgcn_mfma_f32_16x16x32_bf16(At[m][k], Bt_[n][k], acc[ai][bj][m][n], 0, 0, 0); \
;     __builtin_amdgcn_s_setprio(0); } while (0)
; #define WAIT_V(n) asm volatile("s_waitcnt vmcnt(" #n ")" ::: "memory")
; #define BAR __builtin_amdgcn_s_barrier()
; __device__ __forceinline__ void gemm_main(acc_t& acc, const u16* A, int lda, const u16* Bt, int ldb, int nt, const int tidx) {
;     ...
;         LDB(B0, 1, 0); SCHED; LDA(At, 1, 0); STAGE(SA(0, 1), A, lda, HALF, t + 2);
;         WAIT_L(8); BAR; WAIT_L(0); MMA(0, 0, At, B0); BAR; SCHED;
;         LDB(B1, 1, 1); STAGE(SB(1, 0), Bt, ldb, 0, t + 3);
;         BAR; WAIT_L(0); MMA(0, 1, At, B1); BAR;
;         LDA(At, 1, 1); STAGE(SA(1, 0), A, lda, 0, t + 3);
;         BAR; WAIT_L(0); MMA(1, 0, At, B0); BAR; SCHED;
;         STAGE(SB(1, 1), Bt, ldb, HALF, t + 3);
;         WAIT_V(6); BAR; MMA(1, 1, At, B1); BAR;
;     }
;     { LDB(B0, 0, 0); LDA(At, 0, 0); STAGE(SA(1, 1), A, lda, HALF, nt - 1);
;       BAR; WAIT_L(0); MMA(0, 0, At, B0); BAR;
;       LDB(B1, 0, 1); BAR; WAIT_L(0); MMA(0, 1, At, B1); BAR;
;       LDA(At, 0, 1); WAIT_V(4); BAR; WAIT_L(0); MMA(1, 0, At, B0); MMA(1, 1, At, B1); BAR; }
;     { LDB(B0, 1, 0); LDA(At, 1, 0); WAIT_V(2); BAR; WAIT_L(0); MMA(0, 0, At, B0); BAR;
;       LDB(B1, 1, 1); WAIT_V(0); BAR; WAIT_L(0); MMA(0, 1, At, B1); BAR;
;       LDA(At, 1, 1); BAR; WAIT_L(0); MMA(1, 0, At, B0); MMA(1, 1, At, B1); BAR; }
	ds_read_b128 v[174:177], v192 offset:49152
	ds_read_b128 v[178:181], v192 offset:50176
	ds_read_b128 v[194:197], v193 offset:49152
	ds_read_b128 v[198:201], v193 offset:50176
	ds_read_b128 v[202:205], v234 offset:49152
	ds_read_b128 v[206:209], v234 offset:50176
	ds_read_b128 v[210:213], v235 offset:49152
	ds_read_b128 v[214:217], v235 offset:50176
	global_load_lds_dwordx4 v[190:191], off
	v_lshl_add_u64 v[190:191], s[24:25], 0, v[130:131]
	v_readfirstlane_b32 s11, v155
	v_lshl_add_u64 v[190:191], v[190:191], 0, s[0:1]
	s_mov_b32 m0, s11
	s_nop 0
	global_load_lds_dwordx4 v[190:191], off
	s_barrier
	s_waitcnt lgkmcnt(0)
	s_setprio 1
	v_mfma_f32_16x16x32_bf16 v[62:65], v[174:177], v[158:161], v[62:65]
	v_mfma_f32_16x16x32_bf16 v[58:61], v[174:177], v[166:169], v[58:61]
	v_mfma_f32_16x16x32_bf16 v[54:57], v[194:197], v[158:161], v[54:57]
	v_mfma_f32_16x16x32_bf16 v[50:53], v[194:197], v[166:169], v[50:53]
	v_mfma_f32_16x16x32_bf16 v[46:49], v[202:205], v[158:161], v[46:49]
	v_mfma_f32_16x16x32_bf16 v[42:45], v[202:205], v[166:169], v[42:45]
	v_mfma_f32_16x16x32_bf16 v[38:41], v[210:213], v[158:161], v[38:41]
	v_mfma_f32_16x16x32_bf16 v[34:37], v[210:213], v[166:169], v[34:37]
	v_mfma_f32_16x16x32_bf16 v[62:65], v[178:181], v[162:165], v[62:65]
	v_mfma_f32_16x16x32_bf16 v[58:61], v[178:181], v[170:173], v[58:61]
	v_mfma_f32_16x16x32_bf16 v[54:57], v[198:201], v[162:165], v[54:57]
	v_mfma_f32_16x16x32_bf16 v[50:53], v[198:201], v[170:173], v[50:53]
	v_mfma_f32_16x16x32_bf16 v[46:49], v[206:209], v[162:165], v[46:49]
	v_mfma_f32_16x16x32_bf16 v[42:45], v[206:209], v[170:173], v[42:45]
	v_mfma_f32_16x16x32_bf16 v[38:41], v[214:217], v[162:165], v[38:41]
	v_mfma_f32_16x16x32_bf16 v[34:37], v[214:217], v[170:173], v[34:37]
	s_setprio 0
	s_barrier
	s_add_i32 s10, s10, 0x400c0
	s_ashr_i32 s11, s10, 31
	s_lshl_b64 s[10:11], s[10:11], 1
	s_add_u32 s10, s8, s10
	s_addc_u32 s11, s9, s11
	v_readfirstlane_b32 s24, v156
	v_lshl_add_u64 v[158:159], s[10:11], 0, v[0:1]
	s_mov_b32 m0, s24
	s_nop 0
	global_load_lds_dwordx4 v[158:159], off
	v_lshl_add_u64 v[158:159], s[10:11], 0, v[130:131]
	v_readfirstlane_b32 s10, v157
	s_mov_b32 m0, s10
	s_nop 0
	global_load_lds_dwordx4 v[158:159], off
	s_waitcnt vmcnt(6)
	s_barrier
	s_setprio 1
	v_mfma_f32_16x16x32_bf16 v[30:33], v[174:177], v[218:221], v[30:33]
	v_mfma_f32_16x16x32_bf16 v[26:29], v[174:177], v[226:229], v[26:29]
	v_mfma_f32_16x16x32_bf16 v[22:25], v[194:197], v[218:221], v[22:25]
	v_mfma_f32_16x16x32_bf16 v[18:21], v[194:197], v[226:229], v[18:21]
	v_mfma_f32_16x16x32_bf16 v[14:17], v[202:205], v[218:221], v[14:17]
	v_mfma_f32_16x16x32_bf16 v[10:13], v[202:205], v[226:229], v[10:13]
	v_mfma_f32_16x16x32_bf16 v[6:9], v[210:213], v[218:221], v[6:9]
	v_mfma_f32_16x16x32_bf16 v[2:5], v[210:213], v[226:229], v[2:5]
	v_mfma_f32_16x16x32_bf16 v[30:33], v[178:181], v[222:225], v[30:33]
	v_mfma_f32_16x16x32_bf16 v[26:29], v[178:181], v[230:233], v[26:29]
	v_mfma_f32_16x16x32_bf16 v[22:25], v[198:201], v[222:225], v[22:25]
	v_mfma_f32_16x16x32_bf16 v[18:21], v[198:201], v[230:233], v[18:21]
	v_mfma_f32_16x16x32_bf16 v[14:17], v[206:209], v[222:225], v[14:17]
	v_mfma_f32_16x16x32_bf16 v[10:13], v[206:209], v[230:233], v[10:13]
	v_mfma_f32_16x16x32_bf16 v[6:9], v[214:217], v[222:225], v[6:9]
	v_mfma_f32_16x16x32_bf16 v[2:5], v[214:217], v[230:233], v[2:5]
	s_setprio 0
	s_cmp_lt_i32 s23, s22
	s_mov_b32 s10, s72
	s_barrier
	s_cbranch_scc1 .LBB0_347
.LBB0_348:
	s_lshl_b32 s5, s5, 6
	s_add_i32 s8, s5, 0x3ffc0
	s_ashr_i32 s9, s8, 31
	s_lshl_b64 s[8:9], s[8:9], 1
	s_add_u32 s6, s6, s8
	s_addc_u32 s7, s7, s9
	v_cmp_gt_u32_e32 vcc, s51, v136
	v_add_u32_e32 v136, 0xc000, v135
	v_lshl_add_u64 v[190:191], s[6:7], 0, v[0:1]
	v_add_u32_e32 v0, v143, v132
	v_readfirstlane_b32 s5, v136
	v_add_u32_e32 v135, 0xe000, v135
	ds_read_b128 v[146:149], v0
	ds_read_b128 v[150:153], v0 offset:1024
	ds_read_b128 v[154:157], v0 offset:2048
	ds_read_b128 v[158:161], v0 offset:3072
	v_add_u32_e32 v0, v144, v141
	v_add_u32_e32 v192, v142, v140
	v_add_u32_e32 v193, v142, v138
	v_add_u32_e32 v234, v142, v139
	s_mov_b32 m0, s5
	v_readfirstlane_b32 s5, v135
	v_lshl_add_u64 v[130:131], s[6:7], 0, v[130:131]
	ds_read_b128 v[162:165], v0
	ds_read_b128 v[166:169], v0 offset:1024
	ds_read_b128 v[170:173], v192
	ds_read_b128 v[174:177], v192 offset:1024
	ds_read_b128 v[178:181], v193
	ds_read_b128 v[194:197], v193 offset:1024
	ds_read_b128 v[138:141], v234
	ds_read_b128 v[142:145], v234 offset:1024
	global_load_lds_dwordx4 v[190:191], off
	s_mov_b32 m0, s5
	s_nop 0
	global_load_lds_dwordx4 v[130:131], off
	s_barrier
	s_waitcnt lgkmcnt(0)
	s_setprio 1
	v_mfma_f32_16x16x32_bf16 v[126:129], v[162:165], v[146:149], v[126:129]
	v_mfma_f32_16x16x32_bf16 v[122:125], v[162:165], v[154:157], v[122:125]
	v_mfma_f32_16x16x32_bf16 v[110:113], v[178:181], v[146:149], v[110:113]
	v_mfma_f32_16x16x32_bf16 v[106:109], v[178:181], v[154:157], v[106:109]
	v_mfma_f32_16x16x32_bf16 v[126:129], v[166:169], v[150:153], v[126:129]
	v_mfma_f32_16x16x32_bf16 v[122:125], v[166:169], v[158:161], v[122:125]
	v_mfma_f32_16x16x32_bf16 v[118:121], v[170:173], v[146:149], v[118:121]
	v_mfma_f32_16x16x32_bf16 v[114:117], v[170:173], v[154:157], v[114:117]
	v_mfma_f32_16x16x32_bf16 v[110:113], v[194:197], v[150:153], v[110:113]
	v_mfma_f32_16x16x32_bf16 v[106:109], v[194:197], v[158:161], v[106:109]
	v_mfma_f32_16x16x32_bf16 v[102:105], v[138:141], v[146:149], v[102:105]
	v_mfma_f32_16x16x32_bf16 v[98:101], v[138:141], v[154:157], v[98:101]
	v_mfma_f32_16x16x32_bf16 v[198:201], v[174:177], v[150:153], v[118:121]
	v_mfma_f32_16x16x32_bf16 v[202:205], v[174:177], v[158:161], v[114:117]
	v_mfma_f32_16x16x32_bf16 v[206:209], v[142:145], v[150:153], v[102:105]
	v_mfma_f32_16x16x32_bf16 v[210:213], v[142:145], v[158:161], v[98:101]
	s_setprio 0
	v_add_u32_e32 v118, v137, v132
	s_barrier
; #define STAGE(P, BASE, LD, br, kt) do { const char* _gp = (const char*)((BASE) + (long)((br) * (LD) + (kt) * BK)); \
;     __builtin_amdgcn_global_load_lds((const unsigned*)(_gp + vo_##BASE##0), (unsigned*)((char*)(P) + tidx * 16), 16, 0, 0); \
;     __builtin_amdgcn_global_load_lds((const unsigned*)(_gp + vo_##BASE##1), (unsigned*)((char*)(P) + tidx * 16 + 8192), 16, 0, 0); } while (0)
; #define LDA(dst, b, h) for (int m = 0; m < 4; ++m) for (int k = 0; k < 2; ++k) \
;     dst[m][k] = *reinterpret_cast<const bf16x8*>((char*)SA(b, h) + lds_byte(wr * 64 + m * 16 + fr, k * 32 + fq * 8))
; #define LDB(dst, b, h) for (int n = 0; n < 2; ++n) for (int k = 0; k < 2; ++k) \
;     dst[n][k] = *reinterpret_cast<const bf16x8*>((char*)SB(b, h) + lds_byte(wc * 32 + n * 16 + fr, k * 32 + fq * 8))
; #define MMA(ai, bj, At, Bt_) do { __builtin_amdgcn_s_setprio(1); \
;     for (int m = 0; m < 4; ++m) for (int n = 0; n < 2; ++n) for (int k = 0; k < 2; ++k) \
;       acc[ai][bj][m][n] = __builtin_amdgcn_mfma_f32_16x16x32_bf16(At[m][k], Bt_[n][k], acc[ai][bj][m][n], 0, 0, 0); \
;     __builtin_amdgcn_s_setprio(0); } while (0)
; #define WAIT_V(n) asm volatile("s_waitcnt vmcnt(" #n ")" ::: "memory")
; #define WAIT_L(n) asm volatile("s_waitcnt lgkmcnt(" #n ")" ::: "memory")
; #define BAR __builtin_amdgcn_s_barrier()
; __device__ __forceinline__ void gemm_main(acc_t& acc, const u16* A, int lda, const u16* Bt, int ldb, int nt, const int tidx) {
;     ...
;     { LDB(B0, 0, 0); LDA(At, 0, 0); STAGE(SA(1, 1), A, lda, HALF, nt - 1);
;       BAR; WAIT_L(0); MMA(0, 0, At, B0); BAR;
;       LDB(B1, 0, 1); BAR; WAIT_L(0); MMA(0, 1, At, B1); BAR;
;       LDA(At, 0, 1); WAIT_V(4); BAR; WAIT_L(0); MMA(1, 0, At, B0); MMA(1, 1, At, B1); BAR; }
;     { LDB(B0, 1, 0); LDA(At, 1, 0); WAIT_V(2); BAR; WAIT_L(0); MMA(0, 0, At, B0); BAR;
;       LDB(B1, 1, 1); WAIT_V(0); BAR; WAIT_L(0); MMA(0, 1, At, B1); BAR;
	s_nop 0
	ds_read_b128 v[98:101], v118
	ds_read_b128 v[102:105], v118 offset:1024
	ds_read_b128 v[114:117], v118 offset:2048
	ds_read_b128 v[118:121], v118 offset:3072
	s_barrier
	s_waitcnt lgkmcnt(0)
	s_setprio 1
	v_mfma_f32_16x16x32_bf16 v[94:97], v[162:165], v[98:101], v[94:97]
	v_mfma_f32_16x16x32_bf16 v[90:93], v[162:165], v[114:117], v[90:93]
	v_mfma_f32_16x16x32_bf16 v[78:81], v[178:181], v[98:101], v[78:81]
	v_mfma_f32_16x16x32_bf16 v[74:77], v[178:181], v[114:117], v[74:77]
	v_mfma_f32_16x16x32_bf16 v[70:73], v[138:141], v[98:101], v[70:73]
	v_mfma_f32_16x16x32_bf16 v[66:69], v[138:141], v[114:117], v[66:69]
	v_mfma_f32_16x16x32_bf16 v[94:97], v[166:169], v[102:105], v[94:97]
	v_mfma_f32_16x16x32_bf16 v[90:93], v[166:169], v[118:121], v[90:93]
	v_mfma_f32_16x16x32_bf16 v[86:89], v[170:173], v[98:101], v[86:89]
	v_mfma_f32_16x16x32_bf16 v[82:85], v[170:173], v[114:117], v[82:85]
	v_mfma_f32_16x16x32_bf16 v[78:81], v[194:197], v[102:105], v[78:81]
	v_mfma_f32_16x16x32_bf16 v[74:77], v[194:197], v[118:121], v[74:77]
	v_mfma_f32_16x16x32_bf16 v[70:73], v[142:145], v[102:105], v[70:73]
	v_mfma_f32_16x16x32_bf16 v[66:69], v[142:145], v[118:121], v[66:69]
	v_mfma_f32_16x16x32_bf16 v[162:165], v[174:177], v[102:105], v[86:89]
	v_mfma_f32_16x16x32_bf16 v[166:169], v[174:177], v[118:121], v[82:85]
	s_setprio 0
	s_barrier
	s_nop 0
	ds_read_b128 v[82:85], v0 offset:16384
	ds_read_b128 v[86:89], v0 offset:17408
	ds_read_b128 v[136:139], v192 offset:16384
	ds_read_b128 v[140:143], v192 offset:17408
	ds_read_b128 v[170:173], v193 offset:16384
	ds_read_b128 v[174:177], v193 offset:17408
	ds_read_b128 v[178:181], v234 offset:16384
	ds_read_b128 v[194:197], v234 offset:17408
	s_waitcnt vmcnt(4)
	s_barrier
	s_waitcnt lgkmcnt(0)
	s_setprio 1
	v_mfma_f32_16x16x32_bf16 v[58:61], v[82:85], v[154:157], v[58:61]
	v_mfma_f32_16x16x32_bf16 v[46:49], v[170:173], v[146:149], v[46:49]
	v_mfma_f32_16x16x32_bf16 v[34:37], v[178:181], v[154:157], v[34:37]
	v_mfma_f32_16x16x32_bf16 v[62:65], v[82:85], v[146:149], v[62:65]
	v_mfma_f32_16x16x32_bf16 v[58:61], v[86:89], v[158:161], v[58:61]
	v_mfma_f32_16x16x32_bf16 v[54:57], v[136:139], v[146:149], v[54:57]
	v_mfma_f32_16x16x32_bf16 v[50:53], v[136:139], v[154:157], v[50:53]
	v_mfma_f32_16x16x32_bf16 v[46:49], v[174:177], v[150:153], v[46:49]
	v_mfma_f32_16x16x32_bf16 v[42:45], v[170:173], v[154:157], v[42:45]
	v_mfma_f32_16x16x32_bf16 v[38:41], v[178:181], v[146:149], v[38:41]
	v_mfma_f32_16x16x32_bf16 v[34:37], v[194:197], v[158:161], v[34:37]
	v_mfma_f32_16x16x32_bf16 v[214:217], v[86:89], v[150:153], v[62:65]
	v_mfma_f32_16x16x32_bf16 v[218:221], v[140:143], v[150:153], v[54:57]
	v_mfma_f32_16x16x32_bf16 v[222:225], v[140:143], v[158:161], v[50:53]
	v_mfma_f32_16x16x32_bf16 v[226:229], v[174:177], v[158:161], v[42:45]
	v_mfma_f32_16x16x32_bf16 v[144:147], v[194:197], v[150:153], v[38:41]
	s_setprio 0
	s_setprio 1
	v_mfma_f32_16x16x32_bf16 v[30:33], v[82:85], v[98:101], v[30:33]
	v_mfma_f32_16x16x32_bf16 v[22:25], v[136:139], v[98:101], v[22:25]
	v_mfma_f32_16x16x32_bf16 v[14:17], v[170:173], v[98:101], v[14:17]
	v_mfma_f32_16x16x32_bf16 v[2:5], v[178:181], v[114:117], v[2:5]
	v_mfma_f32_16x16x32_bf16 v[30:33], v[86:89], v[102:105], v[30:33]
	v_mfma_f32_16x16x32_bf16 v[26:29], v[82:85], v[114:117], v[26:29]
	v_mfma_f32_16x16x32_bf16 v[22:25], v[140:143], v[102:105], v[22:25]
	v_mfma_f32_16x16x32_bf16 v[18:21], v[136:139], v[114:117], v[18:21]
	v_mfma_f32_16x16x32_bf16 v[14:17], v[174:177], v[102:105], v[14:17]
	v_mfma_f32_16x16x32_bf16 v[10:13], v[170:173], v[114:117], v[10:13]
	v_mfma_f32_16x16x32_bf16 v[6:9], v[178:181], v[98:101], v[6:9]
	v_mfma_f32_16x16x32_bf16 v[2:5], v[194:197], v[118:121], v[2:5]
	v_mfma_f32_16x16x32_bf16 v[148:151], v[86:89], v[118:121], v[26:29]
	v_mfma_f32_16x16x32_bf16 v[136:139], v[140:143], v[118:121], v[18:21]
	v_mfma_f32_16x16x32_bf16 v[140:143], v[174:177], v[118:121], v[10:13]
	v_mfma_f32_16x16x32_bf16 v[152:155], v[194:197], v[102:105], v[6:9]
	s_setprio 0
	v_add_u32_e32 v18, v134, v132
	s_barrier
	ds_read_b128 v[6:9], v18
	ds_read_b128 v[10:13], v18 offset:1024
	ds_read_b128 v[156:159], v18 offset:2048
	ds_read_b128 v[170:173], v18 offset:3072
	ds_read_b128 v[18:21], v0 offset:32768
	ds_read_b128 v[26:29], v0 offset:33792
	ds_read_b128 v[38:41], v192 offset:32768
	ds_read_b128 v[42:45], v192 offset:33792
	ds_read_b128 v[54:57], v193 offset:32768
	ds_read_b128 v[174:177], v193 offset:33792
	ds_read_b128 v[178:181], v234 offset:32768
	ds_read_b128 v[194:197], v234 offset:33792
	s_waitcnt vmcnt(2)
	s_barrier
; #define LDA(dst, b, h) for (int m = 0; m < 4; ++m) for (int k = 0; k < 2; ++k) \
;     dst[m][k] = *reinterpret_cast<const bf16x8*>((char*)SA(b, h) + lds_byte(wr * 64 + m * 16 + fr, k * 32 + fq * 8))
; #define LDB(dst, b, h) for (int n = 0; n < 2; ++n) for (int k = 0; k < 2; ++k) \
;     dst[n][k] = *reinterpret_cast<const bf16x8*>((char*)SB(b, h) + lds_byte(wc * 32 + n * 16 + fr, k * 32 + fq * 8))
; #define MMA(ai, bj, At, Bt_) do { __builtin_amdgcn_s_setprio(1); \
;     for (int m = 0; m < 4; ++m) for (int n = 0; n < 2; ++n) for (int k = 0; k < 2; ++k) \
;       acc[ai][bj][m][n] = __builtin_amdgcn_mfma_f32_16x16x32_bf16(At[m][k], Bt_[n][k], acc[ai][bj][m][n], 0, 0, 0); \
;     __builtin_amdgcn_s_setprio(0); } while (0)
; #define WAIT_V(n) asm volatile("s_waitcnt vmcnt(" #n ")" ::: "memory")
; #define WAIT_L(n) asm volatile("s_waitcnt lgkmcnt(" #n ")" ::: "memory")
; #define BAR __builtin_amdgcn_s_barrier()
; __device__ __forceinline__ void gemm_main(acc_t& acc, const u16* A, int lda, const u16* Bt, int ldb, int nt, const int tidx) {
;     ...
;       LDA(At, 0, 1); WAIT_V(4); BAR; WAIT_L(0); MMA(1, 0, At, B0); MMA(1, 1, At, B1); BAR; }
;     { LDB(B0, 1, 0); LDA(At, 1, 0); WAIT_V(2); BAR; WAIT_L(0); MMA(0, 0, At, B0); BAR;
;       LDB(B1, 1, 1); WAIT_V(0); BAR; WAIT_L(0); MMA(0, 1, At, B1); BAR;
;       LDA(At, 1, 1); BAR; WAIT_L(0); MMA(1, 0, At, B0); MMA(1, 1, At, B1); BAR; }
;     if (wr == 0) BAR;
	s_waitcnt lgkmcnt(0)
	s_setprio 1
	v_mfma_f32_16x16x32_bf16 v[50:53], v[18:21], v[6:9], v[126:129]
	v_mfma_f32_16x16x32_bf16 v[118:121], v[26:29], v[10:13], v[50:53]
	v_mfma_f32_16x16x32_bf16 v[50:53], v[18:21], v[156:159], v[122:125]
	v_mfma_f32_16x16x32_bf16 v[114:117], v[26:29], v[170:173], v[50:53]
	v_mfma_f32_16x16x32_bf16 v[50:53], v[38:41], v[6:9], v[198:201]
	v_mfma_f32_16x16x32_bf16 v[102:105], v[42:45], v[10:13], v[50:53]
	v_mfma_f32_16x16x32_bf16 v[50:53], v[38:41], v[156:159], v[202:205]
	v_mfma_f32_16x16x32_bf16 v[98:101], v[42:45], v[170:173], v[50:53]
	v_mfma_f32_16x16x32_bf16 v[50:53], v[54:57], v[6:9], v[110:113]
	v_mfma_f32_16x16x32_bf16 v[86:89], v[174:177], v[10:13], v[50:53]
	v_mfma_f32_16x16x32_bf16 v[50:53], v[54:57], v[156:159], v[106:109]
	v_mfma_f32_16x16x32_bf16 v[82:85], v[174:177], v[170:173], v[50:53]
	v_mfma_f32_16x16x32_bf16 v[50:53], v[178:181], v[6:9], v[206:209]
	v_mfma_f32_16x16x32_bf16 v[62:65], v[194:197], v[10:13], v[50:53]
	v_mfma_f32_16x16x32_bf16 v[50:53], v[178:181], v[156:159], v[210:213]
	v_mfma_f32_16x16x32_bf16 v[50:53], v[194:197], v[170:173], v[50:53]
	s_setprio 0
	v_add_u32_e32 v106, v133, v132
	s_barrier
	ds_read_b128 v[130:133], v106
	ds_read_b128 v[198:201], v106 offset:1024
	ds_read_b128 v[202:205], v106 offset:2048
	ds_read_b128 v[206:209], v106 offset:3072
	s_waitcnt vmcnt(0)
	s_barrier
	s_waitcnt lgkmcnt(0)
	s_setprio 1
	v_mfma_f32_16x16x32_bf16 v[94:97], v[18:21], v[130:133], v[94:97]
	v_mfma_f32_16x16x32_bf16 v[18:21], v[18:21], v[202:205], v[90:93]
	v_mfma_f32_16x16x32_bf16 v[122:125], v[26:29], v[206:209], v[18:21]
	v_mfma_f32_16x16x32_bf16 v[18:21], v[38:41], v[130:133], v[162:165]
	v_mfma_f32_16x16x32_bf16 v[110:113], v[42:45], v[198:201], v[18:21]
	v_mfma_f32_16x16x32_bf16 v[18:21], v[38:41], v[202:205], v[166:169]
	v_mfma_f32_16x16x32_bf16 v[106:109], v[42:45], v[206:209], v[18:21]
	v_mfma_f32_16x16x32_bf16 v[18:21], v[54:57], v[130:133], v[78:81]
	v_mfma_f32_16x16x32_bf16 v[126:129], v[26:29], v[198:201], v[94:97]
	v_mfma_f32_16x16x32_bf16 v[94:97], v[174:177], v[198:201], v[18:21]
	v_mfma_f32_16x16x32_bf16 v[18:21], v[54:57], v[202:205], v[74:77]
	v_mfma_f32_16x16x32_bf16 v[90:93], v[174:177], v[206:209], v[18:21]
	v_mfma_f32_16x16x32_bf16 v[18:21], v[178:181], v[130:133], v[70:73]
	v_mfma_f32_16x16x32_bf16 v[78:81], v[194:197], v[198:201], v[18:21]
	v_mfma_f32_16x16x32_bf16 v[18:21], v[178:181], v[202:205], v[66:69]
	v_mfma_f32_16x16x32_bf16 v[66:69], v[194:197], v[206:209], v[18:21]
	s_setprio 0
	s_barrier
	ds_read_b128 v[160:163], v0 offset:49152
	ds_read_b128 v[164:167], v0 offset:50176
	ds_read_b128 v[174:177], v192 offset:49152
	ds_read_b128 v[178:181], v192 offset:50176
	ds_read_b128 v[194:197], v193 offset:49152
	ds_read_b128 v[210:213], v193 offset:50176
	ds_read_b128 v[230:233], v234 offset:49152
	ds_read_b128 v[234:237], v234 offset:50176
	s_barrier
	s_waitcnt lgkmcnt(0)
	s_setprio 1
	v_mfma_f32_16x16x32_bf16 v[18:21], v[160:163], v[6:9], v[214:217]
	v_mfma_f32_16x16x32_bf16 v[70:73], v[164:167], v[10:13], v[18:21]
	v_mfma_f32_16x16x32_bf16 v[18:21], v[160:163], v[156:159], v[58:61]
	v_mfma_f32_16x16x32_bf16 v[54:57], v[164:167], v[170:173], v[18:21]
	v_mfma_f32_16x16x32_bf16 v[18:21], v[174:177], v[6:9], v[218:221]
	v_mfma_f32_16x16x32_bf16 v[42:45], v[178:181], v[10:13], v[18:21]
	v_mfma_f32_16x16x32_bf16 v[18:21], v[174:177], v[156:159], v[222:225]
	v_mfma_f32_16x16x32_bf16 v[38:41], v[178:181], v[170:173], v[18:21]
	v_mfma_f32_16x16x32_bf16 v[18:21], v[194:197], v[6:9], v[46:49]
	v_mfma_f32_16x16x32_bf16 v[6:9], v[230:233], v[6:9], v[144:147]
	v_mfma_f32_16x16x32_bf16 v[26:29], v[210:213], v[10:13], v[18:21]
	v_mfma_f32_16x16x32_bf16 v[18:21], v[194:197], v[156:159], v[226:229]
	v_mfma_f32_16x16x32_bf16 v[10:13], v[234:237], v[10:13], v[6:9]
	v_mfma_f32_16x16x32_bf16 v[6:9], v[230:233], v[156:159], v[34:37]
	v_mfma_f32_16x16x32_bf16 v[18:21], v[210:213], v[170:173], v[18:21]
	v_mfma_f32_16x16x32_bf16 v[6:9], v[234:237], v[170:173], v[6:9]
	s_setprio 0
	s_setprio 1
	v_mfma_f32_16x16x32_bf16 v[30:33], v[160:163], v[130:133], v[30:33]
	v_mfma_f32_16x16x32_bf16 v[74:77], v[164:167], v[198:201], v[30:33]
	v_mfma_f32_16x16x32_bf16 v[30:33], v[160:163], v[202:205], v[148:151]
	v_mfma_f32_16x16x32_bf16 v[22:25], v[174:177], v[130:133], v[22:25]
	v_mfma_f32_16x16x32_bf16 v[14:17], v[194:197], v[130:133], v[14:17]
	v_mfma_f32_16x16x32_bf16 v[58:61], v[164:167], v[206:209], v[30:33]
	v_mfma_f32_16x16x32_bf16 v[46:49], v[178:181], v[198:201], v[22:25]
	v_mfma_f32_16x16x32_bf16 v[22:25], v[174:177], v[202:205], v[136:139]
	v_mfma_f32_16x16x32_bf16 v[30:33], v[210:213], v[198:201], v[14:17]
	v_mfma_f32_16x16x32_bf16 v[14:17], v[194:197], v[202:205], v[140:143]
	v_mfma_f32_16x16x32_bf16 v[34:37], v[178:181], v[206:209], v[22:25]
	v_mfma_f32_16x16x32_bf16 v[22:25], v[210:213], v[206:209], v[14:17]
	v_mfma_f32_16x16x32_bf16 v[14:17], v[230:233], v[130:133], v[152:155]
	v_mfma_f32_16x16x32_bf16 v[2:5], v[230:233], v[202:205], v[2:5]
	v_mfma_f32_16x16x32_bf16 v[14:17], v[234:237], v[198:201], v[14:17]
	v_mfma_f32_16x16x32_bf16 v[2:5], v[234:237], v[206:209], v[2:5]
	s_setprio 0
	s_barrier
	s_and_saveexec_b64 s[6:7], vcc
	s_cbranch_execz .LBB0_350
	s_barrier

; #define STAGE(P, BASE, LD, br, kt) do { const char* _gp = (const char*)((BASE) + (long)((br) * (LD) + (kt) * BK)); \
;     __builtin_amdgcn_global_load_lds((const unsigned*)(_gp + vo_##BASE##0), (unsigned*)((char*)(P) + tidx * 16), 16, 0, 0); \
;     __builtin_amdgcn_global_load_lds((const unsigned*)(_gp + vo_##BASE##1), (unsigned*)((char*)(P) + tidx * 16 + 8192), 16, 0, 0); } while (0)
; #define LDA(dst, b, h) for (int m = 0; m < 4; ++m) for (int k = 0; k < 2; ++k) \
;     dst[m][k] = *reinterpret_cast<const bf16x8*>((char*)SA(b, h) + lds_byte(wr * 64 + m * 16 + fr, k * 32 + fq * 8))
; #define LDB(dst, b, h) for (int n = 0; n < 2; ++n) for (int k = 0; k < 2; ++k) \
;     dst[n][k] = *reinterpret_cast<const bf16x8*>((char*)SB(b, h) + lds_byte(wc * 32 + n * 16 + fr, k * 32 + fq * 8))
; #define MMA(ai, bj, At, Bt_) do { __builtin_amdgcn_s_setprio(1); \
;     for (int m = 0; m < 4; ++m) for (int n = 0; n < 2; ++n) for (int k = 0; k < 2; ++k) \
;       acc[ai][bj][m][n] = __builtin_amdgcn_mfma_f32_16x16x32_bf16(At[m][k], Bt_[n][k], acc[ai][bj][m][n], 0, 0, 0); \
;     __builtin_amdgcn_s_setprio(0); } while (0)
; #define WAIT_V(n) asm volatile("s_waitcnt vmcnt(" #n ")" ::: "memory")
; #define WAIT_L(n) asm volatile("s_waitcnt lgkmcnt(" #n ")" ::: "memory")
; #define BAR __builtin_amdgcn_s_barrier()
; #define SCHED __builtin_amdgcn_sched_barrier(0)
; __device__ __forceinline__ void gemm_main(acc_t& acc, const u16* A, int lda, const u16* Bt, int ldb, int nt, const int tidx) {
;     ...
;     for (int t = 0; t < nt - 2; t += 2) {
;         LDB(B0, 0, 0); SCHED; LDA(At, 0, 0); STAGE(SA(1, 1), A, lda, HALF, t + 1);
;         WAIT_L(8); BAR; WAIT_L(0); MMA(0, 0, At, B0); BAR; SCHED;
;         LDB(B1, 0, 1); STAGE(SB(0, 0), Bt, ldb, 0, t + 2);
;         BAR; WAIT_L(0); MMA(0, 1, At, B1); BAR;
;         LDA(At, 0, 1); STAGE(SA(0, 0), A, lda, 0, t + 2);
;         BAR; WAIT_L(0); MMA(1, 0, At, B0); BAR; SCHED;
;         STAGE(SB(0, 1), Bt, ldb, HALF, t + 2);
;         WAIT_V(6); BAR; MMA(1, 1, At, B1); BAR;
.LBB0_368:
	v_add_u32_e32 v137, v146, v141
	ds_read_b128 v[160:163], v137
	ds_read_b128 v[164:167], v137 offset:1024
	ds_read_b128 v[168:171], v137 offset:2048
	ds_read_b128 v[172:175], v137 offset:3072
	s_add_i32 s40, s22, 0x40040
	s_ashr_i32 s41, s40, 31
	s_lshl_b64 s[40:41], s[40:41], 1
	s_add_u32 s40, s18, s40
	v_add_u32_e32 v192, 0xc000, v152
	s_addc_u32 s41, s19, s41
	v_readfirstlane_b32 s23, v192
	v_add_u32_e32 v192, 0xe000, v152
	v_add_u32_e32 v137, v150, v142
	v_add_u32_e32 v139, v151, v143
	v_add_u32_e32 v190, v151, v144
	v_add_u32_e32 v191, v151, v145
	v_lshl_add_u64 v[180:181], s[40:41], 0, v[0:1]
	s_mov_b32 m0, s23
	v_readfirstlane_b32 s23, v192
	ds_read_b128 v[176:179], v137
	ds_read_b128 v[194:197], v137 offset:1024
	ds_read_b128 v[198:201], v139
	ds_read_b128 v[202:205], v139 offset:1024
	ds_read_b128 v[206:209], v190
	ds_read_b128 v[210:213], v190 offset:1024
	ds_read_b128 v[214:217], v191
	ds_read_b128 v[218:221], v191 offset:1024
	global_load_lds_dwordx4 v[180:181], off
	v_lshl_add_u64 v[180:181], s[40:41], 0, v[130:131]
	s_mov_b32 m0, s23
	s_nop 0
	global_load_lds_dwordx4 v[180:181], off
	s_waitcnt lgkmcnt(8)
	s_barrier
	s_waitcnt lgkmcnt(0)
	s_setprio 1
	v_mfma_f32_16x16x32_bf16 v[126:129], v[176:179], v[160:163], v[126:129]
	v_mfma_f32_16x16x32_bf16 v[122:125], v[176:179], v[168:171], v[122:125]
	v_mfma_f32_16x16x32_bf16 v[110:113], v[198:201], v[160:163], v[110:113]
	v_mfma_f32_16x16x32_bf16 v[106:109], v[198:201], v[168:171], v[106:109]
	v_mfma_f32_16x16x32_bf16 v[94:97], v[206:209], v[160:163], v[94:97]
	v_mfma_f32_16x16x32_bf16 v[90:93], v[206:209], v[168:171], v[90:93]
	v_mfma_f32_16x16x32_bf16 v[78:81], v[214:217], v[160:163], v[78:81]
	v_mfma_f32_16x16x32_bf16 v[74:77], v[214:217], v[168:171], v[74:77]
	v_mfma_f32_16x16x32_bf16 v[126:129], v[194:197], v[164:167], v[126:129]
	v_mfma_f32_16x16x32_bf16 v[122:125], v[194:197], v[172:175], v[122:125]
	v_mfma_f32_16x16x32_bf16 v[110:113], v[202:205], v[164:167], v[110:113]
	v_mfma_f32_16x16x32_bf16 v[106:109], v[202:205], v[172:175], v[106:109]
	v_mfma_f32_16x16x32_bf16 v[94:97], v[210:213], v[164:167], v[94:97]
	v_mfma_f32_16x16x32_bf16 v[90:93], v[210:213], v[172:175], v[90:93]
	v_mfma_f32_16x16x32_bf16 v[78:81], v[218:221], v[164:167], v[78:81]
	v_mfma_f32_16x16x32_bf16 v[74:77], v[218:221], v[172:175], v[74:77]
	s_setprio 0
	s_barrier
	s_add_i32 s72, s22, 0x80
	s_add_i32 s38, s38, 2
	s_lshl_b64 s[40:41], s[72:73], 1
	s_add_u32 s42, s20, s40
	v_add_u32_e32 v180, v147, v141
	s_addc_u32 s43, s21, s41
	v_readfirstlane_b32 s23, v153
	ds_read_b128 v[222:225], v180
	ds_read_b128 v[226:229], v180 offset:1024
	ds_read_b128 v[230:233], v180 offset:2048
	ds_read_b128 v[234:237], v180 offset:3072
	v_lshl_add_u64 v[180:181], s[42:43], 0, v[0:1]
	s_mov_b32 m0, s23
	v_readfirstlane_b32 s23, v154
	global_load_lds_dwordx4 v[180:181], off
	v_lshl_add_u64 v[180:181], s[42:43], 0, v[130:131]
	s_mov_b32 m0, s23
	s_nop 0
	global_load_lds_dwordx4 v[180:181], off
	s_barrier
	s_waitcnt lgkmcnt(0)
	s_setprio 1
	v_mfma_f32_16x16x32_bf16 v[118:121], v[176:179], v[222:225], v[118:121]
	v_mfma_f32_16x16x32_bf16 v[114:117], v[176:179], v[230:233], v[114:117]
	v_mfma_f32_16x16x32_bf16 v[102:105], v[198:201], v[222:225], v[102:105]
	v_mfma_f32_16x16x32_bf16 v[98:101], v[198:201], v[230:233], v[98:101]
	v_mfma_f32_16x16x32_bf16 v[86:89], v[206:209], v[222:225], v[86:89]
	v_mfma_f32_16x16x32_bf16 v[82:85], v[206:209], v[230:233], v[82:85]
	v_mfma_f32_16x16x32_bf16 v[70:73], v[214:217], v[222:225], v[70:73]
	v_mfma_f32_16x16x32_bf16 v[66:69], v[214:217], v[230:233], v[66:69]
	v_mfma_f32_16x16x32_bf16 v[118:121], v[194:197], v[226:229], v[118:121]
	v_mfma_f32_16x16x32_bf16 v[114:117], v[194:197], v[234:237], v[114:117]
	v_mfma_f32_16x16x32_bf16 v[102:105], v[202:205], v[226:229], v[102:105]
	v_mfma_f32_16x16x32_bf16 v[98:101], v[202:205], v[234:237], v[98:101]
	v_mfma_f32_16x16x32_bf16 v[86:89], v[210:213], v[226:229], v[86:89]
	v_mfma_f32_16x16x32_bf16 v[82:85], v[210:213], v[234:237], v[82:85]
	v_mfma_f32_16x16x32_bf16 v[70:73], v[218:221], v[226:229], v[70:73]
	v_mfma_f32_16x16x32_bf16 v[66:69], v[218:221], v[234:237], v[66:69]
	s_setprio 0
	s_add_u32 s40, s18, s40
	s_addc_u32 s41, s19, s41
	v_readfirstlane_b32 s23, v152
	v_lshl_add_u64 v[180:181], s[40:41], 0, v[0:1]
	s_mov_b32 m0, s23
	v_readfirstlane_b32 s23, v155
	s_barrier
	ds_read_b128 v[176:179], v137 offset:16384
	ds_read_b128 v[194:197], v137 offset:17408
	ds_read_b128 v[198:201], v139 offset:16384
	ds_read_b128 v[202:205], v139 offset:17408
	ds_read_b128 v[206:209], v190 offset:16384
	ds_read_b128 v[210:213], v190 offset:17408
	ds_read_b128 v[214:217], v191 offset:16384
	ds_read_b128 v[218:221], v191 offset:17408
	global_load_lds_dwordx4 v[180:181], off
	v_lshl_add_u64 v[180:181], s[40:41], 0, v[130:131]
	s_mov_b32 m0, s23
	s_nop 0
	global_load_lds_dwordx4 v[180:181], off
	s_barrier
	s_waitcnt lgkmcnt(0)
	s_setprio 1
	v_mfma_f32_16x16x32_bf16 v[62:65], v[176:179], v[160:163], v[62:65]
	v_mfma_f32_16x16x32_bf16 v[58:61], v[176:179], v[168:171], v[58:61]
	v_mfma_f32_16x16x32_bf16 v[46:49], v[198:201], v[160:163], v[46:49]
	v_mfma_f32_16x16x32_bf16 v[42:45], v[198:201], v[168:171], v[42:45]
	v_mfma_f32_16x16x32_bf16 v[30:33], v[206:209], v[160:163], v[30:33]
	v_mfma_f32_16x16x32_bf16 v[26:29], v[206:209], v[168:171], v[26:29]
	v_mfma_f32_16x16x32_bf16 v[14:17], v[214:217], v[160:163], v[14:17]
	v_mfma_f32_16x16x32_bf16 v[10:13], v[214:217], v[168:171], v[10:13]
	v_mfma_f32_16x16x32_bf16 v[62:65], v[194:197], v[164:167], v[62:65]
	v_mfma_f32_16x16x32_bf16 v[58:61], v[194:197], v[172:175], v[58:61]
	v_mfma_f32_16x16x32_bf16 v[46:49], v[202:205], v[164:167], v[46:49]
	v_mfma_f32_16x16x32_bf16 v[42:45], v[202:205], v[172:175], v[42:45]
	v_mfma_f32_16x16x32_bf16 v[30:33], v[210:213], v[164:167], v[30:33]
	v_mfma_f32_16x16x32_bf16 v[26:29], v[210:213], v[172:175], v[26:29]
	v_mfma_f32_16x16x32_bf16 v[14:17], v[218:221], v[164:167], v[14:17]
	v_mfma_f32_16x16x32_bf16 v[10:13], v[218:221], v[172:175], v[10:13]
	s_setprio 0
	s_barrier
; #define STAGE(P, BASE, LD, br, kt) do { const char* _gp = (const char*)((BASE) + (long)((br) * (LD) + (kt) * BK)); \
;     __builtin_amdgcn_global_load_lds((const unsigned*)(_gp + vo_##BASE##0), (unsigned*)((char*)(P) + tidx * 16), 16, 0, 0); \
;     __builtin_amdgcn_global_load_lds((const unsigned*)(_gp + vo_##BASE##1), (unsigned*)((char*)(P) + tidx * 16 + 8192), 16, 0, 0); } while (0)
; #define LDA(dst, b, h) for (int m = 0; m < 4; ++m) for (int k = 0; k < 2; ++k) \
;     dst[m][k] = *reinterpret_cast<const bf16x8*>((char*)SA(b, h) + lds_byte(wr * 64 + m * 16 + fr, k * 32 + fq * 8))
; #define LDB(dst, b, h) for (int n = 0; n < 2; ++n) for (int k = 0; k < 2; ++k) \
;     dst[n][k] = *reinterpret_cast<const bf16x8*>((char*)SB(b, h) + lds_byte(wc * 32 + n * 16 + fr, k * 32 + fq * 8))
; #define MMA(ai, bj, At, Bt_) do { __builtin_amdgcn_s_setprio(1); \
;     for (int m = 0; m < 4; ++m) for (int n = 0; n < 2; ++n) for (int k = 0; k < 2; ++k) \
;       acc[ai][bj][m][n] = __builtin_amdgcn_mfma_f32_16x16x32_bf16(At[m][k], Bt_[n][k], acc[ai][bj][m][n], 0, 0, 0); \
;     __builtin_amdgcn_s_setprio(0); } while (0)
; #define WAIT_V(n) asm volatile("s_waitcnt vmcnt(" #n ")" ::: "memory")
; #define WAIT_L(n) asm volatile("s_waitcnt lgkmcnt(" #n ")" ::: "memory")
; #define BAR __builtin_amdgcn_s_barrier()
; #define SCHED __builtin_amdgcn_sched_barrier(0)
; __device__ __forceinline__ void gemm_main(acc_t& acc, const u16* A, int lda, const u16* Bt, int ldb, int nt, const int tidx) {
;     ...
;         STAGE(SB(0, 1), Bt, ldb, HALF, t + 2);
;         WAIT_V(6); BAR; MMA(1, 1, At, B1); BAR;
;         LDB(B0, 1, 0); SCHED; LDA(At, 1, 0); STAGE(SA(0, 1), A, lda, HALF, t + 2);
;         WAIT_L(8); BAR; WAIT_L(0); MMA(0, 0, At, B0); BAR; SCHED;
;         LDB(B1, 1, 1); STAGE(SB(1, 0), Bt, ldb, 0, t + 3);
;         BAR; WAIT_L(0); MMA(0, 1, At, B1); BAR;
	s_add_i32 s40, s22, 0x40080
	s_mov_b32 s41, s73
	s_lshl_b64 s[40:41], s[40:41], 1
	s_add_u32 s42, s20, s40
	s_addc_u32 s43, s21, s41
	v_readfirstlane_b32 s23, v156
	v_lshl_add_u64 v[160:161], s[42:43], 0, v[0:1]
	s_mov_b32 m0, s23
	v_readfirstlane_b32 s23, v157
	global_load_lds_dwordx4 v[160:161], off
	v_lshl_add_u64 v[160:161], s[42:43], 0, v[130:131]
	s_mov_b32 m0, s23
	s_nop 0
	global_load_lds_dwordx4 v[160:161], off
	s_waitcnt vmcnt(6)
	s_barrier
	s_setprio 1
	v_mfma_f32_16x16x32_bf16 v[54:57], v[176:179], v[222:225], v[54:57]
	v_mfma_f32_16x16x32_bf16 v[50:53], v[176:179], v[230:233], v[50:53]
	v_mfma_f32_16x16x32_bf16 v[38:41], v[198:201], v[222:225], v[38:41]
	v_mfma_f32_16x16x32_bf16 v[34:37], v[198:201], v[230:233], v[34:37]
	v_mfma_f32_16x16x32_bf16 v[22:25], v[206:209], v[222:225], v[22:25]
	v_mfma_f32_16x16x32_bf16 v[18:21], v[206:209], v[230:233], v[18:21]
	v_mfma_f32_16x16x32_bf16 v[6:9], v[214:217], v[222:225], v[6:9]
	v_mfma_f32_16x16x32_bf16 v[2:5], v[214:217], v[230:233], v[2:5]
	v_mfma_f32_16x16x32_bf16 v[54:57], v[194:197], v[226:229], v[54:57]
	v_mfma_f32_16x16x32_bf16 v[50:53], v[194:197], v[234:237], v[50:53]
	v_mfma_f32_16x16x32_bf16 v[38:41], v[202:205], v[226:229], v[38:41]
	v_mfma_f32_16x16x32_bf16 v[34:37], v[202:205], v[234:237], v[34:37]
	v_mfma_f32_16x16x32_bf16 v[22:25], v[210:213], v[226:229], v[22:25]
	v_mfma_f32_16x16x32_bf16 v[18:21], v[210:213], v[234:237], v[18:21]
	v_mfma_f32_16x16x32_bf16 v[6:9], v[218:221], v[226:229], v[6:9]
	v_mfma_f32_16x16x32_bf16 v[2:5], v[218:221], v[234:237], v[2:5]
	s_setprio 0
	v_add_u32_e32 v172, v148, v141
	s_barrier
	ds_read_b128 v[160:163], v172
	ds_read_b128 v[164:167], v172 offset:1024
	ds_read_b128 v[168:171], v172 offset:2048
	ds_read_b128 v[172:175], v172 offset:3072
	s_add_u32 s40, s18, s40
	s_addc_u32 s41, s19, s41
	v_readfirstlane_b32 s23, v158
	v_lshl_add_u64 v[180:181], s[40:41], 0, v[0:1]
	s_mov_b32 m0, s23
	v_readfirstlane_b32 s23, v159
	ds_read_b128 v[176:179], v137 offset:32768
	ds_read_b128 v[194:197], v137 offset:33792
	ds_read_b128 v[198:201], v139 offset:32768
	ds_read_b128 v[202:205], v139 offset:33792
	ds_read_b128 v[206:209], v190 offset:32768
	ds_read_b128 v[210:213], v190 offset:33792
	ds_read_b128 v[214:217], v191 offset:32768
	ds_read_b128 v[218:221], v191 offset:33792
	global_load_lds_dwordx4 v[180:181], off
	v_lshl_add_u64 v[180:181], s[40:41], 0, v[130:131]
	s_mov_b32 m0, s23
	s_nop 0
	global_load_lds_dwordx4 v[180:181], off
	s_waitcnt lgkmcnt(8)
	s_barrier
	s_waitcnt lgkmcnt(0)
	s_setprio 1
	v_mfma_f32_16x16x32_bf16 v[126:129], v[176:179], v[160:163], v[126:129]
	v_mfma_f32_16x16x32_bf16 v[122:125], v[176:179], v[168:171], v[122:125]
	v_mfma_f32_16x16x32_bf16 v[110:113], v[198:201], v[160:163], v[110:113]
	v_mfma_f32_16x16x32_bf16 v[106:109], v[198:201], v[168:171], v[106:109]
	v_mfma_f32_16x16x32_bf16 v[94:97], v[206:209], v[160:163], v[94:97]
	v_mfma_f32_16x16x32_bf16 v[90:93], v[206:209], v[168:171], v[90:93]
	v_mfma_f32_16x16x32_bf16 v[78:81], v[214:217], v[160:163], v[78:81]
	v_mfma_f32_16x16x32_bf16 v[74:77], v[214:217], v[168:171], v[74:77]
	v_mfma_f32_16x16x32_bf16 v[126:129], v[194:197], v[164:167], v[126:129]
	v_mfma_f32_16x16x32_bf16 v[122:125], v[194:197], v[172:175], v[122:125]
	v_mfma_f32_16x16x32_bf16 v[110:113], v[202:205], v[164:167], v[110:113]
	v_mfma_f32_16x16x32_bf16 v[106:109], v[202:205], v[172:175], v[106:109]
	v_mfma_f32_16x16x32_bf16 v[94:97], v[210:213], v[164:167], v[94:97]
	v_mfma_f32_16x16x32_bf16 v[90:93], v[210:213], v[172:175], v[90:93]
	v_mfma_f32_16x16x32_bf16 v[78:81], v[218:221], v[164:167], v[78:81]
	v_mfma_f32_16x16x32_bf16 v[74:77], v[218:221], v[172:175], v[74:77]
	s_setprio 0
	s_barrier
	s_ashr_i32 s23, s22, 31
	s_lshl_b64 s[40:41], s[22:23], 1
	s_add_u32 s42, s20, s40
	v_add_u32_e32 v180, v149, v141
	s_addc_u32 s43, s21, s41
	ds_read_b128 v[222:225], v180
	ds_read_b128 v[226:229], v180 offset:1024
	ds_read_b128 v[230:233], v180 offset:2048
	ds_read_b128 v[234:237], v180 offset:3072
	v_lshl_add_u64 v[180:181], s[42:43], 0, v[0:1]
	v_readfirstlane_b32 s23, v138
	v_lshl_add_u64 v[180:181], v[180:181], 0, s[0:1]
	s_mov_b32 m0, s23
	v_readfirstlane_b32 s23, v134
	global_load_lds_dwordx4 v[180:181], off
	v_lshl_add_u64 v[180:181], s[42:43], 0, v[130:131]
	v_lshl_add_u64 v[180:181], v[180:181], 0, s[0:1]
	s_mov_b32 m0, s23
	s_nop 0
	global_load_lds_dwordx4 v[180:181], off
	s_barrier
	s_waitcnt lgkmcnt(0)
	s_setprio 1
	v_mfma_f32_16x16x32_bf16 v[118:121], v[176:179], v[222:225], v[118:121]
	v_mfma_f32_16x16x32_bf16 v[114:117], v[176:179], v[230:233], v[114:117]
	v_mfma_f32_16x16x32_bf16 v[102:105], v[198:201], v[222:225], v[102:105]
	v_mfma_f32_16x16x32_bf16 v[98:101], v[198:201], v[230:233], v[98:101]
	v_mfma_f32_16x16x32_bf16 v[86:89], v[206:209], v[222:225], v[86:89]
	v_mfma_f32_16x16x32_bf16 v[82:85], v[206:209], v[230:233], v[82:85]
	v_mfma_f32_16x16x32_bf16 v[70:73], v[214:217], v[222:225], v[70:73]
	v_mfma_f32_16x16x32_bf16 v[66:69], v[214:217], v[230:233], v[66:69]
	v_mfma_f32_16x16x32_bf16 v[118:121], v[194:197], v[226:229], v[118:121]
	v_mfma_f32_16x16x32_bf16 v[114:117], v[194:197], v[234:237], v[114:117]
	v_mfma_f32_16x16x32_bf16 v[102:105], v[202:205], v[226:229], v[102:105]
	v_mfma_f32_16x16x32_bf16 v[98:101], v[202:205], v[234:237], v[98:101]
	v_mfma_f32_16x16x32_bf16 v[86:89], v[210:213], v[226:229], v[86:89]
	v_mfma_f32_16x16x32_bf16 v[82:85], v[210:213], v[234:237], v[82:85]
	v_mfma_f32_16x16x32_bf16 v[70:73], v[218:221], v[226:229], v[70:73]
	v_mfma_f32_16x16x32_bf16 v[66:69], v[218:221], v[234:237], v[66:69]
	s_setprio 0
	s_add_u32 s40, s18, s40
	s_addc_u32 s41, s19, s41
	v_lshl_add_u64 v[180:181], s[40:41], 0, v[0:1]
	v_readfirstlane_b32 s23, v135
	v_lshl_add_u64 v[180:181], v[180:181], 0, s[0:1]
	s_mov_b32 m0, s23
	s_barrier
; #define STAGE(P, BASE, LD, br, kt) do { const char* _gp = (const char*)((BASE) + (long)((br) * (LD) + (kt) * BK)); \
;     __builtin_amdgcn_global_load_lds((const unsigned*)(_gp + vo_##BASE##0), (unsigned*)((char*)(P) + tidx * 16), 16, 0, 0); \
;     __builtin_amdgcn_global_load_lds((const unsigned*)(_gp + vo_##BASE##1), (unsigned*)((char*)(P) + tidx * 16 + 8192), 16, 0, 0); } while (0)
; #define LDA(dst, b, h) for (int m = 0; m < 4; ++m) for (int k = 0; k < 2; ++k) \
;     dst[m][k] = *reinterpret_cast<const bf16x8*>((char*)SA(b, h) + lds_byte(wr * 64 + m * 16 + fr, k * 32 + fq * 8))
; #define LDB(dst, b, h) for (int n = 0; n < 2; ++n) for (int k = 0; k < 2; ++k) \
;     dst[n][k] = *reinterpret_cast<const bf16x8*>((char*)SB(b, h) + lds_byte(wc * 32 + n * 16 + fr, k * 32 + fq * 8))
; #define MMA(ai, bj, At, Bt_) do { __builtin_amdgcn_s_setprio(1); \
;     for (int m = 0; m < 4; ++m) for (int n = 0; n < 2; ++n) for (int k = 0; k < 2; ++k) \
;       acc[ai][bj][m][n] = __builtin_amdgcn_mfma_f32_16x16x32_bf16(At[m][k], Bt_[n][k], acc[ai][bj][m][n], 0, 0, 0); \
;     __builtin_amdgcn_s_setprio(0); } while (0)
; #define WAIT_V(n) asm volatile("s_waitcnt vmcnt(" #n ")" ::: "memory")
; #define WAIT_L(n) asm volatile("s_waitcnt lgkmcnt(" #n ")" ::: "memory")
; #define BAR __builtin_amdgcn_s_barrier()
; #define SCHED __builtin_amdgcn_sched_barrier(0)
; __device__ __forceinline__ void gemm_main(acc_t& acc, const u16* A, int lda, const u16* Bt, int ldb, int nt, const int tidx) {
;     ...
;         LDA(At, 1, 1); STAGE(SA(1, 0), A, lda, 0, t + 3);
;         BAR; WAIT_L(0); MMA(1, 0, At, B0); BAR; SCHED;
;         STAGE(SB(1, 1), Bt, ldb, HALF, t + 3);
;         WAIT_V(6); BAR; MMA(1, 1, At, B1); BAR;
;     }
;     { LDB(B0, 0, 0); LDA(At, 0, 0); STAGE(SA(1, 1), A, lda, HALF, nt - 1);
;       BAR; WAIT_L(0); MMA(0, 0, At, B0); BAR;
	ds_read_b128 v[176:179], v137 offset:49152
	ds_read_b128 v[194:197], v137 offset:50176
	ds_read_b128 v[198:201], v139 offset:49152
	ds_read_b128 v[202:205], v139 offset:50176
	ds_read_b128 v[206:209], v190 offset:49152
	ds_read_b128 v[210:213], v190 offset:50176
	ds_read_b128 v[214:217], v191 offset:49152
	ds_read_b128 v[218:221], v191 offset:50176
	global_load_lds_dwordx4 v[180:181], off
	v_lshl_add_u64 v[180:181], s[40:41], 0, v[130:131]
	v_readfirstlane_b32 s23, v132
	v_lshl_add_u64 v[180:181], v[180:181], 0, s[0:1]
	s_mov_b32 m0, s23
	s_nop 0
	global_load_lds_dwordx4 v[180:181], off
	s_barrier
	s_waitcnt lgkmcnt(0)
	s_setprio 1
	v_mfma_f32_16x16x32_bf16 v[62:65], v[176:179], v[160:163], v[62:65]
	v_mfma_f32_16x16x32_bf16 v[58:61], v[176:179], v[168:171], v[58:61]
	v_mfma_f32_16x16x32_bf16 v[46:49], v[198:201], v[160:163], v[46:49]
	v_mfma_f32_16x16x32_bf16 v[42:45], v[198:201], v[168:171], v[42:45]
	v_mfma_f32_16x16x32_bf16 v[30:33], v[206:209], v[160:163], v[30:33]
	v_mfma_f32_16x16x32_bf16 v[26:29], v[206:209], v[168:171], v[26:29]
	v_mfma_f32_16x16x32_bf16 v[14:17], v[214:217], v[160:163], v[14:17]
	v_mfma_f32_16x16x32_bf16 v[10:13], v[214:217], v[168:171], v[10:13]
	v_mfma_f32_16x16x32_bf16 v[62:65], v[194:197], v[164:167], v[62:65]
	v_mfma_f32_16x16x32_bf16 v[58:61], v[194:197], v[172:175], v[58:61]
	v_mfma_f32_16x16x32_bf16 v[46:49], v[202:205], v[164:167], v[46:49]
	v_mfma_f32_16x16x32_bf16 v[42:45], v[202:205], v[172:175], v[42:45]
	v_mfma_f32_16x16x32_bf16 v[30:33], v[210:213], v[164:167], v[30:33]
	v_mfma_f32_16x16x32_bf16 v[26:29], v[210:213], v[172:175], v[26:29]
	v_mfma_f32_16x16x32_bf16 v[14:17], v[218:221], v[164:167], v[14:17]
	v_mfma_f32_16x16x32_bf16 v[10:13], v[218:221], v[172:175], v[10:13]
	s_setprio 0
	s_barrier
	s_add_i32 s22, s22, 0x400c0
	s_ashr_i32 s23, s22, 31
	s_lshl_b64 s[22:23], s[22:23], 1
	s_add_u32 s22, s20, s22
	s_addc_u32 s23, s21, s23
	v_readfirstlane_b32 s39, v133
	v_lshl_add_u64 v[160:161], s[22:23], 0, v[0:1]
	s_mov_b32 m0, s39
	s_nop 0
	global_load_lds_dwordx4 v[160:161], off
	v_lshl_add_u64 v[160:161], s[22:23], 0, v[130:131]
	v_readfirstlane_b32 s22, v136
	s_mov_b32 m0, s22
	s_nop 0
	global_load_lds_dwordx4 v[160:161], off
	s_waitcnt vmcnt(6)
	s_barrier
	s_setprio 1
	v_mfma_f32_16x16x32_bf16 v[54:57], v[176:179], v[222:225], v[54:57]
	v_mfma_f32_16x16x32_bf16 v[50:53], v[176:179], v[230:233], v[50:53]
	v_mfma_f32_16x16x32_bf16 v[38:41], v[198:201], v[222:225], v[38:41]
	v_mfma_f32_16x16x32_bf16 v[34:37], v[198:201], v[230:233], v[34:37]
	v_mfma_f32_16x16x32_bf16 v[22:25], v[206:209], v[222:225], v[22:25]
	v_mfma_f32_16x16x32_bf16 v[18:21], v[206:209], v[230:233], v[18:21]
	v_mfma_f32_16x16x32_bf16 v[6:9], v[214:217], v[222:225], v[6:9]
	v_mfma_f32_16x16x32_bf16 v[2:5], v[214:217], v[230:233], v[2:5]
	v_mfma_f32_16x16x32_bf16 v[54:57], v[194:197], v[226:229], v[54:57]
	v_mfma_f32_16x16x32_bf16 v[50:53], v[194:197], v[234:237], v[50:53]
	v_mfma_f32_16x16x32_bf16 v[38:41], v[202:205], v[226:229], v[38:41]
	v_mfma_f32_16x16x32_bf16 v[34:37], v[202:205], v[234:237], v[34:37]
	v_mfma_f32_16x16x32_bf16 v[22:25], v[210:213], v[226:229], v[22:25]
	v_mfma_f32_16x16x32_bf16 v[18:21], v[210:213], v[234:237], v[18:21]
	v_mfma_f32_16x16x32_bf16 v[6:9], v[218:221], v[226:229], v[6:9]
	v_mfma_f32_16x16x32_bf16 v[2:5], v[218:221], v[234:237], v[2:5]
	s_setprio 0
	s_cmp_lt_i32 s38, s36
	s_mov_b32 s22, s72
	s_barrier
	s_cbranch_scc1 .LBB0_368
.LBB0_369:
	v_add_u32_e32 v153, v146, v141
	ds_read_b128 v[132:135], v153
	ds_read_b128 v[136:139], v153 offset:1024
	ds_read_b128 v[154:157], v153 offset:2048
	ds_read_b128 v[158:161], v153 offset:3072
	s_add_u32 s18, s18, s14
	v_add_u32_e32 v153, 0xc000, v152
	s_addc_u32 s19, s19, s15
	v_readfirstlane_b32 s20, v153
	v_add_u32_e32 v192, v150, v142
	v_add_u32_e32 v193, v151, v143
	v_add_u32_e32 v222, v151, v144
	v_add_u32_e32 v223, v151, v145
	v_lshl_add_u64 v[190:191], s[18:19], 0, v[0:1]
	s_mov_b32 m0, s20
	v_add_u32_e32 v152, 0xe000, v152
	ds_read_b128 v[162:165], v192
	ds_read_b128 v[166:169], v192 offset:1024
	ds_read_b128 v[170:173], v193
	ds_read_b128 v[174:177], v193 offset:1024
	ds_read_b128 v[178:181], v222
	ds_read_b128 v[194:197], v222 offset:1024
	ds_read_b128 v[198:201], v223
	ds_read_b128 v[202:205], v223 offset:1024
	global_load_lds_dwordx4 v[190:191], off
	v_lshl_add_u64 v[190:191], s[18:19], 0, v[130:131]
	v_readfirstlane_b32 s18, v152
	s_mov_b32 m0, s18
	s_nop 0
	global_load_lds_dwordx4 v[190:191], off
	s_barrier
	s_waitcnt lgkmcnt(0)
	s_setprio 1
	v_mfma_f32_16x16x32_bf16 v[126:129], v[162:165], v[132:135], v[126:129]
	v_mfma_f32_16x16x32_bf16 v[122:125], v[162:165], v[154:157], v[122:125]
	v_mfma_f32_16x16x32_bf16 v[110:113], v[170:173], v[132:135], v[110:113]
	v_mfma_f32_16x16x32_bf16 v[106:109], v[170:173], v[154:157], v[106:109]
	v_mfma_f32_16x16x32_bf16 v[94:97], v[178:181], v[132:135], v[94:97]
	v_mfma_f32_16x16x32_bf16 v[90:93], v[178:181], v[154:157], v[90:93]
	v_mfma_f32_16x16x32_bf16 v[78:81], v[198:201], v[132:135], v[78:81]
	v_mfma_f32_16x16x32_bf16 v[74:77], v[198:201], v[154:157], v[74:77]
	v_mfma_f32_16x16x32_bf16 v[126:129], v[166:169], v[136:139], v[126:129]
	v_mfma_f32_16x16x32_bf16 v[122:125], v[166:169], v[158:161], v[122:125]
	v_mfma_f32_16x16x32_bf16 v[110:113], v[174:177], v[136:139], v[110:113]
	v_mfma_f32_16x16x32_bf16 v[106:109], v[174:177], v[158:161], v[106:109]
	v_mfma_f32_16x16x32_bf16 v[94:97], v[194:197], v[136:139], v[94:97]
	v_mfma_f32_16x16x32_bf16 v[90:93], v[194:197], v[158:161], v[90:93]
	v_mfma_f32_16x16x32_bf16 v[78:81], v[202:205], v[136:139], v[78:81]
	v_mfma_f32_16x16x32_bf16 v[74:77], v[202:205], v[158:161], v[74:77]
	s_setprio 0
	v_add_u32_e32 v152, v147, v141
	s_barrier
; #define LDA(dst, b, h) for (int m = 0; m < 4; ++m) for (int k = 0; k < 2; ++k) \
;     dst[m][k] = *reinterpret_cast<const bf16x8*>((char*)SA(b, h) + lds_byte(wr * 64 + m * 16 + fr, k * 32 + fq * 8))
; #define LDB(dst, b, h) for (int n = 0; n < 2; ++n) for (int k = 0; k < 2; ++k) \
;     dst[n][k] = *reinterpret_cast<const bf16x8*>((char*)SB(b, h) + lds_byte(wc * 32 + n * 16 + fr, k * 32 + fq * 8))
; #define MMA(ai, bj, At, Bt_) do { __builtin_amdgcn_s_setprio(1); \
;     for (int m = 0; m < 4; ++m) for (int n = 0; n < 2; ++n) for (int k = 0; k < 2; ++k) \
;       acc[ai][bj][m][n] = __builtin_amdgcn_mfma_f32_16x16x32_bf16(At[m][k], Bt_[n][k], acc[ai][bj][m][n], 0, 0, 0); \
;     __builtin_amdgcn_s_setprio(0); } while (0)
; #define WAIT_V(n) asm volatile("s_waitcnt vmcnt(" #n ")" ::: "memory")
; #define WAIT_L(n) asm volatile("s_waitcnt lgkmcnt(" #n ")" ::: "memory")
; #define BAR __builtin_amdgcn_s_barrier()
; __device__ __forceinline__ void gemm_main(acc_t& acc, const u16* A, int lda, const u16* Bt, int ldb, int nt, const int tidx) {
;     ...
;       LDB(B1, 0, 1); BAR; WAIT_L(0); MMA(0, 1, At, B1); BAR;
;       LDA(At, 0, 1); WAIT_V(4); BAR; WAIT_L(0); MMA(1, 0, At, B0); MMA(1, 1, At, B1); BAR; }
;     { LDB(B0, 1, 0); LDA(At, 1, 0); WAIT_V(2); BAR; WAIT_L(0); MMA(0, 0, At, B0); BAR;
	ds_read_b128 v[206:209], v152
	ds_read_b128 v[210:213], v152 offset:1024
	ds_read_b128 v[214:217], v152 offset:2048
	ds_read_b128 v[218:221], v152 offset:3072
	s_barrier
	s_waitcnt lgkmcnt(0)
	s_setprio 1
	v_mfma_f32_16x16x32_bf16 v[118:121], v[162:165], v[206:209], v[118:121]
	v_mfma_f32_16x16x32_bf16 v[114:117], v[162:165], v[214:217], v[114:117]
	v_mfma_f32_16x16x32_bf16 v[102:105], v[170:173], v[206:209], v[102:105]
	v_mfma_f32_16x16x32_bf16 v[98:101], v[170:173], v[214:217], v[98:101]
	v_mfma_f32_16x16x32_bf16 v[86:89], v[178:181], v[206:209], v[86:89]
	v_mfma_f32_16x16x32_bf16 v[82:85], v[178:181], v[214:217], v[82:85]
	v_mfma_f32_16x16x32_bf16 v[70:73], v[198:201], v[206:209], v[70:73]
	v_mfma_f32_16x16x32_bf16 v[66:69], v[198:201], v[214:217], v[66:69]
	v_mfma_f32_16x16x32_bf16 v[118:121], v[166:169], v[210:213], v[118:121]
	v_mfma_f32_16x16x32_bf16 v[114:117], v[166:169], v[218:221], v[114:117]
	v_mfma_f32_16x16x32_bf16 v[102:105], v[174:177], v[210:213], v[102:105]
	v_mfma_f32_16x16x32_bf16 v[98:101], v[174:177], v[218:221], v[98:101]
	v_mfma_f32_16x16x32_bf16 v[86:89], v[194:197], v[210:213], v[86:89]
	v_mfma_f32_16x16x32_bf16 v[82:85], v[194:197], v[218:221], v[82:85]
	v_mfma_f32_16x16x32_bf16 v[70:73], v[202:205], v[210:213], v[70:73]
	v_mfma_f32_16x16x32_bf16 v[66:69], v[202:205], v[218:221], v[66:69]
	s_setprio 0
	s_barrier
	ds_read_b128 v[162:165], v192 offset:16384
	ds_read_b128 v[166:169], v192 offset:17408
	ds_read_b128 v[170:173], v193 offset:16384
	ds_read_b128 v[174:177], v193 offset:17408
	ds_read_b128 v[178:181], v222 offset:16384
	ds_read_b128 v[194:197], v222 offset:17408
	ds_read_b128 v[198:201], v223 offset:16384
	ds_read_b128 v[202:205], v223 offset:17408
	s_waitcnt vmcnt(4)
	s_barrier
	s_waitcnt lgkmcnt(0)
	s_setprio 1
	v_mfma_f32_16x16x32_bf16 v[62:65], v[162:165], v[132:135], v[62:65]
	v_mfma_f32_16x16x32_bf16 v[58:61], v[162:165], v[154:157], v[58:61]
	v_mfma_f32_16x16x32_bf16 v[46:49], v[170:173], v[132:135], v[46:49]
	v_mfma_f32_16x16x32_bf16 v[42:45], v[170:173], v[154:157], v[42:45]
	v_mfma_f32_16x16x32_bf16 v[30:33], v[178:181], v[132:135], v[30:33]
	v_mfma_f32_16x16x32_bf16 v[26:29], v[178:181], v[154:157], v[26:29]
	v_mfma_f32_16x16x32_bf16 v[14:17], v[198:201], v[132:135], v[14:17]
	v_mfma_f32_16x16x32_bf16 v[10:13], v[198:201], v[154:157], v[10:13]
	v_mfma_f32_16x16x32_bf16 v[62:65], v[166:169], v[136:139], v[62:65]
	v_mfma_f32_16x16x32_bf16 v[58:61], v[166:169], v[158:161], v[58:61]
	v_mfma_f32_16x16x32_bf16 v[46:49], v[174:177], v[136:139], v[46:49]
	v_mfma_f32_16x16x32_bf16 v[42:45], v[174:177], v[158:161], v[42:45]
	v_mfma_f32_16x16x32_bf16 v[30:33], v[194:197], v[136:139], v[30:33]
	v_mfma_f32_16x16x32_bf16 v[26:29], v[194:197], v[158:161], v[26:29]
	v_mfma_f32_16x16x32_bf16 v[14:17], v[202:205], v[136:139], v[14:17]
	v_mfma_f32_16x16x32_bf16 v[10:13], v[202:205], v[158:161], v[10:13]
	s_setprio 0
	s_setprio 1
	v_mfma_f32_16x16x32_bf16 v[54:57], v[162:165], v[206:209], v[54:57]
	v_mfma_f32_16x16x32_bf16 v[50:53], v[162:165], v[214:217], v[50:53]
	v_mfma_f32_16x16x32_bf16 v[38:41], v[170:173], v[206:209], v[38:41]
	v_mfma_f32_16x16x32_bf16 v[34:37], v[170:173], v[214:217], v[34:37]
	v_mfma_f32_16x16x32_bf16 v[22:25], v[178:181], v[206:209], v[22:25]
	v_mfma_f32_16x16x32_bf16 v[18:21], v[178:181], v[214:217], v[18:21]
	v_mfma_f32_16x16x32_bf16 v[6:9], v[198:201], v[206:209], v[6:9]
	v_mfma_f32_16x16x32_bf16 v[2:5], v[198:201], v[214:217], v[2:5]
	v_mfma_f32_16x16x32_bf16 v[54:57], v[166:169], v[210:213], v[54:57]
	v_mfma_f32_16x16x32_bf16 v[50:53], v[166:169], v[218:221], v[50:53]
	v_mfma_f32_16x16x32_bf16 v[38:41], v[174:177], v[210:213], v[38:41]
	v_mfma_f32_16x16x32_bf16 v[34:37], v[174:177], v[218:221], v[34:37]
	v_mfma_f32_16x16x32_bf16 v[22:25], v[194:197], v[210:213], v[22:25]
	v_mfma_f32_16x16x32_bf16 v[18:21], v[194:197], v[218:221], v[18:21]
	v_mfma_f32_16x16x32_bf16 v[6:9], v[202:205], v[210:213], v[6:9]
	v_mfma_f32_16x16x32_bf16 v[2:5], v[202:205], v[218:221], v[2:5]
	s_setprio 0
	v_add_u32_e32 v156, v148, v141
	s_barrier
	ds_read_b128 v[132:135], v156
	ds_read_b128 v[136:139], v156 offset:1024
	ds_read_b128 v[152:155], v156 offset:2048
	ds_read_b128 v[156:159], v156 offset:3072
	ds_read_b128 v[160:163], v192 offset:32768
	ds_read_b128 v[164:167], v192 offset:33792
	ds_read_b128 v[168:171], v193 offset:32768
	ds_read_b128 v[172:175], v193 offset:33792
	ds_read_b128 v[176:179], v222 offset:32768
	ds_read_b128 v[194:197], v222 offset:33792
	ds_read_b128 v[198:201], v223 offset:32768
	ds_read_b128 v[202:205], v223 offset:33792
	s_waitcnt vmcnt(2)
	s_barrier
; #define LDA(dst, b, h) for (int m = 0; m < 4; ++m) for (int k = 0; k < 2; ++k) \
;     dst[m][k] = *reinterpret_cast<const bf16x8*>((char*)SA(b, h) + lds_byte(wr * 64 + m * 16 + fr, k * 32 + fq * 8))
; #define LDB(dst, b, h) for (int n = 0; n < 2; ++n) for (int k = 0; k < 2; ++k) \
;     dst[n][k] = *reinterpret_cast<const bf16x8*>((char*)SB(b, h) + lds_byte(wc * 32 + n * 16 + fr, k * 32 + fq * 8))
; #define MMA(ai, bj, At, Bt_) do { __builtin_amdgcn_s_setprio(1); \
;     for (int m = 0; m < 4; ++m) for (int n = 0; n < 2; ++n) for (int k = 0; k < 2; ++k) \
;       acc[ai][bj][m][n] = __builtin_amdgcn_mfma_f32_16x16x32_bf16(At[m][k], Bt_[n][k], acc[ai][bj][m][n], 0, 0, 0); \
;     __builtin_amdgcn_s_setprio(0); } while (0)
; #define WAIT_V(n) asm volatile("s_waitcnt vmcnt(" #n ")" ::: "memory")
; #define WAIT_L(n) asm volatile("s_waitcnt lgkmcnt(" #n ")" ::: "memory")
; #define BAR __builtin_amdgcn_s_barrier()
; __device__ __forceinline__ void gemm_main(acc_t& acc, const u16* A, int lda, const u16* Bt, int ldb, int nt, const int tidx) {
;     ...
;     { LDB(B0, 1, 0); LDA(At, 1, 0); WAIT_V(2); BAR; WAIT_L(0); MMA(0, 0, At, B0); BAR;
;       LDB(B1, 1, 1); WAIT_V(0); BAR; WAIT_L(0); MMA(0, 1, At, B1); BAR;
;       LDA(At, 1, 1); BAR; WAIT_L(0); MMA(1, 0, At, B0); MMA(1, 1, At, B1); BAR; }
;     if (wr == 0) BAR;
	s_waitcnt lgkmcnt(0)
	s_setprio 1
	v_mfma_f32_16x16x32_bf16 v[126:129], v[160:163], v[132:135], v[126:129]
	v_mfma_f32_16x16x32_bf16 v[122:125], v[160:163], v[152:155], v[122:125]
	v_mfma_f32_16x16x32_bf16 v[110:113], v[168:171], v[132:135], v[110:113]
	v_mfma_f32_16x16x32_bf16 v[106:109], v[168:171], v[152:155], v[106:109]
	v_mfma_f32_16x16x32_bf16 v[94:97], v[176:179], v[132:135], v[94:97]
	v_mfma_f32_16x16x32_bf16 v[90:93], v[176:179], v[152:155], v[90:93]
	v_mfma_f32_16x16x32_bf16 v[78:81], v[198:201], v[132:135], v[78:81]
	v_mfma_f32_16x16x32_bf16 v[74:77], v[198:201], v[152:155], v[74:77]
	v_mfma_f32_16x16x32_bf16 v[126:129], v[164:167], v[136:139], v[126:129]
	v_mfma_f32_16x16x32_bf16 v[122:125], v[164:167], v[156:159], v[122:125]
	v_mfma_f32_16x16x32_bf16 v[110:113], v[172:175], v[136:139], v[110:113]
	v_mfma_f32_16x16x32_bf16 v[106:109], v[172:175], v[156:159], v[106:109]
	v_mfma_f32_16x16x32_bf16 v[94:97], v[194:197], v[136:139], v[94:97]
	v_mfma_f32_16x16x32_bf16 v[90:93], v[194:197], v[156:159], v[90:93]
	v_mfma_f32_16x16x32_bf16 v[78:81], v[202:205], v[136:139], v[78:81]
	v_mfma_f32_16x16x32_bf16 v[74:77], v[202:205], v[156:159], v[74:77]
	s_setprio 0
	v_add_u32_e32 v180, v149, v141
	s_barrier
	ds_read_b128 v[206:209], v180
	ds_read_b128 v[210:213], v180 offset:1024
	ds_read_b128 v[214:217], v180 offset:2048
	ds_read_b128 v[218:221], v180 offset:3072
	s_waitcnt vmcnt(0)
	s_barrier
	s_waitcnt lgkmcnt(0)
	s_setprio 1
	v_mfma_f32_16x16x32_bf16 v[118:121], v[160:163], v[206:209], v[118:121]
	v_mfma_f32_16x16x32_bf16 v[114:117], v[160:163], v[214:217], v[114:117]
	v_mfma_f32_16x16x32_bf16 v[102:105], v[168:171], v[206:209], v[102:105]
	v_mfma_f32_16x16x32_bf16 v[98:101], v[168:171], v[214:217], v[98:101]
	v_mfma_f32_16x16x32_bf16 v[86:89], v[176:179], v[206:209], v[86:89]
	v_mfma_f32_16x16x32_bf16 v[82:85], v[176:179], v[214:217], v[82:85]
	v_mfma_f32_16x16x32_bf16 v[70:73], v[198:201], v[206:209], v[70:73]
	v_mfma_f32_16x16x32_bf16 v[66:69], v[198:201], v[214:217], v[66:69]
	v_mfma_f32_16x16x32_bf16 v[118:121], v[164:167], v[210:213], v[118:121]
	v_mfma_f32_16x16x32_bf16 v[114:117], v[164:167], v[218:221], v[114:117]
	v_mfma_f32_16x16x32_bf16 v[102:105], v[172:175], v[210:213], v[102:105]
	v_mfma_f32_16x16x32_bf16 v[98:101], v[172:175], v[218:221], v[98:101]
	v_mfma_f32_16x16x32_bf16 v[86:89], v[194:197], v[210:213], v[86:89]
	v_mfma_f32_16x16x32_bf16 v[82:85], v[194:197], v[218:221], v[82:85]
	v_mfma_f32_16x16x32_bf16 v[70:73], v[202:205], v[210:213], v[70:73]
	v_mfma_f32_16x16x32_bf16 v[66:69], v[202:205], v[218:221], v[66:69]
	s_setprio 0
	s_barrier
	ds_read_b128 v[160:163], v192 offset:49152
	ds_read_b128 v[164:167], v192 offset:50176
	ds_read_b128 v[168:171], v193 offset:49152
	ds_read_b128 v[172:175], v193 offset:50176
	ds_read_b128 v[176:179], v222 offset:49152
	ds_read_b128 v[194:197], v222 offset:50176
	ds_read_b128 v[198:201], v223 offset:49152
	ds_read_b128 v[202:205], v223 offset:50176
	s_barrier
	s_waitcnt lgkmcnt(0)
	s_setprio 1
	v_mfma_f32_16x16x32_bf16 v[62:65], v[160:163], v[132:135], v[62:65]
	v_mfma_f32_16x16x32_bf16 v[58:61], v[160:163], v[152:155], v[58:61]
	v_mfma_f32_16x16x32_bf16 v[46:49], v[168:171], v[132:135], v[46:49]
	v_mfma_f32_16x16x32_bf16 v[42:45], v[168:171], v[152:155], v[42:45]
	v_mfma_f32_16x16x32_bf16 v[30:33], v[176:179], v[132:135], v[30:33]
	v_mfma_f32_16x16x32_bf16 v[26:29], v[176:179], v[152:155], v[26:29]
	v_mfma_f32_16x16x32_bf16 v[14:17], v[198:201], v[132:135], v[14:17]
	v_mfma_f32_16x16x32_bf16 v[10:13], v[198:201], v[152:155], v[10:13]
	v_mfma_f32_16x16x32_bf16 v[62:65], v[164:167], v[136:139], v[62:65]
	v_mfma_f32_16x16x32_bf16 v[58:61], v[164:167], v[156:159], v[58:61]
	v_mfma_f32_16x16x32_bf16 v[46:49], v[172:175], v[136:139], v[46:49]
	v_mfma_f32_16x16x32_bf16 v[42:45], v[172:175], v[156:159], v[42:45]
	v_mfma_f32_16x16x32_bf16 v[30:33], v[194:197], v[136:139], v[30:33]
	v_mfma_f32_16x16x32_bf16 v[26:29], v[194:197], v[156:159], v[26:29]
	v_mfma_f32_16x16x32_bf16 v[14:17], v[202:205], v[136:139], v[14:17]
	v_mfma_f32_16x16x32_bf16 v[10:13], v[202:205], v[156:159], v[10:13]
	s_setprio 0
	s_setprio 1
	v_mfma_f32_16x16x32_bf16 v[54:57], v[160:163], v[206:209], v[54:57]
	v_mfma_f32_16x16x32_bf16 v[50:53], v[160:163], v[214:217], v[50:53]
	v_mfma_f32_16x16x32_bf16 v[38:41], v[168:171], v[206:209], v[38:41]
	v_mfma_f32_16x16x32_bf16 v[34:37], v[168:171], v[214:217], v[34:37]
	v_mfma_f32_16x16x32_bf16 v[22:25], v[176:179], v[206:209], v[22:25]
	v_mfma_f32_16x16x32_bf16 v[18:21], v[176:179], v[214:217], v[18:21]
	v_mfma_f32_16x16x32_bf16 v[6:9], v[198:201], v[206:209], v[6:9]
	v_mfma_f32_16x16x32_bf16 v[2:5], v[198:201], v[214:217], v[2:5]
	v_mfma_f32_16x16x32_bf16 v[54:57], v[164:167], v[210:213], v[54:57]
	v_mfma_f32_16x16x32_bf16 v[50:53], v[164:167], v[218:221], v[50:53]
	v_mfma_f32_16x16x32_bf16 v[38:41], v[172:175], v[210:213], v[38:41]
	v_mfma_f32_16x16x32_bf16 v[34:37], v[172:175], v[218:221], v[34:37]
	v_mfma_f32_16x16x32_bf16 v[22:25], v[194:197], v[210:213], v[22:25]
	v_mfma_f32_16x16x32_bf16 v[18:21], v[194:197], v[218:221], v[18:21]
	v_mfma_f32_16x16x32_bf16 v[6:9], v[202:205], v[210:213], v[6:9]
	v_mfma_f32_16x16x32_bf16 v[2:5], v[202:205], v[218:221], v[2:5]
	s_setprio 0
	s_barrier
	s_and_saveexec_b64 s[18:19], s[6:7]
	s_cbranch_execz .LBB0_361
	s_barrier
	s_branch .LBB0_361

; #define STAGE(P, BASE, LD, br, kt) do { const char* _gp = (const char*)((BASE) + (long)((br) * (LD) + (kt) * BK)); \
;     __builtin_amdgcn_global_load_lds((const unsigned*)(_gp + vo_##BASE##0), (unsigned*)((char*)(P) + tidx * 16), 16, 0, 0); \
;     __builtin_amdgcn_global_load_lds((const unsigned*)(_gp + vo_##BASE##1), (unsigned*)((char*)(P) + tidx * 16 + 8192), 16, 0, 0); } while (0)
; #define LDA(dst, b, h) for (int m = 0; m < 4; ++m) for (int k = 0; k < 2; ++k) \
;     dst[m][k] = *reinterpret_cast<const bf16x8*>((char*)SA(b, h) + lds_byte(wr * 64 + m * 16 + fr, k * 32 + fq * 8))
; #define LDB(dst, b, h) for (int n = 0; n < 2; ++n) for (int k = 0; k < 2; ++k) \
;     dst[n][k] = *reinterpret_cast<const bf16x8*>((char*)SB(b, h) + lds_byte(wc * 32 + n * 16 + fr, k * 32 + fq * 8))
; #define MMA(ai, bj, At, Bt_) do { __builtin_amdgcn_s_setprio(1); \
;     for (int m = 0; m < 4; ++m) for (int n = 0; n < 2; ++n) for (int k = 0; k < 2; ++k) \
;       acc[ai][bj][m][n] = __builtin_amdgcn_mfma_f32_16x16x32_bf16(At[m][k], Bt_[n][k], acc[ai][bj][m][n], 0, 0, 0); \
;     __builtin_amdgcn_s_setprio(0); } while (0)
; #define WAIT_L(n) asm volatile("s_waitcnt lgkmcnt(" #n ")" ::: "memory")
; #define BAR __builtin_amdgcn_s_barrier()
; #define SCHED __builtin_amdgcn_sched_barrier(0)
; __device__ __forceinline__ void gemm_main(acc_t& acc, const u16* A, int lda, const u16* Bt, int ldb, int nt, const int tidx) {
;     ...
;         LDB(B0, 0, 0); SCHED; LDA(At, 0, 0); STAGE(SA(1, 1), A, lda, HALF, t + 1);
;         WAIT_L(8); BAR; WAIT_L(0); MMA(0, 0, At, B0); BAR; SCHED;
;         LDB(B1, 0, 1); STAGE(SB(0, 0), Bt, ldb, 0, t + 2);
;         BAR; WAIT_L(0); MMA(0, 1, At, B1); BAR;
;         LDA(At, 0, 1); STAGE(SA(0, 0), A, lda, 0, t + 2);
;         BAR; WAIT_L(0); MMA(1, 0, At, B0); BAR; SCHED;
.LBB0_382:
	v_add_u32_e32 v170, v143, v132
	ds_read_b128 v[158:161], v170
	ds_read_b128 v[162:165], v170 offset:1024
	ds_read_b128 v[166:169], v170 offset:2048
	ds_read_b128 v[170:173], v170 offset:3072
	s_add_i32 s34, s20, 0x10040
	s_ashr_i32 s35, s34, 31
	s_lshl_b64 s[34:35], s[34:35], 1
	s_add_u32 s34, s10, s34
	v_add_u32_e32 v218, 0xc000, v135
	s_addc_u32 s35, s11, s35
	v_readfirstlane_b32 s21, v218
	v_add_u32_e32 v218, 0xe000, v135
	v_add_u32_e32 v192, v144, v140
	v_add_u32_e32 v193, v142, v139
	v_add_u32_e32 v234, v142, v137
	v_add_u32_e32 v235, v142, v138
	v_lshl_add_u64 v[190:191], s[34:35], 0, v[0:1]
	s_mov_b32 m0, s21
	v_readfirstlane_b32 s21, v218
	ds_read_b128 v[174:177], v192
	ds_read_b128 v[178:181], v192 offset:1024
	ds_read_b128 v[194:197], v193
	ds_read_b128 v[198:201], v193 offset:1024
	ds_read_b128 v[202:205], v234
	ds_read_b128 v[206:209], v234 offset:1024
	ds_read_b128 v[210:213], v235
	ds_read_b128 v[214:217], v235 offset:1024
	global_load_lds_dwordx4 v[190:191], off
	v_lshl_add_u64 v[190:191], s[34:35], 0, v[130:131]
	s_mov_b32 m0, s21
	s_nop 0
	global_load_lds_dwordx4 v[190:191], off
	s_waitcnt lgkmcnt(8)
	s_barrier
	s_waitcnt lgkmcnt(0)
	s_setprio 1
	v_mfma_f32_16x16x32_bf16 v[126:129], v[174:177], v[158:161], v[126:129]
	v_mfma_f32_16x16x32_bf16 v[122:125], v[174:177], v[166:169], v[122:125]
	v_mfma_f32_16x16x32_bf16 v[118:121], v[194:197], v[158:161], v[118:121]
	v_mfma_f32_16x16x32_bf16 v[114:117], v[194:197], v[166:169], v[114:117]
	v_mfma_f32_16x16x32_bf16 v[110:113], v[202:205], v[158:161], v[110:113]
	v_mfma_f32_16x16x32_bf16 v[106:109], v[202:205], v[166:169], v[106:109]
	v_mfma_f32_16x16x32_bf16 v[102:105], v[210:213], v[158:161], v[102:105]
	v_mfma_f32_16x16x32_bf16 v[98:101], v[210:213], v[166:169], v[98:101]
	v_mfma_f32_16x16x32_bf16 v[126:129], v[178:181], v[162:165], v[126:129]
	v_mfma_f32_16x16x32_bf16 v[122:125], v[178:181], v[170:173], v[122:125]
	v_mfma_f32_16x16x32_bf16 v[118:121], v[198:201], v[162:165], v[118:121]
	v_mfma_f32_16x16x32_bf16 v[114:117], v[198:201], v[170:173], v[114:117]
	v_mfma_f32_16x16x32_bf16 v[110:113], v[206:209], v[162:165], v[110:113]
	v_mfma_f32_16x16x32_bf16 v[106:109], v[206:209], v[170:173], v[106:109]
	v_mfma_f32_16x16x32_bf16 v[102:105], v[214:217], v[162:165], v[102:105]
	v_mfma_f32_16x16x32_bf16 v[98:101], v[214:217], v[170:173], v[98:101]
	s_setprio 0
	s_barrier
	s_add_i32 s72, s20, 0x80
	s_add_i32 s31, s31, 2
	s_lshl_b64 s[34:35], s[72:73], 1
	s_add_u32 s36, s14, s34
	v_add_u32_e32 v190, v136, v132
	s_addc_u32 s37, s15, s35
	v_readfirstlane_b32 s21, v145
	ds_read_b128 v[218:221], v190
	ds_read_b128 v[222:225], v190 offset:1024
	ds_read_b128 v[226:229], v190 offset:2048
	ds_read_b128 v[230:233], v190 offset:3072
	v_lshl_add_u64 v[190:191], s[36:37], 0, v[0:1]
	s_mov_b32 m0, s21
	v_readfirstlane_b32 s21, v146
	global_load_lds_dwordx4 v[190:191], off
	v_lshl_add_u64 v[190:191], s[36:37], 0, v[130:131]
	s_mov_b32 m0, s21
	s_nop 0
	global_load_lds_dwordx4 v[190:191], off
	s_barrier
	s_waitcnt lgkmcnt(0)
	s_setprio 1
	v_mfma_f32_16x16x32_bf16 v[94:97], v[174:177], v[218:221], v[94:97]
	v_mfma_f32_16x16x32_bf16 v[90:93], v[174:177], v[226:229], v[90:93]
	v_mfma_f32_16x16x32_bf16 v[86:89], v[194:197], v[218:221], v[86:89]
	v_mfma_f32_16x16x32_bf16 v[82:85], v[194:197], v[226:229], v[82:85]
	v_mfma_f32_16x16x32_bf16 v[78:81], v[202:205], v[218:221], v[78:81]
	v_mfma_f32_16x16x32_bf16 v[74:77], v[202:205], v[226:229], v[74:77]
	v_mfma_f32_16x16x32_bf16 v[70:73], v[210:213], v[218:221], v[70:73]
	v_mfma_f32_16x16x32_bf16 v[66:69], v[210:213], v[226:229], v[66:69]
	v_mfma_f32_16x16x32_bf16 v[94:97], v[178:181], v[222:225], v[94:97]
	v_mfma_f32_16x16x32_bf16 v[90:93], v[178:181], v[230:233], v[90:93]
	v_mfma_f32_16x16x32_bf16 v[86:89], v[198:201], v[222:225], v[86:89]
	v_mfma_f32_16x16x32_bf16 v[82:85], v[198:201], v[230:233], v[82:85]
	v_mfma_f32_16x16x32_bf16 v[78:81], v[206:209], v[222:225], v[78:81]
	v_mfma_f32_16x16x32_bf16 v[74:77], v[206:209], v[230:233], v[74:77]
	v_mfma_f32_16x16x32_bf16 v[70:73], v[214:217], v[222:225], v[70:73]
	v_mfma_f32_16x16x32_bf16 v[66:69], v[214:217], v[230:233], v[66:69]
	s_setprio 0
	s_add_u32 s34, s10, s34
	s_addc_u32 s35, s11, s35
	v_readfirstlane_b32 s21, v135
	v_lshl_add_u64 v[190:191], s[34:35], 0, v[0:1]
	s_mov_b32 m0, s21
	v_readfirstlane_b32 s21, v147
	s_barrier
	ds_read_b128 v[174:177], v192 offset:16384
	ds_read_b128 v[178:181], v192 offset:17408
	ds_read_b128 v[194:197], v193 offset:16384
	ds_read_b128 v[198:201], v193 offset:17408
	ds_read_b128 v[202:205], v234 offset:16384
	ds_read_b128 v[206:209], v234 offset:17408
	ds_read_b128 v[210:213], v235 offset:16384
	ds_read_b128 v[214:217], v235 offset:17408
	global_load_lds_dwordx4 v[190:191], off
	v_lshl_add_u64 v[190:191], s[34:35], 0, v[130:131]
	s_mov_b32 m0, s21
	s_nop 0
	global_load_lds_dwordx4 v[190:191], off
	s_barrier
	s_waitcnt lgkmcnt(0)
	s_setprio 1
	v_mfma_f32_16x16x32_bf16 v[62:65], v[174:177], v[158:161], v[62:65]
	v_mfma_f32_16x16x32_bf16 v[58:61], v[174:177], v[166:169], v[58:61]
	v_mfma_f32_16x16x32_bf16 v[54:57], v[194:197], v[158:161], v[54:57]
	v_mfma_f32_16x16x32_bf16 v[50:53], v[194:197], v[166:169], v[50:53]
	v_mfma_f32_16x16x32_bf16 v[46:49], v[202:205], v[158:161], v[46:49]
	v_mfma_f32_16x16x32_bf16 v[42:45], v[202:205], v[166:169], v[42:45]
	v_mfma_f32_16x16x32_bf16 v[38:41], v[210:213], v[158:161], v[38:41]
	v_mfma_f32_16x16x32_bf16 v[34:37], v[210:213], v[166:169], v[34:37]
	v_mfma_f32_16x16x32_bf16 v[62:65], v[178:181], v[162:165], v[62:65]
	v_mfma_f32_16x16x32_bf16 v[58:61], v[178:181], v[170:173], v[58:61]
	v_mfma_f32_16x16x32_bf16 v[54:57], v[198:201], v[162:165], v[54:57]
	v_mfma_f32_16x16x32_bf16 v[50:53], v[198:201], v[170:173], v[50:53]
	v_mfma_f32_16x16x32_bf16 v[46:49], v[206:209], v[162:165], v[46:49]
	v_mfma_f32_16x16x32_bf16 v[42:45], v[206:209], v[170:173], v[42:45]
	v_mfma_f32_16x16x32_bf16 v[38:41], v[214:217], v[162:165], v[38:41]
	v_mfma_f32_16x16x32_bf16 v[34:37], v[214:217], v[170:173], v[34:37]
	s_setprio 0
	s_barrier
; #define STAGE(P, BASE, LD, br, kt) do { const char* _gp = (const char*)((BASE) + (long)((br) * (LD) + (kt) * BK)); \
;     __builtin_amdgcn_global_load_lds((const unsigned*)(_gp + vo_##BASE##0), (unsigned*)((char*)(P) + tidx * 16), 16, 0, 0); \
;     __builtin_amdgcn_global_load_lds((const unsigned*)(_gp + vo_##BASE##1), (unsigned*)((char*)(P) + tidx * 16 + 8192), 16, 0, 0); } while (0)
; #define LDA(dst, b, h) for (int m = 0; m < 4; ++m) for (int k = 0; k < 2; ++k) \
;     dst[m][k] = *reinterpret_cast<const bf16x8*>((char*)SA(b, h) + lds_byte(wr * 64 + m * 16 + fr, k * 32 + fq * 8))
; #define LDB(dst, b, h) for (int n = 0; n < 2; ++n) for (int k = 0; k < 2; ++k) \
;     dst[n][k] = *reinterpret_cast<const bf16x8*>((char*)SB(b, h) + lds_byte(wc * 32 + n * 16 + fr, k * 32 + fq * 8))
; #define MMA(ai, bj, At, Bt_) do { __builtin_amdgcn_s_setprio(1); \
;     for (int m = 0; m < 4; ++m) for (int n = 0; n < 2; ++n) for (int k = 0; k < 2; ++k) \
;       acc[ai][bj][m][n] = __builtin_amdgcn_mfma_f32_16x16x32_bf16(At[m][k], Bt_[n][k], acc[ai][bj][m][n], 0, 0, 0); \
;     __builtin_amdgcn_s_setprio(0); } while (0)
; #define WAIT_V(n) asm volatile("s_waitcnt vmcnt(" #n ")" ::: "memory")
; #define WAIT_L(n) asm volatile("s_waitcnt lgkmcnt(" #n ")" ::: "memory")
; #define BAR __builtin_amdgcn_s_barrier()
; #define SCHED __builtin_amdgcn_sched_barrier(0)
; __device__ __forceinline__ void gemm_main(acc_t& acc, const u16* A, int lda, const u16* Bt, int ldb, int nt, const int tidx) {
;     ...
;         STAGE(SB(0, 1), Bt, ldb, HALF, t + 2);
;         WAIT_V(6); BAR; MMA(1, 1, At, B1); BAR;
;         LDB(B0, 1, 0); SCHED; LDA(At, 1, 0); STAGE(SA(0, 1), A, lda, HALF, t + 2);
;         WAIT_L(8); BAR; WAIT_L(0); MMA(0, 0, At, B0); BAR; SCHED;
;         LDB(B1, 1, 1); STAGE(SB(1, 0), Bt, ldb, 0, t + 3);
;         BAR; WAIT_L(0); MMA(0, 1, At, B1); BAR;
	s_ashr_i32 s35, s72, 31
	s_mov_b32 s34, s72
	s_lshl_b64 s[34:35], s[34:35], 1
	s_add_u32 s36, s18, s34
	s_addc_u32 s37, s19, s35
	v_readfirstlane_b32 s21, v148
	v_lshl_add_u64 v[158:159], s[36:37], 0, v[0:1]
	s_mov_b32 m0, s21
	v_readfirstlane_b32 s21, v149
	global_load_lds_dwordx4 v[158:159], off
	v_lshl_add_u64 v[158:159], s[36:37], 0, v[130:131]
	s_mov_b32 m0, s21
	s_nop 0
	global_load_lds_dwordx4 v[158:159], off
	s_waitcnt vmcnt(6)
	s_barrier
	s_setprio 1
	v_mfma_f32_16x16x32_bf16 v[30:33], v[174:177], v[218:221], v[30:33]
	v_mfma_f32_16x16x32_bf16 v[26:29], v[174:177], v[226:229], v[26:29]
	v_mfma_f32_16x16x32_bf16 v[22:25], v[194:197], v[218:221], v[22:25]
	v_mfma_f32_16x16x32_bf16 v[18:21], v[194:197], v[226:229], v[18:21]
	v_mfma_f32_16x16x32_bf16 v[14:17], v[202:205], v[218:221], v[14:17]
	v_mfma_f32_16x16x32_bf16 v[10:13], v[202:205], v[226:229], v[10:13]
	v_mfma_f32_16x16x32_bf16 v[6:9], v[210:213], v[218:221], v[6:9]
	v_mfma_f32_16x16x32_bf16 v[2:5], v[210:213], v[226:229], v[2:5]
	v_mfma_f32_16x16x32_bf16 v[30:33], v[178:181], v[222:225], v[30:33]
	v_mfma_f32_16x16x32_bf16 v[26:29], v[178:181], v[230:233], v[26:29]
	v_mfma_f32_16x16x32_bf16 v[22:25], v[198:201], v[222:225], v[22:25]
	v_mfma_f32_16x16x32_bf16 v[18:21], v[198:201], v[230:233], v[18:21]
	v_mfma_f32_16x16x32_bf16 v[14:17], v[206:209], v[222:225], v[14:17]
	v_mfma_f32_16x16x32_bf16 v[10:13], v[206:209], v[230:233], v[10:13]
	v_mfma_f32_16x16x32_bf16 v[6:9], v[214:217], v[222:225], v[6:9]
	v_mfma_f32_16x16x32_bf16 v[2:5], v[214:217], v[230:233], v[2:5]
	s_setprio 0
	v_add_u32_e32 v170, v134, v132
	s_barrier
	ds_read_b128 v[158:161], v170
	ds_read_b128 v[162:165], v170 offset:1024
	ds_read_b128 v[166:169], v170 offset:2048
	ds_read_b128 v[170:173], v170 offset:3072
	s_add_u32 s34, s12, s34
	s_addc_u32 s35, s13, s35
	v_readfirstlane_b32 s21, v150
	v_lshl_add_u64 v[190:191], s[34:35], 0, v[0:1]
	s_mov_b32 m0, s21
	v_readfirstlane_b32 s21, v151
	ds_read_b128 v[174:177], v192 offset:32768
	ds_read_b128 v[178:181], v192 offset:33792
	ds_read_b128 v[194:197], v193 offset:32768
	ds_read_b128 v[198:201], v193 offset:33792
	ds_read_b128 v[202:205], v234 offset:32768
	ds_read_b128 v[206:209], v234 offset:33792
	ds_read_b128 v[210:213], v235 offset:32768
	ds_read_b128 v[214:217], v235 offset:33792
	global_load_lds_dwordx4 v[190:191], off
	v_lshl_add_u64 v[190:191], s[34:35], 0, v[130:131]
	s_mov_b32 m0, s21
	s_nop 0
	global_load_lds_dwordx4 v[190:191], off
	s_waitcnt lgkmcnt(8)
	s_barrier
	s_waitcnt lgkmcnt(0)
	s_setprio 1
	v_mfma_f32_16x16x32_bf16 v[126:129], v[174:177], v[158:161], v[126:129]
	v_mfma_f32_16x16x32_bf16 v[122:125], v[174:177], v[166:169], v[122:125]
	v_mfma_f32_16x16x32_bf16 v[118:121], v[194:197], v[158:161], v[118:121]
	v_mfma_f32_16x16x32_bf16 v[114:117], v[194:197], v[166:169], v[114:117]
	v_mfma_f32_16x16x32_bf16 v[110:113], v[202:205], v[158:161], v[110:113]
	v_mfma_f32_16x16x32_bf16 v[106:109], v[202:205], v[166:169], v[106:109]
	v_mfma_f32_16x16x32_bf16 v[102:105], v[210:213], v[158:161], v[102:105]
	v_mfma_f32_16x16x32_bf16 v[98:101], v[210:213], v[166:169], v[98:101]
	v_mfma_f32_16x16x32_bf16 v[126:129], v[178:181], v[162:165], v[126:129]
	v_mfma_f32_16x16x32_bf16 v[122:125], v[178:181], v[170:173], v[122:125]
	v_mfma_f32_16x16x32_bf16 v[118:121], v[198:201], v[162:165], v[118:121]
	v_mfma_f32_16x16x32_bf16 v[114:117], v[198:201], v[170:173], v[114:117]
	v_mfma_f32_16x16x32_bf16 v[110:113], v[206:209], v[162:165], v[110:113]
	v_mfma_f32_16x16x32_bf16 v[106:109], v[206:209], v[170:173], v[106:109]
	v_mfma_f32_16x16x32_bf16 v[102:105], v[214:217], v[162:165], v[102:105]
	v_mfma_f32_16x16x32_bf16 v[98:101], v[214:217], v[170:173], v[98:101]
	s_setprio 0
	s_barrier
	s_ashr_i32 s21, s20, 31
	s_lshl_b64 s[34:35], s[20:21], 1
	s_add_u32 s36, s14, s34
	v_add_u32_e32 v190, v133, v132
	s_addc_u32 s37, s15, s35
	ds_read_b128 v[218:221], v190
	ds_read_b128 v[222:225], v190 offset:1024
	ds_read_b128 v[226:229], v190 offset:2048
	ds_read_b128 v[230:233], v190 offset:3072
	v_lshl_add_u64 v[190:191], s[36:37], 0, v[0:1]
	v_readfirstlane_b32 s21, v152
	v_lshl_add_u64 v[190:191], v[190:191], 0, s[0:1]
	s_mov_b32 m0, s21
	v_readfirstlane_b32 s21, v153
	global_load_lds_dwordx4 v[190:191], off
	v_lshl_add_u64 v[190:191], s[36:37], 0, v[130:131]
	v_lshl_add_u64 v[190:191], v[190:191], 0, s[0:1]
	s_mov_b32 m0, s21
	s_nop 0
	global_load_lds_dwordx4 v[190:191], off
	s_barrier
	s_waitcnt lgkmcnt(0)
	s_setprio 1
	v_mfma_f32_16x16x32_bf16 v[94:97], v[174:177], v[218:221], v[94:97]
	v_mfma_f32_16x16x32_bf16 v[90:93], v[174:177], v[226:229], v[90:93]
	v_mfma_f32_16x16x32_bf16 v[86:89], v[194:197], v[218:221], v[86:89]
	v_mfma_f32_16x16x32_bf16 v[82:85], v[194:197], v[226:229], v[82:85]
	v_mfma_f32_16x16x32_bf16 v[78:81], v[202:205], v[218:221], v[78:81]
	v_mfma_f32_16x16x32_bf16 v[74:77], v[202:205], v[226:229], v[74:77]
	v_mfma_f32_16x16x32_bf16 v[70:73], v[210:213], v[218:221], v[70:73]
	v_mfma_f32_16x16x32_bf16 v[66:69], v[210:213], v[226:229], v[66:69]
	v_mfma_f32_16x16x32_bf16 v[94:97], v[178:181], v[222:225], v[94:97]
	v_mfma_f32_16x16x32_bf16 v[90:93], v[178:181], v[230:233], v[90:93]
	v_mfma_f32_16x16x32_bf16 v[86:89], v[198:201], v[222:225], v[86:89]
	v_mfma_f32_16x16x32_bf16 v[82:85], v[198:201], v[230:233], v[82:85]
	v_mfma_f32_16x16x32_bf16 v[78:81], v[206:209], v[222:225], v[78:81]
	v_mfma_f32_16x16x32_bf16 v[74:77], v[206:209], v[230:233], v[74:77]
	v_mfma_f32_16x16x32_bf16 v[70:73], v[214:217], v[222:225], v[70:73]
	v_mfma_f32_16x16x32_bf16 v[66:69], v[214:217], v[230:233], v[66:69]
	s_setprio 0
	s_add_u32 s34, s10, s34
	s_addc_u32 s35, s11, s35
	v_lshl_add_u64 v[190:191], s[34:35], 0, v[0:1]
	v_readfirstlane_b32 s21, v154
	v_lshl_add_u64 v[190:191], v[190:191], 0, s[0:1]
	s_mov_b32 m0, s21
	s_barrier
; #define STAGE(P, BASE, LD, br, kt) do { const char* _gp = (const char*)((BASE) + (long)((br) * (LD) + (kt) * BK)); \
;     __builtin_amdgcn_global_load_lds((const unsigned*)(_gp + vo_##BASE##0), (unsigned*)((char*)(P) + tidx * 16), 16, 0, 0); \
;     __builtin_amdgcn_global_load_lds((const unsigned*)(_gp + vo_##BASE##1), (unsigned*)((char*)(P) + tidx * 16 + 8192), 16, 0, 0); } while (0)
; #define LDA(dst, b, h) for (int m = 0; m < 4; ++m) for (int k = 0; k < 2; ++k) \
;     dst[m][k] = *reinterpret_cast<const bf16x8*>((char*)SA(b, h) + lds_byte(wr * 64 + m * 16 + fr, k * 32 + fq * 8))
; #define LDB(dst, b, h) for (int n = 0; n < 2; ++n) for (int k = 0; k < 2; ++k) \
;     dst[n][k] = *reinterpret_cast<const bf16x8*>((char*)SB(b, h) + lds_byte(wc * 32 + n * 16 + fr, k * 32 + fq * 8))
; #define MMA(ai, bj, At, Bt_) do { __builtin_amdgcn_s_setprio(1); \
;     for (int m = 0; m < 4; ++m) for (int n = 0; n < 2; ++n) for (int k = 0; k < 2; ++k) \
;       acc[ai][bj][m][n] = __builtin_amdgcn_mfma_f32_16x16x32_bf16(At[m][k], Bt_[n][k], acc[ai][bj][m][n], 0, 0, 0); \
;     __builtin_amdgcn_s_setprio(0); } while (0)
; #define WAIT_V(n) asm volatile("s_waitcnt vmcnt(" #n ")" ::: "memory")
; #define WAIT_L(n) asm volatile("s_waitcnt lgkmcnt(" #n ")" ::: "memory")
; #define BAR __builtin_amdgcn_s_barrier()
; #define SCHED __builtin_amdgcn_sched_barrier(0)
; __device__ __forceinline__ void gemm_main(acc_t& acc, const u16* A, int lda, const u16* Bt, int ldb, int nt, const int tidx) {
;     ...
;         LDA(At, 1, 1); STAGE(SA(1, 0), A, lda, 0, t + 3);
;         BAR; WAIT_L(0); MMA(1, 0, At, B0); BAR; SCHED;
;         STAGE(SB(1, 1), Bt, ldb, HALF, t + 3);
;         WAIT_V(6); BAR; MMA(1, 1, At, B1); BAR;
;     }
;     { LDB(B0, 0, 0); LDA(At, 0, 0); STAGE(SA(1, 1), A, lda, HALF, nt - 1);
;       BAR; WAIT_L(0); MMA(0, 0, At, B0); BAR;
	ds_read_b128 v[174:177], v192 offset:49152
	ds_read_b128 v[178:181], v192 offset:50176
	ds_read_b128 v[194:197], v193 offset:49152
	ds_read_b128 v[198:201], v193 offset:50176
	ds_read_b128 v[202:205], v234 offset:49152
	ds_read_b128 v[206:209], v234 offset:50176
	ds_read_b128 v[210:213], v235 offset:49152
	ds_read_b128 v[214:217], v235 offset:50176
	global_load_lds_dwordx4 v[190:191], off
	v_lshl_add_u64 v[190:191], s[34:35], 0, v[130:131]
	v_readfirstlane_b32 s21, v155
	v_lshl_add_u64 v[190:191], v[190:191], 0, s[0:1]
	s_mov_b32 m0, s21
	s_nop 0
	global_load_lds_dwordx4 v[190:191], off
	s_barrier
	s_waitcnt lgkmcnt(0)
	s_setprio 1
	v_mfma_f32_16x16x32_bf16 v[62:65], v[174:177], v[158:161], v[62:65]
	v_mfma_f32_16x16x32_bf16 v[58:61], v[174:177], v[166:169], v[58:61]
	v_mfma_f32_16x16x32_bf16 v[54:57], v[194:197], v[158:161], v[54:57]
	v_mfma_f32_16x16x32_bf16 v[50:53], v[194:197], v[166:169], v[50:53]
	v_mfma_f32_16x16x32_bf16 v[46:49], v[202:205], v[158:161], v[46:49]
	v_mfma_f32_16x16x32_bf16 v[42:45], v[202:205], v[166:169], v[42:45]
	v_mfma_f32_16x16x32_bf16 v[38:41], v[210:213], v[158:161], v[38:41]
	v_mfma_f32_16x16x32_bf16 v[34:37], v[210:213], v[166:169], v[34:37]
	v_mfma_f32_16x16x32_bf16 v[62:65], v[178:181], v[162:165], v[62:65]
	v_mfma_f32_16x16x32_bf16 v[58:61], v[178:181], v[170:173], v[58:61]
	v_mfma_f32_16x16x32_bf16 v[54:57], v[198:201], v[162:165], v[54:57]
	v_mfma_f32_16x16x32_bf16 v[50:53], v[198:201], v[170:173], v[50:53]
	v_mfma_f32_16x16x32_bf16 v[46:49], v[206:209], v[162:165], v[46:49]
	v_mfma_f32_16x16x32_bf16 v[42:45], v[206:209], v[170:173], v[42:45]
	v_mfma_f32_16x16x32_bf16 v[38:41], v[214:217], v[162:165], v[38:41]
	v_mfma_f32_16x16x32_bf16 v[34:37], v[214:217], v[170:173], v[34:37]
	s_setprio 0
	s_barrier
	s_add_i32 s20, s20, 0x100c0
	s_ashr_i32 s21, s20, 31
	s_lshl_b64 s[20:21], s[20:21], 1
	s_add_u32 s20, s14, s20
	s_addc_u32 s21, s15, s21
	v_readfirstlane_b32 s33, v156
	v_lshl_add_u64 v[158:159], s[20:21], 0, v[0:1]
	s_mov_b32 m0, s33
	s_nop 0
	global_load_lds_dwordx4 v[158:159], off
	v_lshl_add_u64 v[158:159], s[20:21], 0, v[130:131]
	v_readfirstlane_b32 s20, v157
	s_mov_b32 m0, s20
	s_nop 0
	global_load_lds_dwordx4 v[158:159], off
	s_waitcnt vmcnt(6)
	s_barrier
	s_setprio 1
	v_mfma_f32_16x16x32_bf16 v[30:33], v[174:177], v[218:221], v[30:33]
	v_mfma_f32_16x16x32_bf16 v[26:29], v[174:177], v[226:229], v[26:29]
	v_mfma_f32_16x16x32_bf16 v[22:25], v[194:197], v[218:221], v[22:25]
	v_mfma_f32_16x16x32_bf16 v[18:21], v[194:197], v[226:229], v[18:21]
	v_mfma_f32_16x16x32_bf16 v[14:17], v[202:205], v[218:221], v[14:17]
	v_mfma_f32_16x16x32_bf16 v[10:13], v[202:205], v[226:229], v[10:13]
	v_mfma_f32_16x16x32_bf16 v[6:9], v[210:213], v[218:221], v[6:9]
	v_mfma_f32_16x16x32_bf16 v[2:5], v[210:213], v[226:229], v[2:5]
	v_mfma_f32_16x16x32_bf16 v[30:33], v[178:181], v[222:225], v[30:33]
	v_mfma_f32_16x16x32_bf16 v[26:29], v[178:181], v[230:233], v[26:29]
	v_mfma_f32_16x16x32_bf16 v[22:25], v[198:201], v[222:225], v[22:25]
	v_mfma_f32_16x16x32_bf16 v[18:21], v[198:201], v[230:233], v[18:21]
	v_mfma_f32_16x16x32_bf16 v[14:17], v[206:209], v[222:225], v[14:17]
	v_mfma_f32_16x16x32_bf16 v[10:13], v[206:209], v[230:233], v[10:13]
	v_mfma_f32_16x16x32_bf16 v[6:9], v[214:217], v[222:225], v[6:9]
	v_mfma_f32_16x16x32_bf16 v[2:5], v[214:217], v[230:233], v[2:5]
	s_setprio 0
	s_cmp_lt_i32 s31, s30
	s_mov_b32 s20, s72
	s_barrier
	s_cbranch_scc1 .LBB0_382
.LBB0_383:
	s_lshl_b32 s5, s5, 6
	s_add_i32 s12, s5, 0xffc0
	s_ashr_i32 s13, s12, 31
	s_lshl_b64 s[12:13], s[12:13], 1
	s_add_u32 s10, s10, s12
	s_addc_u32 s11, s11, s13
	v_add_u32_e32 v193, v142, v137
	v_add_u32_e32 v137, 0xc000, v135
	v_lshl_add_u64 v[190:191], s[10:11], 0, v[0:1]
	v_add_u32_e32 v0, v143, v132
	v_readfirstlane_b32 s5, v137
	v_add_u32_e32 v135, 0xe000, v135
	ds_read_b128 v[146:149], v0
	ds_read_b128 v[150:153], v0 offset:1024
	ds_read_b128 v[154:157], v0 offset:2048
	ds_read_b128 v[158:161], v0 offset:3072
	v_add_u32_e32 v0, v144, v140
	v_add_u32_e32 v192, v142, v139
	v_add_u32_e32 v234, v142, v138
	s_mov_b32 m0, s5
	v_readfirstlane_b32 s5, v135
	v_lshl_add_u64 v[130:131], s[10:11], 0, v[130:131]
	v_cmp_gt_u32_e32 vcc, s51, v141
	ds_read_b128 v[162:165], v0
	ds_read_b128 v[166:169], v0 offset:1024
	ds_read_b128 v[170:173], v192
	ds_read_b128 v[174:177], v192 offset:1024
	ds_read_b128 v[178:181], v193
	ds_read_b128 v[194:197], v193 offset:1024
	ds_read_b128 v[138:141], v234
	ds_read_b128 v[142:145], v234 offset:1024
	global_load_lds_dwordx4 v[190:191], off
	s_mov_b32 m0, s5
	s_nop 0
	global_load_lds_dwordx4 v[130:131], off
	s_barrier
	s_waitcnt lgkmcnt(0)
	s_setprio 1
	v_mfma_f32_16x16x32_bf16 v[126:129], v[162:165], v[146:149], v[126:129]
	v_mfma_f32_16x16x32_bf16 v[122:125], v[162:165], v[154:157], v[122:125]
	v_mfma_f32_16x16x32_bf16 v[110:113], v[178:181], v[146:149], v[110:113]
	v_mfma_f32_16x16x32_bf16 v[106:109], v[178:181], v[154:157], v[106:109]
	v_mfma_f32_16x16x32_bf16 v[126:129], v[166:169], v[150:153], v[126:129]
	v_mfma_f32_16x16x32_bf16 v[122:125], v[166:169], v[158:161], v[122:125]
	v_mfma_f32_16x16x32_bf16 v[118:121], v[170:173], v[146:149], v[118:121]
	v_mfma_f32_16x16x32_bf16 v[114:117], v[170:173], v[154:157], v[114:117]
	v_mfma_f32_16x16x32_bf16 v[110:113], v[194:197], v[150:153], v[110:113]
	v_mfma_f32_16x16x32_bf16 v[106:109], v[194:197], v[158:161], v[106:109]
	v_mfma_f32_16x16x32_bf16 v[102:105], v[138:141], v[146:149], v[102:105]
	v_mfma_f32_16x16x32_bf16 v[98:101], v[138:141], v[154:157], v[98:101]
	v_mfma_f32_16x16x32_bf16 v[198:201], v[174:177], v[150:153], v[118:121]
	v_mfma_f32_16x16x32_bf16 v[202:205], v[174:177], v[158:161], v[114:117]
	v_mfma_f32_16x16x32_bf16 v[206:209], v[142:145], v[150:153], v[102:105]
	v_mfma_f32_16x16x32_bf16 v[210:213], v[142:145], v[158:161], v[98:101]
	s_setprio 0
	v_add_u32_e32 v118, v136, v132
	s_barrier
; #define LDA(dst, b, h) for (int m = 0; m < 4; ++m) for (int k = 0; k < 2; ++k) \
;     dst[m][k] = *reinterpret_cast<const bf16x8*>((char*)SA(b, h) + lds_byte(wr * 64 + m * 16 + fr, k * 32 + fq * 8))
; #define LDB(dst, b, h) for (int n = 0; n < 2; ++n) for (int k = 0; k < 2; ++k) \
;     dst[n][k] = *reinterpret_cast<const bf16x8*>((char*)SB(b, h) + lds_byte(wc * 32 + n * 16 + fr, k * 32 + fq * 8))
; #define MMA(ai, bj, At, Bt_) do { __builtin_amdgcn_s_setprio(1); \
;     for (int m = 0; m < 4; ++m) for (int n = 0; n < 2; ++n) for (int k = 0; k < 2; ++k) \
;       acc[ai][bj][m][n] = __builtin_amdgcn_mfma_f32_16x16x32_bf16(At[m][k], Bt_[n][k], acc[ai][bj][m][n], 0, 0, 0); \
;     __builtin_amdgcn_s_setprio(0); } while (0)
; #define WAIT_V(n) asm volatile("s_waitcnt vmcnt(" #n ")" ::: "memory")
; #define WAIT_L(n) asm volatile("s_waitcnt lgkmcnt(" #n ")" ::: "memory")
; #define BAR __builtin_amdgcn_s_barrier()
; __device__ __forceinline__ void gemm_main(acc_t& acc, const u16* A, int lda, const u16* Bt, int ldb, int nt, const int tidx) {
;     ...
;       LDB(B1, 0, 1); BAR; WAIT_L(0); MMA(0, 1, At, B1); BAR;
;       LDA(At, 0, 1); WAIT_V(4); BAR; WAIT_L(0); MMA(1, 0, At, B0); MMA(1, 1, At, B1); BAR; }
;     { LDB(B0, 1, 0); LDA(At, 1, 0); WAIT_V(2); BAR; WAIT_L(0); MMA(0, 0, At, B0); BAR;
	s_nop 0
	ds_read_b128 v[98:101], v118
	ds_read_b128 v[102:105], v118 offset:1024
	ds_read_b128 v[114:117], v118 offset:2048
	ds_read_b128 v[118:121], v118 offset:3072
	s_barrier
	s_waitcnt lgkmcnt(0)
	s_setprio 1
	v_mfma_f32_16x16x32_bf16 v[94:97], v[162:165], v[98:101], v[94:97]
	v_mfma_f32_16x16x32_bf16 v[90:93], v[162:165], v[114:117], v[90:93]
	v_mfma_f32_16x16x32_bf16 v[78:81], v[178:181], v[98:101], v[78:81]
	v_mfma_f32_16x16x32_bf16 v[74:77], v[178:181], v[114:117], v[74:77]
	v_mfma_f32_16x16x32_bf16 v[70:73], v[138:141], v[98:101], v[70:73]
	v_mfma_f32_16x16x32_bf16 v[66:69], v[138:141], v[114:117], v[66:69]
	v_mfma_f32_16x16x32_bf16 v[94:97], v[166:169], v[102:105], v[94:97]
	v_mfma_f32_16x16x32_bf16 v[90:93], v[166:169], v[118:121], v[90:93]
	v_mfma_f32_16x16x32_bf16 v[86:89], v[170:173], v[98:101], v[86:89]
	v_mfma_f32_16x16x32_bf16 v[82:85], v[170:173], v[114:117], v[82:85]
	v_mfma_f32_16x16x32_bf16 v[78:81], v[194:197], v[102:105], v[78:81]
	v_mfma_f32_16x16x32_bf16 v[74:77], v[194:197], v[118:121], v[74:77]
	v_mfma_f32_16x16x32_bf16 v[70:73], v[142:145], v[102:105], v[70:73]
	v_mfma_f32_16x16x32_bf16 v[66:69], v[142:145], v[118:121], v[66:69]
	v_mfma_f32_16x16x32_bf16 v[162:165], v[174:177], v[102:105], v[86:89]
	v_mfma_f32_16x16x32_bf16 v[166:169], v[174:177], v[118:121], v[82:85]
	s_setprio 0
	s_barrier
	s_nop 0
	ds_read_b128 v[82:85], v0 offset:16384
	ds_read_b128 v[86:89], v0 offset:17408
	ds_read_b128 v[136:139], v192 offset:16384
	ds_read_b128 v[140:143], v192 offset:17408
	ds_read_b128 v[170:173], v193 offset:16384
	ds_read_b128 v[174:177], v193 offset:17408
	ds_read_b128 v[178:181], v234 offset:16384
	ds_read_b128 v[194:197], v234 offset:17408
	s_waitcnt vmcnt(4)
	s_barrier
	s_waitcnt lgkmcnt(0)
	s_setprio 1
	v_mfma_f32_16x16x32_bf16 v[58:61], v[82:85], v[154:157], v[58:61]
	v_mfma_f32_16x16x32_bf16 v[46:49], v[170:173], v[146:149], v[46:49]
	v_mfma_f32_16x16x32_bf16 v[34:37], v[178:181], v[154:157], v[34:37]
	v_mfma_f32_16x16x32_bf16 v[62:65], v[82:85], v[146:149], v[62:65]
	v_mfma_f32_16x16x32_bf16 v[58:61], v[86:89], v[158:161], v[58:61]
	v_mfma_f32_16x16x32_bf16 v[54:57], v[136:139], v[146:149], v[54:57]
	v_mfma_f32_16x16x32_bf16 v[50:53], v[136:139], v[154:157], v[50:53]
	v_mfma_f32_16x16x32_bf16 v[46:49], v[174:177], v[150:153], v[46:49]
	v_mfma_f32_16x16x32_bf16 v[42:45], v[170:173], v[154:157], v[42:45]
	v_mfma_f32_16x16x32_bf16 v[38:41], v[178:181], v[146:149], v[38:41]
	v_mfma_f32_16x16x32_bf16 v[34:37], v[194:197], v[158:161], v[34:37]
	v_mfma_f32_16x16x32_bf16 v[214:217], v[86:89], v[150:153], v[62:65]
	v_mfma_f32_16x16x32_bf16 v[218:221], v[140:143], v[150:153], v[54:57]
	v_mfma_f32_16x16x32_bf16 v[222:225], v[140:143], v[158:161], v[50:53]
	v_mfma_f32_16x16x32_bf16 v[226:229], v[174:177], v[158:161], v[42:45]
	v_mfma_f32_16x16x32_bf16 v[144:147], v[194:197], v[150:153], v[38:41]
	s_setprio 0
	s_setprio 1
	v_mfma_f32_16x16x32_bf16 v[30:33], v[82:85], v[98:101], v[30:33]
	v_mfma_f32_16x16x32_bf16 v[22:25], v[136:139], v[98:101], v[22:25]
	v_mfma_f32_16x16x32_bf16 v[14:17], v[170:173], v[98:101], v[14:17]
	v_mfma_f32_16x16x32_bf16 v[2:5], v[178:181], v[114:117], v[2:5]
	v_mfma_f32_16x16x32_bf16 v[30:33], v[86:89], v[102:105], v[30:33]
	v_mfma_f32_16x16x32_bf16 v[26:29], v[82:85], v[114:117], v[26:29]
	v_mfma_f32_16x16x32_bf16 v[22:25], v[140:143], v[102:105], v[22:25]
	v_mfma_f32_16x16x32_bf16 v[18:21], v[136:139], v[114:117], v[18:21]
	v_mfma_f32_16x16x32_bf16 v[14:17], v[174:177], v[102:105], v[14:17]
	v_mfma_f32_16x16x32_bf16 v[10:13], v[170:173], v[114:117], v[10:13]
	v_mfma_f32_16x16x32_bf16 v[6:9], v[178:181], v[98:101], v[6:9]
	v_mfma_f32_16x16x32_bf16 v[2:5], v[194:197], v[118:121], v[2:5]
	v_mfma_f32_16x16x32_bf16 v[148:151], v[86:89], v[118:121], v[26:29]
	v_mfma_f32_16x16x32_bf16 v[136:139], v[140:143], v[118:121], v[18:21]
	v_mfma_f32_16x16x32_bf16 v[140:143], v[174:177], v[118:121], v[10:13]
	v_mfma_f32_16x16x32_bf16 v[152:155], v[194:197], v[102:105], v[6:9]
	s_setprio 0
	v_add_u32_e32 v18, v134, v132
	s_barrier
	ds_read_b128 v[6:9], v18
	ds_read_b128 v[10:13], v18 offset:1024
	ds_read_b128 v[156:159], v18 offset:2048
	ds_read_b128 v[170:173], v18 offset:3072
	ds_read_b128 v[18:21], v0 offset:32768
	ds_read_b128 v[26:29], v0 offset:33792
	ds_read_b128 v[38:41], v192 offset:32768
	ds_read_b128 v[42:45], v192 offset:33792
	ds_read_b128 v[54:57], v193 offset:32768
	ds_read_b128 v[174:177], v193 offset:33792
	ds_read_b128 v[178:181], v234 offset:32768
	ds_read_b128 v[194:197], v234 offset:33792
	s_waitcnt vmcnt(2)
	s_barrier
; #define LDA(dst, b, h) for (int m = 0; m < 4; ++m) for (int k = 0; k < 2; ++k) \
;     dst[m][k] = *reinterpret_cast<const bf16x8*>((char*)SA(b, h) + lds_byte(wr * 64 + m * 16 + fr, k * 32 + fq * 8))
; #define LDB(dst, b, h) for (int n = 0; n < 2; ++n) for (int k = 0; k < 2; ++k) \
;     dst[n][k] = *reinterpret_cast<const bf16x8*>((char*)SB(b, h) + lds_byte(wc * 32 + n * 16 + fr, k * 32 + fq * 8))
; #define MMA(ai, bj, At, Bt_) do { __builtin_amdgcn_s_setprio(1); \
;     for (int m = 0; m < 4; ++m) for (int n = 0; n < 2; ++n) for (int k = 0; k < 2; ++k) \
;       acc[ai][bj][m][n] = __builtin_amdgcn_mfma_f32_16x16x32_bf16(At[m][k], Bt_[n][k], acc[ai][bj][m][n], 0, 0, 0); \
;     __builtin_amdgcn_s_setprio(0); } while (0)
; #define WAIT_V(n) asm volatile("s_waitcnt vmcnt(" #n ")" ::: "memory")
; #define WAIT_L(n) asm volatile("s_waitcnt lgkmcnt(" #n ")" ::: "memory")
; #define BAR __builtin_amdgcn_s_barrier()
; __device__ __forceinline__ void gemm_main(acc_t& acc, const u16* A, int lda, const u16* Bt, int ldb, int nt, const int tidx) {
;     ...
;     { LDB(B0, 1, 0); LDA(At, 1, 0); WAIT_V(2); BAR; WAIT_L(0); MMA(0, 0, At, B0); BAR;
;       LDB(B1, 1, 1); WAIT_V(0); BAR; WAIT_L(0); MMA(0, 1, At, B1); BAR;
;       LDA(At, 1, 1); BAR; WAIT_L(0); MMA(1, 0, At, B0); MMA(1, 1, At, B1); BAR; }
;     if (wr == 0) BAR;
	s_waitcnt lgkmcnt(0)
	s_setprio 1
	v_mfma_f32_16x16x32_bf16 v[50:53], v[18:21], v[6:9], v[126:129]
	v_mfma_f32_16x16x32_bf16 v[118:121], v[26:29], v[10:13], v[50:53]
	v_mfma_f32_16x16x32_bf16 v[50:53], v[18:21], v[156:159], v[122:125]
	v_mfma_f32_16x16x32_bf16 v[114:117], v[26:29], v[170:173], v[50:53]
	v_mfma_f32_16x16x32_bf16 v[50:53], v[38:41], v[6:9], v[198:201]
	v_mfma_f32_16x16x32_bf16 v[102:105], v[42:45], v[10:13], v[50:53]
	v_mfma_f32_16x16x32_bf16 v[50:53], v[38:41], v[156:159], v[202:205]
	v_mfma_f32_16x16x32_bf16 v[98:101], v[42:45], v[170:173], v[50:53]
	v_mfma_f32_16x16x32_bf16 v[50:53], v[54:57], v[6:9], v[110:113]
	v_mfma_f32_16x16x32_bf16 v[86:89], v[174:177], v[10:13], v[50:53]
	v_mfma_f32_16x16x32_bf16 v[50:53], v[54:57], v[156:159], v[106:109]
	v_mfma_f32_16x16x32_bf16 v[82:85], v[174:177], v[170:173], v[50:53]
	v_mfma_f32_16x16x32_bf16 v[50:53], v[178:181], v[6:9], v[206:209]
	v_mfma_f32_16x16x32_bf16 v[62:65], v[194:197], v[10:13], v[50:53]
	v_mfma_f32_16x16x32_bf16 v[50:53], v[178:181], v[156:159], v[210:213]
	v_mfma_f32_16x16x32_bf16 v[50:53], v[194:197], v[170:173], v[50:53]
	s_setprio 0
	v_add_u32_e32 v106, v133, v132
	s_barrier
	ds_read_b128 v[130:133], v106
	ds_read_b128 v[198:201], v106 offset:1024
	ds_read_b128 v[202:205], v106 offset:2048
	ds_read_b128 v[206:209], v106 offset:3072
	s_waitcnt vmcnt(0)
	s_barrier
	s_waitcnt lgkmcnt(0)
	s_setprio 1
	v_mfma_f32_16x16x32_bf16 v[94:97], v[18:21], v[130:133], v[94:97]
	v_mfma_f32_16x16x32_bf16 v[18:21], v[18:21], v[202:205], v[90:93]
	v_mfma_f32_16x16x32_bf16 v[122:125], v[26:29], v[206:209], v[18:21]
	v_mfma_f32_16x16x32_bf16 v[18:21], v[38:41], v[130:133], v[162:165]
	v_mfma_f32_16x16x32_bf16 v[110:113], v[42:45], v[198:201], v[18:21]
	v_mfma_f32_16x16x32_bf16 v[18:21], v[38:41], v[202:205], v[166:169]
	v_mfma_f32_16x16x32_bf16 v[106:109], v[42:45], v[206:209], v[18:21]
	v_mfma_f32_16x16x32_bf16 v[18:21], v[54:57], v[130:133], v[78:81]
	v_mfma_f32_16x16x32_bf16 v[126:129], v[26:29], v[198:201], v[94:97]
	v_mfma_f32_16x16x32_bf16 v[94:97], v[174:177], v[198:201], v[18:21]
	v_mfma_f32_16x16x32_bf16 v[18:21], v[54:57], v[202:205], v[74:77]
	v_mfma_f32_16x16x32_bf16 v[90:93], v[174:177], v[206:209], v[18:21]
	v_mfma_f32_16x16x32_bf16 v[18:21], v[178:181], v[130:133], v[70:73]
	v_mfma_f32_16x16x32_bf16 v[78:81], v[194:197], v[198:201], v[18:21]
	v_mfma_f32_16x16x32_bf16 v[18:21], v[178:181], v[202:205], v[66:69]
	v_mfma_f32_16x16x32_bf16 v[66:69], v[194:197], v[206:209], v[18:21]
	s_setprio 0
	s_barrier
	ds_read_b128 v[160:163], v0 offset:49152
	ds_read_b128 v[164:167], v0 offset:50176
	ds_read_b128 v[174:177], v192 offset:49152
	ds_read_b128 v[178:181], v192 offset:50176
	ds_read_b128 v[194:197], v193 offset:49152
	ds_read_b128 v[210:213], v193 offset:50176
	ds_read_b128 v[230:233], v234 offset:49152
	ds_read_b128 v[234:237], v234 offset:50176
	s_barrier
	s_waitcnt lgkmcnt(0)
	s_setprio 1
	v_mfma_f32_16x16x32_bf16 v[18:21], v[160:163], v[6:9], v[214:217]
	v_mfma_f32_16x16x32_bf16 v[70:73], v[164:167], v[10:13], v[18:21]
	v_mfma_f32_16x16x32_bf16 v[18:21], v[160:163], v[156:159], v[58:61]
	v_mfma_f32_16x16x32_bf16 v[54:57], v[164:167], v[170:173], v[18:21]
	v_mfma_f32_16x16x32_bf16 v[18:21], v[174:177], v[6:9], v[218:221]
	v_mfma_f32_16x16x32_bf16 v[42:45], v[178:181], v[10:13], v[18:21]
	v_mfma_f32_16x16x32_bf16 v[18:21], v[174:177], v[156:159], v[222:225]
	v_mfma_f32_16x16x32_bf16 v[38:41], v[178:181], v[170:173], v[18:21]
	v_mfma_f32_16x16x32_bf16 v[18:21], v[194:197], v[6:9], v[46:49]
	v_mfma_f32_16x16x32_bf16 v[6:9], v[230:233], v[6:9], v[144:147]
	v_mfma_f32_16x16x32_bf16 v[26:29], v[210:213], v[10:13], v[18:21]
	v_mfma_f32_16x16x32_bf16 v[18:21], v[194:197], v[156:159], v[226:229]
	v_mfma_f32_16x16x32_bf16 v[10:13], v[234:237], v[10:13], v[6:9]
	v_mfma_f32_16x16x32_bf16 v[6:9], v[230:233], v[156:159], v[34:37]
	v_mfma_f32_16x16x32_bf16 v[18:21], v[210:213], v[170:173], v[18:21]
	v_mfma_f32_16x16x32_bf16 v[6:9], v[234:237], v[170:173], v[6:9]
	s_setprio 0
	s_setprio 1
	v_mfma_f32_16x16x32_bf16 v[30:33], v[160:163], v[130:133], v[30:33]
	v_mfma_f32_16x16x32_bf16 v[74:77], v[164:167], v[198:201], v[30:33]
	v_mfma_f32_16x16x32_bf16 v[30:33], v[160:163], v[202:205], v[148:151]
	v_mfma_f32_16x16x32_bf16 v[22:25], v[174:177], v[130:133], v[22:25]
	v_mfma_f32_16x16x32_bf16 v[14:17], v[194:197], v[130:133], v[14:17]
	v_mfma_f32_16x16x32_bf16 v[58:61], v[164:167], v[206:209], v[30:33]
	v_mfma_f32_16x16x32_bf16 v[46:49], v[178:181], v[198:201], v[22:25]
	v_mfma_f32_16x16x32_bf16 v[22:25], v[174:177], v[202:205], v[136:139]
	v_mfma_f32_16x16x32_bf16 v[30:33], v[210:213], v[198:201], v[14:17]
	v_mfma_f32_16x16x32_bf16 v[14:17], v[194:197], v[202:205], v[140:143]
	v_mfma_f32_16x16x32_bf16 v[34:37], v[178:181], v[206:209], v[22:25]
	v_mfma_f32_16x16x32_bf16 v[22:25], v[210:213], v[206:209], v[14:17]
	v_mfma_f32_16x16x32_bf16 v[14:17], v[230:233], v[130:133], v[152:155]
	v_mfma_f32_16x16x32_bf16 v[2:5], v[230:233], v[202:205], v[2:5]
	v_mfma_f32_16x16x32_bf16 v[14:17], v[234:237], v[198:201], v[14:17]
	v_mfma_f32_16x16x32_bf16 v[2:5], v[234:237], v[206:209], v[2:5]
	s_setprio 0
	s_barrier
	s_and_saveexec_b64 s[10:11], vcc
	s_cbranch_execz .LBB0_385
	s_barrier

; #define STAGE(P, BASE, LD, br, kt) do { const char* _gp = (const char*)((BASE) + (long)((br) * (LD) + (kt) * BK)); \
;     __builtin_amdgcn_global_load_lds((const unsigned*)(_gp + vo_##BASE##0), (unsigned*)((char*)(P) + tidx * 16), 16, 0, 0); \
;     __builtin_amdgcn_global_load_lds((const unsigned*)(_gp + vo_##BASE##1), (unsigned*)((char*)(P) + tidx * 16 + 8192), 16, 0, 0); } while (0)
; #define LDA(dst, b, h) for (int m = 0; m < 4; ++m) for (int k = 0; k < 2; ++k) \
;     dst[m][k] = *reinterpret_cast<const bf16x8*>((char*)SA(b, h) + lds_byte(wr * 64 + m * 16 + fr, k * 32 + fq * 8))
; #define LDB(dst, b, h) for (int n = 0; n < 2; ++n) for (int k = 0; k < 2; ++k) \
;     dst[n][k] = *reinterpret_cast<const bf16x8*>((char*)SB(b, h) + lds_byte(wc * 32 + n * 16 + fr, k * 32 + fq * 8))
; #define MMA(ai, bj, At, Bt_) do { __builtin_amdgcn_s_setprio(1); \
;     for (int m = 0; m < 4; ++m) for (int n = 0; n < 2; ++n) for (int k = 0; k < 2; ++k) \
;       acc[ai][bj][m][n] = __builtin_amdgcn_mfma_f32_16x16x32_bf16(At[m][k], Bt_[n][k], acc[ai][bj][m][n], 0, 0, 0); \
;     __builtin_amdgcn_s_setprio(0); } while (0)
; #define WAIT_L(n) asm volatile("s_waitcnt lgkmcnt(" #n ")" ::: "memory")
; #define BAR __builtin_amdgcn_s_barrier()
; #define SCHED __builtin_amdgcn_sched_barrier(0)
; __device__ __forceinline__ void gemm_main(acc_t& acc, const u16* A, int lda, const u16* Bt, int ldb, int nt, const int tidx) {
;     ...
;         LDB(B0, 0, 0); SCHED; LDA(At, 0, 0); STAGE(SA(1, 1), A, lda, HALF, t + 1);
;         WAIT_L(8); BAR; WAIT_L(0); MMA(0, 0, At, B0); BAR; SCHED;
;         LDB(B1, 0, 1); STAGE(SB(0, 0), Bt, ldb, 0, t + 2);
;         BAR; WAIT_L(0); MMA(0, 1, At, B1); BAR;
;         LDA(At, 0, 1); STAGE(SA(0, 0), A, lda, 0, t + 2);
;         BAR; WAIT_L(0); MMA(1, 0, At, B0); BAR; SCHED;
.LBB0_588:
	v_add_u32_e32 v0, v156, v146
	ds_read_b128 v[172:175], v0
	ds_read_b128 v[176:179], v0 offset:1024
	ds_read_b128 v[194:197], v0 offset:2048
	ds_read_b128 v[198:201], v0 offset:3072
	v_add_u32_e32 v0, s2, v136
	v_add_u32_e32 v180, 64, v0
	v_ashrrev_i32_e32 v181, 31, v180
	v_add_u32_e32 v143, 0xc000, v149
	v_lshl_add_u64 v[180:181], v[180:181], 1, v[130:131]
	v_readfirstlane_b32 s3, v143
	v_add_u32_e32 v143, 0xe000, v149
	v_add_u32_e32 v171, v157, v154
	v_add_u32_e32 v252, v155, v153
	v_add_u32_e32 v192, v155, v151
	v_add_u32_e32 v193, v155, v152
	v_lshl_add_u64 v[234:235], v[180:181], 0, v[132:133]
	s_mov_b32 m0, s3
	v_readfirstlane_b32 s3, v143
	ds_read_b128 v[202:205], v171
	ds_read_b128 v[206:209], v171 offset:1024
	ds_read_b128 v[210:213], v252
	ds_read_b128 v[214:217], v252 offset:1024
	ds_read_b128 v[218:221], v192
	ds_read_b128 v[222:225], v192 offset:1024
	ds_read_b128 v[226:229], v193
	ds_read_b128 v[230:233], v193 offset:1024
	global_load_lds_dwordx4 v[234:235], off
	v_lshl_add_u64 v[180:181], v[180:181], 0, v[134:135]
	s_mov_b32 m0, s3
	s_nop 0
	global_load_lds_dwordx4 v[180:181], off
	s_waitcnt lgkmcnt(8)
	s_barrier
	s_waitcnt lgkmcnt(0)
	s_setprio 1
	v_mfma_f32_16x16x32_bf16 v[126:129], v[202:205], v[172:175], v[126:129]
	v_mfma_f32_16x16x32_bf16 v[122:125], v[202:205], v[194:197], v[122:125]
	v_mfma_f32_16x16x32_bf16 v[118:121], v[210:213], v[172:175], v[118:121]
	v_mfma_f32_16x16x32_bf16 v[114:117], v[210:213], v[194:197], v[114:117]
	v_mfma_f32_16x16x32_bf16 v[110:113], v[218:221], v[172:175], v[110:113]
	v_mfma_f32_16x16x32_bf16 v[106:109], v[218:221], v[194:197], v[106:109]
	v_mfma_f32_16x16x32_bf16 v[102:105], v[226:229], v[172:175], v[102:105]
	v_mfma_f32_16x16x32_bf16 v[98:101], v[226:229], v[194:197], v[98:101]
	v_mfma_f32_16x16x32_bf16 v[126:129], v[206:209], v[176:179], v[126:129]
	v_mfma_f32_16x16x32_bf16 v[122:125], v[206:209], v[198:201], v[122:125]
	v_mfma_f32_16x16x32_bf16 v[118:121], v[214:217], v[176:179], v[118:121]
	v_mfma_f32_16x16x32_bf16 v[114:117], v[214:217], v[198:201], v[114:117]
	v_mfma_f32_16x16x32_bf16 v[110:113], v[222:225], v[176:179], v[110:113]
	v_mfma_f32_16x16x32_bf16 v[106:109], v[222:225], v[198:201], v[106:109]
	v_mfma_f32_16x16x32_bf16 v[102:105], v[230:233], v[176:179], v[102:105]
	v_mfma_f32_16x16x32_bf16 v[98:101], v[230:233], v[198:201], v[98:101]
	s_setprio 0
	s_barrier
	s_add_i32 s72, s2, 0x80
	s_lshl_b64 s[20:21], s[72:73], 1
	v_lshl_add_u64 v[180:181], v[138:139], 0, s[20:21]
	v_readfirstlane_b32 s3, v158
	v_add_u32_e32 v143, v150, v146
	v_lshl_add_u64 v[250:251], v[180:181], 0, v[132:133]
	s_mov_b32 m0, s3
	v_readfirstlane_b32 s3, v159
	ds_read_b128 v[234:237], v143
	ds_read_b128 v[238:241], v143 offset:1024
	ds_read_b128 v[242:245], v143 offset:2048
	ds_read_b128 v[246:249], v143 offset:3072
	global_load_lds_dwordx4 v[250:251], off
	v_lshl_add_u64 v[250:251], v[180:181], 0, v[134:135]
	s_mov_b32 m0, s3
	s_add_i32 s18, s18, 2
	global_load_lds_dwordx4 v[250:251], off
	s_barrier
	s_waitcnt lgkmcnt(0)
	s_setprio 1
	v_mfma_f32_16x16x32_bf16 v[94:97], v[202:205], v[234:237], v[94:97]
	v_mfma_f32_16x16x32_bf16 v[90:93], v[202:205], v[242:245], v[90:93]
	v_mfma_f32_16x16x32_bf16 v[86:89], v[210:213], v[234:237], v[86:89]
	v_mfma_f32_16x16x32_bf16 v[82:85], v[210:213], v[242:245], v[82:85]
	v_mfma_f32_16x16x32_bf16 v[78:81], v[218:221], v[234:237], v[78:81]
	v_mfma_f32_16x16x32_bf16 v[74:77], v[218:221], v[242:245], v[74:77]
	v_mfma_f32_16x16x32_bf16 v[70:73], v[226:229], v[234:237], v[70:73]
	v_mfma_f32_16x16x32_bf16 v[66:69], v[226:229], v[242:245], v[66:69]
	v_mfma_f32_16x16x32_bf16 v[94:97], v[206:209], v[238:241], v[94:97]
	v_mfma_f32_16x16x32_bf16 v[90:93], v[206:209], v[246:249], v[90:93]
	v_mfma_f32_16x16x32_bf16 v[86:89], v[214:217], v[238:241], v[86:89]
	v_mfma_f32_16x16x32_bf16 v[82:85], v[214:217], v[246:249], v[82:85]
	v_mfma_f32_16x16x32_bf16 v[78:81], v[222:225], v[238:241], v[78:81]
	v_mfma_f32_16x16x32_bf16 v[74:77], v[222:225], v[246:249], v[74:77]
	v_mfma_f32_16x16x32_bf16 v[70:73], v[230:233], v[238:241], v[70:73]
	v_mfma_f32_16x16x32_bf16 v[66:69], v[230:233], v[246:249], v[66:69]
	s_setprio 0
	v_lshl_add_u64 v[250:251], v[130:131], 0, s[20:21]
	v_readfirstlane_b32 s3, v149
	v_lshl_add_u64 v[190:191], v[250:251], 0, v[132:133]
	s_mov_b32 m0, s3
	v_readfirstlane_b32 s3, v160
	s_barrier
	ds_read_b128 v[202:205], v171 offset:16384
	ds_read_b128 v[206:209], v171 offset:17408
	ds_read_b128 v[210:213], v252 offset:16384
	ds_read_b128 v[214:217], v252 offset:17408
	ds_read_b128 v[218:221], v192 offset:16384
	ds_read_b128 v[222:225], v192 offset:17408
	ds_read_b128 v[226:229], v193 offset:16384
	ds_read_b128 v[230:233], v193 offset:17408
	global_load_lds_dwordx4 v[190:191], off
	v_lshl_add_u64 v[190:191], v[250:251], 0, v[134:135]
	s_mov_b32 m0, s3
	s_nop 0
	global_load_lds_dwordx4 v[190:191], off
	s_barrier
	s_waitcnt lgkmcnt(0)
	s_setprio 1
	v_mfma_f32_16x16x32_bf16 v[62:65], v[202:205], v[172:175], v[62:65]
	v_mfma_f32_16x16x32_bf16 v[58:61], v[202:205], v[194:197], v[58:61]
	v_mfma_f32_16x16x32_bf16 v[54:57], v[210:213], v[172:175], v[54:57]
	v_mfma_f32_16x16x32_bf16 v[50:53], v[210:213], v[194:197], v[50:53]
	v_mfma_f32_16x16x32_bf16 v[46:49], v[218:221], v[172:175], v[46:49]
	v_mfma_f32_16x16x32_bf16 v[42:45], v[218:221], v[194:197], v[42:45]
	v_mfma_f32_16x16x32_bf16 v[38:41], v[226:229], v[172:175], v[38:41]
	v_mfma_f32_16x16x32_bf16 v[34:37], v[226:229], v[194:197], v[34:37]
	v_mfma_f32_16x16x32_bf16 v[62:65], v[206:209], v[176:179], v[62:65]
	v_mfma_f32_16x16x32_bf16 v[58:61], v[206:209], v[198:201], v[58:61]
	v_mfma_f32_16x16x32_bf16 v[54:57], v[214:217], v[176:179], v[54:57]
	v_mfma_f32_16x16x32_bf16 v[50:53], v[214:217], v[198:201], v[50:53]
	v_mfma_f32_16x16x32_bf16 v[46:49], v[222:225], v[176:179], v[46:49]
	v_mfma_f32_16x16x32_bf16 v[42:45], v[222:225], v[198:201], v[42:45]
	v_mfma_f32_16x16x32_bf16 v[38:41], v[230:233], v[176:179], v[38:41]
	v_mfma_f32_16x16x32_bf16 v[34:37], v[230:233], v[198:201], v[34:37]
	s_setprio 0
	s_barrier
; #define STAGE(P, BASE, LD, br, kt) do { const char* _gp = (const char*)((BASE) + (long)((br) * (LD) + (kt) * BK)); \
;     __builtin_amdgcn_global_load_lds((const unsigned*)(_gp + vo_##BASE##0), (unsigned*)((char*)(P) + tidx * 16), 16, 0, 0); \
;     __builtin_amdgcn_global_load_lds((const unsigned*)(_gp + vo_##BASE##1), (unsigned*)((char*)(P) + tidx * 16 + 8192), 16, 0, 0); } while (0)
; #define LDA(dst, b, h) for (int m = 0; m < 4; ++m) for (int k = 0; k < 2; ++k) \
;     dst[m][k] = *reinterpret_cast<const bf16x8*>((char*)SA(b, h) + lds_byte(wr * 64 + m * 16 + fr, k * 32 + fq * 8))
; #define LDB(dst, b, h) for (int n = 0; n < 2; ++n) for (int k = 0; k < 2; ++k) \
;     dst[n][k] = *reinterpret_cast<const bf16x8*>((char*)SB(b, h) + lds_byte(wc * 32 + n * 16 + fr, k * 32 + fq * 8))
; #define MMA(ai, bj, At, Bt_) do { __builtin_amdgcn_s_setprio(1); \
;     for (int m = 0; m < 4; ++m) for (int n = 0; n < 2; ++n) for (int k = 0; k < 2; ++k) \
;       acc[ai][bj][m][n] = __builtin_amdgcn_mfma_f32_16x16x32_bf16(At[m][k], Bt_[n][k], acc[ai][bj][m][n], 0, 0, 0); \
;     __builtin_amdgcn_s_setprio(0); } while (0)
; #define WAIT_V(n) asm volatile("s_waitcnt vmcnt(" #n ")" ::: "memory")
; #define WAIT_L(n) asm volatile("s_waitcnt lgkmcnt(" #n ")" ::: "memory")
; #define BAR __builtin_amdgcn_s_barrier()
; #define SCHED __builtin_amdgcn_sched_barrier(0)
; __device__ __forceinline__ void gemm_main(acc_t& acc, const u16* A, int lda, const u16* Bt, int ldb, int nt, const int tidx) {
;     ...
;         STAGE(SB(0, 1), Bt, ldb, HALF, t + 2);
;         WAIT_V(6); BAR; MMA(1, 1, At, B1); BAR;
;         LDB(B0, 1, 0); SCHED; LDA(At, 1, 0); STAGE(SA(0, 1), A, lda, HALF, t + 2);
;         WAIT_L(8); BAR; WAIT_L(0); MMA(0, 0, At, B0); BAR; SCHED;
;         LDB(B1, 1, 1); STAGE(SB(1, 0), Bt, ldb, 0, t + 3);
;         BAR; WAIT_L(0); MMA(0, 1, At, B1); BAR;
	v_mov_b32_e32 v143, v1
	v_lshl_add_u64 v[172:173], v[180:181], 0, v[142:143]
	v_readfirstlane_b32 s3, v161
	v_lshl_add_u64 v[174:175], v[172:173], 0, v[132:133]
	s_mov_b32 m0, s3
	v_readfirstlane_b32 s3, v162
	global_load_lds_dwordx4 v[174:175], off
	v_lshl_add_u64 v[172:173], v[172:173], 0, v[134:135]
	s_mov_b32 m0, s3
	v_add_u32_e32 v0, 0x80, v0
	global_load_lds_dwordx4 v[172:173], off
	s_waitcnt vmcnt(6)
	s_barrier
	s_setprio 1
	v_mfma_f32_16x16x32_bf16 v[30:33], v[202:205], v[234:237], v[30:33]
	v_mfma_f32_16x16x32_bf16 v[26:29], v[202:205], v[242:245], v[26:29]
	v_mfma_f32_16x16x32_bf16 v[22:25], v[210:213], v[234:237], v[22:25]
	v_mfma_f32_16x16x32_bf16 v[18:21], v[210:213], v[242:245], v[18:21]
	v_mfma_f32_16x16x32_bf16 v[14:17], v[218:221], v[234:237], v[14:17]
	v_mfma_f32_16x16x32_bf16 v[10:13], v[218:221], v[242:245], v[10:13]
	v_mfma_f32_16x16x32_bf16 v[6:9], v[226:229], v[234:237], v[6:9]
	v_mfma_f32_16x16x32_bf16 v[2:5], v[226:229], v[242:245], v[2:5]
	v_mfma_f32_16x16x32_bf16 v[30:33], v[206:209], v[238:241], v[30:33]
	v_mfma_f32_16x16x32_bf16 v[26:29], v[206:209], v[246:249], v[26:29]
	v_mfma_f32_16x16x32_bf16 v[22:25], v[214:217], v[238:241], v[22:25]
	v_mfma_f32_16x16x32_bf16 v[18:21], v[214:217], v[246:249], v[18:21]
	v_mfma_f32_16x16x32_bf16 v[14:17], v[222:225], v[238:241], v[14:17]
	v_mfma_f32_16x16x32_bf16 v[10:13], v[222:225], v[246:249], v[10:13]
	v_mfma_f32_16x16x32_bf16 v[6:9], v[230:233], v[238:241], v[6:9]
	v_mfma_f32_16x16x32_bf16 v[2:5], v[230:233], v[246:249], v[2:5]
	s_setprio 0
	v_add_u32_e32 v143, v148, v146
	s_barrier
	ds_read_b128 v[172:175], v143
	ds_read_b128 v[176:179], v143 offset:1024
	ds_read_b128 v[194:197], v143 offset:2048
	ds_read_b128 v[198:201], v143 offset:3072
	v_lshl_add_u64 v[180:181], v[0:1], 1, v[130:131]
	v_readfirstlane_b32 s3, v163
	v_lshl_add_u64 v[190:191], v[180:181], 0, v[132:133]
	s_mov_b32 m0, s3
	v_readfirstlane_b32 s3, v164
	ds_read_b128 v[202:205], v171 offset:32768
	ds_read_b128 v[206:209], v171 offset:33792
	ds_read_b128 v[210:213], v252 offset:32768
	ds_read_b128 v[214:217], v252 offset:33792
	ds_read_b128 v[218:221], v192 offset:32768
	ds_read_b128 v[222:225], v192 offset:33792
	ds_read_b128 v[226:229], v193 offset:32768
	ds_read_b128 v[230:233], v193 offset:33792
	global_load_lds_dwordx4 v[190:191], off
	v_lshl_add_u64 v[180:181], v[180:181], 0, v[134:135]
	s_mov_b32 m0, s3
	s_nop 0
	global_load_lds_dwordx4 v[180:181], off
	s_waitcnt lgkmcnt(8)
	s_barrier
	s_waitcnt lgkmcnt(0)
	s_setprio 1
	v_mfma_f32_16x16x32_bf16 v[126:129], v[202:205], v[172:175], v[126:129]
	v_mfma_f32_16x16x32_bf16 v[122:125], v[202:205], v[194:197], v[122:125]
	v_mfma_f32_16x16x32_bf16 v[118:121], v[210:213], v[172:175], v[118:121]
	v_mfma_f32_16x16x32_bf16 v[114:117], v[210:213], v[194:197], v[114:117]
	v_mfma_f32_16x16x32_bf16 v[110:113], v[218:221], v[172:175], v[110:113]
	v_mfma_f32_16x16x32_bf16 v[106:109], v[218:221], v[194:197], v[106:109]
	v_mfma_f32_16x16x32_bf16 v[102:105], v[226:229], v[172:175], v[102:105]
	v_mfma_f32_16x16x32_bf16 v[98:101], v[226:229], v[194:197], v[98:101]
	v_mfma_f32_16x16x32_bf16 v[126:129], v[206:209], v[176:179], v[126:129]
	v_mfma_f32_16x16x32_bf16 v[122:125], v[206:209], v[198:201], v[122:125]
	v_mfma_f32_16x16x32_bf16 v[118:121], v[214:217], v[176:179], v[118:121]
	v_mfma_f32_16x16x32_bf16 v[114:117], v[214:217], v[198:201], v[114:117]
	v_mfma_f32_16x16x32_bf16 v[110:113], v[222:225], v[176:179], v[110:113]
	v_mfma_f32_16x16x32_bf16 v[106:109], v[222:225], v[198:201], v[106:109]
	v_mfma_f32_16x16x32_bf16 v[102:105], v[230:233], v[176:179], v[102:105]
	v_mfma_f32_16x16x32_bf16 v[98:101], v[230:233], v[198:201], v[98:101]
	s_setprio 0
	s_barrier
	s_ashr_i32 s3, s2, 31
	s_lshl_b64 s[20:21], s[2:3], 1
	v_lshl_add_u64 v[180:181], v[138:139], 0, s[20:21]
	v_lshl_add_u64 v[190:191], v[180:181], 0, v[132:133]
	v_readfirstlane_b32 s3, v165
	v_add_u32_e32 v0, v147, v146
	v_lshl_add_u64 v[190:191], v[190:191], 0, s[0:1]
	s_mov_b32 m0, s3
	v_lshl_add_u64 v[180:181], v[180:181], 0, v[134:135]
	v_readfirstlane_b32 s3, v166
	ds_read_b128 v[234:237], v0
	ds_read_b128 v[238:241], v0 offset:1024
	ds_read_b128 v[242:245], v0 offset:2048
	ds_read_b128 v[246:249], v0 offset:3072
	global_load_lds_dwordx4 v[190:191], off
	v_lshl_add_u64 v[180:181], v[180:181], 0, s[0:1]
	s_mov_b32 m0, s3
	s_addk_i32 s2, 0xc0
	global_load_lds_dwordx4 v[180:181], off
	s_barrier
	s_waitcnt lgkmcnt(0)
	s_setprio 1
	v_mfma_f32_16x16x32_bf16 v[94:97], v[202:205], v[234:237], v[94:97]
	v_mfma_f32_16x16x32_bf16 v[90:93], v[202:205], v[242:245], v[90:93]
	v_mfma_f32_16x16x32_bf16 v[86:89], v[210:213], v[234:237], v[86:89]
	v_mfma_f32_16x16x32_bf16 v[82:85], v[210:213], v[242:245], v[82:85]
	v_mfma_f32_16x16x32_bf16 v[78:81], v[218:221], v[234:237], v[78:81]
	v_mfma_f32_16x16x32_bf16 v[74:77], v[218:221], v[242:245], v[74:77]
	v_mfma_f32_16x16x32_bf16 v[70:73], v[226:229], v[234:237], v[70:73]
	v_mfma_f32_16x16x32_bf16 v[66:69], v[226:229], v[242:245], v[66:69]
	v_mfma_f32_16x16x32_bf16 v[94:97], v[206:209], v[238:241], v[94:97]
	v_mfma_f32_16x16x32_bf16 v[90:93], v[206:209], v[246:249], v[90:93]
	v_mfma_f32_16x16x32_bf16 v[86:89], v[214:217], v[238:241], v[86:89]
	v_mfma_f32_16x16x32_bf16 v[82:85], v[214:217], v[246:249], v[82:85]
	v_mfma_f32_16x16x32_bf16 v[78:81], v[222:225], v[238:241], v[78:81]
	v_mfma_f32_16x16x32_bf16 v[74:77], v[222:225], v[246:249], v[74:77]
	v_mfma_f32_16x16x32_bf16 v[70:73], v[230:233], v[238:241], v[70:73]
	v_mfma_f32_16x16x32_bf16 v[66:69], v[230:233], v[246:249], v[66:69]
	s_setprio 0
	v_lshl_add_u64 v[180:181], v[130:131], 0, s[20:21]
	v_lshl_add_u64 v[190:191], v[180:181], 0, v[132:133]
	v_readfirstlane_b32 s3, v167
	v_lshl_add_u64 v[190:191], v[190:191], 0, s[0:1]
	s_mov_b32 m0, s3
	v_lshl_add_u64 v[180:181], v[180:181], 0, v[134:135]
	v_readfirstlane_b32 s3, v168
	s_barrier
; #define STAGE(P, BASE, LD, br, kt) do { const char* _gp = (const char*)((BASE) + (long)((br) * (LD) + (kt) * BK)); \
;     __builtin_amdgcn_global_load_lds((const unsigned*)(_gp + vo_##BASE##0), (unsigned*)((char*)(P) + tidx * 16), 16, 0, 0); \
;     __builtin_amdgcn_global_load_lds((const unsigned*)(_gp + vo_##BASE##1), (unsigned*)((char*)(P) + tidx * 16 + 8192), 16, 0, 0); } while (0)
; #define LDA(dst, b, h) for (int m = 0; m < 4; ++m) for (int k = 0; k < 2; ++k) \
;     dst[m][k] = *reinterpret_cast<const bf16x8*>((char*)SA(b, h) + lds_byte(wr * 64 + m * 16 + fr, k * 32 + fq * 8))
; #define LDB(dst, b, h) for (int n = 0; n < 2; ++n) for (int k = 0; k < 2; ++k) \
;     dst[n][k] = *reinterpret_cast<const bf16x8*>((char*)SB(b, h) + lds_byte(wc * 32 + n * 16 + fr, k * 32 + fq * 8))
; #define MMA(ai, bj, At, Bt_) do { __builtin_amdgcn_s_setprio(1); \
;     for (int m = 0; m < 4; ++m) for (int n = 0; n < 2; ++n) for (int k = 0; k < 2; ++k) \
;       acc[ai][bj][m][n] = __builtin_amdgcn_mfma_f32_16x16x32_bf16(At[m][k], Bt_[n][k], acc[ai][bj][m][n], 0, 0, 0); \
;     __builtin_amdgcn_s_setprio(0); } while (0)
; #define WAIT_V(n) asm volatile("s_waitcnt vmcnt(" #n ")" ::: "memory")
; #define WAIT_L(n) asm volatile("s_waitcnt lgkmcnt(" #n ")" ::: "memory")
; #define BAR __builtin_amdgcn_s_barrier()
; #define SCHED __builtin_amdgcn_sched_barrier(0)
; __device__ __forceinline__ void gemm_main(acc_t& acc, const u16* A, int lda, const u16* Bt, int ldb, int nt, const int tidx) {
;     ...
;         LDA(At, 1, 1); STAGE(SA(1, 0), A, lda, 0, t + 3);
;         BAR; WAIT_L(0); MMA(1, 0, At, B0); BAR; SCHED;
;         STAGE(SB(1, 1), Bt, ldb, HALF, t + 3);
;         WAIT_V(6); BAR; MMA(1, 1, At, B1); BAR;
;     }
;     { LDB(B0, 0, 0); LDA(At, 0, 0); STAGE(SA(1, 1), A, lda, HALF, nt - 1);
;       BAR; WAIT_L(0); MMA(0, 0, At, B0); BAR;
	ds_read_b128 v[202:205], v171 offset:49152
	ds_read_b128 v[206:209], v171 offset:50176
	ds_read_b128 v[210:213], v252 offset:49152
	ds_read_b128 v[214:217], v252 offset:50176
	ds_read_b128 v[218:221], v192 offset:49152
	ds_read_b128 v[222:225], v192 offset:50176
	ds_read_b128 v[226:229], v193 offset:49152
	ds_read_b128 v[230:233], v193 offset:50176
	global_load_lds_dwordx4 v[190:191], off
	v_lshl_add_u64 v[180:181], v[180:181], 0, s[0:1]
	s_mov_b32 m0, s3
	s_nop 0
	global_load_lds_dwordx4 v[180:181], off
	s_barrier
	s_waitcnt lgkmcnt(0)
	s_setprio 1
	v_mfma_f32_16x16x32_bf16 v[62:65], v[202:205], v[172:175], v[62:65]
	v_mfma_f32_16x16x32_bf16 v[58:61], v[202:205], v[194:197], v[58:61]
	v_mfma_f32_16x16x32_bf16 v[54:57], v[210:213], v[172:175], v[54:57]
	v_mfma_f32_16x16x32_bf16 v[50:53], v[210:213], v[194:197], v[50:53]
	v_mfma_f32_16x16x32_bf16 v[46:49], v[218:221], v[172:175], v[46:49]
	v_mfma_f32_16x16x32_bf16 v[42:45], v[218:221], v[194:197], v[42:45]
	v_mfma_f32_16x16x32_bf16 v[38:41], v[226:229], v[172:175], v[38:41]
	v_mfma_f32_16x16x32_bf16 v[34:37], v[226:229], v[194:197], v[34:37]
	v_mfma_f32_16x16x32_bf16 v[62:65], v[206:209], v[176:179], v[62:65]
	v_mfma_f32_16x16x32_bf16 v[58:61], v[206:209], v[198:201], v[58:61]
	v_mfma_f32_16x16x32_bf16 v[54:57], v[214:217], v[176:179], v[54:57]
	v_mfma_f32_16x16x32_bf16 v[50:53], v[214:217], v[198:201], v[50:53]
	v_mfma_f32_16x16x32_bf16 v[46:49], v[222:225], v[176:179], v[46:49]
	v_mfma_f32_16x16x32_bf16 v[42:45], v[222:225], v[198:201], v[42:45]
	v_mfma_f32_16x16x32_bf16 v[38:41], v[230:233], v[176:179], v[38:41]
	v_mfma_f32_16x16x32_bf16 v[34:37], v[230:233], v[198:201], v[34:37]
	s_setprio 0
	s_barrier
	s_ashr_i32 s3, s2, 31
	v_lshl_add_u64 v[172:173], s[2:3], 1, v[140:141]
	v_readfirstlane_b32 s2, v169
	v_lshl_add_u64 v[174:175], v[172:173], 0, v[132:133]
	s_mov_b32 m0, s2
	v_readfirstlane_b32 s2, v170
	global_load_lds_dwordx4 v[174:175], off
	v_lshl_add_u64 v[172:173], v[172:173], 0, v[134:135]
	s_mov_b32 m0, s2
	s_nop 0
	global_load_lds_dwordx4 v[172:173], off
	s_waitcnt vmcnt(6)
	s_barrier
	s_setprio 1
	v_mfma_f32_16x16x32_bf16 v[30:33], v[202:205], v[234:237], v[30:33]
	v_mfma_f32_16x16x32_bf16 v[26:29], v[202:205], v[242:245], v[26:29]
	v_mfma_f32_16x16x32_bf16 v[22:25], v[210:213], v[234:237], v[22:25]
	v_mfma_f32_16x16x32_bf16 v[18:21], v[210:213], v[242:245], v[18:21]
	v_mfma_f32_16x16x32_bf16 v[14:17], v[218:221], v[234:237], v[14:17]
	v_mfma_f32_16x16x32_bf16 v[10:13], v[218:221], v[242:245], v[10:13]
	v_mfma_f32_16x16x32_bf16 v[6:9], v[226:229], v[234:237], v[6:9]
	v_mfma_f32_16x16x32_bf16 v[2:5], v[226:229], v[242:245], v[2:5]
	v_mfma_f32_16x16x32_bf16 v[30:33], v[206:209], v[238:241], v[30:33]
	v_mfma_f32_16x16x32_bf16 v[26:29], v[206:209], v[246:249], v[26:29]
	v_mfma_f32_16x16x32_bf16 v[22:25], v[214:217], v[238:241], v[22:25]
	v_mfma_f32_16x16x32_bf16 v[18:21], v[214:217], v[246:249], v[18:21]
	v_mfma_f32_16x16x32_bf16 v[14:17], v[222:225], v[238:241], v[14:17]
	v_mfma_f32_16x16x32_bf16 v[10:13], v[222:225], v[246:249], v[10:13]
	v_mfma_f32_16x16x32_bf16 v[6:9], v[230:233], v[238:241], v[6:9]
	v_mfma_f32_16x16x32_bf16 v[2:5], v[230:233], v[246:249], v[2:5]
	s_setprio 0
	s_cmp_lt_i32 s18, s17
	s_mov_b32 s2, s72
	s_barrier
	s_cbranch_scc1 .LBB0_588
	v_mov_b32_e32 v251, v189
	v_mov_b32_e32 v189, v188
	v_mov_b32_e32 v188, v187
	v_mov_b32_e32 v187, v182
	v_mov_b32_e32 v182, 0x358637bd
.LBB0_590:
	v_lshl_add_u32 v0, s16, 6, v136
	v_subrev_u32_e32 v138, 64, v0
	v_ashrrev_i32_e32 v139, 31, v138
	v_add_u32_e32 v190, v155, v151
	v_add_u32_e32 v151, 0xc000, v149
	v_lshl_add_u64 v[130:131], v[138:139], 1, v[130:131]
	v_add_u32_e32 v0, v156, v146
	v_readfirstlane_b32 s2, v151
	v_lshl_add_u64 v[142:143], v[130:131], 0, v[132:133]
	v_lshl_add_u64 v[134:135], v[130:131], 0, v[134:135]
	ds_read_b128 v[130:133], v0
	ds_read_b128 v[138:141], v0 offset:1024
	ds_read_b128 v[158:161], v0 offset:2048
	ds_read_b128 v[162:165], v0 offset:3072
	v_add_u32_e32 v0, v157, v154
	v_add_u32_e32 v136, v155, v153
	v_add_u32_e32 v191, v155, v152
	s_mov_b32 m0, s2
	ds_read_b128 v[166:169], v0
	ds_read_b128 v[170:173], v0 offset:1024
	ds_read_b128 v[174:177], v136
	ds_read_b128 v[178:181], v136 offset:1024
	ds_read_b128 v[194:197], v190
	ds_read_b128 v[198:201], v190 offset:1024
	ds_read_b128 v[152:155], v191
	ds_read_b128 v[202:205], v191 offset:1024
	global_load_lds_dwordx4 v[142:143], off
	v_add_u32_e32 v142, 0xe000, v149
	v_cmp_gt_u32_e32 vcc, s51, v144
	v_readfirstlane_b32 s2, v142
	s_mov_b32 m0, s2
	s_nop 0
	global_load_lds_dwordx4 v[134:135], off
	s_barrier
	s_waitcnt lgkmcnt(0)
	s_setprio 1
	v_mfma_f32_16x16x32_bf16 v[126:129], v[166:169], v[130:133], v[126:129]
	v_mfma_f32_16x16x32_bf16 v[122:125], v[166:169], v[158:161], v[122:125]
	v_mfma_f32_16x16x32_bf16 v[118:121], v[174:177], v[130:133], v[118:121]
	v_mfma_f32_16x16x32_bf16 v[114:117], v[174:177], v[158:161], v[114:117]
	v_mfma_f32_16x16x32_bf16 v[110:113], v[194:197], v[130:133], v[110:113]
	v_mfma_f32_16x16x32_bf16 v[102:105], v[152:155], v[130:133], v[102:105]
	v_mfma_f32_16x16x32_bf16 v[98:101], v[152:155], v[158:161], v[98:101]
	v_mfma_f32_16x16x32_bf16 v[126:129], v[170:173], v[138:141], v[126:129]
	v_mfma_f32_16x16x32_bf16 v[122:125], v[170:173], v[162:165], v[122:125]
	v_mfma_f32_16x16x32_bf16 v[118:121], v[178:181], v[138:141], v[118:121]
	v_mfma_f32_16x16x32_bf16 v[114:117], v[178:181], v[162:165], v[114:117]
	v_mfma_f32_16x16x32_bf16 v[110:113], v[198:201], v[138:141], v[110:113]
	v_mfma_f32_16x16x32_bf16 v[106:109], v[194:197], v[158:161], v[106:109]
	v_mfma_f32_16x16x32_bf16 v[102:105], v[202:205], v[138:141], v[102:105]
	v_mfma_f32_16x16x32_bf16 v[98:101], v[202:205], v[162:165], v[98:101]
	v_mfma_f32_16x16x32_bf16 v[206:209], v[198:201], v[162:165], v[106:109]
	s_setprio 0
	v_add_u32_e32 v134, v150, v146
	s_barrier
; #define LDA(dst, b, h) for (int m = 0; m < 4; ++m) for (int k = 0; k < 2; ++k) \
;     dst[m][k] = *reinterpret_cast<const bf16x8*>((char*)SA(b, h) + lds_byte(wr * 64 + m * 16 + fr, k * 32 + fq * 8))
; #define LDB(dst, b, h) for (int n = 0; n < 2; ++n) for (int k = 0; k < 2; ++k) \
;     dst[n][k] = *reinterpret_cast<const bf16x8*>((char*)SB(b, h) + lds_byte(wc * 32 + n * 16 + fr, k * 32 + fq * 8))
; #define MMA(ai, bj, At, Bt_) do { __builtin_amdgcn_s_setprio(1); \
;     for (int m = 0; m < 4; ++m) for (int n = 0; n < 2; ++n) for (int k = 0; k < 2; ++k) \
;       acc[ai][bj][m][n] = __builtin_amdgcn_mfma_f32_16x16x32_bf16(At[m][k], Bt_[n][k], acc[ai][bj][m][n], 0, 0, 0); \
;     __builtin_amdgcn_s_setprio(0); } while (0)
; #define WAIT_V(n) asm volatile("s_waitcnt vmcnt(" #n ")" ::: "memory")
; #define WAIT_L(n) asm volatile("s_waitcnt lgkmcnt(" #n ")" ::: "memory")
; #define BAR __builtin_amdgcn_s_barrier()
; __device__ __forceinline__ void gemm_main(acc_t& acc, const u16* A, int lda, const u16* Bt, int ldb, int nt, const int tidx) {
;     ...
;       LDB(B1, 0, 1); BAR; WAIT_L(0); MMA(0, 1, At, B1); BAR;
;       LDA(At, 0, 1); WAIT_V(4); BAR; WAIT_L(0); MMA(1, 0, At, B0); MMA(1, 1, At, B1); BAR; }
;     { LDB(B0, 1, 0); LDA(At, 1, 0); WAIT_V(2); BAR; WAIT_L(0); MMA(0, 0, At, B0); BAR;
	s_nop 1
	ds_read_b128 v[106:109], v134
	ds_read_b128 v[210:213], v134 offset:1024
	ds_read_b128 v[214:217], v134 offset:2048
	ds_read_b128 v[218:221], v134 offset:3072
	s_barrier
	s_waitcnt lgkmcnt(0)
	s_setprio 1
	v_mfma_f32_16x16x32_bf16 v[90:93], v[166:169], v[214:217], v[90:93]
	v_mfma_f32_16x16x32_bf16 v[78:81], v[194:197], v[106:109], v[78:81]
	v_mfma_f32_16x16x32_bf16 v[70:73], v[152:155], v[106:109], v[70:73]
	v_mfma_f32_16x16x32_bf16 v[66:69], v[152:155], v[214:217], v[66:69]
	v_mfma_f32_16x16x32_bf16 v[94:97], v[166:169], v[106:109], v[94:97]
	v_mfma_f32_16x16x32_bf16 v[90:93], v[170:173], v[218:221], v[90:93]
	v_mfma_f32_16x16x32_bf16 v[86:89], v[174:177], v[106:109], v[86:89]
	v_mfma_f32_16x16x32_bf16 v[82:85], v[174:177], v[214:217], v[82:85]
	v_mfma_f32_16x16x32_bf16 v[78:81], v[198:201], v[210:213], v[78:81]
	v_mfma_f32_16x16x32_bf16 v[74:77], v[194:197], v[214:217], v[74:77]
	v_mfma_f32_16x16x32_bf16 v[70:73], v[202:205], v[210:213], v[70:73]
	v_mfma_f32_16x16x32_bf16 v[66:69], v[202:205], v[218:221], v[66:69]
	v_mfma_f32_16x16x32_bf16 v[222:225], v[170:173], v[210:213], v[94:97]
	v_mfma_f32_16x16x32_bf16 v[166:169], v[178:181], v[210:213], v[86:89]
	v_mfma_f32_16x16x32_bf16 v[170:173], v[178:181], v[218:221], v[82:85]
	v_mfma_f32_16x16x32_bf16 v[174:177], v[198:201], v[218:221], v[74:77]
	s_setprio 0
	s_barrier
	s_nop 0
	ds_read_b128 v[74:77], v0 offset:16384
	ds_read_b128 v[82:85], v0 offset:17408
	ds_read_b128 v[86:89], v136 offset:16384
	ds_read_b128 v[94:97], v136 offset:17408
	ds_read_b128 v[150:153], v190 offset:16384
	ds_read_b128 v[154:157], v190 offset:17408
	ds_read_b128 v[178:181], v191 offset:16384
	ds_read_b128 v[194:197], v191 offset:17408
	s_waitcnt vmcnt(4)
	s_barrier
	s_waitcnt lgkmcnt(0)
	s_setprio 1
	v_mfma_f32_16x16x32_bf16 v[58:61], v[74:77], v[158:161], v[58:61]
	v_mfma_f32_16x16x32_bf16 v[46:49], v[150:153], v[130:133], v[46:49]
	v_mfma_f32_16x16x32_bf16 v[38:41], v[178:181], v[130:133], v[38:41]
	v_mfma_f32_16x16x32_bf16 v[34:37], v[178:181], v[158:161], v[34:37]
	v_mfma_f32_16x16x32_bf16 v[62:65], v[74:77], v[130:133], v[62:65]
	v_mfma_f32_16x16x32_bf16 v[58:61], v[82:85], v[162:165], v[58:61]
	v_mfma_f32_16x16x32_bf16 v[54:57], v[86:89], v[130:133], v[54:57]
	v_mfma_f32_16x16x32_bf16 v[50:53], v[86:89], v[158:161], v[50:53]
	v_mfma_f32_16x16x32_bf16 v[46:49], v[154:157], v[138:141], v[46:49]
	v_mfma_f32_16x16x32_bf16 v[42:45], v[150:153], v[158:161], v[42:45]
	v_mfma_f32_16x16x32_bf16 v[38:41], v[194:197], v[138:141], v[38:41]
	v_mfma_f32_16x16x32_bf16 v[34:37], v[194:197], v[162:165], v[34:37]
	v_mfma_f32_16x16x32_bf16 v[198:201], v[82:85], v[138:141], v[62:65]
	v_mfma_f32_16x16x32_bf16 v[202:205], v[94:97], v[138:141], v[54:57]
	v_mfma_f32_16x16x32_bf16 v[226:229], v[94:97], v[162:165], v[50:53]
	v_mfma_f32_16x16x32_bf16 v[230:233], v[154:157], v[162:165], v[42:45]
	s_setprio 0
	s_setprio 1
	v_mfma_f32_16x16x32_bf16 v[26:29], v[74:77], v[214:217], v[26:29]
	v_mfma_f32_16x16x32_bf16 v[18:21], v[86:89], v[214:217], v[18:21]
	v_mfma_f32_16x16x32_bf16 v[10:13], v[150:153], v[214:217], v[10:13]
	v_mfma_f32_16x16x32_bf16 v[2:5], v[178:181], v[214:217], v[2:5]
	v_mfma_f32_16x16x32_bf16 v[30:33], v[74:77], v[106:109], v[30:33]
	v_mfma_f32_16x16x32_bf16 v[26:29], v[82:85], v[218:221], v[26:29]
	v_mfma_f32_16x16x32_bf16 v[22:25], v[86:89], v[106:109], v[22:25]
	v_mfma_f32_16x16x32_bf16 v[18:21], v[94:97], v[218:221], v[18:21]
	v_mfma_f32_16x16x32_bf16 v[14:17], v[150:153], v[106:109], v[14:17]
	v_mfma_f32_16x16x32_bf16 v[10:13], v[154:157], v[218:221], v[10:13]
	v_mfma_f32_16x16x32_bf16 v[6:9], v[178:181], v[106:109], v[6:9]
	v_mfma_f32_16x16x32_bf16 v[2:5], v[194:197], v[218:221], v[2:5]
	v_mfma_f32_16x16x32_bf16 v[130:133], v[82:85], v[210:213], v[30:33]
	v_mfma_f32_16x16x32_bf16 v[138:141], v[94:97], v[210:213], v[22:25]
	v_mfma_f32_16x16x32_bf16 v[158:161], v[154:157], v[210:213], v[14:17]
	v_mfma_f32_16x16x32_bf16 v[150:153], v[194:197], v[210:213], v[6:9]
	s_setprio 0
	s_nop 0
	v_add_u32_e32 v14, v148, v146
	s_barrier
	ds_read_b128 v[6:9], v14
	ds_read_b128 v[154:157], v14 offset:1024
	ds_read_b128 v[162:165], v14 offset:2048
	ds_read_b128 v[178:181], v14 offset:3072
	ds_read_b128 v[14:17], v0 offset:32768
	ds_read_b128 v[22:25], v0 offset:33792
	ds_read_b128 v[30:33], v136 offset:32768
	ds_read_b128 v[42:45], v136 offset:33792
	ds_read_b128 v[194:197], v190 offset:32768
	ds_read_b128 v[210:213], v190 offset:33792
	ds_read_b128 v[214:217], v191 offset:32768
	ds_read_b128 v[218:221], v191 offset:33792
	s_waitcnt vmcnt(2)
	s_barrier
; #define LDA(dst, b, h) for (int m = 0; m < 4; ++m) for (int k = 0; k < 2; ++k) \
;     dst[m][k] = *reinterpret_cast<const bf16x8*>((char*)SA(b, h) + lds_byte(wr * 64 + m * 16 + fr, k * 32 + fq * 8))
; #define LDB(dst, b, h) for (int n = 0; n < 2; ++n) for (int k = 0; k < 2; ++k) \
;     dst[n][k] = *reinterpret_cast<const bf16x8*>((char*)SB(b, h) + lds_byte(wc * 32 + n * 16 + fr, k * 32 + fq * 8))
; #define MMA(ai, bj, At, Bt_) do { __builtin_amdgcn_s_setprio(1); \
;     for (int m = 0; m < 4; ++m) for (int n = 0; n < 2; ++n) for (int k = 0; k < 2; ++k) \
;       acc[ai][bj][m][n] = __builtin_amdgcn_mfma_f32_16x16x32_bf16(At[m][k], Bt_[n][k], acc[ai][bj][m][n], 0, 0, 0); \
;     __builtin_amdgcn_s_setprio(0); } while (0)
; #define WAIT_V(n) asm volatile("s_waitcnt vmcnt(" #n ")" ::: "memory")
; #define WAIT_L(n) asm volatile("s_waitcnt lgkmcnt(" #n ")" ::: "memory")
; #define BAR __builtin_amdgcn_s_barrier()
; __device__ __forceinline__ void gemm_main(acc_t& acc, const u16* A, int lda, const u16* Bt, int ldb, int nt, const int tidx) {
;     ...
;     { LDB(B0, 1, 0); LDA(At, 1, 0); WAIT_V(2); BAR; WAIT_L(0); MMA(0, 0, At, B0); BAR;
;       LDB(B1, 1, 1); WAIT_V(0); BAR; WAIT_L(0); MMA(0, 1, At, B1); BAR;
;       LDA(At, 1, 1); BAR; WAIT_L(0); MMA(1, 0, At, B0); MMA(1, 1, At, B1); BAR; }
;     if (wr == 0) BAR;
	s_waitcnt lgkmcnt(0)
	s_setprio 1
	v_mfma_f32_16x16x32_bf16 v[50:53], v[14:17], v[6:9], v[126:129]
	v_mfma_f32_16x16x32_bf16 v[126:129], v[22:25], v[154:157], v[50:53]
	v_mfma_f32_16x16x32_bf16 v[50:53], v[14:17], v[162:165], v[122:125]
	v_mfma_f32_16x16x32_bf16 v[106:109], v[22:25], v[178:181], v[50:53]
	v_mfma_f32_16x16x32_bf16 v[50:53], v[30:33], v[6:9], v[118:121]
	v_mfma_f32_16x16x32_bf16 v[118:121], v[42:45], v[154:157], v[50:53]
	v_mfma_f32_16x16x32_bf16 v[50:53], v[30:33], v[162:165], v[114:117]
	v_mfma_f32_16x16x32_bf16 v[94:97], v[42:45], v[178:181], v[50:53]
	v_mfma_f32_16x16x32_bf16 v[50:53], v[194:197], v[6:9], v[110:113]
	v_mfma_f32_16x16x32_bf16 v[110:113], v[210:213], v[154:157], v[50:53]
	v_mfma_f32_16x16x32_bf16 v[50:53], v[194:197], v[162:165], v[206:209]
	v_mfma_f32_16x16x32_bf16 v[86:89], v[210:213], v[178:181], v[50:53]
	v_mfma_f32_16x16x32_bf16 v[50:53], v[214:217], v[6:9], v[102:105]
	v_mfma_f32_16x16x32_bf16 v[102:105], v[218:221], v[154:157], v[50:53]
	v_mfma_f32_16x16x32_bf16 v[50:53], v[214:217], v[162:165], v[98:101]
	v_mfma_f32_16x16x32_bf16 v[74:77], v[218:221], v[178:181], v[50:53]
	s_setprio 0
	s_nop 5
	v_add_u32_e32 v50, v147, v146
	s_barrier
	ds_read_b128 v[146:149], v50
	ds_read_b128 v[206:209], v50 offset:1024
	ds_read_b128 v[234:237], v50 offset:2048
	ds_read_b128 v[238:241], v50 offset:3072
	s_waitcnt vmcnt(0)
	s_barrier
	s_waitcnt lgkmcnt(0)
	s_setprio 1
	v_mfma_f32_16x16x32_bf16 v[50:53], v[14:17], v[146:149], v[222:225]
	v_mfma_f32_16x16x32_bf16 v[14:17], v[14:17], v[234:237], v[90:93]
	v_mfma_f32_16x16x32_bf16 v[82:85], v[22:25], v[206:209], v[50:53]
	v_mfma_f32_16x16x32_bf16 v[50:53], v[22:25], v[238:241], v[14:17]
	v_mfma_f32_16x16x32_bf16 v[14:17], v[30:33], v[146:149], v[166:169]
	v_mfma_f32_16x16x32_bf16 v[62:65], v[42:45], v[206:209], v[14:17]
	v_mfma_f32_16x16x32_bf16 v[14:17], v[30:33], v[234:237], v[170:173]
	v_mfma_f32_16x16x32_bf16 v[30:33], v[42:45], v[238:241], v[14:17]
	v_mfma_f32_16x16x32_bf16 v[14:17], v[194:197], v[146:149], v[78:81]
	v_mfma_f32_16x16x32_bf16 v[54:57], v[210:213], v[206:209], v[14:17]
	v_mfma_f32_16x16x32_bf16 v[14:17], v[194:197], v[234:237], v[174:177]
	v_mfma_f32_16x16x32_bf16 v[22:25], v[210:213], v[238:241], v[14:17]
	v_mfma_f32_16x16x32_bf16 v[14:17], v[214:217], v[146:149], v[70:73]
	v_mfma_f32_16x16x32_bf16 v[42:45], v[218:221], v[206:209], v[14:17]
	v_mfma_f32_16x16x32_bf16 v[14:17], v[214:217], v[234:237], v[66:69]
	v_mfma_f32_16x16x32_bf16 v[14:17], v[218:221], v[238:241], v[14:17]
	s_setprio 0
	s_barrier
	ds_read_b128 v[166:169], v0 offset:49152
	ds_read_b128 v[170:173], v0 offset:50176
	ds_read_b128 v[174:177], v136 offset:49152
	ds_read_b128 v[194:197], v136 offset:50176
	ds_read_b128 v[210:213], v190 offset:49152
	ds_read_b128 v[214:217], v190 offset:50176
	ds_read_b128 v[218:221], v191 offset:49152
	ds_read_b128 v[222:225], v191 offset:50176
	s_barrier
	s_waitcnt lgkmcnt(0)
	s_setprio 1
	v_mfma_f32_16x16x32_bf16 v[58:61], v[166:169], v[162:165], v[58:61]
	v_mfma_f32_16x16x32_bf16 v[66:69], v[166:169], v[6:9], v[198:201]
	v_mfma_f32_16x16x32_bf16 v[90:93], v[170:173], v[178:181], v[58:61]
	v_mfma_f32_16x16x32_bf16 v[58:61], v[174:177], v[6:9], v[202:205]
	v_mfma_f32_16x16x32_bf16 v[46:49], v[210:213], v[6:9], v[46:49]
	v_mfma_f32_16x16x32_bf16 v[6:9], v[218:221], v[6:9], v[38:41]
	v_mfma_f32_16x16x32_bf16 v[114:117], v[194:197], v[154:157], v[58:61]
	v_mfma_f32_16x16x32_bf16 v[58:61], v[174:177], v[162:165], v[226:229]
	v_mfma_f32_16x16x32_bf16 v[98:101], v[214:217], v[154:157], v[46:49]
	v_mfma_f32_16x16x32_bf16 v[46:49], v[210:213], v[162:165], v[230:233]
	v_mfma_f32_16x16x32_bf16 v[70:73], v[222:225], v[154:157], v[6:9]
	v_mfma_f32_16x16x32_bf16 v[6:9], v[218:221], v[162:165], v[34:37]
	v_mfma_f32_16x16x32_bf16 v[122:125], v[170:173], v[154:157], v[66:69]
	v_mfma_f32_16x16x32_bf16 v[78:81], v[194:197], v[178:181], v[58:61]
	v_mfma_f32_16x16x32_bf16 v[66:69], v[214:217], v[178:181], v[46:49]
	v_mfma_f32_16x16x32_bf16 v[38:41], v[222:225], v[178:181], v[6:9]
	s_setprio 0
	s_setprio 1
	v_mfma_f32_16x16x32_bf16 v[6:9], v[166:169], v[146:149], v[130:133]
	v_mfma_f32_16x16x32_bf16 v[58:61], v[170:173], v[206:209], v[6:9]
	v_mfma_f32_16x16x32_bf16 v[6:9], v[166:169], v[234:237], v[26:29]
	v_mfma_f32_16x16x32_bf16 v[26:29], v[170:173], v[238:241], v[6:9]
	v_mfma_f32_16x16x32_bf16 v[6:9], v[174:177], v[146:149], v[138:141]
	v_mfma_f32_16x16x32_bf16 v[46:49], v[194:197], v[206:209], v[6:9]
	v_mfma_f32_16x16x32_bf16 v[6:9], v[174:177], v[234:237], v[18:21]
	v_mfma_f32_16x16x32_bf16 v[18:21], v[194:197], v[238:241], v[6:9]
	v_mfma_f32_16x16x32_bf16 v[6:9], v[210:213], v[146:149], v[158:161]
	v_mfma_f32_16x16x32_bf16 v[34:37], v[214:217], v[206:209], v[6:9]
	v_mfma_f32_16x16x32_bf16 v[6:9], v[210:213], v[234:237], v[10:13]
	v_mfma_f32_16x16x32_bf16 v[10:13], v[218:221], v[146:149], v[150:153]
	v_mfma_f32_16x16x32_bf16 v[2:5], v[218:221], v[234:237], v[2:5]
	v_mfma_f32_16x16x32_bf16 v[6:9], v[214:217], v[238:241], v[6:9]
	v_mfma_f32_16x16x32_bf16 v[10:13], v[222:225], v[206:209], v[10:13]
	v_mfma_f32_16x16x32_bf16 v[2:5], v[222:225], v[238:241], v[2:5]
	s_setprio 0
	s_barrier
	s_and_saveexec_b64 s[2:3], vcc
	s_cbranch_execz .LBB0_592
	s_barrier

; #define STAGE(P, BASE, LD, br, kt) do { const char* _gp = (const char*)((BASE) + (long)((br) * (LD) + (kt) * BK)); \
;     __builtin_amdgcn_global_load_lds((const unsigned*)(_gp + vo_##BASE##0), (unsigned*)((char*)(P) + tidx * 16), 16, 0, 0); \
;     __builtin_amdgcn_global_load_lds((const unsigned*)(_gp + vo_##BASE##1), (unsigned*)((char*)(P) + tidx * 16 + 8192), 16, 0, 0); } while (0)
; #define LDA(dst, b, h) for (int m = 0; m < 4; ++m) for (int k = 0; k < 2; ++k) \
;     dst[m][k] = *reinterpret_cast<const bf16x8*>((char*)SA(b, h) + lds_byte(wr * 64 + m * 16 + fr, k * 32 + fq * 8))
; #define LDB(dst, b, h) for (int n = 0; n < 2; ++n) for (int k = 0; k < 2; ++k) \
;     dst[n][k] = *reinterpret_cast<const bf16x8*>((char*)SB(b, h) + lds_byte(wc * 32 + n * 16 + fr, k * 32 + fq * 8))
; #define MMA(ai, bj, At, Bt_) do { __builtin_amdgcn_s_setprio(1); \
;     for (int m = 0; m < 4; ++m) for (int n = 0; n < 2; ++n) for (int k = 0; k < 2; ++k) \
;       acc[ai][bj][m][n] = __builtin_amdgcn_mfma_f32_16x16x32_bf16(At[m][k], Bt_[n][k], acc[ai][bj][m][n], 0, 0, 0); \
;     __builtin_amdgcn_s_setprio(0); } while (0)
; #define WAIT_L(n) asm volatile("s_waitcnt lgkmcnt(" #n ")" ::: "memory")
; #define BAR __builtin_amdgcn_s_barrier()
; #define SCHED __builtin_amdgcn_sched_barrier(0)
; __device__ __forceinline__ void gemm_main(acc_t& acc, const u16* A, int lda, const u16* Bt, int ldb, int nt, const int tidx) {
;     ...
;         LDB(B0, 0, 0); SCHED; LDA(At, 0, 0); STAGE(SA(1, 1), A, lda, HALF, t + 1);
;         WAIT_L(8); BAR; WAIT_L(0); MMA(0, 0, At, B0); BAR; SCHED;
;         LDB(B1, 0, 1); STAGE(SB(0, 0), Bt, ldb, 0, t + 2);
;         BAR; WAIT_L(0); MMA(0, 1, At, B1); BAR;
;         LDA(At, 0, 1); STAGE(SA(0, 0), A, lda, 0, t + 2);
;         BAR; WAIT_L(0); MMA(1, 0, At, B0); BAR; SCHED;
.LBB0_610:
	v_add_u32_e32 v174, v147, v136
	ds_read_b128 v[162:165], v174
	ds_read_b128 v[166:169], v174 offset:1024
	ds_read_b128 v[170:173], v174 offset:2048
	ds_read_b128 v[174:177], v174 offset:3072
	s_add_i32 s24, s16, 0x8040
	s_ashr_i32 s25, s24, 31
	s_lshl_b64 s[24:25], s[24:25], 1
	s_add_u32 s24, s12, s24
	v_add_u32_e32 v224, 0xc000, v139
	s_addc_u32 s25, s13, s25
	v_readfirstlane_b32 s17, v224
	v_add_u32_e32 v224, 0xe000, v139
	v_add_u32_e32 v190, v148, v145
	v_add_u32_e32 v191, v146, v144
	v_add_u32_e32 v240, v146, v142
	v_add_u32_e32 v241, v146, v143
	v_lshl_add_u64 v[222:223], s[24:25], 0, v[130:131]
	s_mov_b32 m0, s17
	v_readfirstlane_b32 s17, v224
	ds_read_b128 v[178:181], v190
	ds_read_b128 v[194:197], v190 offset:1024
	ds_read_b128 v[198:201], v191
	ds_read_b128 v[202:205], v191 offset:1024
	ds_read_b128 v[206:209], v240
	ds_read_b128 v[210:213], v240 offset:1024
	ds_read_b128 v[214:217], v241
	ds_read_b128 v[218:221], v241 offset:1024
	global_load_lds_dwordx4 v[222:223], off
	v_lshl_add_u64 v[222:223], s[24:25], 0, v[132:133]
	s_mov_b32 m0, s17
	s_nop 0
	global_load_lds_dwordx4 v[222:223], off
	s_waitcnt lgkmcnt(8)
	s_barrier
	s_waitcnt lgkmcnt(0)
	s_setprio 1
	v_mfma_f32_16x16x32_bf16 v[126:129], v[178:181], v[162:165], v[126:129]
	v_mfma_f32_16x16x32_bf16 v[122:125], v[178:181], v[170:173], v[122:125]
	v_mfma_f32_16x16x32_bf16 v[118:121], v[198:201], v[162:165], v[118:121]
	v_mfma_f32_16x16x32_bf16 v[114:117], v[198:201], v[170:173], v[114:117]
	v_mfma_f32_16x16x32_bf16 v[110:113], v[206:209], v[162:165], v[110:113]
	v_mfma_f32_16x16x32_bf16 v[106:109], v[206:209], v[170:173], v[106:109]
	v_mfma_f32_16x16x32_bf16 v[102:105], v[214:217], v[162:165], v[102:105]
	v_mfma_f32_16x16x32_bf16 v[98:101], v[214:217], v[170:173], v[98:101]
	v_mfma_f32_16x16x32_bf16 v[126:129], v[194:197], v[166:169], v[126:129]
	v_mfma_f32_16x16x32_bf16 v[122:125], v[194:197], v[174:177], v[122:125]
	v_mfma_f32_16x16x32_bf16 v[118:121], v[202:205], v[166:169], v[118:121]
	v_mfma_f32_16x16x32_bf16 v[114:117], v[202:205], v[174:177], v[114:117]
	v_mfma_f32_16x16x32_bf16 v[110:113], v[210:213], v[166:169], v[110:113]
	v_mfma_f32_16x16x32_bf16 v[106:109], v[210:213], v[174:177], v[106:109]
	v_mfma_f32_16x16x32_bf16 v[102:105], v[218:221], v[166:169], v[102:105]
	v_mfma_f32_16x16x32_bf16 v[98:101], v[218:221], v[174:177], v[98:101]
	s_setprio 0
	s_barrier
	s_add_i32 s72, s16, 0x80
	s_add_i32 s11, s11, 2
	s_lshl_b64 s[24:25], s[72:73], 1
	s_add_u32 s26, s14, s24
	s_addc_u32 s27, s15, s25
	v_readfirstlane_b32 s17, v149
	v_add_u32_e32 v234, v141, v136
	v_lshl_add_u64 v[238:239], s[26:27], 0, v[0:1]
	s_mov_b32 m0, s17
	v_readfirstlane_b32 s17, v150
	ds_read_b128 v[222:225], v234
	ds_read_b128 v[226:229], v234 offset:1024
	ds_read_b128 v[230:233], v234 offset:2048
	ds_read_b128 v[234:237], v234 offset:3072
	global_load_lds_dwordx4 v[238:239], off
	v_lshl_add_u64 v[238:239], s[26:27], 0, v[134:135]
	s_mov_b32 m0, s17
	s_nop 0
	global_load_lds_dwordx4 v[238:239], off
	s_barrier
	s_waitcnt lgkmcnt(0)
	s_setprio 1
	v_mfma_f32_16x16x32_bf16 v[94:97], v[178:181], v[222:225], v[94:97]
	v_mfma_f32_16x16x32_bf16 v[90:93], v[178:181], v[230:233], v[90:93]
	v_mfma_f32_16x16x32_bf16 v[86:89], v[198:201], v[222:225], v[86:89]
	v_mfma_f32_16x16x32_bf16 v[82:85], v[198:201], v[230:233], v[82:85]
	v_mfma_f32_16x16x32_bf16 v[78:81], v[206:209], v[222:225], v[78:81]
	v_mfma_f32_16x16x32_bf16 v[74:77], v[206:209], v[230:233], v[74:77]
	v_mfma_f32_16x16x32_bf16 v[70:73], v[214:217], v[222:225], v[70:73]
	v_mfma_f32_16x16x32_bf16 v[66:69], v[214:217], v[230:233], v[66:69]
	v_mfma_f32_16x16x32_bf16 v[94:97], v[194:197], v[226:229], v[94:97]
	v_mfma_f32_16x16x32_bf16 v[90:93], v[194:197], v[234:237], v[90:93]
	v_mfma_f32_16x16x32_bf16 v[86:89], v[202:205], v[226:229], v[86:89]
	v_mfma_f32_16x16x32_bf16 v[82:85], v[202:205], v[234:237], v[82:85]
	v_mfma_f32_16x16x32_bf16 v[78:81], v[210:213], v[226:229], v[78:81]
	v_mfma_f32_16x16x32_bf16 v[74:77], v[210:213], v[234:237], v[74:77]
	v_mfma_f32_16x16x32_bf16 v[70:73], v[218:221], v[226:229], v[70:73]
	v_mfma_f32_16x16x32_bf16 v[66:69], v[218:221], v[234:237], v[66:69]
	s_setprio 0
	s_add_u32 s24, s12, s24
	s_addc_u32 s25, s13, s25
	v_readfirstlane_b32 s17, v139
	v_lshl_add_u64 v[238:239], s[24:25], 0, v[130:131]
	s_mov_b32 m0, s17
	v_readfirstlane_b32 s17, v151
	s_barrier
	ds_read_b128 v[178:181], v190 offset:16384
	ds_read_b128 v[194:197], v190 offset:17408
	ds_read_b128 v[198:201], v191 offset:16384
	ds_read_b128 v[202:205], v191 offset:17408
	ds_read_b128 v[206:209], v240 offset:16384
	ds_read_b128 v[210:213], v240 offset:17408
	ds_read_b128 v[214:217], v241 offset:16384
	ds_read_b128 v[218:221], v241 offset:17408
	global_load_lds_dwordx4 v[238:239], off
	v_lshl_add_u64 v[238:239], s[24:25], 0, v[132:133]
	s_mov_b32 m0, s17
	s_nop 0
	global_load_lds_dwordx4 v[238:239], off
	s_barrier
	s_waitcnt lgkmcnt(0)
	s_setprio 1
	v_mfma_f32_16x16x32_bf16 v[62:65], v[178:181], v[162:165], v[62:65]
	v_mfma_f32_16x16x32_bf16 v[58:61], v[178:181], v[170:173], v[58:61]
	v_mfma_f32_16x16x32_bf16 v[54:57], v[198:201], v[162:165], v[54:57]
	v_mfma_f32_16x16x32_bf16 v[50:53], v[198:201], v[170:173], v[50:53]
	v_mfma_f32_16x16x32_bf16 v[46:49], v[206:209], v[162:165], v[46:49]
	v_mfma_f32_16x16x32_bf16 v[42:45], v[206:209], v[170:173], v[42:45]
	v_mfma_f32_16x16x32_bf16 v[38:41], v[214:217], v[162:165], v[38:41]
	v_mfma_f32_16x16x32_bf16 v[30:33], v[214:217], v[170:173], v[30:33]
	v_mfma_f32_16x16x32_bf16 v[62:65], v[194:197], v[166:169], v[62:65]
	v_mfma_f32_16x16x32_bf16 v[58:61], v[194:197], v[174:177], v[58:61]
	v_mfma_f32_16x16x32_bf16 v[54:57], v[202:205], v[166:169], v[54:57]
	v_mfma_f32_16x16x32_bf16 v[50:53], v[202:205], v[174:177], v[50:53]
	v_mfma_f32_16x16x32_bf16 v[46:49], v[210:213], v[166:169], v[46:49]
	v_mfma_f32_16x16x32_bf16 v[42:45], v[210:213], v[174:177], v[42:45]
	v_mfma_f32_16x16x32_bf16 v[38:41], v[218:221], v[166:169], v[38:41]
	v_mfma_f32_16x16x32_bf16 v[30:33], v[218:221], v[174:177], v[30:33]
	s_setprio 0
	s_barrier
; #define STAGE(P, BASE, LD, br, kt) do { const char* _gp = (const char*)((BASE) + (long)((br) * (LD) + (kt) * BK)); \
;     __builtin_amdgcn_global_load_lds((const unsigned*)(_gp + vo_##BASE##0), (unsigned*)((char*)(P) + tidx * 16), 16, 0, 0); \
;     __builtin_amdgcn_global_load_lds((const unsigned*)(_gp + vo_##BASE##1), (unsigned*)((char*)(P) + tidx * 16 + 8192), 16, 0, 0); } while (0)
; #define LDA(dst, b, h) for (int m = 0; m < 4; ++m) for (int k = 0; k < 2; ++k) \
;     dst[m][k] = *reinterpret_cast<const bf16x8*>((char*)SA(b, h) + lds_byte(wr * 64 + m * 16 + fr, k * 32 + fq * 8))
; #define LDB(dst, b, h) for (int n = 0; n < 2; ++n) for (int k = 0; k < 2; ++k) \
;     dst[n][k] = *reinterpret_cast<const bf16x8*>((char*)SB(b, h) + lds_byte(wc * 32 + n * 16 + fr, k * 32 + fq * 8))
; #define MMA(ai, bj, At, Bt_) do { __builtin_amdgcn_s_setprio(1); \
;     for (int m = 0; m < 4; ++m) for (int n = 0; n < 2; ++n) for (int k = 0; k < 2; ++k) \
;       acc[ai][bj][m][n] = __builtin_amdgcn_mfma_f32_16x16x32_bf16(At[m][k], Bt_[n][k], acc[ai][bj][m][n], 0, 0, 0); \
;     __builtin_amdgcn_s_setprio(0); } while (0)
; #define WAIT_V(n) asm volatile("s_waitcnt vmcnt(" #n ")" ::: "memory")
; #define WAIT_L(n) asm volatile("s_waitcnt lgkmcnt(" #n ")" ::: "memory")
; #define BAR __builtin_amdgcn_s_barrier()
; #define SCHED __builtin_amdgcn_sched_barrier(0)
; __device__ __forceinline__ void gemm_main(acc_t& acc, const u16* A, int lda, const u16* Bt, int ldb, int nt, const int tidx) {
;     ...
;         STAGE(SB(0, 1), Bt, ldb, HALF, t + 2);
;         WAIT_V(6); BAR; MMA(1, 1, At, B1); BAR;
;         LDB(B0, 1, 0); SCHED; LDA(At, 1, 0); STAGE(SA(0, 1), A, lda, HALF, t + 2);
;         WAIT_L(8); BAR; WAIT_L(0); MMA(0, 0, At, B0); BAR; SCHED;
;         LDB(B1, 1, 1); STAGE(SB(1, 0), Bt, ldb, 0, t + 3);
;         BAR; WAIT_L(0); MMA(0, 1, At, B1); BAR;
	s_add_u32 s26, s26, 0x20000
	s_addc_u32 s27, s27, 0
	v_readfirstlane_b32 s17, v152
	v_lshl_add_u64 v[162:163], s[26:27], 0, v[0:1]
	s_mov_b32 m0, s17
	v_readfirstlane_b32 s17, v153
	global_load_lds_dwordx4 v[162:163], off
	v_lshl_add_u64 v[162:163], s[26:27], 0, v[134:135]
	s_mov_b32 m0, s17
	s_nop 0
	global_load_lds_dwordx4 v[162:163], off
	s_waitcnt vmcnt(6)
	s_barrier
	s_setprio 1
	v_mfma_f32_16x16x32_bf16 v[34:37], v[178:181], v[222:225], v[34:37]
	v_mfma_f32_16x16x32_bf16 v[26:29], v[178:181], v[230:233], v[26:29]
	v_mfma_f32_16x16x32_bf16 v[22:25], v[198:201], v[222:225], v[22:25]
	v_mfma_f32_16x16x32_bf16 v[18:21], v[198:201], v[230:233], v[18:21]
	v_mfma_f32_16x16x32_bf16 v[14:17], v[206:209], v[222:225], v[14:17]
	v_mfma_f32_16x16x32_bf16 v[10:13], v[206:209], v[230:233], v[10:13]
	v_mfma_f32_16x16x32_bf16 v[6:9], v[214:217], v[222:225], v[6:9]
	v_mfma_f32_16x16x32_bf16 v[2:5], v[214:217], v[230:233], v[2:5]
	v_mfma_f32_16x16x32_bf16 v[34:37], v[194:197], v[226:229], v[34:37]
	v_mfma_f32_16x16x32_bf16 v[26:29], v[194:197], v[234:237], v[26:29]
	v_mfma_f32_16x16x32_bf16 v[22:25], v[202:205], v[226:229], v[22:25]
	v_mfma_f32_16x16x32_bf16 v[18:21], v[202:205], v[234:237], v[18:21]
	v_mfma_f32_16x16x32_bf16 v[14:17], v[210:213], v[226:229], v[14:17]
	v_mfma_f32_16x16x32_bf16 v[10:13], v[210:213], v[234:237], v[10:13]
	v_mfma_f32_16x16x32_bf16 v[6:9], v[218:221], v[226:229], v[6:9]
	v_mfma_f32_16x16x32_bf16 v[2:5], v[218:221], v[234:237], v[2:5]
	s_setprio 0
	v_add_u32_e32 v174, v138, v136
	s_barrier
	ds_read_b128 v[162:165], v174
	ds_read_b128 v[166:169], v174 offset:1024
	ds_read_b128 v[170:173], v174 offset:2048
	ds_read_b128 v[174:177], v174 offset:3072
	s_add_u32 s24, s24, 0x10000
	s_addc_u32 s25, s25, 0
	v_readfirstlane_b32 s17, v154
	v_lshl_add_u64 v[222:223], s[24:25], 0, v[130:131]
	s_mov_b32 m0, s17
	v_readfirstlane_b32 s17, v155
	ds_read_b128 v[178:181], v190 offset:32768
	ds_read_b128 v[194:197], v190 offset:33792
	ds_read_b128 v[198:201], v191 offset:32768
	ds_read_b128 v[202:205], v191 offset:33792
	ds_read_b128 v[206:209], v240 offset:32768
	ds_read_b128 v[210:213], v240 offset:33792
	ds_read_b128 v[214:217], v241 offset:32768
	ds_read_b128 v[218:221], v241 offset:33792
	global_load_lds_dwordx4 v[222:223], off
	v_lshl_add_u64 v[222:223], s[24:25], 0, v[132:133]
	s_mov_b32 m0, s17
	s_nop 0
	global_load_lds_dwordx4 v[222:223], off
	s_waitcnt lgkmcnt(8)
	s_barrier
	s_waitcnt lgkmcnt(0)
	s_setprio 1
	v_mfma_f32_16x16x32_bf16 v[126:129], v[178:181], v[162:165], v[126:129]
	v_mfma_f32_16x16x32_bf16 v[122:125], v[178:181], v[170:173], v[122:125]
	v_mfma_f32_16x16x32_bf16 v[118:121], v[198:201], v[162:165], v[118:121]
	v_mfma_f32_16x16x32_bf16 v[114:117], v[198:201], v[170:173], v[114:117]
	v_mfma_f32_16x16x32_bf16 v[110:113], v[206:209], v[162:165], v[110:113]
	v_mfma_f32_16x16x32_bf16 v[106:109], v[206:209], v[170:173], v[106:109]
	v_mfma_f32_16x16x32_bf16 v[102:105], v[214:217], v[162:165], v[102:105]
	v_mfma_f32_16x16x32_bf16 v[98:101], v[214:217], v[170:173], v[98:101]
	v_mfma_f32_16x16x32_bf16 v[126:129], v[194:197], v[166:169], v[126:129]
	v_mfma_f32_16x16x32_bf16 v[122:125], v[194:197], v[174:177], v[122:125]
	v_mfma_f32_16x16x32_bf16 v[118:121], v[202:205], v[166:169], v[118:121]
	v_mfma_f32_16x16x32_bf16 v[114:117], v[202:205], v[174:177], v[114:117]
	v_mfma_f32_16x16x32_bf16 v[110:113], v[210:213], v[166:169], v[110:113]
	v_mfma_f32_16x16x32_bf16 v[106:109], v[210:213], v[174:177], v[106:109]
	v_mfma_f32_16x16x32_bf16 v[102:105], v[218:221], v[166:169], v[102:105]
	v_mfma_f32_16x16x32_bf16 v[98:101], v[218:221], v[174:177], v[98:101]
	s_setprio 0
	s_barrier
	s_ashr_i32 s17, s16, 31
	s_lshl_b64 s[24:25], s[16:17], 1
	s_add_u32 s26, s14, s24
	s_addc_u32 s27, s15, s25
	v_lshl_add_u64 v[238:239], s[26:27], 0, v[0:1]
	v_readfirstlane_b32 s17, v156
	v_add_u32_e32 v234, v137, v136
	v_lshl_add_u64 v[238:239], v[238:239], 0, s[0:1]
	s_mov_b32 m0, s17
	ds_read_b128 v[222:225], v234
	ds_read_b128 v[226:229], v234 offset:1024
	ds_read_b128 v[230:233], v234 offset:2048
	ds_read_b128 v[234:237], v234 offset:3072
	global_load_lds_dwordx4 v[238:239], off
	v_lshl_add_u64 v[238:239], s[26:27], 0, v[134:135]
	v_readfirstlane_b32 s17, v157
	v_lshl_add_u64 v[238:239], v[238:239], 0, s[0:1]
	s_mov_b32 m0, s17
	s_nop 0
	global_load_lds_dwordx4 v[238:239], off
	s_barrier
	s_waitcnt lgkmcnt(0)
	s_setprio 1
	v_mfma_f32_16x16x32_bf16 v[94:97], v[178:181], v[222:225], v[94:97]
	v_mfma_f32_16x16x32_bf16 v[90:93], v[178:181], v[230:233], v[90:93]
	v_mfma_f32_16x16x32_bf16 v[86:89], v[198:201], v[222:225], v[86:89]
	v_mfma_f32_16x16x32_bf16 v[82:85], v[198:201], v[230:233], v[82:85]
	v_mfma_f32_16x16x32_bf16 v[78:81], v[206:209], v[222:225], v[78:81]
	v_mfma_f32_16x16x32_bf16 v[74:77], v[206:209], v[230:233], v[74:77]
	v_mfma_f32_16x16x32_bf16 v[70:73], v[214:217], v[222:225], v[70:73]
	v_mfma_f32_16x16x32_bf16 v[66:69], v[214:217], v[230:233], v[66:69]
	v_mfma_f32_16x16x32_bf16 v[94:97], v[194:197], v[226:229], v[94:97]
	v_mfma_f32_16x16x32_bf16 v[90:93], v[194:197], v[234:237], v[90:93]
	v_mfma_f32_16x16x32_bf16 v[86:89], v[202:205], v[226:229], v[86:89]
	v_mfma_f32_16x16x32_bf16 v[82:85], v[202:205], v[234:237], v[82:85]
	v_mfma_f32_16x16x32_bf16 v[78:81], v[210:213], v[226:229], v[78:81]
	v_mfma_f32_16x16x32_bf16 v[74:77], v[210:213], v[234:237], v[74:77]
	v_mfma_f32_16x16x32_bf16 v[70:73], v[218:221], v[226:229], v[70:73]
	v_mfma_f32_16x16x32_bf16 v[66:69], v[218:221], v[234:237], v[66:69]
	s_setprio 0
	s_add_u32 s24, s12, s24
	s_addc_u32 s25, s13, s25
	v_lshl_add_u64 v[238:239], s[24:25], 0, v[130:131]
	v_readfirstlane_b32 s17, v158
	v_lshl_add_u64 v[238:239], v[238:239], 0, s[0:1]
	s_mov_b32 m0, s17
	s_barrier
; #define STAGE(P, BASE, LD, br, kt) do { const char* _gp = (const char*)((BASE) + (long)((br) * (LD) + (kt) * BK)); \
;     __builtin_amdgcn_global_load_lds((const unsigned*)(_gp + vo_##BASE##0), (unsigned*)((char*)(P) + tidx * 16), 16, 0, 0); \
;     __builtin_amdgcn_global_load_lds((const unsigned*)(_gp + vo_##BASE##1), (unsigned*)((char*)(P) + tidx * 16 + 8192), 16, 0, 0); } while (0)
; #define LDA(dst, b, h) for (int m = 0; m < 4; ++m) for (int k = 0; k < 2; ++k) \
;     dst[m][k] = *reinterpret_cast<const bf16x8*>((char*)SA(b, h) + lds_byte(wr * 64 + m * 16 + fr, k * 32 + fq * 8))
; #define LDB(dst, b, h) for (int n = 0; n < 2; ++n) for (int k = 0; k < 2; ++k) \
;     dst[n][k] = *reinterpret_cast<const bf16x8*>((char*)SB(b, h) + lds_byte(wc * 32 + n * 16 + fr, k * 32 + fq * 8))
; #define MMA(ai, bj, At, Bt_) do { __builtin_amdgcn_s_setprio(1); \
;     for (int m = 0; m < 4; ++m) for (int n = 0; n < 2; ++n) for (int k = 0; k < 2; ++k) \
;       acc[ai][bj][m][n] = __builtin_amdgcn_mfma_f32_16x16x32_bf16(At[m][k], Bt_[n][k], acc[ai][bj][m][n], 0, 0, 0); \
;     __builtin_amdgcn_s_setprio(0); } while (0)
; #define WAIT_V(n) asm volatile("s_waitcnt vmcnt(" #n ")" ::: "memory")
; #define WAIT_L(n) asm volatile("s_waitcnt lgkmcnt(" #n ")" ::: "memory")
; #define BAR __builtin_amdgcn_s_barrier()
; #define SCHED __builtin_amdgcn_sched_barrier(0)
; __device__ __forceinline__ void gemm_main(acc_t& acc, const u16* A, int lda, const u16* Bt, int ldb, int nt, const int tidx) {
;     ...
;         LDA(At, 1, 1); STAGE(SA(1, 0), A, lda, 0, t + 3);
;         BAR; WAIT_L(0); MMA(1, 0, At, B0); BAR; SCHED;
;         STAGE(SB(1, 1), Bt, ldb, HALF, t + 3);
;         WAIT_V(6); BAR; MMA(1, 1, At, B1); BAR;
;     }
;     { LDB(B0, 0, 0); LDA(At, 0, 0); STAGE(SA(1, 1), A, lda, HALF, nt - 1);
;       BAR; WAIT_L(0); MMA(0, 0, At, B0); BAR;
	ds_read_b128 v[178:181], v190 offset:49152
	ds_read_b128 v[194:197], v190 offset:50176
	ds_read_b128 v[198:201], v191 offset:49152
	ds_read_b128 v[202:205], v191 offset:50176
	ds_read_b128 v[206:209], v240 offset:49152
	ds_read_b128 v[210:213], v240 offset:50176
	ds_read_b128 v[214:217], v241 offset:49152
	ds_read_b128 v[218:221], v241 offset:50176
	global_load_lds_dwordx4 v[238:239], off
	v_lshl_add_u64 v[238:239], s[24:25], 0, v[132:133]
	v_readfirstlane_b32 s17, v159
	v_lshl_add_u64 v[238:239], v[238:239], 0, s[0:1]
	s_mov_b32 m0, s17
	s_nop 0
	global_load_lds_dwordx4 v[238:239], off
	s_barrier
	s_waitcnt lgkmcnt(0)
	s_setprio 1
	v_mfma_f32_16x16x32_bf16 v[62:65], v[178:181], v[162:165], v[62:65]
	v_mfma_f32_16x16x32_bf16 v[58:61], v[178:181], v[170:173], v[58:61]
	v_mfma_f32_16x16x32_bf16 v[54:57], v[198:201], v[162:165], v[54:57]
	v_mfma_f32_16x16x32_bf16 v[50:53], v[198:201], v[170:173], v[50:53]
	v_mfma_f32_16x16x32_bf16 v[46:49], v[206:209], v[162:165], v[46:49]
	v_mfma_f32_16x16x32_bf16 v[42:45], v[206:209], v[170:173], v[42:45]
	v_mfma_f32_16x16x32_bf16 v[38:41], v[214:217], v[162:165], v[38:41]
	v_mfma_f32_16x16x32_bf16 v[30:33], v[214:217], v[170:173], v[30:33]
	v_mfma_f32_16x16x32_bf16 v[62:65], v[194:197], v[166:169], v[62:65]
	v_mfma_f32_16x16x32_bf16 v[58:61], v[194:197], v[174:177], v[58:61]
	v_mfma_f32_16x16x32_bf16 v[54:57], v[202:205], v[166:169], v[54:57]
	v_mfma_f32_16x16x32_bf16 v[50:53], v[202:205], v[174:177], v[50:53]
	v_mfma_f32_16x16x32_bf16 v[46:49], v[210:213], v[166:169], v[46:49]
	v_mfma_f32_16x16x32_bf16 v[42:45], v[210:213], v[174:177], v[42:45]
	v_mfma_f32_16x16x32_bf16 v[38:41], v[218:221], v[166:169], v[38:41]
	v_mfma_f32_16x16x32_bf16 v[30:33], v[218:221], v[174:177], v[30:33]
	s_setprio 0
	s_barrier
	s_add_i32 s16, s16, 0x100c0
	s_ashr_i32 s17, s16, 31
	s_lshl_b64 s[16:17], s[16:17], 1
	s_add_u32 s16, s14, s16
	s_addc_u32 s17, s15, s17
	v_readfirstlane_b32 s24, v160
	v_lshl_add_u64 v[162:163], s[16:17], 0, v[0:1]
	s_mov_b32 m0, s24
	s_nop 0
	global_load_lds_dwordx4 v[162:163], off
	v_lshl_add_u64 v[162:163], s[16:17], 0, v[134:135]
	v_readfirstlane_b32 s16, v161
	s_mov_b32 m0, s16
	s_nop 0
	global_load_lds_dwordx4 v[162:163], off
	s_waitcnt vmcnt(6)
	s_barrier
	s_setprio 1
	v_mfma_f32_16x16x32_bf16 v[34:37], v[178:181], v[222:225], v[34:37]
	v_mfma_f32_16x16x32_bf16 v[26:29], v[178:181], v[230:233], v[26:29]
	v_mfma_f32_16x16x32_bf16 v[22:25], v[198:201], v[222:225], v[22:25]
	v_mfma_f32_16x16x32_bf16 v[18:21], v[198:201], v[230:233], v[18:21]
	v_mfma_f32_16x16x32_bf16 v[14:17], v[206:209], v[222:225], v[14:17]
	v_mfma_f32_16x16x32_bf16 v[10:13], v[206:209], v[230:233], v[10:13]
	v_mfma_f32_16x16x32_bf16 v[6:9], v[214:217], v[222:225], v[6:9]
	v_mfma_f32_16x16x32_bf16 v[2:5], v[214:217], v[230:233], v[2:5]
	v_mfma_f32_16x16x32_bf16 v[34:37], v[194:197], v[226:229], v[34:37]
	v_mfma_f32_16x16x32_bf16 v[26:29], v[194:197], v[234:237], v[26:29]
	v_mfma_f32_16x16x32_bf16 v[22:25], v[202:205], v[226:229], v[22:25]
	v_mfma_f32_16x16x32_bf16 v[18:21], v[202:205], v[234:237], v[18:21]
	v_mfma_f32_16x16x32_bf16 v[14:17], v[210:213], v[226:229], v[14:17]
	v_mfma_f32_16x16x32_bf16 v[10:13], v[210:213], v[234:237], v[10:13]
	v_mfma_f32_16x16x32_bf16 v[6:9], v[218:221], v[226:229], v[6:9]
	v_mfma_f32_16x16x32_bf16 v[2:5], v[218:221], v[234:237], v[2:5]
	s_setprio 0
	s_cmp_lt_i32 s11, s9
	s_mov_b32 s16, s72
	s_barrier
	s_cbranch_scc1 .LBB0_610
.LBB0_611:
	s_lshl_b32 s5, s5, 6
	s_add_i32 s14, s5, 0x7fc0
	s_ashr_i32 s15, s14, 31
	s_lshl_b64 s[14:15], s[14:15], 1
	s_add_u32 s12, s12, s14
	v_cmp_gt_u32_e32 vcc, s51, v140
	v_add_u32_e32 v140, 0xc000, v139
	s_addc_u32 s13, s13, s15
	v_add_u32_e32 v0, v147, v136
	v_readfirstlane_b32 s5, v140
	v_lshl_add_u64 v[134:135], s[12:13], 0, v[130:131]
	v_lshl_add_u64 v[198:199], s[12:13], 0, v[132:133]
	ds_read_b128 v[130:133], v0
	ds_read_b128 v[150:153], v0 offset:1024
	ds_read_b128 v[154:157], v0 offset:2048
	ds_read_b128 v[158:161], v0 offset:3072
	v_add_u32_e32 v0, v148, v145
	v_add_u32_e32 v190, v146, v144
	v_add_u32_e32 v191, v146, v142
	v_add_u32_e32 v226, v146, v143
	s_mov_b32 m0, s5
	ds_read_b128 v[162:165], v0
	ds_read_b128 v[166:169], v0 offset:1024
	ds_read_b128 v[170:173], v190
	ds_read_b128 v[174:177], v190 offset:1024
	ds_read_b128 v[178:181], v191
	ds_read_b128 v[194:197], v191 offset:1024
	ds_read_b128 v[142:145], v226
	ds_read_b128 v[146:149], v226 offset:1024
	global_load_lds_dwordx4 v[134:135], off
	v_add_u32_e32 v134, 0xe000, v139
	s_nop 0
	v_readfirstlane_b32 s5, v134
	s_mov_b32 m0, s5
	s_nop 0
	global_load_lds_dwordx4 v[198:199], off
	s_barrier
	s_waitcnt lgkmcnt(0)
	s_setprio 1
	v_mfma_f32_16x16x32_bf16 v[126:129], v[162:165], v[130:133], v[126:129]
	v_mfma_f32_16x16x32_bf16 v[122:125], v[162:165], v[154:157], v[122:125]
	v_mfma_f32_16x16x32_bf16 v[114:117], v[170:173], v[154:157], v[114:117]
	v_mfma_f32_16x16x32_bf16 v[106:109], v[178:181], v[154:157], v[106:109]
	v_mfma_f32_16x16x32_bf16 v[98:101], v[142:145], v[154:157], v[98:101]
	v_mfma_f32_16x16x32_bf16 v[126:129], v[166:169], v[150:153], v[126:129]
	v_mfma_f32_16x16x32_bf16 v[122:125], v[166:169], v[158:161], v[122:125]
	v_mfma_f32_16x16x32_bf16 v[118:121], v[170:173], v[130:133], v[118:121]
	v_mfma_f32_16x16x32_bf16 v[114:117], v[174:177], v[158:161], v[114:117]
	v_mfma_f32_16x16x32_bf16 v[110:113], v[178:181], v[130:133], v[110:113]
	v_mfma_f32_16x16x32_bf16 v[106:109], v[194:197], v[158:161], v[106:109]
	v_mfma_f32_16x16x32_bf16 v[102:105], v[142:145], v[130:133], v[102:105]
	v_mfma_f32_16x16x32_bf16 v[98:101], v[146:149], v[158:161], v[98:101]
	v_mfma_f32_16x16x32_bf16 v[198:201], v[174:177], v[150:153], v[118:121]
	v_mfma_f32_16x16x32_bf16 v[202:205], v[194:197], v[150:153], v[110:113]
	v_mfma_f32_16x16x32_bf16 v[206:209], v[146:149], v[150:153], v[102:105]
	s_setprio 0
	v_add_u32_e32 v134, v141, v136
	s_barrier
; #define LDA(dst, b, h) for (int m = 0; m < 4; ++m) for (int k = 0; k < 2; ++k) \
;     dst[m][k] = *reinterpret_cast<const bf16x8*>((char*)SA(b, h) + lds_byte(wr * 64 + m * 16 + fr, k * 32 + fq * 8))
; #define LDB(dst, b, h) for (int n = 0; n < 2; ++n) for (int k = 0; k < 2; ++k) \
;     dst[n][k] = *reinterpret_cast<const bf16x8*>((char*)SB(b, h) + lds_byte(wc * 32 + n * 16 + fr, k * 32 + fq * 8))
; #define MMA(ai, bj, At, Bt_) do { __builtin_amdgcn_s_setprio(1); \
;     for (int m = 0; m < 4; ++m) for (int n = 0; n < 2; ++n) for (int k = 0; k < 2; ++k) \
;       acc[ai][bj][m][n] = __builtin_amdgcn_mfma_f32_16x16x32_bf16(At[m][k], Bt_[n][k], acc[ai][bj][m][n], 0, 0, 0); \
;     __builtin_amdgcn_s_setprio(0); } while (0)
; #define WAIT_V(n) asm volatile("s_waitcnt vmcnt(" #n ")" ::: "memory")
; #define WAIT_L(n) asm volatile("s_waitcnt lgkmcnt(" #n ")" ::: "memory")
; #define BAR __builtin_amdgcn_s_barrier()
; __device__ __forceinline__ void gemm_main(acc_t& acc, const u16* A, int lda, const u16* Bt, int ldb, int nt, const int tidx) {
;     ...
;       LDB(B1, 0, 1); BAR; WAIT_L(0); MMA(0, 1, At, B1); BAR;
;       LDA(At, 0, 1); WAIT_V(4); BAR; WAIT_L(0); MMA(1, 0, At, B0); MMA(1, 1, At, B1); BAR; }
;     { LDB(B0, 1, 0); LDA(At, 1, 0); WAIT_V(2); BAR; WAIT_L(0); MMA(0, 0, At, B0); BAR;
	s_nop 0
	ds_read_b128 v[102:105], v134
	ds_read_b128 v[110:113], v134 offset:1024
	ds_read_b128 v[118:121], v134 offset:2048
	ds_read_b128 v[210:213], v134 offset:3072
	s_barrier
	s_waitcnt lgkmcnt(0)
	s_setprio 1
	v_mfma_f32_16x16x32_bf16 v[90:93], v[162:165], v[118:121], v[90:93]
	v_mfma_f32_16x16x32_bf16 v[82:85], v[170:173], v[118:121], v[82:85]
	v_mfma_f32_16x16x32_bf16 v[74:77], v[178:181], v[118:121], v[74:77]
	v_mfma_f32_16x16x32_bf16 v[66:69], v[142:145], v[118:121], v[66:69]
	v_mfma_f32_16x16x32_bf16 v[94:97], v[162:165], v[102:105], v[94:97]
	v_mfma_f32_16x16x32_bf16 v[90:93], v[166:169], v[210:213], v[90:93]
	v_mfma_f32_16x16x32_bf16 v[86:89], v[170:173], v[102:105], v[86:89]
	v_mfma_f32_16x16x32_bf16 v[82:85], v[174:177], v[210:213], v[82:85]
	v_mfma_f32_16x16x32_bf16 v[78:81], v[178:181], v[102:105], v[78:81]
	v_mfma_f32_16x16x32_bf16 v[74:77], v[194:197], v[210:213], v[74:77]
	v_mfma_f32_16x16x32_bf16 v[70:73], v[142:145], v[102:105], v[70:73]
	v_mfma_f32_16x16x32_bf16 v[66:69], v[146:149], v[210:213], v[66:69]
	v_mfma_f32_16x16x32_bf16 v[214:217], v[166:169], v[110:113], v[94:97]
	v_mfma_f32_16x16x32_bf16 v[162:165], v[174:177], v[110:113], v[86:89]
	v_mfma_f32_16x16x32_bf16 v[166:169], v[194:197], v[110:113], v[78:81]
	v_mfma_f32_16x16x32_bf16 v[170:173], v[146:149], v[110:113], v[70:73]
	s_setprio 0
	s_barrier
	s_nop 0
	ds_read_b128 v[70:73], v0 offset:16384
	ds_read_b128 v[78:81], v0 offset:17408
	ds_read_b128 v[86:89], v190 offset:16384
	ds_read_b128 v[94:97], v190 offset:17408
	ds_read_b128 v[140:143], v191 offset:16384
	ds_read_b128 v[144:147], v191 offset:17408
	ds_read_b128 v[174:177], v226 offset:16384
	ds_read_b128 v[178:181], v226 offset:17408
	s_waitcnt vmcnt(4)
	s_barrier
	s_waitcnt lgkmcnt(0)
	s_setprio 1
	v_mfma_f32_16x16x32_bf16 v[62:65], v[70:73], v[130:133], v[62:65]
	v_mfma_f32_16x16x32_bf16 v[58:61], v[70:73], v[154:157], v[58:61]
	v_mfma_f32_16x16x32_bf16 v[50:53], v[86:89], v[154:157], v[50:53]
	v_mfma_f32_16x16x32_bf16 v[38:41], v[174:177], v[130:133], v[38:41]
	v_mfma_f32_16x16x32_bf16 v[62:65], v[78:81], v[150:153], v[62:65]
	v_mfma_f32_16x16x32_bf16 v[58:61], v[78:81], v[158:161], v[58:61]
	v_mfma_f32_16x16x32_bf16 v[54:57], v[86:89], v[130:133], v[54:57]
	v_mfma_f32_16x16x32_bf16 v[50:53], v[94:97], v[158:161], v[50:53]
	v_mfma_f32_16x16x32_bf16 v[46:49], v[140:143], v[130:133], v[46:49]
	v_mfma_f32_16x16x32_bf16 v[42:45], v[140:143], v[154:157], v[42:45]
	v_mfma_f32_16x16x32_bf16 v[38:41], v[178:181], v[150:153], v[38:41]
	v_mfma_f32_16x16x32_bf16 v[30:33], v[174:177], v[154:157], v[30:33]
	v_mfma_f32_16x16x32_bf16 v[194:197], v[94:97], v[150:153], v[54:57]
	v_mfma_f32_16x16x32_bf16 v[218:221], v[144:147], v[150:153], v[46:49]
	v_mfma_f32_16x16x32_bf16 v[222:225], v[144:147], v[158:161], v[42:45]
	v_mfma_f32_16x16x32_bf16 v[130:133], v[178:181], v[158:161], v[30:33]
	s_setprio 0
	s_setprio 1
	v_mfma_f32_16x16x32_bf16 v[30:33], v[70:73], v[102:105], v[34:37]
	v_mfma_f32_16x16x32_bf16 v[22:25], v[86:89], v[102:105], v[22:25]
	v_mfma_f32_16x16x32_bf16 v[18:21], v[86:89], v[118:121], v[18:21]
	v_mfma_f32_16x16x32_bf16 v[6:9], v[174:177], v[102:105], v[6:9]
	v_mfma_f32_16x16x32_bf16 v[2:5], v[174:177], v[118:121], v[2:5]
	v_mfma_f32_16x16x32_bf16 v[34:37], v[78:81], v[110:113], v[30:33]
	v_mfma_f32_16x16x32_bf16 v[26:29], v[70:73], v[118:121], v[26:29]
	v_mfma_f32_16x16x32_bf16 v[22:25], v[94:97], v[110:113], v[22:25]
	v_mfma_f32_16x16x32_bf16 v[18:21], v[94:97], v[210:213], v[18:21]
	v_mfma_f32_16x16x32_bf16 v[14:17], v[140:143], v[102:105], v[14:17]
	v_mfma_f32_16x16x32_bf16 v[10:13], v[140:143], v[118:121], v[10:13]
	v_mfma_f32_16x16x32_bf16 v[6:9], v[178:181], v[110:113], v[6:9]
	v_mfma_f32_16x16x32_bf16 v[2:5], v[178:181], v[210:213], v[2:5]
	v_mfma_f32_16x16x32_bf16 v[148:151], v[78:81], v[210:213], v[26:29]
	v_mfma_f32_16x16x32_bf16 v[152:155], v[144:147], v[110:113], v[14:17]
	v_mfma_f32_16x16x32_bf16 v[140:143], v[144:147], v[210:213], v[10:13]
	s_setprio 0
	v_add_u32_e32 v26, v138, v136
	s_barrier
	ds_read_b128 v[10:13], v26
	ds_read_b128 v[14:17], v26 offset:1024
	ds_read_b128 v[144:147], v26 offset:2048
	ds_read_b128 v[156:159], v26 offset:3072
	ds_read_b128 v[26:29], v0 offset:32768
	ds_read_b128 v[30:33], v0 offset:33792
	ds_read_b128 v[42:45], v190 offset:32768
	ds_read_b128 v[46:49], v190 offset:33792
	ds_read_b128 v[54:57], v191 offset:32768
	ds_read_b128 v[174:177], v191 offset:33792
	ds_read_b128 v[178:181], v226 offset:32768
	ds_read_b128 v[210:213], v226 offset:33792
	s_waitcnt vmcnt(2)
	s_barrier
; #define LDA(dst, b, h) for (int m = 0; m < 4; ++m) for (int k = 0; k < 2; ++k) \
;     dst[m][k] = *reinterpret_cast<const bf16x8*>((char*)SA(b, h) + lds_byte(wr * 64 + m * 16 + fr, k * 32 + fq * 8))
; #define LDB(dst, b, h) for (int n = 0; n < 2; ++n) for (int k = 0; k < 2; ++k) \
;     dst[n][k] = *reinterpret_cast<const bf16x8*>((char*)SB(b, h) + lds_byte(wc * 32 + n * 16 + fr, k * 32 + fq * 8))
; #define MMA(ai, bj, At, Bt_) do { __builtin_amdgcn_s_setprio(1); \
;     for (int m = 0; m < 4; ++m) for (int n = 0; n < 2; ++n) for (int k = 0; k < 2; ++k) \
;       acc[ai][bj][m][n] = __builtin_amdgcn_mfma_f32_16x16x32_bf16(At[m][k], Bt_[n][k], acc[ai][bj][m][n], 0, 0, 0); \
;     __builtin_amdgcn_s_setprio(0); } while (0)
; #define WAIT_V(n) asm volatile("s_waitcnt vmcnt(" #n ")" ::: "memory")
; #define WAIT_L(n) asm volatile("s_waitcnt lgkmcnt(" #n ")" ::: "memory")
; #define BAR __builtin_amdgcn_s_barrier()
; __device__ __forceinline__ void gemm_main(acc_t& acc, const u16* A, int lda, const u16* Bt, int ldb, int nt, const int tidx) {
;     ...
;     { LDB(B0, 1, 0); LDA(At, 1, 0); WAIT_V(2); BAR; WAIT_L(0); MMA(0, 0, At, B0); BAR;
;       LDB(B1, 1, 1); WAIT_V(0); BAR; WAIT_L(0); MMA(0, 1, At, B1); BAR;
;       LDA(At, 1, 1); BAR; WAIT_L(0); MMA(1, 0, At, B0); MMA(1, 1, At, B1); BAR; }
;     if (wr == 0) BAR;
	s_waitcnt lgkmcnt(0)
	s_setprio 1
	v_mfma_f32_16x16x32_bf16 v[70:73], v[26:29], v[10:13], v[126:129]
	v_mfma_f32_16x16x32_bf16 v[126:129], v[30:33], v[14:17], v[70:73]
	v_mfma_f32_16x16x32_bf16 v[70:73], v[26:29], v[144:147], v[122:125]
	v_mfma_f32_16x16x32_bf16 v[118:121], v[30:33], v[156:159], v[70:73]
	v_mfma_f32_16x16x32_bf16 v[70:73], v[42:45], v[10:13], v[198:201]
	v_mfma_f32_16x16x32_bf16 v[110:113], v[46:49], v[14:17], v[70:73]
	v_mfma_f32_16x16x32_bf16 v[70:73], v[42:45], v[144:147], v[114:117]
	v_mfma_f32_16x16x32_bf16 v[102:105], v[46:49], v[156:159], v[70:73]
	v_mfma_f32_16x16x32_bf16 v[70:73], v[54:57], v[10:13], v[202:205]
	v_mfma_f32_16x16x32_bf16 v[94:97], v[174:177], v[14:17], v[70:73]
	v_mfma_f32_16x16x32_bf16 v[70:73], v[54:57], v[144:147], v[106:109]
	v_mfma_f32_16x16x32_bf16 v[86:89], v[174:177], v[156:159], v[70:73]
	v_mfma_f32_16x16x32_bf16 v[70:73], v[178:181], v[10:13], v[206:209]
	v_mfma_f32_16x16x32_bf16 v[78:81], v[210:213], v[14:17], v[70:73]
	v_mfma_f32_16x16x32_bf16 v[70:73], v[178:181], v[144:147], v[98:101]
	v_mfma_f32_16x16x32_bf16 v[70:73], v[210:213], v[156:159], v[70:73]
	s_setprio 0
	s_nop 0
	v_add_u32_e32 v98, v137, v136
	s_barrier
	ds_read_b128 v[134:137], v98
	ds_read_b128 v[198:201], v98 offset:1024
	ds_read_b128 v[202:205], v98 offset:2048
	ds_read_b128 v[206:209], v98 offset:3072
	s_waitcnt vmcnt(0)
	s_barrier
	s_waitcnt lgkmcnt(0)
	s_setprio 1
	v_mfma_f32_16x16x32_bf16 v[98:101], v[26:29], v[134:137], v[214:217]
	v_mfma_f32_16x16x32_bf16 v[26:29], v[26:29], v[202:205], v[90:93]
	v_mfma_f32_16x16x32_bf16 v[114:117], v[30:33], v[206:209], v[26:29]
	v_mfma_f32_16x16x32_bf16 v[26:29], v[42:45], v[134:137], v[162:165]
	v_mfma_f32_16x16x32_bf16 v[106:109], v[46:49], v[198:201], v[26:29]
	v_mfma_f32_16x16x32_bf16 v[26:29], v[42:45], v[202:205], v[82:85]
	v_mfma_f32_16x16x32_bf16 v[122:125], v[30:33], v[198:201], v[98:101]
	v_mfma_f32_16x16x32_bf16 v[98:101], v[46:49], v[206:209], v[26:29]
	v_mfma_f32_16x16x32_bf16 v[26:29], v[54:57], v[134:137], v[166:169]
	v_mfma_f32_16x16x32_bf16 v[90:93], v[174:177], v[198:201], v[26:29]
	v_mfma_f32_16x16x32_bf16 v[26:29], v[54:57], v[202:205], v[74:77]
	v_mfma_f32_16x16x32_bf16 v[82:85], v[174:177], v[206:209], v[26:29]
	v_mfma_f32_16x16x32_bf16 v[26:29], v[178:181], v[134:137], v[170:173]
	v_mfma_f32_16x16x32_bf16 v[74:77], v[210:213], v[198:201], v[26:29]
	v_mfma_f32_16x16x32_bf16 v[26:29], v[178:181], v[202:205], v[66:69]
	v_mfma_f32_16x16x32_bf16 v[66:69], v[210:213], v[206:209], v[26:29]
	s_setprio 0
	s_barrier
	ds_read_b128 v[160:163], v0 offset:49152
	ds_read_b128 v[164:167], v0 offset:50176
	ds_read_b128 v[168:171], v190 offset:49152
	ds_read_b128 v[172:175], v190 offset:50176
	ds_read_b128 v[176:179], v191 offset:49152
	ds_read_b128 v[210:213], v191 offset:50176
	ds_read_b128 v[214:217], v226 offset:49152
	ds_read_b128 v[226:229], v226 offset:50176
	s_barrier
	s_waitcnt lgkmcnt(0)
	s_setprio 1
	v_mfma_f32_16x16x32_bf16 v[26:29], v[160:163], v[10:13], v[62:65]
	v_mfma_f32_16x16x32_bf16 v[62:65], v[164:167], v[14:17], v[26:29]
	v_mfma_f32_16x16x32_bf16 v[26:29], v[160:163], v[144:147], v[58:61]
	v_mfma_f32_16x16x32_bf16 v[54:57], v[164:167], v[156:159], v[26:29]
	v_mfma_f32_16x16x32_bf16 v[26:29], v[168:171], v[10:13], v[194:197]
	v_mfma_f32_16x16x32_bf16 v[46:49], v[172:175], v[14:17], v[26:29]
	v_mfma_f32_16x16x32_bf16 v[26:29], v[168:171], v[144:147], v[50:53]
	v_mfma_f32_16x16x32_bf16 v[42:45], v[172:175], v[156:159], v[26:29]
	v_mfma_f32_16x16x32_bf16 v[26:29], v[176:179], v[10:13], v[218:221]
	v_mfma_f32_16x16x32_bf16 v[10:13], v[214:217], v[10:13], v[38:41]
	v_mfma_f32_16x16x32_bf16 v[30:33], v[210:213], v[14:17], v[26:29]
	v_mfma_f32_16x16x32_bf16 v[26:29], v[176:179], v[144:147], v[222:225]
	v_mfma_f32_16x16x32_bf16 v[14:17], v[226:229], v[14:17], v[10:13]
	v_mfma_f32_16x16x32_bf16 v[10:13], v[214:217], v[144:147], v[130:133]
	v_mfma_f32_16x16x32_bf16 v[26:29], v[210:213], v[156:159], v[26:29]
	v_mfma_f32_16x16x32_bf16 v[10:13], v[226:229], v[156:159], v[10:13]
	s_setprio 0
	s_setprio 1
	v_mfma_f32_16x16x32_bf16 v[34:37], v[160:163], v[134:137], v[34:37]
	v_mfma_f32_16x16x32_bf16 v[58:61], v[164:167], v[198:201], v[34:37]
	v_mfma_f32_16x16x32_bf16 v[34:37], v[160:163], v[202:205], v[148:151]
	v_mfma_f32_16x16x32_bf16 v[18:21], v[168:171], v[202:205], v[18:21]
	v_mfma_f32_16x16x32_bf16 v[50:53], v[164:167], v[206:209], v[34:37]
	v_mfma_f32_16x16x32_bf16 v[22:25], v[168:171], v[134:137], v[22:25]
	v_mfma_f32_16x16x32_bf16 v[34:37], v[172:175], v[206:209], v[18:21]
	v_mfma_f32_16x16x32_bf16 v[18:21], v[176:179], v[134:137], v[152:155]
	v_mfma_f32_16x16x32_bf16 v[38:41], v[172:175], v[198:201], v[22:25]
	v_mfma_f32_16x16x32_bf16 v[22:25], v[210:213], v[198:201], v[18:21]
	v_mfma_f32_16x16x32_bf16 v[18:21], v[176:179], v[202:205], v[140:143]
	v_mfma_f32_16x16x32_bf16 v[6:9], v[214:217], v[134:137], v[6:9]
	v_mfma_f32_16x16x32_bf16 v[2:5], v[214:217], v[202:205], v[2:5]
	v_mfma_f32_16x16x32_bf16 v[18:21], v[210:213], v[206:209], v[18:21]
	v_mfma_f32_16x16x32_bf16 v[6:9], v[226:229], v[198:201], v[6:9]
	v_mfma_f32_16x16x32_bf16 v[2:5], v[226:229], v[206:209], v[2:5]
	s_setprio 0
	s_barrier
	s_and_saveexec_b64 s[12:13], vcc
	s_cbranch_execz .LBB0_613
	s_barrier

; #define STAGE(P, BASE, LD, br, kt) do { const char* _gp = (const char*)((BASE) + (long)((br) * (LD) + (kt) * BK)); \
;     __builtin_amdgcn_global_load_lds((const unsigned*)(_gp + vo_##BASE##0), (unsigned*)((char*)(P) + tidx * 16), 16, 0, 0); \
;     __builtin_amdgcn_global_load_lds((const unsigned*)(_gp + vo_##BASE##1), (unsigned*)((char*)(P) + tidx * 16 + 8192), 16, 0, 0); } while (0)
; #define LDA(dst, b, h) for (int m = 0; m < 4; ++m) for (int k = 0; k < 2; ++k) \
;     dst[m][k] = *reinterpret_cast<const bf16x8*>((char*)SA(b, h) + lds_byte(wr * 64 + m * 16 + fr, k * 32 + fq * 8))
; #define LDB(dst, b, h) for (int n = 0; n < 2; ++n) for (int k = 0; k < 2; ++k) \
;     dst[n][k] = *reinterpret_cast<const bf16x8*>((char*)SB(b, h) + lds_byte(wc * 32 + n * 16 + fr, k * 32 + fq * 8))
; #define MMA(ai, bj, At, Bt_) do { __builtin_amdgcn_s_setprio(1); \
;     for (int m = 0; m < 4; ++m) for (int n = 0; n < 2; ++n) for (int k = 0; k < 2; ++k) \
;       acc[ai][bj][m][n] = __builtin_amdgcn_mfma_f32_16x16x32_bf16(At[m][k], Bt_[n][k], acc[ai][bj][m][n], 0, 0, 0); \
;     __builtin_amdgcn_s_setprio(0); } while (0)
; #define WAIT_L(n) asm volatile("s_waitcnt lgkmcnt(" #n ")" ::: "memory")
; #define BAR __builtin_amdgcn_s_barrier()
; #define SCHED __builtin_amdgcn_sched_barrier(0)
; __device__ __forceinline__ void gemm_main(acc_t& acc, const u16* A, int lda, const u16* Bt, int ldb, int nt, const int tidx) {
;     ...
;         LDB(B0, 0, 0); SCHED; LDA(At, 0, 0); STAGE(SA(1, 1), A, lda, HALF, t + 1);
;         WAIT_L(8); BAR; WAIT_L(0); MMA(0, 0, At, B0); BAR; SCHED;
;         LDB(B1, 0, 1); STAGE(SB(0, 0), Bt, ldb, 0, t + 2);
;         BAR; WAIT_L(0); MMA(0, 1, At, B1); BAR;
;         LDA(At, 0, 1); STAGE(SA(0, 0), A, lda, 0, t + 2);
;         BAR; WAIT_L(0); MMA(1, 0, At, B0); BAR; SCHED;
.LBB0_633:
	v_add_u32_e32 v170, v143, v132
	ds_read_b128 v[158:161], v170
	ds_read_b128 v[162:165], v170 offset:1024
	ds_read_b128 v[166:169], v170 offset:2048
	ds_read_b128 v[170:173], v170 offset:3072
	s_add_i32 s31, s33, s30
	s_add_i32 s46, s31, 64
	s_ashr_i32 s47, s46, 31
	s_lshl_b64 s[46:47], s[46:47], 1
	s_add_u32 s46, s6, s46
	v_add_u32_e32 v218, 0xc000, v135
	s_addc_u32 s47, s7, s47
	v_readfirstlane_b32 s48, v218
	v_add_u32_e32 v192, v144, v141
	v_add_u32_e32 v193, v142, v140
	v_add_u32_e32 v234, v142, v138
	v_add_u32_e32 v235, v142, v139
	v_lshl_add_u64 v[190:191], s[46:47], 0, v[0:1]
	s_mov_b32 m0, s48
	v_add_u32_e32 v218, 0xe000, v135
	ds_read_b128 v[174:177], v192
	ds_read_b128 v[178:181], v192 offset:1024
	ds_read_b128 v[194:197], v193
	ds_read_b128 v[198:201], v193 offset:1024
	ds_read_b128 v[202:205], v234
	ds_read_b128 v[206:209], v234 offset:1024
	ds_read_b128 v[210:213], v235
	ds_read_b128 v[214:217], v235 offset:1024
	global_load_lds_dwordx4 v[190:191], off
	v_lshl_add_u64 v[190:191], s[46:47], 0, v[130:131]
	v_readfirstlane_b32 s46, v218
	s_mov_b32 m0, s46
	s_nop 0
	global_load_lds_dwordx4 v[190:191], off
	s_waitcnt lgkmcnt(8)
	s_barrier
	s_waitcnt lgkmcnt(0)
	s_setprio 1
	v_mfma_f32_16x16x32_bf16 v[126:129], v[174:177], v[158:161], v[126:129]
	v_mfma_f32_16x16x32_bf16 v[122:125], v[174:177], v[166:169], v[122:125]
	v_mfma_f32_16x16x32_bf16 v[118:121], v[194:197], v[158:161], v[118:121]
	v_mfma_f32_16x16x32_bf16 v[114:117], v[194:197], v[166:169], v[114:117]
	v_mfma_f32_16x16x32_bf16 v[110:113], v[202:205], v[158:161], v[110:113]
	v_mfma_f32_16x16x32_bf16 v[106:109], v[202:205], v[166:169], v[106:109]
	v_mfma_f32_16x16x32_bf16 v[102:105], v[210:213], v[158:161], v[102:105]
	v_mfma_f32_16x16x32_bf16 v[98:101], v[210:213], v[166:169], v[98:101]
	v_mfma_f32_16x16x32_bf16 v[126:129], v[178:181], v[162:165], v[126:129]
	v_mfma_f32_16x16x32_bf16 v[122:125], v[178:181], v[170:173], v[122:125]
	v_mfma_f32_16x16x32_bf16 v[118:121], v[198:201], v[162:165], v[118:121]
	v_mfma_f32_16x16x32_bf16 v[114:117], v[198:201], v[170:173], v[114:117]
	v_mfma_f32_16x16x32_bf16 v[110:113], v[206:209], v[162:165], v[110:113]
	v_mfma_f32_16x16x32_bf16 v[106:109], v[206:209], v[170:173], v[106:109]
	v_mfma_f32_16x16x32_bf16 v[102:105], v[214:217], v[162:165], v[102:105]
	v_mfma_f32_16x16x32_bf16 v[98:101], v[214:217], v[170:173], v[98:101]
	s_setprio 0
	s_barrier
	s_add_i32 s72, s30, 0x80
	s_add_i32 s45, s45, 2
	s_lshl_b64 s[46:47], s[72:73], 1
	s_add_u32 s48, s2, s46
	v_add_u32_e32 v190, v136, v132
	s_addc_u32 s49, s3, s47
	v_readfirstlane_b32 s50, v145
	ds_read_b128 v[218:221], v190
	ds_read_b128 v[222:225], v190 offset:1024
	ds_read_b128 v[226:229], v190 offset:2048
	ds_read_b128 v[230:233], v190 offset:3072
	v_lshl_add_u64 v[190:191], s[48:49], 0, v[0:1]
	s_mov_b32 m0, s50
	v_readfirstlane_b32 s50, v146
	global_load_lds_dwordx4 v[190:191], off
	v_lshl_add_u64 v[190:191], s[48:49], 0, v[130:131]
	s_mov_b32 m0, s50
	s_nop 0
	global_load_lds_dwordx4 v[190:191], off
	s_barrier
	s_waitcnt lgkmcnt(0)
	s_setprio 1
	v_mfma_f32_16x16x32_bf16 v[94:97], v[174:177], v[218:221], v[94:97]
	v_mfma_f32_16x16x32_bf16 v[90:93], v[174:177], v[226:229], v[90:93]
	v_mfma_f32_16x16x32_bf16 v[86:89], v[194:197], v[218:221], v[86:89]
	v_mfma_f32_16x16x32_bf16 v[82:85], v[194:197], v[226:229], v[82:85]
	v_mfma_f32_16x16x32_bf16 v[78:81], v[202:205], v[218:221], v[78:81]
	v_mfma_f32_16x16x32_bf16 v[74:77], v[202:205], v[226:229], v[74:77]
	v_mfma_f32_16x16x32_bf16 v[70:73], v[210:213], v[218:221], v[70:73]
	v_mfma_f32_16x16x32_bf16 v[66:69], v[210:213], v[226:229], v[66:69]
	v_mfma_f32_16x16x32_bf16 v[94:97], v[178:181], v[222:225], v[94:97]
	v_mfma_f32_16x16x32_bf16 v[90:93], v[178:181], v[230:233], v[90:93]
	v_mfma_f32_16x16x32_bf16 v[86:89], v[198:201], v[222:225], v[86:89]
	v_mfma_f32_16x16x32_bf16 v[82:85], v[198:201], v[230:233], v[82:85]
	v_mfma_f32_16x16x32_bf16 v[78:81], v[206:209], v[222:225], v[78:81]
	v_mfma_f32_16x16x32_bf16 v[74:77], v[206:209], v[230:233], v[74:77]
	v_mfma_f32_16x16x32_bf16 v[70:73], v[214:217], v[222:225], v[70:73]
	v_mfma_f32_16x16x32_bf16 v[66:69], v[214:217], v[230:233], v[66:69]
	s_setprio 0
	s_add_u32 s46, s6, s46
	s_addc_u32 s47, s7, s47
	v_readfirstlane_b32 s50, v135
	v_lshl_add_u64 v[190:191], s[46:47], 0, v[0:1]
	s_mov_b32 m0, s50
	s_barrier
	ds_read_b128 v[174:177], v192 offset:16384
	ds_read_b128 v[178:181], v192 offset:17408
	ds_read_b128 v[194:197], v193 offset:16384
	ds_read_b128 v[198:201], v193 offset:17408
	ds_read_b128 v[202:205], v234 offset:16384
	ds_read_b128 v[206:209], v234 offset:17408
	ds_read_b128 v[210:213], v235 offset:16384
	ds_read_b128 v[214:217], v235 offset:17408
	global_load_lds_dwordx4 v[190:191], off
	v_lshl_add_u64 v[190:191], s[46:47], 0, v[130:131]
	v_readfirstlane_b32 s46, v147
	s_mov_b32 m0, s46
	s_nop 0
	global_load_lds_dwordx4 v[190:191], off
	s_barrier
	s_waitcnt lgkmcnt(0)
	s_setprio 1
	v_mfma_f32_16x16x32_bf16 v[62:65], v[174:177], v[158:161], v[62:65]
	v_mfma_f32_16x16x32_bf16 v[58:61], v[174:177], v[166:169], v[58:61]
	v_mfma_f32_16x16x32_bf16 v[54:57], v[194:197], v[158:161], v[54:57]
	v_mfma_f32_16x16x32_bf16 v[50:53], v[194:197], v[166:169], v[50:53]
	v_mfma_f32_16x16x32_bf16 v[46:49], v[202:205], v[158:161], v[46:49]
	v_mfma_f32_16x16x32_bf16 v[42:45], v[202:205], v[166:169], v[42:45]
	v_mfma_f32_16x16x32_bf16 v[38:41], v[210:213], v[158:161], v[38:41]
	v_mfma_f32_16x16x32_bf16 v[34:37], v[210:213], v[166:169], v[34:37]
	v_mfma_f32_16x16x32_bf16 v[62:65], v[178:181], v[162:165], v[62:65]
	v_mfma_f32_16x16x32_bf16 v[58:61], v[178:181], v[170:173], v[58:61]
	v_mfma_f32_16x16x32_bf16 v[54:57], v[198:201], v[162:165], v[54:57]
	v_mfma_f32_16x16x32_bf16 v[50:53], v[198:201], v[170:173], v[50:53]
	v_mfma_f32_16x16x32_bf16 v[46:49], v[206:209], v[162:165], v[46:49]
	v_mfma_f32_16x16x32_bf16 v[42:45], v[206:209], v[170:173], v[42:45]
	v_mfma_f32_16x16x32_bf16 v[38:41], v[214:217], v[162:165], v[38:41]
	v_mfma_f32_16x16x32_bf16 v[34:37], v[214:217], v[170:173], v[34:37]
	s_setprio 0
	s_barrier
; #define STAGE(P, BASE, LD, br, kt) do { const char* _gp = (const char*)((BASE) + (long)((br) * (LD) + (kt) * BK)); \
;     __builtin_amdgcn_global_load_lds((const unsigned*)(_gp + vo_##BASE##0), (unsigned*)((char*)(P) + tidx * 16), 16, 0, 0); \
;     __builtin_amdgcn_global_load_lds((const unsigned*)(_gp + vo_##BASE##1), (unsigned*)((char*)(P) + tidx * 16 + 8192), 16, 0, 0); } while (0)
; #define LDA(dst, b, h) for (int m = 0; m < 4; ++m) for (int k = 0; k < 2; ++k) \
;     dst[m][k] = *reinterpret_cast<const bf16x8*>((char*)SA(b, h) + lds_byte(wr * 64 + m * 16 + fr, k * 32 + fq * 8))
; #define LDB(dst, b, h) for (int n = 0; n < 2; ++n) for (int k = 0; k < 2; ++k) \
;     dst[n][k] = *reinterpret_cast<const bf16x8*>((char*)SB(b, h) + lds_byte(wc * 32 + n * 16 + fr, k * 32 + fq * 8))
; #define MMA(ai, bj, At, Bt_) do { __builtin_amdgcn_s_setprio(1); \
;     for (int m = 0; m < 4; ++m) for (int n = 0; n < 2; ++n) for (int k = 0; k < 2; ++k) \
;       acc[ai][bj][m][n] = __builtin_amdgcn_mfma_f32_16x16x32_bf16(At[m][k], Bt_[n][k], acc[ai][bj][m][n], 0, 0, 0); \
;     __builtin_amdgcn_s_setprio(0); } while (0)
; #define WAIT_V(n) asm volatile("s_waitcnt vmcnt(" #n ")" ::: "memory")
; #define WAIT_L(n) asm volatile("s_waitcnt lgkmcnt(" #n ")" ::: "memory")
; #define BAR __builtin_amdgcn_s_barrier()
; #define SCHED __builtin_amdgcn_sched_barrier(0)
; __device__ __forceinline__ void gemm_main(acc_t& acc, const u16* A, int lda, const u16* Bt, int ldb, int nt, const int tidx) {
;     ...
;         STAGE(SB(0, 1), Bt, ldb, HALF, t + 2);
;         WAIT_V(6); BAR; MMA(1, 1, At, B1); BAR;
;         LDB(B0, 1, 0); SCHED; LDA(At, 1, 0); STAGE(SA(0, 1), A, lda, HALF, t + 2);
;         WAIT_L(8); BAR; WAIT_L(0); MMA(0, 0, At, B0); BAR; SCHED;
;         LDB(B1, 1, 1); STAGE(SB(1, 0), Bt, ldb, 0, t + 3);
;         BAR; WAIT_L(0); MMA(0, 1, At, B1); BAR;
	s_add_i32 s46, s31, 0x80
	s_add_u32 s48, s48, s44
	s_addc_u32 s49, s49, 0
	v_readfirstlane_b32 s31, v148
	v_lshl_add_u64 v[158:159], s[48:49], 0, v[0:1]
	s_mov_b32 m0, s31
	v_readfirstlane_b32 s31, v149
	global_load_lds_dwordx4 v[158:159], off
	v_lshl_add_u64 v[158:159], s[48:49], 0, v[130:131]
	s_mov_b32 m0, s31
	s_mov_b32 s47, s73
	global_load_lds_dwordx4 v[158:159], off
	s_waitcnt vmcnt(6)
	s_barrier
	s_setprio 1
	v_mfma_f32_16x16x32_bf16 v[30:33], v[174:177], v[218:221], v[30:33]
	v_mfma_f32_16x16x32_bf16 v[26:29], v[174:177], v[226:229], v[26:29]
	v_mfma_f32_16x16x32_bf16 v[22:25], v[194:197], v[218:221], v[22:25]
	v_mfma_f32_16x16x32_bf16 v[18:21], v[194:197], v[226:229], v[18:21]
	v_mfma_f32_16x16x32_bf16 v[14:17], v[202:205], v[218:221], v[14:17]
	v_mfma_f32_16x16x32_bf16 v[10:13], v[202:205], v[226:229], v[10:13]
	v_mfma_f32_16x16x32_bf16 v[6:9], v[210:213], v[218:221], v[6:9]
	v_mfma_f32_16x16x32_bf16 v[2:5], v[210:213], v[226:229], v[2:5]
	v_mfma_f32_16x16x32_bf16 v[30:33], v[178:181], v[222:225], v[30:33]
	v_mfma_f32_16x16x32_bf16 v[26:29], v[178:181], v[230:233], v[26:29]
	v_mfma_f32_16x16x32_bf16 v[22:25], v[198:201], v[222:225], v[22:25]
	v_mfma_f32_16x16x32_bf16 v[18:21], v[198:201], v[230:233], v[18:21]
	v_mfma_f32_16x16x32_bf16 v[14:17], v[206:209], v[222:225], v[14:17]
	v_mfma_f32_16x16x32_bf16 v[10:13], v[206:209], v[230:233], v[10:13]
	v_mfma_f32_16x16x32_bf16 v[6:9], v[214:217], v[222:225], v[6:9]
	v_mfma_f32_16x16x32_bf16 v[2:5], v[214:217], v[230:233], v[2:5]
	s_setprio 0
	v_add_u32_e32 v170, v134, v132
	s_barrier
	ds_read_b128 v[158:161], v170
	ds_read_b128 v[162:165], v170 offset:1024
	ds_read_b128 v[166:169], v170 offset:2048
	ds_read_b128 v[170:173], v170 offset:3072
	s_lshl_b64 s[46:47], s[46:47], 1
	s_add_u32 s46, s6, s46
	s_addc_u32 s47, s7, s47
	v_readfirstlane_b32 s31, v150
	v_lshl_add_u64 v[190:191], s[46:47], 0, v[0:1]
	s_mov_b32 m0, s31
	v_readfirstlane_b32 s31, v151
	ds_read_b128 v[174:177], v192 offset:32768
	ds_read_b128 v[178:181], v192 offset:33792
	ds_read_b128 v[194:197], v193 offset:32768
	ds_read_b128 v[198:201], v193 offset:33792
	ds_read_b128 v[202:205], v234 offset:32768
	ds_read_b128 v[206:209], v234 offset:33792
	ds_read_b128 v[210:213], v235 offset:32768
	ds_read_b128 v[214:217], v235 offset:33792
	global_load_lds_dwordx4 v[190:191], off
	v_lshl_add_u64 v[190:191], s[46:47], 0, v[130:131]
	s_mov_b32 m0, s31
	s_nop 0
	global_load_lds_dwordx4 v[190:191], off
	s_waitcnt lgkmcnt(8)
	s_barrier
	s_waitcnt lgkmcnt(0)
	s_setprio 1
	v_mfma_f32_16x16x32_bf16 v[126:129], v[174:177], v[158:161], v[126:129]
	v_mfma_f32_16x16x32_bf16 v[122:125], v[174:177], v[166:169], v[122:125]
	v_mfma_f32_16x16x32_bf16 v[118:121], v[194:197], v[158:161], v[118:121]
	v_mfma_f32_16x16x32_bf16 v[114:117], v[194:197], v[166:169], v[114:117]
	v_mfma_f32_16x16x32_bf16 v[110:113], v[202:205], v[158:161], v[110:113]
	v_mfma_f32_16x16x32_bf16 v[106:109], v[202:205], v[166:169], v[106:109]
	v_mfma_f32_16x16x32_bf16 v[102:105], v[210:213], v[158:161], v[102:105]
	v_mfma_f32_16x16x32_bf16 v[98:101], v[210:213], v[166:169], v[98:101]
	v_mfma_f32_16x16x32_bf16 v[126:129], v[178:181], v[162:165], v[126:129]
	v_mfma_f32_16x16x32_bf16 v[122:125], v[178:181], v[170:173], v[122:125]
	v_mfma_f32_16x16x32_bf16 v[118:121], v[198:201], v[162:165], v[118:121]
	v_mfma_f32_16x16x32_bf16 v[114:117], v[198:201], v[170:173], v[114:117]
	v_mfma_f32_16x16x32_bf16 v[110:113], v[206:209], v[162:165], v[110:113]
	v_mfma_f32_16x16x32_bf16 v[106:109], v[206:209], v[170:173], v[106:109]
	v_mfma_f32_16x16x32_bf16 v[102:105], v[214:217], v[162:165], v[102:105]
	v_mfma_f32_16x16x32_bf16 v[98:101], v[214:217], v[170:173], v[98:101]
	s_setprio 0
	s_barrier
	s_ashr_i32 s31, s30, 31
	s_add_i32 s46, s30, 0xc0
	s_lshl_b64 s[30:31], s[30:31], 1
	s_add_u32 s48, s2, s30
	v_add_u32_e32 v190, v133, v132
	s_addc_u32 s49, s3, s31
	ds_read_b128 v[218:221], v190
	ds_read_b128 v[222:225], v190 offset:1024
	ds_read_b128 v[226:229], v190 offset:2048
	ds_read_b128 v[230:233], v190 offset:3072
	v_lshl_add_u64 v[190:191], s[48:49], 0, v[0:1]
	v_readfirstlane_b32 s47, v152
	v_lshl_add_u64 v[190:191], v[190:191], 0, s[0:1]
	s_mov_b32 m0, s47
	v_readfirstlane_b32 s47, v153
	global_load_lds_dwordx4 v[190:191], off
	v_lshl_add_u64 v[190:191], s[48:49], 0, v[130:131]
	v_lshl_add_u64 v[190:191], v[190:191], 0, s[0:1]
	s_mov_b32 m0, s47
	s_nop 0
	global_load_lds_dwordx4 v[190:191], off
	s_barrier
	s_waitcnt lgkmcnt(0)
	s_setprio 1
	v_mfma_f32_16x16x32_bf16 v[94:97], v[174:177], v[218:221], v[94:97]
	v_mfma_f32_16x16x32_bf16 v[90:93], v[174:177], v[226:229], v[90:93]
	v_mfma_f32_16x16x32_bf16 v[86:89], v[194:197], v[218:221], v[86:89]
	v_mfma_f32_16x16x32_bf16 v[82:85], v[194:197], v[226:229], v[82:85]
	v_mfma_f32_16x16x32_bf16 v[78:81], v[202:205], v[218:221], v[78:81]
	v_mfma_f32_16x16x32_bf16 v[74:77], v[202:205], v[226:229], v[74:77]
	v_mfma_f32_16x16x32_bf16 v[70:73], v[210:213], v[218:221], v[70:73]
	v_mfma_f32_16x16x32_bf16 v[66:69], v[210:213], v[226:229], v[66:69]
	v_mfma_f32_16x16x32_bf16 v[94:97], v[178:181], v[222:225], v[94:97]
	v_mfma_f32_16x16x32_bf16 v[90:93], v[178:181], v[230:233], v[90:93]
	v_mfma_f32_16x16x32_bf16 v[86:89], v[198:201], v[222:225], v[86:89]
	v_mfma_f32_16x16x32_bf16 v[82:85], v[198:201], v[230:233], v[82:85]
	v_mfma_f32_16x16x32_bf16 v[78:81], v[206:209], v[222:225], v[78:81]
	v_mfma_f32_16x16x32_bf16 v[74:77], v[206:209], v[230:233], v[74:77]
	v_mfma_f32_16x16x32_bf16 v[70:73], v[214:217], v[222:225], v[70:73]
	v_mfma_f32_16x16x32_bf16 v[66:69], v[214:217], v[230:233], v[66:69]
	s_setprio 0
	s_add_u32 s30, s6, s30
	s_addc_u32 s31, s7, s31
	v_lshl_add_u64 v[190:191], s[30:31], 0, v[0:1]
	v_readfirstlane_b32 s47, v154
	v_lshl_add_u64 v[190:191], v[190:191], 0, s[0:1]
	s_mov_b32 m0, s47
	s_barrier
; #define STAGE(P, BASE, LD, br, kt) do { const char* _gp = (const char*)((BASE) + (long)((br) * (LD) + (kt) * BK)); \
;     __builtin_amdgcn_global_load_lds((const unsigned*)(_gp + vo_##BASE##0), (unsigned*)((char*)(P) + tidx * 16), 16, 0, 0); \
;     __builtin_amdgcn_global_load_lds((const unsigned*)(_gp + vo_##BASE##1), (unsigned*)((char*)(P) + tidx * 16 + 8192), 16, 0, 0); } while (0)
; #define LDA(dst, b, h) for (int m = 0; m < 4; ++m) for (int k = 0; k < 2; ++k) \
;     dst[m][k] = *reinterpret_cast<const bf16x8*>((char*)SA(b, h) + lds_byte(wr * 64 + m * 16 + fr, k * 32 + fq * 8))
; #define LDB(dst, b, h) for (int n = 0; n < 2; ++n) for (int k = 0; k < 2; ++k) \
;     dst[n][k] = *reinterpret_cast<const bf16x8*>((char*)SB(b, h) + lds_byte(wc * 32 + n * 16 + fr, k * 32 + fq * 8))
; #define MMA(ai, bj, At, Bt_) do { __builtin_amdgcn_s_setprio(1); \
;     for (int m = 0; m < 4; ++m) for (int n = 0; n < 2; ++n) for (int k = 0; k < 2; ++k) \
;       acc[ai][bj][m][n] = __builtin_amdgcn_mfma_f32_16x16x32_bf16(At[m][k], Bt_[n][k], acc[ai][bj][m][n], 0, 0, 0); \
;     __builtin_amdgcn_s_setprio(0); } while (0)
; #define WAIT_V(n) asm volatile("s_waitcnt vmcnt(" #n ")" ::: "memory")
; #define WAIT_L(n) asm volatile("s_waitcnt lgkmcnt(" #n ")" ::: "memory")
; #define BAR __builtin_amdgcn_s_barrier()
; #define SCHED __builtin_amdgcn_sched_barrier(0)
; __device__ __forceinline__ void gemm_main(acc_t& acc, const u16* A, int lda, const u16* Bt, int ldb, int nt, const int tidx) {
;     ...
;         LDA(At, 1, 1); STAGE(SA(1, 0), A, lda, 0, t + 3);
;         BAR; WAIT_L(0); MMA(1, 0, At, B0); BAR; SCHED;
;         STAGE(SB(1, 1), Bt, ldb, HALF, t + 3);
;         WAIT_V(6); BAR; MMA(1, 1, At, B1); BAR;
;     }
;     { LDB(B0, 0, 0); LDA(At, 0, 0); STAGE(SA(1, 1), A, lda, HALF, nt - 1);
;       BAR; WAIT_L(0); MMA(0, 0, At, B0); BAR;
	ds_read_b128 v[174:177], v192 offset:49152
	ds_read_b128 v[178:181], v192 offset:50176
	ds_read_b128 v[194:197], v193 offset:49152
	ds_read_b128 v[198:201], v193 offset:50176
	ds_read_b128 v[202:205], v234 offset:49152
	ds_read_b128 v[206:209], v234 offset:50176
	ds_read_b128 v[210:213], v235 offset:49152
	ds_read_b128 v[214:217], v235 offset:50176
	global_load_lds_dwordx4 v[190:191], off
	v_lshl_add_u64 v[190:191], s[30:31], 0, v[130:131]
	v_readfirstlane_b32 s30, v155
	v_lshl_add_u64 v[190:191], v[190:191], 0, s[0:1]
	s_mov_b32 m0, s30
	s_nop 0
	global_load_lds_dwordx4 v[190:191], off
	s_barrier
	s_waitcnt lgkmcnt(0)
	s_setprio 1
	v_mfma_f32_16x16x32_bf16 v[62:65], v[174:177], v[158:161], v[62:65]
	v_mfma_f32_16x16x32_bf16 v[58:61], v[174:177], v[166:169], v[58:61]
	v_mfma_f32_16x16x32_bf16 v[54:57], v[194:197], v[158:161], v[54:57]
	v_mfma_f32_16x16x32_bf16 v[50:53], v[194:197], v[166:169], v[50:53]
	v_mfma_f32_16x16x32_bf16 v[46:49], v[202:205], v[158:161], v[46:49]
	v_mfma_f32_16x16x32_bf16 v[42:45], v[202:205], v[166:169], v[42:45]
	v_mfma_f32_16x16x32_bf16 v[38:41], v[210:213], v[158:161], v[38:41]
	v_mfma_f32_16x16x32_bf16 v[34:37], v[210:213], v[166:169], v[34:37]
	v_mfma_f32_16x16x32_bf16 v[62:65], v[178:181], v[162:165], v[62:65]
	v_mfma_f32_16x16x32_bf16 v[58:61], v[178:181], v[170:173], v[58:61]
	v_mfma_f32_16x16x32_bf16 v[54:57], v[198:201], v[162:165], v[54:57]
	v_mfma_f32_16x16x32_bf16 v[50:53], v[198:201], v[170:173], v[50:53]
	v_mfma_f32_16x16x32_bf16 v[46:49], v[206:209], v[162:165], v[46:49]
	v_mfma_f32_16x16x32_bf16 v[42:45], v[206:209], v[170:173], v[42:45]
	v_mfma_f32_16x16x32_bf16 v[38:41], v[214:217], v[162:165], v[38:41]
	v_mfma_f32_16x16x32_bf16 v[34:37], v[214:217], v[170:173], v[34:37]
	s_setprio 0
	s_barrier
	s_ashr_i32 s47, s46, 31
	s_lshl_b64 s[30:31], s[46:47], 1
	s_add_u32 s30, s28, s30
	s_addc_u32 s31, s29, s31
	v_readfirstlane_b32 s46, v156
	v_lshl_add_u64 v[158:159], s[30:31], 0, v[0:1]
	s_mov_b32 m0, s46
	s_nop 0
	global_load_lds_dwordx4 v[158:159], off
	v_lshl_add_u64 v[158:159], s[30:31], 0, v[130:131]
	v_readfirstlane_b32 s30, v157
	s_mov_b32 m0, s30
	s_nop 0
	global_load_lds_dwordx4 v[158:159], off
	s_waitcnt vmcnt(6)
	s_barrier
	s_setprio 1
	v_mfma_f32_16x16x32_bf16 v[30:33], v[174:177], v[218:221], v[30:33]
	v_mfma_f32_16x16x32_bf16 v[26:29], v[174:177], v[226:229], v[26:29]
	v_mfma_f32_16x16x32_bf16 v[22:25], v[194:197], v[218:221], v[22:25]
	v_mfma_f32_16x16x32_bf16 v[18:21], v[194:197], v[226:229], v[18:21]
	v_mfma_f32_16x16x32_bf16 v[14:17], v[202:205], v[218:221], v[14:17]
	v_mfma_f32_16x16x32_bf16 v[10:13], v[202:205], v[226:229], v[10:13]
	v_mfma_f32_16x16x32_bf16 v[6:9], v[210:213], v[218:221], v[6:9]
	v_mfma_f32_16x16x32_bf16 v[2:5], v[210:213], v[226:229], v[2:5]
	v_mfma_f32_16x16x32_bf16 v[30:33], v[178:181], v[222:225], v[30:33]
	v_mfma_f32_16x16x32_bf16 v[26:29], v[178:181], v[230:233], v[26:29]
	v_mfma_f32_16x16x32_bf16 v[22:25], v[198:201], v[222:225], v[22:25]
	v_mfma_f32_16x16x32_bf16 v[18:21], v[198:201], v[230:233], v[18:21]
	v_mfma_f32_16x16x32_bf16 v[14:17], v[206:209], v[222:225], v[14:17]
	v_mfma_f32_16x16x32_bf16 v[10:13], v[206:209], v[230:233], v[10:13]
	v_mfma_f32_16x16x32_bf16 v[6:9], v[214:217], v[222:225], v[6:9]
	v_mfma_f32_16x16x32_bf16 v[2:5], v[214:217], v[230:233], v[2:5]
	s_setprio 0
	s_cmp_lt_i32 s45, s43
	s_mov_b32 s30, s72
	s_barrier
	s_cbranch_scc1 .LBB0_633
	v_readlane_b32 s49, v254, 19
	v_readlane_b32 s50, v254, 20
.LBB0_635:
	s_xor_b64 s[2:3], s[4:5], -1
	s_lshl_b32 s4, s42, 6
	s_add_i32 s4, s33, s4
	s_sub_i32 s4, s4, 64
	s_ashr_i32 s5, s4, 31
	s_lshl_b64 s[4:5], s[4:5], 1
	s_add_u32 s4, s6, s4
	s_addc_u32 s5, s7, s5
	v_cmp_gt_u32_e32 vcc, s51, v137
	v_add_u32_e32 v137, 0xc000, v135
	v_lshl_add_u64 v[190:191], s[4:5], 0, v[0:1]
	v_lshl_add_u64 v[130:131], s[4:5], 0, v[130:131]
	v_add_u32_e32 v0, v143, v132
	v_readfirstlane_b32 s4, v137
	v_add_u32_e32 v135, 0xe000, v135
	ds_read_b128 v[146:149], v0
	ds_read_b128 v[150:153], v0 offset:1024
	ds_read_b128 v[154:157], v0 offset:2048
	ds_read_b128 v[158:161], v0 offset:3072
	v_add_u32_e32 v0, v144, v141
	v_add_u32_e32 v192, v142, v140
	v_add_u32_e32 v193, v142, v138
	v_add_u32_e32 v250, v142, v139
	s_mov_b32 m0, s4
	v_readfirstlane_b32 s4, v135
	ds_read_b128 v[162:165], v0
	ds_read_b128 v[166:169], v0 offset:1024
	ds_read_b128 v[170:173], v192
	ds_read_b128 v[174:177], v192 offset:1024
	ds_read_b128 v[178:181], v193
	ds_read_b128 v[194:197], v193 offset:1024
	ds_read_b128 v[138:141], v250
	ds_read_b128 v[142:145], v250 offset:1024
	global_load_lds_dwordx4 v[190:191], off
	s_mov_b32 m0, s4
	s_nop 0
	global_load_lds_dwordx4 v[130:131], off
	s_barrier
	s_waitcnt lgkmcnt(0)
	s_setprio 1
	v_mfma_f32_16x16x32_bf16 v[126:129], v[162:165], v[146:149], v[126:129]
	v_mfma_f32_16x16x32_bf16 v[110:113], v[178:181], v[146:149], v[110:113]
	v_mfma_f32_16x16x32_bf16 v[126:129], v[166:169], v[150:153], v[126:129]
	v_mfma_f32_16x16x32_bf16 v[122:125], v[162:165], v[154:157], v[122:125]
	v_mfma_f32_16x16x32_bf16 v[118:121], v[170:173], v[146:149], v[118:121]
	v_mfma_f32_16x16x32_bf16 v[114:117], v[170:173], v[154:157], v[114:117]
	v_mfma_f32_16x16x32_bf16 v[110:113], v[194:197], v[150:153], v[110:113]
	v_mfma_f32_16x16x32_bf16 v[106:109], v[178:181], v[154:157], v[106:109]
	v_mfma_f32_16x16x32_bf16 v[102:105], v[138:141], v[146:149], v[102:105]
	v_mfma_f32_16x16x32_bf16 v[98:101], v[138:141], v[154:157], v[98:101]
	v_mfma_f32_16x16x32_bf16 v[198:201], v[166:169], v[158:161], v[122:125]
	v_mfma_f32_16x16x32_bf16 v[202:205], v[174:177], v[150:153], v[118:121]
	v_mfma_f32_16x16x32_bf16 v[206:209], v[174:177], v[158:161], v[114:117]
	v_mfma_f32_16x16x32_bf16 v[210:213], v[194:197], v[158:161], v[106:109]
	v_mfma_f32_16x16x32_bf16 v[214:217], v[142:145], v[150:153], v[102:105]
	v_mfma_f32_16x16x32_bf16 v[218:221], v[142:145], v[158:161], v[98:101]
	s_setprio 0
	v_add_u32_e32 v114, v136, v132
	s_barrier
; #define STAGE(P, BASE, LD, br, kt) do { const char* _gp = (const char*)((BASE) + (long)((br) * (LD) + (kt) * BK)); \
;     __builtin_amdgcn_global_load_lds((const unsigned*)(_gp + vo_##BASE##0), (unsigned*)((char*)(P) + tidx * 16), 16, 0, 0); \
;     __builtin_amdgcn_global_load_lds((const unsigned*)(_gp + vo_##BASE##1), (unsigned*)((char*)(P) + tidx * 16 + 8192), 16, 0, 0); } while (0)
; #define LDA(dst, b, h) for (int m = 0; m < 4; ++m) for (int k = 0; k < 2; ++k) \
;     dst[m][k] = *reinterpret_cast<const bf16x8*>((char*)SA(b, h) + lds_byte(wr * 64 + m * 16 + fr, k * 32 + fq * 8))
; #define LDB(dst, b, h) for (int n = 0; n < 2; ++n) for (int k = 0; k < 2; ++k) \
;     dst[n][k] = *reinterpret_cast<const bf16x8*>((char*)SB(b, h) + lds_byte(wc * 32 + n * 16 + fr, k * 32 + fq * 8))
; #define MMA(ai, bj, At, Bt_) do { __builtin_amdgcn_s_setprio(1); \
;     for (int m = 0; m < 4; ++m) for (int n = 0; n < 2; ++n) for (int k = 0; k < 2; ++k) \
;       acc[ai][bj][m][n] = __builtin_amdgcn_mfma_f32_16x16x32_bf16(At[m][k], Bt_[n][k], acc[ai][bj][m][n], 0, 0, 0); \
;     __builtin_amdgcn_s_setprio(0); } while (0)
; #define WAIT_V(n) asm volatile("s_waitcnt vmcnt(" #n ")" ::: "memory")
; #define WAIT_L(n) asm volatile("s_waitcnt lgkmcnt(" #n ")" ::: "memory")
; #define BAR __builtin_amdgcn_s_barrier()
; __device__ __forceinline__ void gemm_main(acc_t& acc, const u16* A, int lda, const u16* Bt, int ldb, int nt, const int tidx) {
;     ...
;     { LDB(B0, 0, 0); LDA(At, 0, 0); STAGE(SA(1, 1), A, lda, HALF, nt - 1);
;       BAR; WAIT_L(0); MMA(0, 0, At, B0); BAR;
;       LDB(B1, 0, 1); BAR; WAIT_L(0); MMA(0, 1, At, B1); BAR;
;       LDA(At, 0, 1); WAIT_V(4); BAR; WAIT_L(0); MMA(1, 0, At, B0); MMA(1, 1, At, B1); BAR; }
;     { LDB(B0, 1, 0); LDA(At, 1, 0); WAIT_V(2); BAR; WAIT_L(0); MMA(0, 0, At, B0); BAR;
	ds_read_b128 v[98:101], v114
	ds_read_b128 v[102:105], v114 offset:1024
	ds_read_b128 v[106:109], v114 offset:2048
	ds_read_b128 v[114:117], v114 offset:3072
	s_barrier
	s_waitcnt lgkmcnt(0)
	s_setprio 1
	v_mfma_f32_16x16x32_bf16 v[94:97], v[162:165], v[98:101], v[94:97]
	v_mfma_f32_16x16x32_bf16 v[78:81], v[178:181], v[98:101], v[78:81]
	v_mfma_f32_16x16x32_bf16 v[74:77], v[178:181], v[106:109], v[74:77]
	v_mfma_f32_16x16x32_bf16 v[70:73], v[138:141], v[98:101], v[70:73]
	v_mfma_f32_16x16x32_bf16 v[66:69], v[138:141], v[106:109], v[66:69]
	v_mfma_f32_16x16x32_bf16 v[94:97], v[166:169], v[102:105], v[94:97]
	v_mfma_f32_16x16x32_bf16 v[90:93], v[162:165], v[106:109], v[90:93]
	v_mfma_f32_16x16x32_bf16 v[86:89], v[170:173], v[98:101], v[86:89]
	v_mfma_f32_16x16x32_bf16 v[82:85], v[170:173], v[106:109], v[82:85]
	v_mfma_f32_16x16x32_bf16 v[78:81], v[194:197], v[102:105], v[78:81]
	v_mfma_f32_16x16x32_bf16 v[74:77], v[194:197], v[114:117], v[74:77]
	v_mfma_f32_16x16x32_bf16 v[70:73], v[142:145], v[102:105], v[70:73]
	v_mfma_f32_16x16x32_bf16 v[66:69], v[142:145], v[114:117], v[66:69]
	v_mfma_f32_16x16x32_bf16 v[162:165], v[166:169], v[114:117], v[90:93]
	v_mfma_f32_16x16x32_bf16 v[166:169], v[174:177], v[102:105], v[86:89]
	v_mfma_f32_16x16x32_bf16 v[170:173], v[174:177], v[114:117], v[82:85]
	s_setprio 0
	s_barrier
	s_nop 0
	ds_read_b128 v[82:85], v0 offset:16384
	ds_read_b128 v[86:89], v0 offset:17408
	ds_read_b128 v[90:93], v192 offset:16384
	ds_read_b128 v[118:121], v192 offset:17408
	ds_read_b128 v[122:125], v193 offset:16384
	ds_read_b128 v[136:139], v193 offset:17408
	ds_read_b128 v[140:143], v250 offset:16384
	ds_read_b128 v[174:177], v250 offset:17408
	s_waitcnt vmcnt(4)
	s_barrier
	s_waitcnt lgkmcnt(0)
	s_setprio 1
	v_mfma_f32_16x16x32_bf16 v[62:65], v[82:85], v[146:149], v[62:65]
	v_mfma_f32_16x16x32_bf16 v[50:53], v[90:93], v[154:157], v[50:53]
	v_mfma_f32_16x16x32_bf16 v[46:49], v[122:125], v[146:149], v[46:49]
	v_mfma_f32_16x16x32_bf16 v[34:37], v[140:143], v[154:157], v[34:37]
	v_mfma_f32_16x16x32_bf16 v[62:65], v[86:89], v[150:153], v[62:65]
	v_mfma_f32_16x16x32_bf16 v[58:61], v[82:85], v[154:157], v[58:61]
	v_mfma_f32_16x16x32_bf16 v[54:57], v[90:93], v[146:149], v[54:57]
	v_mfma_f32_16x16x32_bf16 v[222:225], v[118:121], v[158:161], v[50:53]
	v_mfma_f32_16x16x32_bf16 v[48:51], v[136:139], v[150:153], v[46:49]
	v_mfma_f32_16x16x32_bf16 v[42:45], v[122:125], v[154:157], v[42:45]
	v_mfma_f32_16x16x32_bf16 v[38:41], v[140:143], v[146:149], v[38:41]
	v_mfma_f32_16x16x32_bf16 v[34:37], v[174:177], v[158:161], v[34:37]
	v_mfma_f32_16x16x32_bf16 v[178:181], v[86:89], v[158:161], v[58:61]
	v_mfma_f32_16x16x32_bf16 v[194:197], v[118:121], v[150:153], v[54:57]
	v_mfma_f32_16x16x32_bf16 v[226:229], v[136:139], v[158:161], v[42:45]
	v_mfma_f32_16x16x32_bf16 v[144:147], v[174:177], v[150:153], v[38:41]
	s_setprio 0
	s_setprio 1
	v_mfma_f32_16x16x32_bf16 v[26:29], v[82:85], v[106:109], v[26:29]
	v_mfma_f32_16x16x32_bf16 v[22:25], v[90:93], v[98:101], v[22:25]
	v_mfma_f32_16x16x32_bf16 v[18:21], v[90:93], v[106:109], v[18:21]
	v_mfma_f32_16x16x32_bf16 v[14:17], v[122:125], v[98:101], v[14:17]
	v_mfma_f32_16x16x32_bf16 v[2:5], v[140:143], v[106:109], v[2:5]
	v_mfma_f32_16x16x32_bf16 v[30:33], v[82:85], v[98:101], v[30:33]
	v_mfma_f32_16x16x32_bf16 v[152:155], v[86:89], v[114:117], v[26:29]
	v_mfma_f32_16x16x32_bf16 v[24:27], v[118:121], v[102:105], v[22:25]
	v_mfma_f32_16x16x32_bf16 v[156:159], v[118:121], v[114:117], v[18:21]
	v_mfma_f32_16x16x32_bf16 v[16:19], v[136:139], v[102:105], v[14:17]
	v_mfma_f32_16x16x32_bf16 v[10:13], v[122:125], v[106:109], v[10:13]
	v_mfma_f32_16x16x32_bf16 v[6:9], v[140:143], v[98:101], v[6:9]
	v_mfma_f32_16x16x32_bf16 v[2:5], v[174:177], v[114:117], v[2:5]
	v_mfma_f32_16x16x32_bf16 v[148:151], v[86:89], v[102:105], v[30:33]
	v_mfma_f32_16x16x32_bf16 v[136:139], v[136:139], v[114:117], v[10:13]
	v_mfma_f32_16x16x32_bf16 v[230:233], v[174:177], v[102:105], v[6:9]
	s_setprio 0
	v_add_u32_e32 v14, v134, v132
	s_barrier
	s_nop 0
	ds_read_b128 v[6:9], v14
	ds_read_b128 v[10:13], v14 offset:1024
	ds_read_b128 v[140:143], v14 offset:2048
	ds_read_b128 v[174:177], v14 offset:3072
	ds_read_b128 v[20:23], v0 offset:32768
	ds_read_b128 v[28:31], v0 offset:33792
	ds_read_b128 v[38:41], v192 offset:32768
	ds_read_b128 v[42:45], v192 offset:33792
	ds_read_b128 v[234:237], v193 offset:32768
	ds_read_b128 v[238:241], v193 offset:33792
	ds_read_b128 v[242:245], v250 offset:32768
	ds_read_b128 v[246:249], v250 offset:33792
	s_waitcnt vmcnt(2)
	s_barrier
; #define LDA(dst, b, h) for (int m = 0; m < 4; ++m) for (int k = 0; k < 2; ++k) \
;     dst[m][k] = *reinterpret_cast<const bf16x8*>((char*)SA(b, h) + lds_byte(wr * 64 + m * 16 + fr, k * 32 + fq * 8))
; #define LDB(dst, b, h) for (int n = 0; n < 2; ++n) for (int k = 0; k < 2; ++k) \
;     dst[n][k] = *reinterpret_cast<const bf16x8*>((char*)SB(b, h) + lds_byte(wc * 32 + n * 16 + fr, k * 32 + fq * 8))
; #define MMA(ai, bj, At, Bt_) do { __builtin_amdgcn_s_setprio(1); \
;     for (int m = 0; m < 4; ++m) for (int n = 0; n < 2; ++n) for (int k = 0; k < 2; ++k) \
;       acc[ai][bj][m][n] = __builtin_amdgcn_mfma_f32_16x16x32_bf16(At[m][k], Bt_[n][k], acc[ai][bj][m][n], 0, 0, 0); \
;     __builtin_amdgcn_s_setprio(0); } while (0)
; #define WAIT_V(n) asm volatile("s_waitcnt vmcnt(" #n ")" ::: "memory")
; #define WAIT_L(n) asm volatile("s_waitcnt lgkmcnt(" #n ")" ::: "memory")
; #define BAR __builtin_amdgcn_s_barrier()
; __device__ __forceinline__ void gemm_main(acc_t& acc, const u16* A, int lda, const u16* Bt, int ldb, int nt, const int tidx) {
;     ...
;     { LDB(B0, 1, 0); LDA(At, 1, 0); WAIT_V(2); BAR; WAIT_L(0); MMA(0, 0, At, B0); BAR;
;       LDB(B1, 1, 1); WAIT_V(0); BAR; WAIT_L(0); MMA(0, 1, At, B1); BAR;
;       LDA(At, 1, 1); BAR; WAIT_L(0); MMA(1, 0, At, B0); MMA(1, 1, At, B1); BAR; }
;     if (wr == 0) BAR;
	s_waitcnt lgkmcnt(0)
	s_setprio 1
	v_mfma_f32_16x16x32_bf16 v[52:55], v[20:23], v[6:9], v[126:129]
	v_mfma_f32_16x16x32_bf16 v[120:123], v[28:31], v[10:13], v[52:55]
	v_mfma_f32_16x16x32_bf16 v[52:55], v[20:23], v[140:143], v[198:201]
	v_mfma_f32_16x16x32_bf16 v[116:119], v[28:31], v[174:177], v[52:55]
	v_mfma_f32_16x16x32_bf16 v[52:55], v[38:41], v[6:9], v[202:205]
	v_mfma_f32_16x16x32_bf16 v[104:107], v[42:45], v[10:13], v[52:55]
	v_mfma_f32_16x16x32_bf16 v[52:55], v[38:41], v[140:143], v[206:209]
	v_mfma_f32_16x16x32_bf16 v[100:103], v[42:45], v[174:177], v[52:55]
	v_mfma_f32_16x16x32_bf16 v[52:55], v[234:237], v[6:9], v[110:113]
	v_mfma_f32_16x16x32_bf16 v[88:91], v[238:241], v[10:13], v[52:55]
	v_mfma_f32_16x16x32_bf16 v[52:55], v[234:237], v[140:143], v[210:213]
	v_mfma_f32_16x16x32_bf16 v[84:87], v[238:241], v[174:177], v[52:55]
	v_mfma_f32_16x16x32_bf16 v[52:55], v[242:245], v[6:9], v[214:217]
	v_mfma_f32_16x16x32_bf16 v[56:59], v[246:249], v[10:13], v[52:55]
	v_mfma_f32_16x16x32_bf16 v[52:55], v[242:245], v[140:143], v[218:221]
	v_mfma_f32_16x16x32_bf16 v[52:55], v[246:249], v[174:177], v[52:55]
	s_setprio 0
	v_add_u32_e32 v14, v133, v132
	s_barrier
	ds_read_b128 v[132:135], v14
	ds_read_b128 v[198:201], v14 offset:1024
	ds_read_b128 v[202:205], v14 offset:2048
	ds_read_b128 v[206:209], v14 offset:3072
	s_waitcnt vmcnt(0)
	s_barrier
	s_waitcnt lgkmcnt(0)
	s_setprio 1
	v_mfma_f32_16x16x32_bf16 v[92:95], v[20:23], v[132:135], v[94:97]
	v_mfma_f32_16x16x32_bf16 v[20:23], v[20:23], v[202:205], v[162:165]
	v_mfma_f32_16x16x32_bf16 v[124:127], v[28:31], v[206:209], v[20:23]
	v_mfma_f32_16x16x32_bf16 v[20:23], v[38:41], v[132:135], v[166:169]
	v_mfma_f32_16x16x32_bf16 v[112:115], v[42:45], v[198:201], v[20:23]
	v_mfma_f32_16x16x32_bf16 v[20:23], v[38:41], v[202:205], v[170:173]
	v_mfma_f32_16x16x32_bf16 v[108:111], v[42:45], v[206:209], v[20:23]
	v_mfma_f32_16x16x32_bf16 v[20:23], v[234:237], v[132:135], v[78:81]
	v_mfma_f32_16x16x32_bf16 v[96:99], v[238:241], v[198:201], v[20:23]
	v_mfma_f32_16x16x32_bf16 v[20:23], v[234:237], v[202:205], v[74:77]
	v_mfma_f32_16x16x32_bf16 v[128:131], v[28:31], v[198:201], v[92:95]
	v_mfma_f32_16x16x32_bf16 v[92:95], v[238:241], v[206:209], v[20:23]
	v_mfma_f32_16x16x32_bf16 v[20:23], v[242:245], v[132:135], v[70:73]
	v_mfma_f32_16x16x32_bf16 v[80:83], v[246:249], v[198:201], v[20:23]
	v_mfma_f32_16x16x32_bf16 v[20:23], v[242:245], v[202:205], v[66:69]
	v_mfma_f32_16x16x32_bf16 v[68:71], v[246:249], v[206:209], v[20:23]
	s_setprio 0
	s_barrier
	ds_read_b128 v[160:163], v0 offset:49152
	ds_read_b128 v[164:167], v0 offset:50176
	ds_read_b128 v[168:171], v192 offset:49152
	ds_read_b128 v[210:213], v192 offset:50176
	ds_read_b128 v[214:217], v193 offset:49152
	ds_read_b128 v[218:221], v193 offset:50176
	ds_read_b128 v[234:237], v250 offset:49152
	ds_read_b128 v[238:241], v250 offset:50176
	s_barrier
	s_waitcnt lgkmcnt(0)
	s_setprio 1
	v_mfma_f32_16x16x32_bf16 v[20:23], v[160:163], v[6:9], v[62:65]
	v_mfma_f32_16x16x32_bf16 v[72:75], v[164:167], v[10:13], v[20:23]
	v_mfma_f32_16x16x32_bf16 v[20:23], v[160:163], v[140:143], v[178:181]
	v_mfma_f32_16x16x32_bf16 v[60:63], v[164:167], v[174:177], v[20:23]
	v_mfma_f32_16x16x32_bf16 v[20:23], v[168:171], v[6:9], v[194:197]
	v_mfma_f32_16x16x32_bf16 v[44:47], v[210:213], v[10:13], v[20:23]
	v_mfma_f32_16x16x32_bf16 v[20:23], v[168:171], v[140:143], v[222:225]
	v_mfma_f32_16x16x32_bf16 v[40:43], v[210:213], v[174:177], v[20:23]
	v_mfma_f32_16x16x32_bf16 v[20:23], v[214:217], v[6:9], v[48:51]
	v_mfma_f32_16x16x32_bf16 v[6:9], v[234:237], v[6:9], v[144:147]
	v_mfma_f32_16x16x32_bf16 v[28:31], v[218:221], v[10:13], v[20:23]
	v_mfma_f32_16x16x32_bf16 v[20:23], v[214:217], v[140:143], v[226:229]
	v_mfma_f32_16x16x32_bf16 v[12:15], v[238:241], v[10:13], v[6:9]
	v_mfma_f32_16x16x32_bf16 v[6:9], v[234:237], v[140:143], v[34:37]
	v_mfma_f32_16x16x32_bf16 v[20:23], v[218:221], v[174:177], v[20:23]
	v_mfma_f32_16x16x32_bf16 v[8:11], v[238:241], v[174:177], v[6:9]
	s_setprio 0
	s_setprio 1
	v_mfma_f32_16x16x32_bf16 v[32:35], v[160:163], v[132:135], v[148:151]
	v_mfma_f32_16x16x32_bf16 v[76:79], v[164:167], v[198:201], v[32:35]
	v_mfma_f32_16x16x32_bf16 v[32:35], v[160:163], v[202:205], v[152:155]
	v_mfma_f32_16x16x32_bf16 v[24:27], v[168:171], v[132:135], v[24:27]
	v_mfma_f32_16x16x32_bf16 v[16:19], v[214:217], v[132:135], v[16:19]
	v_mfma_f32_16x16x32_bf16 v[64:67], v[164:167], v[206:209], v[32:35]
	v_mfma_f32_16x16x32_bf16 v[48:51], v[210:213], v[198:201], v[24:27]
	v_mfma_f32_16x16x32_bf16 v[24:27], v[168:171], v[202:205], v[156:159]
	v_mfma_f32_16x16x32_bf16 v[32:35], v[218:221], v[198:201], v[16:19]
	v_mfma_f32_16x16x32_bf16 v[16:19], v[214:217], v[202:205], v[136:139]
	v_mfma_f32_16x16x32_bf16 v[36:39], v[210:213], v[206:209], v[24:27]
	v_mfma_f32_16x16x32_bf16 v[24:27], v[218:221], v[206:209], v[16:19]
	v_mfma_f32_16x16x32_bf16 v[16:19], v[234:237], v[132:135], v[230:233]
	v_mfma_f32_16x16x32_bf16 v[2:5], v[234:237], v[202:205], v[2:5]
	v_mfma_f32_16x16x32_bf16 v[16:19], v[238:241], v[198:201], v[16:19]
	v_mfma_f32_16x16x32_bf16 v[4:7], v[238:241], v[206:209], v[2:5]
	s_setprio 0
	s_barrier
	s_and_saveexec_b64 s[4:5], vcc
	s_cbranch_execz .LBB0_637
	s_barrier

; #define STAGE(P, BASE, LD, br, kt) do { const char* _gp = (const char*)((BASE) + (long)((br) * (LD) + (kt) * BK)); \
;     __builtin_amdgcn_global_load_lds((const unsigned*)(_gp + vo_##BASE##0), (unsigned*)((char*)(P) + tidx * 16), 16, 0, 0); \
;     __builtin_amdgcn_global_load_lds((const unsigned*)(_gp + vo_##BASE##1), (unsigned*)((char*)(P) + tidx * 16 + 8192), 16, 0, 0); } while (0)
; #define LDA(dst, b, h) for (int m = 0; m < 4; ++m) for (int k = 0; k < 2; ++k) \
;     dst[m][k] = *reinterpret_cast<const bf16x8*>((char*)SA(b, h) + lds_byte(wr * 64 + m * 16 + fr, k * 32 + fq * 8))
; #define LDB(dst, b, h) for (int n = 0; n < 2; ++n) for (int k = 0; k < 2; ++k) \
;     dst[n][k] = *reinterpret_cast<const bf16x8*>((char*)SB(b, h) + lds_byte(wc * 32 + n * 16 + fr, k * 32 + fq * 8))
; #define MMA(ai, bj, At, Bt_) do { __builtin_amdgcn_s_setprio(1); \
;     for (int m = 0; m < 4; ++m) for (int n = 0; n < 2; ++n) for (int k = 0; k < 2; ++k) \
;       acc[ai][bj][m][n] = __builtin_amdgcn_mfma_f32_16x16x32_bf16(At[m][k], Bt_[n][k], acc[ai][bj][m][n], 0, 0, 0); \
;     __builtin_amdgcn_s_setprio(0); } while (0)
; #define WAIT_L(n) asm volatile("s_waitcnt lgkmcnt(" #n ")" ::: "memory")
; #define BAR __builtin_amdgcn_s_barrier()
; #define SCHED __builtin_amdgcn_sched_barrier(0)
; __device__ __forceinline__ void gemm_main(acc_t& acc, const u16* A, int lda, const u16* Bt, int ldb, int nt, const int tidx) {
;     ...
;     for (int t = 0; t < nt - 2; t += 2) {
;         LDB(B0, 0, 0); SCHED; LDA(At, 0, 0); STAGE(SA(1, 1), A, lda, HALF, t + 1);
;         WAIT_L(8); BAR; WAIT_L(0); MMA(0, 0, At, B0); BAR; SCHED;
;         LDB(B1, 0, 1); STAGE(SB(0, 0), Bt, ldb, 0, t + 2);
;         BAR; WAIT_L(0); MMA(0, 1, At, B1); BAR;
;         LDA(At, 0, 1); STAGE(SA(0, 0), A, lda, 0, t + 2);
;         BAR; WAIT_L(0); MMA(1, 0, At, B0); BAR; SCHED;
.LBB0_673:
	v_add_u32_e32 v170, v143, v132
	ds_read_b128 v[158:161], v170
	ds_read_b128 v[162:165], v170 offset:1024
	ds_read_b128 v[166:169], v170 offset:2048
	ds_read_b128 v[170:173], v170 offset:3072
	s_add_i32 s42, s18, 0x20040
	s_ashr_i32 s43, s42, 31
	s_lshl_b64 s[42:43], s[42:43], 1
	s_add_u32 s42, s2, s42
	v_add_u32_e32 v220, 0xc000, v136
	s_addc_u32 s43, s3, s43
	v_readfirstlane_b32 s19, v220
	v_add_u32_e32 v220, 0xe000, v136
	v_add_u32_e32 v190, v144, v141
	v_add_u32_e32 v191, v142, v140
	v_add_u32_e32 v236, v142, v138
	v_add_u32_e32 v237, v142, v139
	v_lshl_add_u64 v[218:219], s[42:43], 0, v[0:1]
	s_mov_b32 m0, s19
	v_readfirstlane_b32 s19, v220
	ds_read_b128 v[174:177], v190
	ds_read_b128 v[178:181], v190 offset:1024
	ds_read_b128 v[194:197], v191
	ds_read_b128 v[198:201], v191 offset:1024
	ds_read_b128 v[202:205], v236
	ds_read_b128 v[206:209], v236 offset:1024
	ds_read_b128 v[210:213], v237
	ds_read_b128 v[214:217], v237 offset:1024
	global_load_lds_dwordx4 v[218:219], off
	v_lshl_add_u64 v[218:219], s[42:43], 0, v[130:131]
	s_mov_b32 m0, s19
	s_nop 0
	global_load_lds_dwordx4 v[218:219], off
	s_waitcnt lgkmcnt(8)
	s_barrier
	s_waitcnt lgkmcnt(0)
	s_setprio 1
	v_mfma_f32_16x16x32_bf16 v[126:129], v[174:177], v[158:161], v[126:129]
	v_mfma_f32_16x16x32_bf16 v[122:125], v[174:177], v[166:169], v[122:125]
	v_mfma_f32_16x16x32_bf16 v[118:121], v[194:197], v[158:161], v[118:121]
	v_mfma_f32_16x16x32_bf16 v[114:117], v[194:197], v[166:169], v[114:117]
	v_mfma_f32_16x16x32_bf16 v[110:113], v[202:205], v[158:161], v[110:113]
	v_mfma_f32_16x16x32_bf16 v[106:109], v[202:205], v[166:169], v[106:109]
	v_mfma_f32_16x16x32_bf16 v[102:105], v[210:213], v[158:161], v[102:105]
	v_mfma_f32_16x16x32_bf16 v[98:101], v[210:213], v[166:169], v[98:101]
	v_mfma_f32_16x16x32_bf16 v[126:129], v[178:181], v[162:165], v[126:129]
	v_mfma_f32_16x16x32_bf16 v[122:125], v[178:181], v[170:173], v[122:125]
	v_mfma_f32_16x16x32_bf16 v[118:121], v[198:201], v[162:165], v[118:121]
	v_mfma_f32_16x16x32_bf16 v[114:117], v[198:201], v[170:173], v[114:117]
	v_mfma_f32_16x16x32_bf16 v[110:113], v[206:209], v[162:165], v[110:113]
	v_mfma_f32_16x16x32_bf16 v[106:109], v[206:209], v[170:173], v[106:109]
	v_mfma_f32_16x16x32_bf16 v[102:105], v[214:217], v[162:165], v[102:105]
	v_mfma_f32_16x16x32_bf16 v[98:101], v[214:217], v[170:173], v[98:101]
	s_setprio 0
	s_barrier
	s_add_i32 s72, s18, 0x80
	s_add_i32 s41, s41, 2
	s_lshl_b64 s[42:43], s[72:73], 1
	s_add_u32 s44, s16, s42
	s_addc_u32 s45, s17, s43
	v_readfirstlane_b32 s19, v145
	v_add_u32_e32 v230, v137, v132
	v_lshl_add_u64 v[234:235], s[44:45], 0, v[0:1]
	s_mov_b32 m0, s19
	v_readfirstlane_b32 s19, v146
	ds_read_b128 v[218:221], v230
	ds_read_b128 v[222:225], v230 offset:1024
	ds_read_b128 v[226:229], v230 offset:2048
	ds_read_b128 v[230:233], v230 offset:3072
	global_load_lds_dwordx4 v[234:235], off
	v_lshl_add_u64 v[234:235], s[44:45], 0, v[130:131]
	s_mov_b32 m0, s19
	s_nop 0
	global_load_lds_dwordx4 v[234:235], off
	s_barrier
	s_waitcnt lgkmcnt(0)
	s_setprio 1
	v_mfma_f32_16x16x32_bf16 v[94:97], v[174:177], v[218:221], v[94:97]
	v_mfma_f32_16x16x32_bf16 v[90:93], v[174:177], v[226:229], v[90:93]
	v_mfma_f32_16x16x32_bf16 v[86:89], v[194:197], v[218:221], v[86:89]
	v_mfma_f32_16x16x32_bf16 v[82:85], v[194:197], v[226:229], v[82:85]
	v_mfma_f32_16x16x32_bf16 v[78:81], v[202:205], v[218:221], v[78:81]
	v_mfma_f32_16x16x32_bf16 v[74:77], v[202:205], v[226:229], v[74:77]
	v_mfma_f32_16x16x32_bf16 v[70:73], v[210:213], v[218:221], v[70:73]
	v_mfma_f32_16x16x32_bf16 v[66:69], v[210:213], v[226:229], v[66:69]
	v_mfma_f32_16x16x32_bf16 v[94:97], v[178:181], v[222:225], v[94:97]
	v_mfma_f32_16x16x32_bf16 v[90:93], v[178:181], v[230:233], v[90:93]
	v_mfma_f32_16x16x32_bf16 v[86:89], v[198:201], v[222:225], v[86:89]
	v_mfma_f32_16x16x32_bf16 v[82:85], v[198:201], v[230:233], v[82:85]
	v_mfma_f32_16x16x32_bf16 v[78:81], v[206:209], v[222:225], v[78:81]
	v_mfma_f32_16x16x32_bf16 v[74:77], v[206:209], v[230:233], v[74:77]
	v_mfma_f32_16x16x32_bf16 v[70:73], v[214:217], v[222:225], v[70:73]
	v_mfma_f32_16x16x32_bf16 v[66:69], v[214:217], v[230:233], v[66:69]
	s_setprio 0
	s_add_u32 s42, s2, s42
	s_addc_u32 s43, s3, s43
	v_readfirstlane_b32 s19, v136
	v_lshl_add_u64 v[234:235], s[42:43], 0, v[0:1]
	s_mov_b32 m0, s19
	v_readfirstlane_b32 s19, v147
	s_barrier
	ds_read_b128 v[174:177], v190 offset:16384
	ds_read_b128 v[178:181], v190 offset:17408
	ds_read_b128 v[194:197], v191 offset:16384
	ds_read_b128 v[198:201], v191 offset:17408
	ds_read_b128 v[202:205], v236 offset:16384
	ds_read_b128 v[206:209], v236 offset:17408
	ds_read_b128 v[210:213], v237 offset:16384
	ds_read_b128 v[214:217], v237 offset:17408
	global_load_lds_dwordx4 v[234:235], off
	v_lshl_add_u64 v[234:235], s[42:43], 0, v[130:131]
	s_mov_b32 m0, s19
	s_nop 0
	global_load_lds_dwordx4 v[234:235], off
	s_barrier
	s_waitcnt lgkmcnt(0)
	s_setprio 1
	v_mfma_f32_16x16x32_bf16 v[62:65], v[174:177], v[158:161], v[62:65]
	v_mfma_f32_16x16x32_bf16 v[58:61], v[174:177], v[166:169], v[58:61]
	v_mfma_f32_16x16x32_bf16 v[54:57], v[194:197], v[158:161], v[54:57]
	v_mfma_f32_16x16x32_bf16 v[50:53], v[194:197], v[166:169], v[50:53]
	v_mfma_f32_16x16x32_bf16 v[46:49], v[202:205], v[158:161], v[46:49]
	v_mfma_f32_16x16x32_bf16 v[42:45], v[202:205], v[166:169], v[42:45]
	v_mfma_f32_16x16x32_bf16 v[38:41], v[210:213], v[158:161], v[38:41]
	v_mfma_f32_16x16x32_bf16 v[34:37], v[210:213], v[166:169], v[34:37]
	v_mfma_f32_16x16x32_bf16 v[62:65], v[178:181], v[162:165], v[62:65]
	v_mfma_f32_16x16x32_bf16 v[58:61], v[178:181], v[170:173], v[58:61]
	v_mfma_f32_16x16x32_bf16 v[54:57], v[198:201], v[162:165], v[54:57]
	v_mfma_f32_16x16x32_bf16 v[50:53], v[198:201], v[170:173], v[50:53]
	v_mfma_f32_16x16x32_bf16 v[46:49], v[206:209], v[162:165], v[46:49]
	v_mfma_f32_16x16x32_bf16 v[42:45], v[206:209], v[170:173], v[42:45]
	v_mfma_f32_16x16x32_bf16 v[38:41], v[214:217], v[162:165], v[38:41]
	v_mfma_f32_16x16x32_bf16 v[34:37], v[214:217], v[170:173], v[34:37]
	s_setprio 0
	s_barrier
; #define STAGE(P, BASE, LD, br, kt) do { const char* _gp = (const char*)((BASE) + (long)((br) * (LD) + (kt) * BK)); \
;     __builtin_amdgcn_global_load_lds((const unsigned*)(_gp + vo_##BASE##0), (unsigned*)((char*)(P) + tidx * 16), 16, 0, 0); \
;     __builtin_amdgcn_global_load_lds((const unsigned*)(_gp + vo_##BASE##1), (unsigned*)((char*)(P) + tidx * 16 + 8192), 16, 0, 0); } while (0)
; #define LDA(dst, b, h) for (int m = 0; m < 4; ++m) for (int k = 0; k < 2; ++k) \
;     dst[m][k] = *reinterpret_cast<const bf16x8*>((char*)SA(b, h) + lds_byte(wr * 64 + m * 16 + fr, k * 32 + fq * 8))
; #define LDB(dst, b, h) for (int n = 0; n < 2; ++n) for (int k = 0; k < 2; ++k) \
;     dst[n][k] = *reinterpret_cast<const bf16x8*>((char*)SB(b, h) + lds_byte(wc * 32 + n * 16 + fr, k * 32 + fq * 8))
; #define MMA(ai, bj, At, Bt_) do { __builtin_amdgcn_s_setprio(1); \
;     for (int m = 0; m < 4; ++m) for (int n = 0; n < 2; ++n) for (int k = 0; k < 2; ++k) \
;       acc[ai][bj][m][n] = __builtin_amdgcn_mfma_f32_16x16x32_bf16(At[m][k], Bt_[n][k], acc[ai][bj][m][n], 0, 0, 0); \
;     __builtin_amdgcn_s_setprio(0); } while (0)
; #define WAIT_V(n) asm volatile("s_waitcnt vmcnt(" #n ")" ::: "memory")
; #define WAIT_L(n) asm volatile("s_waitcnt lgkmcnt(" #n ")" ::: "memory")
; #define BAR __builtin_amdgcn_s_barrier()
; #define SCHED __builtin_amdgcn_sched_barrier(0)
; __device__ __forceinline__ void gemm_main(acc_t& acc, const u16* A, int lda, const u16* Bt, int ldb, int nt, const int tidx) {
;     ...
;         STAGE(SB(0, 1), Bt, ldb, HALF, t + 2);
;         WAIT_V(6); BAR; MMA(1, 1, At, B1); BAR;
;         LDB(B0, 1, 0); SCHED; LDA(At, 1, 0); STAGE(SA(0, 1), A, lda, HALF, t + 2);
;         WAIT_L(8); BAR; WAIT_L(0); MMA(0, 0, At, B0); BAR; SCHED;
;         LDB(B1, 1, 1); STAGE(SB(1, 0), Bt, ldb, 0, t + 3);
;         BAR; WAIT_L(0); MMA(0, 1, At, B1); BAR;
	s_add_i32 s42, s18, 0x20080
	s_mov_b32 s43, s73
	s_lshl_b64 s[42:43], s[42:43], 1
	s_add_u32 s44, s16, s42
	s_addc_u32 s45, s17, s43
	v_readfirstlane_b32 s19, v148
	v_lshl_add_u64 v[158:159], s[44:45], 0, v[0:1]
	s_mov_b32 m0, s19
	v_readfirstlane_b32 s19, v149
	global_load_lds_dwordx4 v[158:159], off
	v_lshl_add_u64 v[158:159], s[44:45], 0, v[130:131]
	s_mov_b32 m0, s19
	s_nop 0
	global_load_lds_dwordx4 v[158:159], off
	s_waitcnt vmcnt(6)
	s_barrier
	s_setprio 1
	v_mfma_f32_16x16x32_bf16 v[30:33], v[174:177], v[218:221], v[30:33]
	v_mfma_f32_16x16x32_bf16 v[26:29], v[174:177], v[226:229], v[26:29]
	v_mfma_f32_16x16x32_bf16 v[22:25], v[194:197], v[218:221], v[22:25]
	v_mfma_f32_16x16x32_bf16 v[18:21], v[194:197], v[226:229], v[18:21]
	v_mfma_f32_16x16x32_bf16 v[14:17], v[202:205], v[218:221], v[14:17]
	v_mfma_f32_16x16x32_bf16 v[10:13], v[202:205], v[226:229], v[10:13]
	v_mfma_f32_16x16x32_bf16 v[6:9], v[210:213], v[218:221], v[6:9]
	v_mfma_f32_16x16x32_bf16 v[2:5], v[210:213], v[226:229], v[2:5]
	v_mfma_f32_16x16x32_bf16 v[30:33], v[178:181], v[222:225], v[30:33]
	v_mfma_f32_16x16x32_bf16 v[26:29], v[178:181], v[230:233], v[26:29]
	v_mfma_f32_16x16x32_bf16 v[22:25], v[198:201], v[222:225], v[22:25]
	v_mfma_f32_16x16x32_bf16 v[18:21], v[198:201], v[230:233], v[18:21]
	v_mfma_f32_16x16x32_bf16 v[14:17], v[206:209], v[222:225], v[14:17]
	v_mfma_f32_16x16x32_bf16 v[10:13], v[206:209], v[230:233], v[10:13]
	v_mfma_f32_16x16x32_bf16 v[6:9], v[214:217], v[222:225], v[6:9]
	v_mfma_f32_16x16x32_bf16 v[2:5], v[214:217], v[230:233], v[2:5]
	s_setprio 0
	v_add_u32_e32 v170, v134, v132
	s_barrier
	ds_read_b128 v[158:161], v170
	ds_read_b128 v[162:165], v170 offset:1024
	ds_read_b128 v[166:169], v170 offset:2048
	ds_read_b128 v[170:173], v170 offset:3072
	s_add_u32 s42, s2, s42
	s_addc_u32 s43, s3, s43
	v_readfirstlane_b32 s19, v150
	v_lshl_add_u64 v[218:219], s[42:43], 0, v[0:1]
	s_mov_b32 m0, s19
	v_readfirstlane_b32 s19, v151
	ds_read_b128 v[174:177], v190 offset:32768
	ds_read_b128 v[178:181], v190 offset:33792
	ds_read_b128 v[194:197], v191 offset:32768
	ds_read_b128 v[198:201], v191 offset:33792
	ds_read_b128 v[202:205], v236 offset:32768
	ds_read_b128 v[206:209], v236 offset:33792
	ds_read_b128 v[210:213], v237 offset:32768
	ds_read_b128 v[214:217], v237 offset:33792
	global_load_lds_dwordx4 v[218:219], off
	v_lshl_add_u64 v[218:219], s[42:43], 0, v[130:131]
	s_mov_b32 m0, s19
	s_nop 0
	global_load_lds_dwordx4 v[218:219], off
	s_waitcnt lgkmcnt(8)
	s_barrier
	s_waitcnt lgkmcnt(0)
	s_setprio 1
	v_mfma_f32_16x16x32_bf16 v[126:129], v[174:177], v[158:161], v[126:129]
	v_mfma_f32_16x16x32_bf16 v[122:125], v[174:177], v[166:169], v[122:125]
	v_mfma_f32_16x16x32_bf16 v[118:121], v[194:197], v[158:161], v[118:121]
	v_mfma_f32_16x16x32_bf16 v[114:117], v[194:197], v[166:169], v[114:117]
	v_mfma_f32_16x16x32_bf16 v[110:113], v[202:205], v[158:161], v[110:113]
	v_mfma_f32_16x16x32_bf16 v[106:109], v[202:205], v[166:169], v[106:109]
	v_mfma_f32_16x16x32_bf16 v[102:105], v[210:213], v[158:161], v[102:105]
	v_mfma_f32_16x16x32_bf16 v[98:101], v[210:213], v[166:169], v[98:101]
	v_mfma_f32_16x16x32_bf16 v[126:129], v[178:181], v[162:165], v[126:129]
	v_mfma_f32_16x16x32_bf16 v[122:125], v[178:181], v[170:173], v[122:125]
	v_mfma_f32_16x16x32_bf16 v[118:121], v[198:201], v[162:165], v[118:121]
	v_mfma_f32_16x16x32_bf16 v[114:117], v[198:201], v[170:173], v[114:117]
	v_mfma_f32_16x16x32_bf16 v[110:113], v[206:209], v[162:165], v[110:113]
	v_mfma_f32_16x16x32_bf16 v[106:109], v[206:209], v[170:173], v[106:109]
	v_mfma_f32_16x16x32_bf16 v[102:105], v[214:217], v[162:165], v[102:105]
	v_mfma_f32_16x16x32_bf16 v[98:101], v[214:217], v[170:173], v[98:101]
	s_setprio 0
	s_barrier
	s_ashr_i32 s19, s18, 31
	s_lshl_b64 s[42:43], s[18:19], 1
	s_add_u32 s44, s16, s42
	s_addc_u32 s45, s17, s43
	v_lshl_add_u64 v[234:235], s[44:45], 0, v[0:1]
	v_readfirstlane_b32 s19, v152
	v_add_u32_e32 v230, v133, v132
	v_lshl_add_u64 v[234:235], v[234:235], 0, s[0:1]
	s_mov_b32 m0, s19
	ds_read_b128 v[218:221], v230
	ds_read_b128 v[222:225], v230 offset:1024
	ds_read_b128 v[226:229], v230 offset:2048
	ds_read_b128 v[230:233], v230 offset:3072
	global_load_lds_dwordx4 v[234:235], off
	v_lshl_add_u64 v[234:235], s[44:45], 0, v[130:131]
	v_readfirstlane_b32 s19, v153
	v_lshl_add_u64 v[234:235], v[234:235], 0, s[0:1]
	s_mov_b32 m0, s19
	s_nop 0
	global_load_lds_dwordx4 v[234:235], off
	s_barrier
	s_waitcnt lgkmcnt(0)
	s_setprio 1
	v_mfma_f32_16x16x32_bf16 v[94:97], v[174:177], v[218:221], v[94:97]
	v_mfma_f32_16x16x32_bf16 v[90:93], v[174:177], v[226:229], v[90:93]
	v_mfma_f32_16x16x32_bf16 v[86:89], v[194:197], v[218:221], v[86:89]
	v_mfma_f32_16x16x32_bf16 v[82:85], v[194:197], v[226:229], v[82:85]
	v_mfma_f32_16x16x32_bf16 v[78:81], v[202:205], v[218:221], v[78:81]
	v_mfma_f32_16x16x32_bf16 v[74:77], v[202:205], v[226:229], v[74:77]
	v_mfma_f32_16x16x32_bf16 v[70:73], v[210:213], v[218:221], v[70:73]
	v_mfma_f32_16x16x32_bf16 v[66:69], v[210:213], v[226:229], v[66:69]
	v_mfma_f32_16x16x32_bf16 v[94:97], v[178:181], v[222:225], v[94:97]
	v_mfma_f32_16x16x32_bf16 v[90:93], v[178:181], v[230:233], v[90:93]
	v_mfma_f32_16x16x32_bf16 v[86:89], v[198:201], v[222:225], v[86:89]
	v_mfma_f32_16x16x32_bf16 v[82:85], v[198:201], v[230:233], v[82:85]
	v_mfma_f32_16x16x32_bf16 v[78:81], v[206:209], v[222:225], v[78:81]
	v_mfma_f32_16x16x32_bf16 v[74:77], v[206:209], v[230:233], v[74:77]
	v_mfma_f32_16x16x32_bf16 v[70:73], v[214:217], v[222:225], v[70:73]
	v_mfma_f32_16x16x32_bf16 v[66:69], v[214:217], v[230:233], v[66:69]
	s_setprio 0
	s_add_u32 s42, s2, s42
	s_addc_u32 s43, s3, s43
	v_lshl_add_u64 v[234:235], s[42:43], 0, v[0:1]
	v_readfirstlane_b32 s19, v154
	v_lshl_add_u64 v[234:235], v[234:235], 0, s[0:1]
	s_mov_b32 m0, s19
	s_barrier
; #define STAGE(P, BASE, LD, br, kt) do { const char* _gp = (const char*)((BASE) + (long)((br) * (LD) + (kt) * BK)); \
;     __builtin_amdgcn_global_load_lds((const unsigned*)(_gp + vo_##BASE##0), (unsigned*)((char*)(P) + tidx * 16), 16, 0, 0); \
;     __builtin_amdgcn_global_load_lds((const unsigned*)(_gp + vo_##BASE##1), (unsigned*)((char*)(P) + tidx * 16 + 8192), 16, 0, 0); } while (0)
; #define LDA(dst, b, h) for (int m = 0; m < 4; ++m) for (int k = 0; k < 2; ++k) \
;     dst[m][k] = *reinterpret_cast<const bf16x8*>((char*)SA(b, h) + lds_byte(wr * 64 + m * 16 + fr, k * 32 + fq * 8))
; #define LDB(dst, b, h) for (int n = 0; n < 2; ++n) for (int k = 0; k < 2; ++k) \
;     dst[n][k] = *reinterpret_cast<const bf16x8*>((char*)SB(b, h) + lds_byte(wc * 32 + n * 16 + fr, k * 32 + fq * 8))
; #define MMA(ai, bj, At, Bt_) do { __builtin_amdgcn_s_setprio(1); \
;     for (int m = 0; m < 4; ++m) for (int n = 0; n < 2; ++n) for (int k = 0; k < 2; ++k) \
;       acc[ai][bj][m][n] = __builtin_amdgcn_mfma_f32_16x16x32_bf16(At[m][k], Bt_[n][k], acc[ai][bj][m][n], 0, 0, 0); \
;     __builtin_amdgcn_s_setprio(0); } while (0)
; #define WAIT_V(n) asm volatile("s_waitcnt vmcnt(" #n ")" ::: "memory")
; #define WAIT_L(n) asm volatile("s_waitcnt lgkmcnt(" #n ")" ::: "memory")
; #define BAR __builtin_amdgcn_s_barrier()
; #define SCHED __builtin_amdgcn_sched_barrier(0)
; __device__ __forceinline__ void gemm_main(acc_t& acc, const u16* A, int lda, const u16* Bt, int ldb, int nt, const int tidx) {
;     ...
;         LDA(At, 1, 1); STAGE(SA(1, 0), A, lda, 0, t + 3);
;         BAR; WAIT_L(0); MMA(1, 0, At, B0); BAR; SCHED;
;         STAGE(SB(1, 1), Bt, ldb, HALF, t + 3);
;         WAIT_V(6); BAR; MMA(1, 1, At, B1); BAR;
;     }
;     { LDB(B0, 0, 0); LDA(At, 0, 0); STAGE(SA(1, 1), A, lda, HALF, nt - 1);
;       BAR; WAIT_L(0); MMA(0, 0, At, B0); BAR;
	ds_read_b128 v[174:177], v190 offset:49152
	ds_read_b128 v[178:181], v190 offset:50176
	ds_read_b128 v[194:197], v191 offset:49152
	ds_read_b128 v[198:201], v191 offset:50176
	ds_read_b128 v[202:205], v236 offset:49152
	ds_read_b128 v[206:209], v236 offset:50176
	ds_read_b128 v[210:213], v237 offset:49152
	ds_read_b128 v[214:217], v237 offset:50176
	global_load_lds_dwordx4 v[234:235], off
	v_lshl_add_u64 v[234:235], s[42:43], 0, v[130:131]
	v_readfirstlane_b32 s19, v155
	v_lshl_add_u64 v[234:235], v[234:235], 0, s[0:1]
	s_mov_b32 m0, s19
	s_nop 0
	global_load_lds_dwordx4 v[234:235], off
	s_barrier
	s_waitcnt lgkmcnt(0)
	s_setprio 1
	v_mfma_f32_16x16x32_bf16 v[62:65], v[174:177], v[158:161], v[62:65]
	v_mfma_f32_16x16x32_bf16 v[58:61], v[174:177], v[166:169], v[58:61]
	v_mfma_f32_16x16x32_bf16 v[54:57], v[194:197], v[158:161], v[54:57]
	v_mfma_f32_16x16x32_bf16 v[50:53], v[194:197], v[166:169], v[50:53]
	v_mfma_f32_16x16x32_bf16 v[46:49], v[202:205], v[158:161], v[46:49]
	v_mfma_f32_16x16x32_bf16 v[42:45], v[202:205], v[166:169], v[42:45]
	v_mfma_f32_16x16x32_bf16 v[38:41], v[210:213], v[158:161], v[38:41]
	v_mfma_f32_16x16x32_bf16 v[34:37], v[210:213], v[166:169], v[34:37]
	v_mfma_f32_16x16x32_bf16 v[62:65], v[178:181], v[162:165], v[62:65]
	v_mfma_f32_16x16x32_bf16 v[58:61], v[178:181], v[170:173], v[58:61]
	v_mfma_f32_16x16x32_bf16 v[54:57], v[198:201], v[162:165], v[54:57]
	v_mfma_f32_16x16x32_bf16 v[50:53], v[198:201], v[170:173], v[50:53]
	v_mfma_f32_16x16x32_bf16 v[46:49], v[206:209], v[162:165], v[46:49]
	v_mfma_f32_16x16x32_bf16 v[42:45], v[206:209], v[170:173], v[42:45]
	v_mfma_f32_16x16x32_bf16 v[38:41], v[214:217], v[162:165], v[38:41]
	v_mfma_f32_16x16x32_bf16 v[34:37], v[214:217], v[170:173], v[34:37]
	s_setprio 0
	s_barrier
	s_add_i32 s18, s18, 0x200c0
	s_ashr_i32 s19, s18, 31
	s_lshl_b64 s[18:19], s[18:19], 1
	s_add_u32 s18, s16, s18
	s_addc_u32 s19, s17, s19
	v_readfirstlane_b32 s42, v156
	v_lshl_add_u64 v[158:159], s[18:19], 0, v[0:1]
	s_mov_b32 m0, s42
	s_nop 0
	global_load_lds_dwordx4 v[158:159], off
	v_lshl_add_u64 v[158:159], s[18:19], 0, v[130:131]
	v_readfirstlane_b32 s18, v157
	s_mov_b32 m0, s18
	s_nop 0
	global_load_lds_dwordx4 v[158:159], off
	s_waitcnt vmcnt(6)
	s_barrier
	s_setprio 1
	v_mfma_f32_16x16x32_bf16 v[30:33], v[174:177], v[218:221], v[30:33]
	v_mfma_f32_16x16x32_bf16 v[26:29], v[174:177], v[226:229], v[26:29]
	v_mfma_f32_16x16x32_bf16 v[22:25], v[194:197], v[218:221], v[22:25]
	v_mfma_f32_16x16x32_bf16 v[18:21], v[194:197], v[226:229], v[18:21]
	v_mfma_f32_16x16x32_bf16 v[14:17], v[202:205], v[218:221], v[14:17]
	v_mfma_f32_16x16x32_bf16 v[10:13], v[202:205], v[226:229], v[10:13]
	v_mfma_f32_16x16x32_bf16 v[6:9], v[210:213], v[218:221], v[6:9]
	v_mfma_f32_16x16x32_bf16 v[2:5], v[210:213], v[226:229], v[2:5]
	v_mfma_f32_16x16x32_bf16 v[30:33], v[178:181], v[222:225], v[30:33]
	v_mfma_f32_16x16x32_bf16 v[26:29], v[178:181], v[230:233], v[26:29]
	v_mfma_f32_16x16x32_bf16 v[22:25], v[198:201], v[222:225], v[22:25]
	v_mfma_f32_16x16x32_bf16 v[18:21], v[198:201], v[230:233], v[18:21]
	v_mfma_f32_16x16x32_bf16 v[14:17], v[206:209], v[222:225], v[14:17]
	v_mfma_f32_16x16x32_bf16 v[10:13], v[206:209], v[230:233], v[10:13]
	v_mfma_f32_16x16x32_bf16 v[6:9], v[214:217], v[222:225], v[6:9]
	v_mfma_f32_16x16x32_bf16 v[2:5], v[214:217], v[230:233], v[2:5]
	s_setprio 0
	s_cmp_lt_i32 s41, s40
	s_mov_b32 s18, s72
	s_barrier
	s_cbranch_scc1 .LBB0_673
	s_mov_b32 s44, 0x800000
	s_mov_b32 s45, 0xc2fc0000
.LBB0_675:
	s_lshl_b32 s16, s33, 6
	s_add_i32 s16, s16, 0x1ffc0
	s_ashr_i32 s17, s16, 31
	s_lshl_b32 s13, s13, 24
	s_lshl_b64 s[16:17], s[16:17], 1
	s_add_u32 s2, s2, s16
	s_addc_u32 s3, s3, s17
	v_add_u32_e32 v200, 0xc000, v136
	v_lshl_add_u64 v[198:199], s[2:3], 0, v[0:1]
	v_lshl_add_u64 v[130:131], s[2:3], 0, v[130:131]
	v_add_u32_e32 v0, v143, v132
	v_readfirstlane_b32 s2, v200
	v_add_u32_e32 v136, 0xe000, v136
	v_cmp_gt_u32_e32 vcc, s51, v135
	ds_read_b128 v[146:149], v0
	ds_read_b128 v[150:153], v0 offset:1024
	ds_read_b128 v[154:157], v0 offset:2048
	ds_read_b128 v[158:161], v0 offset:3072
	v_add_u32_e32 v0, v144, v141
	v_add_u32_e32 v135, v142, v140
	v_add_u32_e32 v190, v142, v138
	v_add_u32_e32 v191, v142, v139
	s_mov_b32 m0, s2
	v_readfirstlane_b32 s2, v136
	ds_read_b128 v[162:165], v0
	ds_read_b128 v[166:169], v0 offset:1024
	ds_read_b128 v[170:173], v135
	ds_read_b128 v[174:177], v135 offset:1024
	ds_read_b128 v[178:181], v190
	ds_read_b128 v[194:197], v190 offset:1024
	ds_read_b128 v[138:141], v191
	ds_read_b128 v[142:145], v191 offset:1024
	global_load_lds_dwordx4 v[198:199], off
	s_mov_b32 m0, s2
	s_nop 0
	global_load_lds_dwordx4 v[130:131], off
	s_barrier
	s_waitcnt lgkmcnt(0)
	s_setprio 1
	v_mfma_f32_16x16x32_bf16 v[126:129], v[162:165], v[146:149], v[126:129]
	v_mfma_f32_16x16x32_bf16 v[122:125], v[162:165], v[154:157], v[122:125]
	v_mfma_f32_16x16x32_bf16 v[114:117], v[170:173], v[154:157], v[114:117]
	v_mfma_f32_16x16x32_bf16 v[106:109], v[178:181], v[154:157], v[106:109]
	v_mfma_f32_16x16x32_bf16 v[98:101], v[138:141], v[154:157], v[98:101]
	v_mfma_f32_16x16x32_bf16 v[126:129], v[166:169], v[150:153], v[126:129]
	v_mfma_f32_16x16x32_bf16 v[122:125], v[166:169], v[158:161], v[122:125]
	v_mfma_f32_16x16x32_bf16 v[118:121], v[170:173], v[146:149], v[118:121]
	v_mfma_f32_16x16x32_bf16 v[114:117], v[174:177], v[158:161], v[114:117]
	v_mfma_f32_16x16x32_bf16 v[110:113], v[178:181], v[146:149], v[110:113]
	v_mfma_f32_16x16x32_bf16 v[106:109], v[194:197], v[158:161], v[106:109]
	v_mfma_f32_16x16x32_bf16 v[102:105], v[138:141], v[146:149], v[102:105]
	v_mfma_f32_16x16x32_bf16 v[98:101], v[142:145], v[158:161], v[98:101]
	v_mfma_f32_16x16x32_bf16 v[198:201], v[174:177], v[150:153], v[118:121]
	v_mfma_f32_16x16x32_bf16 v[202:205], v[194:197], v[150:153], v[110:113]
	v_mfma_f32_16x16x32_bf16 v[206:209], v[142:145], v[150:153], v[102:105]
	s_setprio 0
	v_add_u32_e32 v130, v137, v132
	s_barrier
; #define LDA(dst, b, h) for (int m = 0; m < 4; ++m) for (int k = 0; k < 2; ++k) \
;     dst[m][k] = *reinterpret_cast<const bf16x8*>((char*)SA(b, h) + lds_byte(wr * 64 + m * 16 + fr, k * 32 + fq * 8))
; #define LDB(dst, b, h) for (int n = 0; n < 2; ++n) for (int k = 0; k < 2; ++k) \
;     dst[n][k] = *reinterpret_cast<const bf16x8*>((char*)SB(b, h) + lds_byte(wc * 32 + n * 16 + fr, k * 32 + fq * 8))
; #define MMA(ai, bj, At, Bt_) do { __builtin_amdgcn_s_setprio(1); \
;     for (int m = 0; m < 4; ++m) for (int n = 0; n < 2; ++n) for (int k = 0; k < 2; ++k) \
;       acc[ai][bj][m][n] = __builtin_amdgcn_mfma_f32_16x16x32_bf16(At[m][k], Bt_[n][k], acc[ai][bj][m][n], 0, 0, 0); \
;     __builtin_amdgcn_s_setprio(0); } while (0)
; #define WAIT_V(n) asm volatile("s_waitcnt vmcnt(" #n ")" ::: "memory")
; #define WAIT_L(n) asm volatile("s_waitcnt lgkmcnt(" #n ")" ::: "memory")
; #define BAR __builtin_amdgcn_s_barrier()
; __device__ __forceinline__ void gemm_main(acc_t& acc, const u16* A, int lda, const u16* Bt, int ldb, int nt, const int tidx) {
;     ...
;       BAR; WAIT_L(0); MMA(0, 0, At, B0); BAR;
;       LDB(B1, 0, 1); BAR; WAIT_L(0); MMA(0, 1, At, B1); BAR;
;       LDA(At, 0, 1); WAIT_V(4); BAR; WAIT_L(0); MMA(1, 0, At, B0); MMA(1, 1, At, B1); BAR; }
;     { LDB(B0, 1, 0); LDA(At, 1, 0); WAIT_V(2); BAR; WAIT_L(0); MMA(0, 0, At, B0); BAR;
	s_nop 0
	ds_read_b128 v[102:105], v130
	ds_read_b128 v[110:113], v130 offset:1024
	ds_read_b128 v[118:121], v130 offset:2048
	ds_read_b128 v[210:213], v130 offset:3072
	s_barrier
	s_waitcnt lgkmcnt(0)
	s_setprio 1
	v_mfma_f32_16x16x32_bf16 v[90:93], v[162:165], v[118:121], v[90:93]
	v_mfma_f32_16x16x32_bf16 v[82:85], v[170:173], v[118:121], v[82:85]
	v_mfma_f32_16x16x32_bf16 v[74:77], v[178:181], v[118:121], v[74:77]
	v_mfma_f32_16x16x32_bf16 v[66:69], v[138:141], v[118:121], v[66:69]
	v_mfma_f32_16x16x32_bf16 v[94:97], v[162:165], v[102:105], v[94:97]
	v_mfma_f32_16x16x32_bf16 v[90:93], v[166:169], v[210:213], v[90:93]
	v_mfma_f32_16x16x32_bf16 v[86:89], v[170:173], v[102:105], v[86:89]
	v_mfma_f32_16x16x32_bf16 v[82:85], v[174:177], v[210:213], v[82:85]
	v_mfma_f32_16x16x32_bf16 v[78:81], v[178:181], v[102:105], v[78:81]
	v_mfma_f32_16x16x32_bf16 v[74:77], v[194:197], v[210:213], v[74:77]
	v_mfma_f32_16x16x32_bf16 v[70:73], v[138:141], v[102:105], v[70:73]
	v_mfma_f32_16x16x32_bf16 v[66:69], v[142:145], v[210:213], v[66:69]
	v_mfma_f32_16x16x32_bf16 v[214:217], v[166:169], v[110:113], v[94:97]
	v_mfma_f32_16x16x32_bf16 v[162:165], v[174:177], v[110:113], v[86:89]
	v_mfma_f32_16x16x32_bf16 v[166:169], v[194:197], v[110:113], v[78:81]
	v_mfma_f32_16x16x32_bf16 v[170:173], v[142:145], v[110:113], v[70:73]
	s_setprio 0
	s_barrier
	s_nop 0
	ds_read_b128 v[70:73], v0 offset:16384
	ds_read_b128 v[78:81], v0 offset:17408
	ds_read_b128 v[86:89], v135 offset:16384
	ds_read_b128 v[94:97], v135 offset:17408
	ds_read_b128 v[136:139], v190 offset:16384
	ds_read_b128 v[140:143], v190 offset:17408
	ds_read_b128 v[174:177], v191 offset:16384
	ds_read_b128 v[178:181], v191 offset:17408
	s_waitcnt vmcnt(4)
	s_barrier
	s_waitcnt lgkmcnt(0)
	s_setprio 1
	v_mfma_f32_16x16x32_bf16 v[58:61], v[70:73], v[154:157], v[58:61]
	v_mfma_f32_16x16x32_bf16 v[50:53], v[86:89], v[154:157], v[50:53]
	v_mfma_f32_16x16x32_bf16 v[42:45], v[136:139], v[154:157], v[42:45]
	v_mfma_f32_16x16x32_bf16 v[34:37], v[174:177], v[154:157], v[34:37]
	v_mfma_f32_16x16x32_bf16 v[62:65], v[70:73], v[146:149], v[62:65]
	v_mfma_f32_16x16x32_bf16 v[58:61], v[78:81], v[158:161], v[58:61]
	v_mfma_f32_16x16x32_bf16 v[54:57], v[86:89], v[146:149], v[54:57]
	v_mfma_f32_16x16x32_bf16 v[50:53], v[94:97], v[158:161], v[50:53]
	v_mfma_f32_16x16x32_bf16 v[46:49], v[136:139], v[146:149], v[46:49]
	v_mfma_f32_16x16x32_bf16 v[42:45], v[140:143], v[158:161], v[42:45]
	v_mfma_f32_16x16x32_bf16 v[38:41], v[174:177], v[146:149], v[38:41]
	v_mfma_f32_16x16x32_bf16 v[34:37], v[178:181], v[158:161], v[34:37]
	v_mfma_f32_16x16x32_bf16 v[194:197], v[78:81], v[150:153], v[62:65]
	v_mfma_f32_16x16x32_bf16 v[218:221], v[94:97], v[150:153], v[54:57]
	v_mfma_f32_16x16x32_bf16 v[222:225], v[140:143], v[150:153], v[46:49]
	v_mfma_f32_16x16x32_bf16 v[144:147], v[178:181], v[150:153], v[38:41]
	s_setprio 0
	s_setprio 1
	v_mfma_f32_16x16x32_bf16 v[26:29], v[70:73], v[118:121], v[26:29]
	v_mfma_f32_16x16x32_bf16 v[18:21], v[86:89], v[118:121], v[18:21]
	v_mfma_f32_16x16x32_bf16 v[10:13], v[136:139], v[118:121], v[10:13]
	v_mfma_f32_16x16x32_bf16 v[6:9], v[174:177], v[102:105], v[6:9]
	v_mfma_f32_16x16x32_bf16 v[30:33], v[70:73], v[102:105], v[30:33]
	v_mfma_f32_16x16x32_bf16 v[26:29], v[78:81], v[210:213], v[26:29]
	v_mfma_f32_16x16x32_bf16 v[22:25], v[86:89], v[102:105], v[22:25]
	v_mfma_f32_16x16x32_bf16 v[18:21], v[94:97], v[210:213], v[18:21]
	v_mfma_f32_16x16x32_bf16 v[14:17], v[136:139], v[102:105], v[14:17]
	v_mfma_f32_16x16x32_bf16 v[10:13], v[140:143], v[210:213], v[10:13]
	v_mfma_f32_16x16x32_bf16 v[6:9], v[178:181], v[110:113], v[6:9]
	v_mfma_f32_16x16x32_bf16 v[2:5], v[174:177], v[118:121], v[2:5]
	v_mfma_f32_16x16x32_bf16 v[148:151], v[78:81], v[110:113], v[30:33]
	v_mfma_f32_16x16x32_bf16 v[152:155], v[94:97], v[110:113], v[22:25]
	v_mfma_f32_16x16x32_bf16 v[156:159], v[140:143], v[110:113], v[14:17]
	v_mfma_f32_16x16x32_bf16 v[136:139], v[178:181], v[210:213], v[2:5]
	s_setprio 0
	v_add_u32_e32 v22, v134, v132
	s_barrier
	s_nop 0
	ds_read_b128 v[2:5], v22
	ds_read_b128 v[14:17], v22 offset:1024
	ds_read_b128 v[140:143], v22 offset:2048
	ds_read_b128 v[174:177], v22 offset:3072
	ds_read_b128 v[22:25], v0 offset:32768
	ds_read_b128 v[30:33], v0 offset:33792
	ds_read_b128 v[38:41], v135 offset:32768
	ds_read_b128 v[46:49], v135 offset:33792
	ds_read_b128 v[54:57], v190 offset:32768
	ds_read_b128 v[62:65], v190 offset:33792
	ds_read_b128 v[178:181], v191 offset:32768
	ds_read_b128 v[210:213], v191 offset:33792
	s_waitcnt vmcnt(2)
	s_barrier
; #define LDA(dst, b, h) for (int m = 0; m < 4; ++m) for (int k = 0; k < 2; ++k) \
;     dst[m][k] = *reinterpret_cast<const bf16x8*>((char*)SA(b, h) + lds_byte(wr * 64 + m * 16 + fr, k * 32 + fq * 8))
; #define LDB(dst, b, h) for (int n = 0; n < 2; ++n) for (int k = 0; k < 2; ++k) \
;     dst[n][k] = *reinterpret_cast<const bf16x8*>((char*)SB(b, h) + lds_byte(wc * 32 + n * 16 + fr, k * 32 + fq * 8))
; #define MMA(ai, bj, At, Bt_) do { __builtin_amdgcn_s_setprio(1); \
;     for (int m = 0; m < 4; ++m) for (int n = 0; n < 2; ++n) for (int k = 0; k < 2; ++k) \
;       acc[ai][bj][m][n] = __builtin_amdgcn_mfma_f32_16x16x32_bf16(At[m][k], Bt_[n][k], acc[ai][bj][m][n], 0, 0, 0); \
;     __builtin_amdgcn_s_setprio(0); } while (0)
; #define WAIT_V(n) asm volatile("s_waitcnt vmcnt(" #n ")" ::: "memory")
; #define WAIT_L(n) asm volatile("s_waitcnt lgkmcnt(" #n ")" ::: "memory")
; #define BAR __builtin_amdgcn_s_barrier()
; __device__ __forceinline__ void gemm_main(acc_t& acc, const u16* A, int lda, const u16* Bt, int ldb, int nt, const int tidx) {
;     ...
;     { LDB(B0, 1, 0); LDA(At, 1, 0); WAIT_V(2); BAR; WAIT_L(0); MMA(0, 0, At, B0); BAR;
;       LDB(B1, 1, 1); WAIT_V(0); BAR; WAIT_L(0); MMA(0, 1, At, B1); BAR;
;       LDA(At, 1, 1); BAR; WAIT_L(0); MMA(1, 0, At, B0); MMA(1, 1, At, B1); BAR; }
;     if (wr == 0) BAR;
	s_waitcnt lgkmcnt(0)
	s_setprio 1
	v_mfma_f32_16x16x32_bf16 v[70:73], v[22:25], v[2:5], v[126:129]
	v_mfma_f32_16x16x32_bf16 v[126:129], v[30:33], v[14:17], v[70:73]
	v_mfma_f32_16x16x32_bf16 v[70:73], v[22:25], v[140:143], v[122:125]
	v_mfma_f32_16x16x32_bf16 v[118:121], v[30:33], v[174:177], v[70:73]
	v_mfma_f32_16x16x32_bf16 v[70:73], v[38:41], v[2:5], v[198:201]
	v_mfma_f32_16x16x32_bf16 v[110:113], v[46:49], v[14:17], v[70:73]
	v_mfma_f32_16x16x32_bf16 v[70:73], v[38:41], v[140:143], v[114:117]
	v_mfma_f32_16x16x32_bf16 v[102:105], v[46:49], v[174:177], v[70:73]
	v_mfma_f32_16x16x32_bf16 v[70:73], v[54:57], v[2:5], v[202:205]
	v_mfma_f32_16x16x32_bf16 v[94:97], v[62:65], v[14:17], v[70:73]
	v_mfma_f32_16x16x32_bf16 v[70:73], v[54:57], v[140:143], v[106:109]
	v_mfma_f32_16x16x32_bf16 v[86:89], v[62:65], v[174:177], v[70:73]
	v_mfma_f32_16x16x32_bf16 v[70:73], v[178:181], v[2:5], v[206:209]
	v_mfma_f32_16x16x32_bf16 v[78:81], v[210:213], v[14:17], v[70:73]
	v_mfma_f32_16x16x32_bf16 v[70:73], v[178:181], v[140:143], v[98:101]
	v_mfma_f32_16x16x32_bf16 v[70:73], v[210:213], v[174:177], v[70:73]
	s_setprio 0
	s_nop 0
	v_add_u32_e32 v98, v133, v132
	s_barrier
	ds_read_b128 v[130:133], v98
	ds_read_b128 v[198:201], v98 offset:1024
	ds_read_b128 v[202:205], v98 offset:2048
	ds_read_b128 v[206:209], v98 offset:3072
	s_waitcnt vmcnt(0)
	s_barrier
	s_waitcnt lgkmcnt(0)
	s_setprio 1
	v_mfma_f32_16x16x32_bf16 v[98:101], v[22:25], v[130:133], v[214:217]
	v_mfma_f32_16x16x32_bf16 v[22:25], v[22:25], v[202:205], v[90:93]
	v_mfma_f32_16x16x32_bf16 v[114:117], v[30:33], v[206:209], v[22:25]
	v_mfma_f32_16x16x32_bf16 v[22:25], v[38:41], v[130:133], v[162:165]
	v_mfma_f32_16x16x32_bf16 v[106:109], v[46:49], v[198:201], v[22:25]
	v_mfma_f32_16x16x32_bf16 v[22:25], v[38:41], v[202:205], v[82:85]
	v_mfma_f32_16x16x32_bf16 v[122:125], v[30:33], v[198:201], v[98:101]
	v_mfma_f32_16x16x32_bf16 v[98:101], v[46:49], v[206:209], v[22:25]
	v_mfma_f32_16x16x32_bf16 v[22:25], v[54:57], v[130:133], v[166:169]
	v_mfma_f32_16x16x32_bf16 v[90:93], v[62:65], v[198:201], v[22:25]
	v_mfma_f32_16x16x32_bf16 v[22:25], v[54:57], v[202:205], v[74:77]
	v_mfma_f32_16x16x32_bf16 v[82:85], v[62:65], v[206:209], v[22:25]
	v_mfma_f32_16x16x32_bf16 v[22:25], v[178:181], v[130:133], v[170:173]
	v_mfma_f32_16x16x32_bf16 v[74:77], v[210:213], v[198:201], v[22:25]
	v_mfma_f32_16x16x32_bf16 v[22:25], v[178:181], v[202:205], v[66:69]
	v_mfma_f32_16x16x32_bf16 v[62:65], v[210:213], v[206:209], v[22:25]
	s_setprio 0
	s_barrier
	ds_read_b128 v[160:163], v0 offset:49152
	ds_read_b128 v[164:167], v0 offset:50176
	ds_read_b128 v[168:171], v135 offset:49152
	ds_read_b128 v[178:181], v135 offset:50176
	ds_read_b128 v[210:213], v190 offset:49152
	ds_read_b128 v[214:217], v190 offset:50176
	ds_read_b128 v[226:229], v191 offset:49152
	ds_read_b128 v[230:233], v191 offset:50176
	s_barrier
	s_waitcnt lgkmcnt(0)
	s_setprio 1
	v_mfma_f32_16x16x32_bf16 v[22:25], v[160:163], v[2:5], v[194:197]
	v_mfma_f32_16x16x32_bf16 v[66:69], v[164:167], v[14:17], v[22:25]
	v_mfma_f32_16x16x32_bf16 v[22:25], v[160:163], v[140:143], v[58:61]
	v_mfma_f32_16x16x32_bf16 v[54:57], v[164:167], v[174:177], v[22:25]
	v_mfma_f32_16x16x32_bf16 v[22:25], v[168:171], v[2:5], v[218:221]
	v_mfma_f32_16x16x32_bf16 v[46:49], v[178:181], v[14:17], v[22:25]
	v_mfma_f32_16x16x32_bf16 v[22:25], v[168:171], v[140:143], v[50:53]
	v_mfma_f32_16x16x32_bf16 v[38:41], v[178:181], v[174:177], v[22:25]
	v_mfma_f32_16x16x32_bf16 v[22:25], v[210:213], v[2:5], v[222:225]
	v_mfma_f32_16x16x32_bf16 v[2:5], v[226:229], v[2:5], v[144:147]
	v_mfma_f32_16x16x32_bf16 v[30:33], v[214:217], v[14:17], v[22:25]
	v_mfma_f32_16x16x32_bf16 v[22:25], v[210:213], v[140:143], v[42:45]
	v_mfma_f32_16x16x32_bf16 v[14:17], v[230:233], v[14:17], v[2:5]
	v_mfma_f32_16x16x32_bf16 v[2:5], v[226:229], v[140:143], v[34:37]
	v_mfma_f32_16x16x32_bf16 v[22:25], v[214:217], v[174:177], v[22:25]
	v_mfma_f32_16x16x32_bf16 v[2:5], v[230:233], v[174:177], v[2:5]
	s_setprio 0
	s_setprio 1
	v_mfma_f32_16x16x32_bf16 v[34:37], v[160:163], v[130:133], v[148:151]
	v_mfma_f32_16x16x32_bf16 v[26:29], v[160:163], v[202:205], v[26:29]
	v_mfma_f32_16x16x32_bf16 v[18:21], v[168:171], v[202:205], v[18:21]
	v_mfma_f32_16x16x32_bf16 v[58:61], v[164:167], v[198:201], v[34:37]
	v_mfma_f32_16x16x32_bf16 v[50:53], v[164:167], v[206:209], v[26:29]
	v_mfma_f32_16x16x32_bf16 v[26:29], v[168:171], v[130:133], v[152:155]
	v_mfma_f32_16x16x32_bf16 v[34:37], v[178:181], v[206:209], v[18:21]
	v_mfma_f32_16x16x32_bf16 v[18:21], v[210:213], v[130:133], v[156:159]
	v_mfma_f32_16x16x32_bf16 v[10:13], v[210:213], v[202:205], v[10:13]
	v_mfma_f32_16x16x32_bf16 v[6:9], v[226:229], v[130:133], v[6:9]
	v_mfma_f32_16x16x32_bf16 v[42:45], v[178:181], v[198:201], v[26:29]
	v_mfma_f32_16x16x32_bf16 v[26:29], v[214:217], v[198:201], v[18:21]
	v_mfma_f32_16x16x32_bf16 v[18:21], v[214:217], v[206:209], v[10:13]
	v_mfma_f32_16x16x32_bf16 v[10:13], v[230:233], v[198:201], v[6:9]
	v_mfma_f32_16x16x32_bf16 v[6:9], v[226:229], v[202:205], v[136:139]
	v_mfma_f32_16x16x32_bf16 v[6:9], v[230:233], v[206:209], v[6:9]
	s_setprio 0
	s_barrier
	s_and_saveexec_b64 s[2:3], vcc
	s_cbranch_execz .LBB0_677
	s_barrier

; #define STAGE(P, BASE, LD, br, kt) do { const char* _gp = (const char*)((BASE) + (long)((br) * (LD) + (kt) * BK)); \
;     __builtin_amdgcn_global_load_lds((const unsigned*)(_gp + vo_##BASE##0), (unsigned*)((char*)(P) + tidx * 16), 16, 0, 0); \
;     __builtin_amdgcn_global_load_lds((const unsigned*)(_gp + vo_##BASE##1), (unsigned*)((char*)(P) + tidx * 16 + 8192), 16, 0, 0); } while (0)
; #define LDA(dst, b, h) for (int m = 0; m < 4; ++m) for (int k = 0; k < 2; ++k) \
;     dst[m][k] = *reinterpret_cast<const bf16x8*>((char*)SA(b, h) + lds_byte(wr * 64 + m * 16 + fr, k * 32 + fq * 8))
; #define LDB(dst, b, h) for (int n = 0; n < 2; ++n) for (int k = 0; k < 2; ++k) \
;     dst[n][k] = *reinterpret_cast<const bf16x8*>((char*)SB(b, h) + lds_byte(wc * 32 + n * 16 + fr, k * 32 + fq * 8))
; #define MMA(ai, bj, At, Bt_) do { __builtin_amdgcn_s_setprio(1); \
;     for (int m = 0; m < 4; ++m) for (int n = 0; n < 2; ++n) for (int k = 0; k < 2; ++k) \
;       acc[ai][bj][m][n] = __builtin_amdgcn_mfma_f32_16x16x32_bf16(At[m][k], Bt_[n][k], acc[ai][bj][m][n], 0, 0, 0); \
;     __builtin_amdgcn_s_setprio(0); } while (0)
; #define WAIT_L(n) asm volatile("s_waitcnt lgkmcnt(" #n ")" ::: "memory")
; #define BAR __builtin_amdgcn_s_barrier()
; #define SCHED __builtin_amdgcn_sched_barrier(0)
; __device__ __forceinline__ void gemm_main(acc_t& acc, const u16* A, int lda, const u16* Bt, int ldb, int nt, const int tidx) {
;     ...
;     for (int t = 0; t < nt - 2; t += 2) {
;         LDB(B0, 0, 0); SCHED; LDA(At, 0, 0); STAGE(SA(1, 1), A, lda, HALF, t + 1);
;         WAIT_L(8); BAR; WAIT_L(0); MMA(0, 0, At, B0); BAR; SCHED;
;         LDB(B1, 0, 1); STAGE(SB(0, 0), Bt, ldb, 0, t + 2);
;         BAR; WAIT_L(0); MMA(0, 1, At, B1); BAR;
;         LDA(At, 0, 1); STAGE(SA(0, 0), A, lda, 0, t + 2);
;         BAR; WAIT_L(0); MMA(1, 0, At, B0); BAR; SCHED;
.LBB0_716:
	v_add_u32_e32 v170, v140, v132
	ds_read_b128 v[158:161], v170
	ds_read_b128 v[162:165], v170 offset:1024
	ds_read_b128 v[166:169], v170 offset:2048
	ds_read_b128 v[170:173], v170 offset:3072
	s_add_i32 s40, s18, 0x20040
	s_ashr_i32 s41, s40, 31
	s_lshl_b64 s[40:41], s[40:41], 1
	s_add_u32 s40, s2, s40
	v_add_u32_e32 v220, 0xc000, v136
	s_addc_u32 s41, s3, s41
	v_readfirstlane_b32 s19, v220
	v_add_u32_e32 v220, 0xe000, v136
	v_add_u32_e32 v190, v141, v138
	v_add_u32_e32 v191, v139, v144
	v_add_u32_e32 v236, v139, v143
	v_add_u32_e32 v237, v139, v142
	v_lshl_add_u64 v[218:219], s[40:41], 0, v[0:1]
	s_mov_b32 m0, s19
	v_readfirstlane_b32 s19, v220
	ds_read_b128 v[174:177], v190
	ds_read_b128 v[178:181], v190 offset:1024
	ds_read_b128 v[194:197], v191
	ds_read_b128 v[198:201], v191 offset:1024
	ds_read_b128 v[202:205], v236
	ds_read_b128 v[206:209], v236 offset:1024
	ds_read_b128 v[210:213], v237
	ds_read_b128 v[214:217], v237 offset:1024
	global_load_lds_dwordx4 v[218:219], off
	v_lshl_add_u64 v[218:219], s[40:41], 0, v[130:131]
	s_mov_b32 m0, s19
	s_nop 0
	global_load_lds_dwordx4 v[218:219], off
	s_waitcnt lgkmcnt(8)
	s_barrier
	s_waitcnt lgkmcnt(0)
	s_setprio 1
	v_mfma_f32_16x16x32_bf16 v[126:129], v[174:177], v[158:161], v[126:129]
	v_mfma_f32_16x16x32_bf16 v[122:125], v[174:177], v[166:169], v[122:125]
	v_mfma_f32_16x16x32_bf16 v[118:121], v[194:197], v[158:161], v[118:121]
	v_mfma_f32_16x16x32_bf16 v[114:117], v[194:197], v[166:169], v[114:117]
	v_mfma_f32_16x16x32_bf16 v[110:113], v[202:205], v[158:161], v[110:113]
	v_mfma_f32_16x16x32_bf16 v[106:109], v[202:205], v[166:169], v[106:109]
	v_mfma_f32_16x16x32_bf16 v[102:105], v[210:213], v[158:161], v[102:105]
	v_mfma_f32_16x16x32_bf16 v[98:101], v[210:213], v[166:169], v[98:101]
	v_mfma_f32_16x16x32_bf16 v[126:129], v[178:181], v[162:165], v[126:129]
	v_mfma_f32_16x16x32_bf16 v[122:125], v[178:181], v[170:173], v[122:125]
	v_mfma_f32_16x16x32_bf16 v[118:121], v[198:201], v[162:165], v[118:121]
	v_mfma_f32_16x16x32_bf16 v[114:117], v[198:201], v[170:173], v[114:117]
	v_mfma_f32_16x16x32_bf16 v[110:113], v[206:209], v[162:165], v[110:113]
	v_mfma_f32_16x16x32_bf16 v[106:109], v[206:209], v[170:173], v[106:109]
	v_mfma_f32_16x16x32_bf16 v[102:105], v[214:217], v[162:165], v[102:105]
	v_mfma_f32_16x16x32_bf16 v[98:101], v[214:217], v[170:173], v[98:101]
	s_setprio 0
	s_barrier
	s_add_i32 s72, s18, 0x80
	s_add_i32 s39, s39, 2
	s_lshl_b64 s[40:41], s[72:73], 1
	s_add_u32 s42, s16, s40
	s_addc_u32 s43, s17, s41
	v_readfirstlane_b32 s19, v145
	v_add_u32_e32 v230, v137, v132
	v_lshl_add_u64 v[234:235], s[42:43], 0, v[0:1]
	s_mov_b32 m0, s19
	v_readfirstlane_b32 s19, v146
	ds_read_b128 v[218:221], v230
	ds_read_b128 v[222:225], v230 offset:1024
	ds_read_b128 v[226:229], v230 offset:2048
	ds_read_b128 v[230:233], v230 offset:3072
	global_load_lds_dwordx4 v[234:235], off
	v_lshl_add_u64 v[234:235], s[42:43], 0, v[130:131]
	s_mov_b32 m0, s19
	s_nop 0
	global_load_lds_dwordx4 v[234:235], off
	s_barrier
	s_waitcnt lgkmcnt(0)
	s_setprio 1
	v_mfma_f32_16x16x32_bf16 v[94:97], v[174:177], v[218:221], v[94:97]
	v_mfma_f32_16x16x32_bf16 v[90:93], v[174:177], v[226:229], v[90:93]
	v_mfma_f32_16x16x32_bf16 v[86:89], v[194:197], v[218:221], v[86:89]
	v_mfma_f32_16x16x32_bf16 v[82:85], v[194:197], v[226:229], v[82:85]
	v_mfma_f32_16x16x32_bf16 v[78:81], v[202:205], v[218:221], v[78:81]
	v_mfma_f32_16x16x32_bf16 v[74:77], v[202:205], v[226:229], v[74:77]
	v_mfma_f32_16x16x32_bf16 v[70:73], v[210:213], v[218:221], v[70:73]
	v_mfma_f32_16x16x32_bf16 v[66:69], v[210:213], v[226:229], v[66:69]
	v_mfma_f32_16x16x32_bf16 v[94:97], v[178:181], v[222:225], v[94:97]
	v_mfma_f32_16x16x32_bf16 v[90:93], v[178:181], v[230:233], v[90:93]
	v_mfma_f32_16x16x32_bf16 v[86:89], v[198:201], v[222:225], v[86:89]
	v_mfma_f32_16x16x32_bf16 v[82:85], v[198:201], v[230:233], v[82:85]
	v_mfma_f32_16x16x32_bf16 v[78:81], v[206:209], v[222:225], v[78:81]
	v_mfma_f32_16x16x32_bf16 v[74:77], v[206:209], v[230:233], v[74:77]
	v_mfma_f32_16x16x32_bf16 v[70:73], v[214:217], v[222:225], v[70:73]
	v_mfma_f32_16x16x32_bf16 v[66:69], v[214:217], v[230:233], v[66:69]
	s_setprio 0
	s_add_u32 s40, s2, s40
	s_addc_u32 s41, s3, s41
	v_readfirstlane_b32 s19, v136
	v_lshl_add_u64 v[234:235], s[40:41], 0, v[0:1]
	s_mov_b32 m0, s19
	v_readfirstlane_b32 s19, v147
	s_barrier
	ds_read_b128 v[174:177], v190 offset:16384
	ds_read_b128 v[178:181], v190 offset:17408
	ds_read_b128 v[194:197], v191 offset:16384
	ds_read_b128 v[198:201], v191 offset:17408
	ds_read_b128 v[202:205], v236 offset:16384
	ds_read_b128 v[206:209], v236 offset:17408
	ds_read_b128 v[210:213], v237 offset:16384
	ds_read_b128 v[214:217], v237 offset:17408
	global_load_lds_dwordx4 v[234:235], off
	v_lshl_add_u64 v[234:235], s[40:41], 0, v[130:131]
	s_mov_b32 m0, s19
	s_nop 0
	global_load_lds_dwordx4 v[234:235], off
	s_barrier
	s_waitcnt lgkmcnt(0)
	s_setprio 1
	v_mfma_f32_16x16x32_bf16 v[62:65], v[174:177], v[158:161], v[62:65]
	v_mfma_f32_16x16x32_bf16 v[58:61], v[174:177], v[166:169], v[58:61]
	v_mfma_f32_16x16x32_bf16 v[54:57], v[194:197], v[158:161], v[54:57]
	v_mfma_f32_16x16x32_bf16 v[50:53], v[194:197], v[166:169], v[50:53]
	v_mfma_f32_16x16x32_bf16 v[46:49], v[202:205], v[158:161], v[46:49]
	v_mfma_f32_16x16x32_bf16 v[42:45], v[202:205], v[166:169], v[42:45]
	v_mfma_f32_16x16x32_bf16 v[38:41], v[210:213], v[158:161], v[38:41]
	v_mfma_f32_16x16x32_bf16 v[34:37], v[210:213], v[166:169], v[34:37]
	v_mfma_f32_16x16x32_bf16 v[62:65], v[178:181], v[162:165], v[62:65]
	v_mfma_f32_16x16x32_bf16 v[58:61], v[178:181], v[170:173], v[58:61]
	v_mfma_f32_16x16x32_bf16 v[54:57], v[198:201], v[162:165], v[54:57]
	v_mfma_f32_16x16x32_bf16 v[50:53], v[198:201], v[170:173], v[50:53]
	v_mfma_f32_16x16x32_bf16 v[46:49], v[206:209], v[162:165], v[46:49]
	v_mfma_f32_16x16x32_bf16 v[42:45], v[206:209], v[170:173], v[42:45]
	v_mfma_f32_16x16x32_bf16 v[38:41], v[214:217], v[162:165], v[38:41]
	v_mfma_f32_16x16x32_bf16 v[34:37], v[214:217], v[170:173], v[34:37]
	s_setprio 0
	s_barrier
; #define STAGE(P, BASE, LD, br, kt) do { const char* _gp = (const char*)((BASE) + (long)((br) * (LD) + (kt) * BK)); \
;     __builtin_amdgcn_global_load_lds((const unsigned*)(_gp + vo_##BASE##0), (unsigned*)((char*)(P) + tidx * 16), 16, 0, 0); \
;     __builtin_amdgcn_global_load_lds((const unsigned*)(_gp + vo_##BASE##1), (unsigned*)((char*)(P) + tidx * 16 + 8192), 16, 0, 0); } while (0)
; #define LDA(dst, b, h) for (int m = 0; m < 4; ++m) for (int k = 0; k < 2; ++k) \
;     dst[m][k] = *reinterpret_cast<const bf16x8*>((char*)SA(b, h) + lds_byte(wr * 64 + m * 16 + fr, k * 32 + fq * 8))
; #define LDB(dst, b, h) for (int n = 0; n < 2; ++n) for (int k = 0; k < 2; ++k) \
;     dst[n][k] = *reinterpret_cast<const bf16x8*>((char*)SB(b, h) + lds_byte(wc * 32 + n * 16 + fr, k * 32 + fq * 8))
; #define MMA(ai, bj, At, Bt_) do { __builtin_amdgcn_s_setprio(1); \
;     for (int m = 0; m < 4; ++m) for (int n = 0; n < 2; ++n) for (int k = 0; k < 2; ++k) \
;       acc[ai][bj][m][n] = __builtin_amdgcn_mfma_f32_16x16x32_bf16(At[m][k], Bt_[n][k], acc[ai][bj][m][n], 0, 0, 0); \
;     __builtin_amdgcn_s_setprio(0); } while (0)
; #define WAIT_V(n) asm volatile("s_waitcnt vmcnt(" #n ")" ::: "memory")
; #define WAIT_L(n) asm volatile("s_waitcnt lgkmcnt(" #n ")" ::: "memory")
; #define BAR __builtin_amdgcn_s_barrier()
; #define SCHED __builtin_amdgcn_sched_barrier(0)
; __device__ __forceinline__ void gemm_main(acc_t& acc, const u16* A, int lda, const u16* Bt, int ldb, int nt, const int tidx) {
;     ...
;         STAGE(SB(0, 1), Bt, ldb, HALF, t + 2);
;         WAIT_V(6); BAR; MMA(1, 1, At, B1); BAR;
;         LDB(B0, 1, 0); SCHED; LDA(At, 1, 0); STAGE(SA(0, 1), A, lda, HALF, t + 2);
;         WAIT_L(8); BAR; WAIT_L(0); MMA(0, 0, At, B0); BAR; SCHED;
;         LDB(B1, 1, 1); STAGE(SB(1, 0), Bt, ldb, 0, t + 3);
;         BAR; WAIT_L(0); MMA(0, 1, At, B1); BAR;
	s_add_i32 s40, s18, 0x20080
	s_mov_b32 s41, s73
	s_lshl_b64 s[40:41], s[40:41], 1
	s_add_u32 s42, s16, s40
	s_addc_u32 s43, s17, s41
	v_readfirstlane_b32 s19, v148
	v_lshl_add_u64 v[158:159], s[42:43], 0, v[0:1]
	s_mov_b32 m0, s19
	v_readfirstlane_b32 s19, v149
	global_load_lds_dwordx4 v[158:159], off
	v_lshl_add_u64 v[158:159], s[42:43], 0, v[130:131]
	s_mov_b32 m0, s19
	s_nop 0
	global_load_lds_dwordx4 v[158:159], off
	s_waitcnt vmcnt(6)
	s_barrier
	s_setprio 1
	v_mfma_f32_16x16x32_bf16 v[30:33], v[174:177], v[218:221], v[30:33]
	v_mfma_f32_16x16x32_bf16 v[26:29], v[174:177], v[226:229], v[26:29]
	v_mfma_f32_16x16x32_bf16 v[22:25], v[194:197], v[218:221], v[22:25]
	v_mfma_f32_16x16x32_bf16 v[18:21], v[194:197], v[226:229], v[18:21]
	v_mfma_f32_16x16x32_bf16 v[14:17], v[202:205], v[218:221], v[14:17]
	v_mfma_f32_16x16x32_bf16 v[10:13], v[202:205], v[226:229], v[10:13]
	v_mfma_f32_16x16x32_bf16 v[6:9], v[210:213], v[218:221], v[6:9]
	v_mfma_f32_16x16x32_bf16 v[2:5], v[210:213], v[226:229], v[2:5]
	v_mfma_f32_16x16x32_bf16 v[30:33], v[178:181], v[222:225], v[30:33]
	v_mfma_f32_16x16x32_bf16 v[26:29], v[178:181], v[230:233], v[26:29]
	v_mfma_f32_16x16x32_bf16 v[22:25], v[198:201], v[222:225], v[22:25]
	v_mfma_f32_16x16x32_bf16 v[18:21], v[198:201], v[230:233], v[18:21]
	v_mfma_f32_16x16x32_bf16 v[14:17], v[206:209], v[222:225], v[14:17]
	v_mfma_f32_16x16x32_bf16 v[10:13], v[206:209], v[230:233], v[10:13]
	v_mfma_f32_16x16x32_bf16 v[6:9], v[214:217], v[222:225], v[6:9]
	v_mfma_f32_16x16x32_bf16 v[2:5], v[214:217], v[230:233], v[2:5]
	s_setprio 0
	v_add_u32_e32 v170, v134, v132
	s_barrier
	ds_read_b128 v[158:161], v170
	ds_read_b128 v[162:165], v170 offset:1024
	ds_read_b128 v[166:169], v170 offset:2048
	ds_read_b128 v[170:173], v170 offset:3072
	s_add_u32 s40, s2, s40
	s_addc_u32 s41, s3, s41
	v_readfirstlane_b32 s19, v150
	v_lshl_add_u64 v[218:219], s[40:41], 0, v[0:1]
	s_mov_b32 m0, s19
	v_readfirstlane_b32 s19, v151
	ds_read_b128 v[174:177], v190 offset:32768
	ds_read_b128 v[178:181], v190 offset:33792
	ds_read_b128 v[194:197], v191 offset:32768
	ds_read_b128 v[198:201], v191 offset:33792
	ds_read_b128 v[202:205], v236 offset:32768
	ds_read_b128 v[206:209], v236 offset:33792
	ds_read_b128 v[210:213], v237 offset:32768
	ds_read_b128 v[214:217], v237 offset:33792
	global_load_lds_dwordx4 v[218:219], off
	v_lshl_add_u64 v[218:219], s[40:41], 0, v[130:131]
	s_mov_b32 m0, s19
	s_nop 0
	global_load_lds_dwordx4 v[218:219], off
	s_waitcnt lgkmcnt(8)
	s_barrier
	s_waitcnt lgkmcnt(0)
	s_setprio 1
	v_mfma_f32_16x16x32_bf16 v[126:129], v[174:177], v[158:161], v[126:129]
	v_mfma_f32_16x16x32_bf16 v[122:125], v[174:177], v[166:169], v[122:125]
	v_mfma_f32_16x16x32_bf16 v[118:121], v[194:197], v[158:161], v[118:121]
	v_mfma_f32_16x16x32_bf16 v[114:117], v[194:197], v[166:169], v[114:117]
	v_mfma_f32_16x16x32_bf16 v[110:113], v[202:205], v[158:161], v[110:113]
	v_mfma_f32_16x16x32_bf16 v[106:109], v[202:205], v[166:169], v[106:109]
	v_mfma_f32_16x16x32_bf16 v[102:105], v[210:213], v[158:161], v[102:105]
	v_mfma_f32_16x16x32_bf16 v[98:101], v[210:213], v[166:169], v[98:101]
	v_mfma_f32_16x16x32_bf16 v[126:129], v[178:181], v[162:165], v[126:129]
	v_mfma_f32_16x16x32_bf16 v[122:125], v[178:181], v[170:173], v[122:125]
	v_mfma_f32_16x16x32_bf16 v[118:121], v[198:201], v[162:165], v[118:121]
	v_mfma_f32_16x16x32_bf16 v[114:117], v[198:201], v[170:173], v[114:117]
	v_mfma_f32_16x16x32_bf16 v[110:113], v[206:209], v[162:165], v[110:113]
	v_mfma_f32_16x16x32_bf16 v[106:109], v[206:209], v[170:173], v[106:109]
	v_mfma_f32_16x16x32_bf16 v[102:105], v[214:217], v[162:165], v[102:105]
	v_mfma_f32_16x16x32_bf16 v[98:101], v[214:217], v[170:173], v[98:101]
	s_setprio 0
	s_barrier
	s_ashr_i32 s19, s18, 31
	s_lshl_b64 s[40:41], s[18:19], 1
	s_add_u32 s42, s16, s40
	s_addc_u32 s43, s17, s41
	v_lshl_add_u64 v[234:235], s[42:43], 0, v[0:1]
	v_readfirstlane_b32 s19, v152
	v_add_u32_e32 v230, v133, v132
	v_lshl_add_u64 v[234:235], v[234:235], 0, s[0:1]
	s_mov_b32 m0, s19
	ds_read_b128 v[218:221], v230
	ds_read_b128 v[222:225], v230 offset:1024
	ds_read_b128 v[226:229], v230 offset:2048
	ds_read_b128 v[230:233], v230 offset:3072
	global_load_lds_dwordx4 v[234:235], off
	v_lshl_add_u64 v[234:235], s[42:43], 0, v[130:131]
	v_readfirstlane_b32 s19, v153
	v_lshl_add_u64 v[234:235], v[234:235], 0, s[0:1]
	s_mov_b32 m0, s19
	s_nop 0
	global_load_lds_dwordx4 v[234:235], off
	s_barrier
	s_waitcnt lgkmcnt(0)
	s_setprio 1
	v_mfma_f32_16x16x32_bf16 v[94:97], v[174:177], v[218:221], v[94:97]
	v_mfma_f32_16x16x32_bf16 v[90:93], v[174:177], v[226:229], v[90:93]
	v_mfma_f32_16x16x32_bf16 v[86:89], v[194:197], v[218:221], v[86:89]
	v_mfma_f32_16x16x32_bf16 v[82:85], v[194:197], v[226:229], v[82:85]
	v_mfma_f32_16x16x32_bf16 v[78:81], v[202:205], v[218:221], v[78:81]
	v_mfma_f32_16x16x32_bf16 v[74:77], v[202:205], v[226:229], v[74:77]
	v_mfma_f32_16x16x32_bf16 v[70:73], v[210:213], v[218:221], v[70:73]
	v_mfma_f32_16x16x32_bf16 v[66:69], v[210:213], v[226:229], v[66:69]
	v_mfma_f32_16x16x32_bf16 v[94:97], v[178:181], v[222:225], v[94:97]
	v_mfma_f32_16x16x32_bf16 v[90:93], v[178:181], v[230:233], v[90:93]
	v_mfma_f32_16x16x32_bf16 v[86:89], v[198:201], v[222:225], v[86:89]
	v_mfma_f32_16x16x32_bf16 v[82:85], v[198:201], v[230:233], v[82:85]
	v_mfma_f32_16x16x32_bf16 v[78:81], v[206:209], v[222:225], v[78:81]
	v_mfma_f32_16x16x32_bf16 v[74:77], v[206:209], v[230:233], v[74:77]
	v_mfma_f32_16x16x32_bf16 v[70:73], v[214:217], v[222:225], v[70:73]
	v_mfma_f32_16x16x32_bf16 v[66:69], v[214:217], v[230:233], v[66:69]
	s_setprio 0
	s_add_u32 s40, s2, s40
	s_addc_u32 s41, s3, s41
	v_lshl_add_u64 v[234:235], s[40:41], 0, v[0:1]
	v_readfirstlane_b32 s19, v154
	v_lshl_add_u64 v[234:235], v[234:235], 0, s[0:1]
	s_mov_b32 m0, s19
	s_barrier
; #define STAGE(P, BASE, LD, br, kt) do { const char* _gp = (const char*)((BASE) + (long)((br) * (LD) + (kt) * BK)); \
;     __builtin_amdgcn_global_load_lds((const unsigned*)(_gp + vo_##BASE##0), (unsigned*)((char*)(P) + tidx * 16), 16, 0, 0); \
;     __builtin_amdgcn_global_load_lds((const unsigned*)(_gp + vo_##BASE##1), (unsigned*)((char*)(P) + tidx * 16 + 8192), 16, 0, 0); } while (0)
; #define LDA(dst, b, h) for (int m = 0; m < 4; ++m) for (int k = 0; k < 2; ++k) \
;     dst[m][k] = *reinterpret_cast<const bf16x8*>((char*)SA(b, h) + lds_byte(wr * 64 + m * 16 + fr, k * 32 + fq * 8))
; #define LDB(dst, b, h) for (int n = 0; n < 2; ++n) for (int k = 0; k < 2; ++k) \
;     dst[n][k] = *reinterpret_cast<const bf16x8*>((char*)SB(b, h) + lds_byte(wc * 32 + n * 16 + fr, k * 32 + fq * 8))
; #define MMA(ai, bj, At, Bt_) do { __builtin_amdgcn_s_setprio(1); \
;     for (int m = 0; m < 4; ++m) for (int n = 0; n < 2; ++n) for (int k = 0; k < 2; ++k) \
;       acc[ai][bj][m][n] = __builtin_amdgcn_mfma_f32_16x16x32_bf16(At[m][k], Bt_[n][k], acc[ai][bj][m][n], 0, 0, 0); \
;     __builtin_amdgcn_s_setprio(0); } while (0)
; #define WAIT_V(n) asm volatile("s_waitcnt vmcnt(" #n ")" ::: "memory")
; #define WAIT_L(n) asm volatile("s_waitcnt lgkmcnt(" #n ")" ::: "memory")
; #define BAR __builtin_amdgcn_s_barrier()
; #define SCHED __builtin_amdgcn_sched_barrier(0)
; __device__ __forceinline__ void gemm_main(acc_t& acc, const u16* A, int lda, const u16* Bt, int ldb, int nt, const int tidx) {
;     ...
;         LDA(At, 1, 1); STAGE(SA(1, 0), A, lda, 0, t + 3);
;         BAR; WAIT_L(0); MMA(1, 0, At, B0); BAR; SCHED;
;         STAGE(SB(1, 1), Bt, ldb, HALF, t + 3);
;         WAIT_V(6); BAR; MMA(1, 1, At, B1); BAR;
;     }
;     { LDB(B0, 0, 0); LDA(At, 0, 0); STAGE(SA(1, 1), A, lda, HALF, nt - 1);
;       BAR; WAIT_L(0); MMA(0, 0, At, B0); BAR;
	ds_read_b128 v[174:177], v190 offset:49152
	ds_read_b128 v[178:181], v190 offset:50176
	ds_read_b128 v[194:197], v191 offset:49152
	ds_read_b128 v[198:201], v191 offset:50176
	ds_read_b128 v[202:205], v236 offset:49152
	ds_read_b128 v[206:209], v236 offset:50176
	ds_read_b128 v[210:213], v237 offset:49152
	ds_read_b128 v[214:217], v237 offset:50176
	global_load_lds_dwordx4 v[234:235], off
	v_lshl_add_u64 v[234:235], s[40:41], 0, v[130:131]
	v_readfirstlane_b32 s19, v155
	v_lshl_add_u64 v[234:235], v[234:235], 0, s[0:1]
	s_mov_b32 m0, s19
	s_nop 0
	global_load_lds_dwordx4 v[234:235], off
	s_barrier
	s_waitcnt lgkmcnt(0)
	s_setprio 1
	v_mfma_f32_16x16x32_bf16 v[62:65], v[174:177], v[158:161], v[62:65]
	v_mfma_f32_16x16x32_bf16 v[58:61], v[174:177], v[166:169], v[58:61]
	v_mfma_f32_16x16x32_bf16 v[54:57], v[194:197], v[158:161], v[54:57]
	v_mfma_f32_16x16x32_bf16 v[50:53], v[194:197], v[166:169], v[50:53]
	v_mfma_f32_16x16x32_bf16 v[46:49], v[202:205], v[158:161], v[46:49]
	v_mfma_f32_16x16x32_bf16 v[42:45], v[202:205], v[166:169], v[42:45]
	v_mfma_f32_16x16x32_bf16 v[38:41], v[210:213], v[158:161], v[38:41]
	v_mfma_f32_16x16x32_bf16 v[34:37], v[210:213], v[166:169], v[34:37]
	v_mfma_f32_16x16x32_bf16 v[62:65], v[178:181], v[162:165], v[62:65]
	v_mfma_f32_16x16x32_bf16 v[58:61], v[178:181], v[170:173], v[58:61]
	v_mfma_f32_16x16x32_bf16 v[54:57], v[198:201], v[162:165], v[54:57]
	v_mfma_f32_16x16x32_bf16 v[50:53], v[198:201], v[170:173], v[50:53]
	v_mfma_f32_16x16x32_bf16 v[46:49], v[206:209], v[162:165], v[46:49]
	v_mfma_f32_16x16x32_bf16 v[42:45], v[206:209], v[170:173], v[42:45]
	v_mfma_f32_16x16x32_bf16 v[38:41], v[214:217], v[162:165], v[38:41]
	v_mfma_f32_16x16x32_bf16 v[34:37], v[214:217], v[170:173], v[34:37]
	s_setprio 0
	s_barrier
	s_add_i32 s18, s18, 0x200c0
	s_ashr_i32 s19, s18, 31
	s_lshl_b64 s[18:19], s[18:19], 1
	s_add_u32 s18, s16, s18
	s_addc_u32 s19, s17, s19
	v_readfirstlane_b32 s40, v156
	v_lshl_add_u64 v[158:159], s[18:19], 0, v[0:1]
	s_mov_b32 m0, s40
	s_nop 0
	global_load_lds_dwordx4 v[158:159], off
	v_lshl_add_u64 v[158:159], s[18:19], 0, v[130:131]
	v_readfirstlane_b32 s18, v157
	s_mov_b32 m0, s18
	s_nop 0
	global_load_lds_dwordx4 v[158:159], off
	s_waitcnt vmcnt(6)
	s_barrier
	s_setprio 1
	v_mfma_f32_16x16x32_bf16 v[30:33], v[174:177], v[218:221], v[30:33]
	v_mfma_f32_16x16x32_bf16 v[26:29], v[174:177], v[226:229], v[26:29]
	v_mfma_f32_16x16x32_bf16 v[22:25], v[194:197], v[218:221], v[22:25]
	v_mfma_f32_16x16x32_bf16 v[18:21], v[194:197], v[226:229], v[18:21]
	v_mfma_f32_16x16x32_bf16 v[14:17], v[202:205], v[218:221], v[14:17]
	v_mfma_f32_16x16x32_bf16 v[10:13], v[202:205], v[226:229], v[10:13]
	v_mfma_f32_16x16x32_bf16 v[6:9], v[210:213], v[218:221], v[6:9]
	v_mfma_f32_16x16x32_bf16 v[2:5], v[210:213], v[226:229], v[2:5]
	v_mfma_f32_16x16x32_bf16 v[30:33], v[178:181], v[222:225], v[30:33]
	v_mfma_f32_16x16x32_bf16 v[26:29], v[178:181], v[230:233], v[26:29]
	v_mfma_f32_16x16x32_bf16 v[22:25], v[198:201], v[222:225], v[22:25]
	v_mfma_f32_16x16x32_bf16 v[18:21], v[198:201], v[230:233], v[18:21]
	v_mfma_f32_16x16x32_bf16 v[14:17], v[206:209], v[222:225], v[14:17]
	v_mfma_f32_16x16x32_bf16 v[10:13], v[206:209], v[230:233], v[10:13]
	v_mfma_f32_16x16x32_bf16 v[6:9], v[214:217], v[222:225], v[6:9]
	v_mfma_f32_16x16x32_bf16 v[2:5], v[214:217], v[230:233], v[2:5]
	s_setprio 0
	s_cmp_lt_i32 s39, s33
	s_mov_b32 s18, s72
	s_barrier
	s_cbranch_scc1 .LBB0_716
.LBB0_717:
	s_lshl_b32 s15, s15, 6
	s_add_i32 s16, s15, 0x1ffc0
	s_ashr_i32 s17, s16, 31
	s_lshl_b64 s[16:17], s[16:17], 1
	s_add_u32 s2, s2, s16
	s_addc_u32 s3, s3, s17
	v_cmp_gt_u32_e32 vcc, s51, v135
	v_add_u32_e32 v135, 0xc000, v136
	v_lshl_add_u64 v[198:199], s[2:3], 0, v[0:1]
	v_lshl_add_u64 v[130:131], s[2:3], 0, v[130:131]
	v_add_u32_e32 v0, v140, v132
	v_readfirstlane_b32 s2, v135
	v_add_u32_e32 v135, 0xe000, v136
	ds_read_b128 v[146:149], v0
	ds_read_b128 v[150:153], v0 offset:1024
	ds_read_b128 v[154:157], v0 offset:2048
	ds_read_b128 v[158:161], v0 offset:3072
	v_add_u32_e32 v0, v141, v138
	v_add_u32_e32 v190, v139, v144
	v_add_u32_e32 v191, v139, v143
	v_add_u32_e32 v246, v139, v142
	s_mov_b32 m0, s2
	v_readfirstlane_b32 s2, v135
	ds_read_b128 v[162:165], v0
	ds_read_b128 v[166:169], v0 offset:1024
	ds_read_b128 v[170:173], v190
	ds_read_b128 v[174:177], v190 offset:1024
	ds_read_b128 v[178:181], v191
	ds_read_b128 v[194:197], v191 offset:1024
	ds_read_b128 v[138:141], v246
	ds_read_b128 v[142:145], v246 offset:1024
	global_load_lds_dwordx4 v[198:199], off
	s_mov_b32 m0, s2
	s_nop 0
	global_load_lds_dwordx4 v[130:131], off
	s_barrier
	s_waitcnt lgkmcnt(0)
	s_setprio 1
	v_mfma_f32_16x16x32_bf16 v[126:129], v[162:165], v[146:149], v[126:129]
	v_mfma_f32_16x16x32_bf16 v[118:121], v[170:173], v[146:149], v[118:121]
	v_mfma_f32_16x16x32_bf16 v[110:113], v[178:181], v[146:149], v[110:113]
	v_mfma_f32_16x16x32_bf16 v[106:109], v[178:181], v[154:157], v[106:109]
	v_mfma_f32_16x16x32_bf16 v[126:129], v[166:169], v[150:153], v[126:129]
	v_mfma_f32_16x16x32_bf16 v[122:125], v[162:165], v[154:157], v[122:125]
	v_mfma_f32_16x16x32_bf16 v[118:121], v[174:177], v[150:153], v[118:121]
	v_mfma_f32_16x16x32_bf16 v[114:117], v[170:173], v[154:157], v[114:117]
	v_mfma_f32_16x16x32_bf16 v[110:113], v[194:197], v[150:153], v[110:113]
	v_mfma_f32_16x16x32_bf16 v[106:109], v[194:197], v[158:161], v[106:109]
	v_mfma_f32_16x16x32_bf16 v[102:105], v[138:141], v[146:149], v[102:105]
	v_mfma_f32_16x16x32_bf16 v[98:101], v[138:141], v[154:157], v[98:101]
	v_mfma_f32_16x16x32_bf16 v[198:201], v[166:169], v[158:161], v[122:125]
	v_mfma_f32_16x16x32_bf16 v[202:205], v[174:177], v[158:161], v[114:117]
	v_mfma_f32_16x16x32_bf16 v[206:209], v[142:145], v[150:153], v[102:105]
	v_mfma_f32_16x16x32_bf16 v[210:213], v[142:145], v[158:161], v[98:101]
	s_setprio 0
	v_add_u32_e32 v122, v137, v132
	s_barrier
; #define LDA(dst, b, h) for (int m = 0; m < 4; ++m) for (int k = 0; k < 2; ++k) \
;     dst[m][k] = *reinterpret_cast<const bf16x8*>((char*)SA(b, h) + lds_byte(wr * 64 + m * 16 + fr, k * 32 + fq * 8))
; #define LDB(dst, b, h) for (int n = 0; n < 2; ++n) for (int k = 0; k < 2; ++k) \
;     dst[n][k] = *reinterpret_cast<const bf16x8*>((char*)SB(b, h) + lds_byte(wc * 32 + n * 16 + fr, k * 32 + fq * 8))
; #define MMA(ai, bj, At, Bt_) do { __builtin_amdgcn_s_setprio(1); \
;     for (int m = 0; m < 4; ++m) for (int n = 0; n < 2; ++n) for (int k = 0; k < 2; ++k) \
;       acc[ai][bj][m][n] = __builtin_amdgcn_mfma_f32_16x16x32_bf16(At[m][k], Bt_[n][k], acc[ai][bj][m][n], 0, 0, 0); \
;     __builtin_amdgcn_s_setprio(0); } while (0)
; #define WAIT_V(n) asm volatile("s_waitcnt vmcnt(" #n ")" ::: "memory")
; #define WAIT_L(n) asm volatile("s_waitcnt lgkmcnt(" #n ")" ::: "memory")
; #define BAR __builtin_amdgcn_s_barrier()
; __device__ __forceinline__ void gemm_main(acc_t& acc, const u16* A, int lda, const u16* Bt, int ldb, int nt, const int tidx) {
;     ...
;       BAR; WAIT_L(0); MMA(0, 0, At, B0); BAR;
;       LDB(B1, 0, 1); BAR; WAIT_L(0); MMA(0, 1, At, B1); BAR;
;       LDA(At, 0, 1); WAIT_V(4); BAR; WAIT_L(0); MMA(1, 0, At, B0); MMA(1, 1, At, B1); BAR; }
;     { LDB(B0, 1, 0); LDA(At, 1, 0); WAIT_V(2); BAR; WAIT_L(0); MMA(0, 0, At, B0); BAR;
	s_nop 0
	ds_read_b128 v[98:101], v122
	ds_read_b128 v[102:105], v122 offset:1024
	ds_read_b128 v[114:117], v122 offset:2048
	ds_read_b128 v[122:125], v122 offset:3072
	s_barrier
	s_waitcnt lgkmcnt(0)
	s_setprio 1
	v_mfma_f32_16x16x32_bf16 v[94:97], v[162:165], v[98:101], v[94:97]
	v_mfma_f32_16x16x32_bf16 v[86:89], v[170:173], v[98:101], v[86:89]
	v_mfma_f32_16x16x32_bf16 v[78:81], v[178:181], v[98:101], v[78:81]
	v_mfma_f32_16x16x32_bf16 v[74:77], v[178:181], v[114:117], v[74:77]
	v_mfma_f32_16x16x32_bf16 v[94:97], v[166:169], v[102:105], v[94:97]
	v_mfma_f32_16x16x32_bf16 v[90:93], v[162:165], v[114:117], v[90:93]
	v_mfma_f32_16x16x32_bf16 v[86:89], v[174:177], v[102:105], v[86:89]
	v_mfma_f32_16x16x32_bf16 v[82:85], v[170:173], v[114:117], v[82:85]
	v_mfma_f32_16x16x32_bf16 v[78:81], v[194:197], v[102:105], v[78:81]
	v_mfma_f32_16x16x32_bf16 v[74:77], v[194:197], v[122:125], v[74:77]
	v_mfma_f32_16x16x32_bf16 v[70:73], v[138:141], v[98:101], v[70:73]
	v_mfma_f32_16x16x32_bf16 v[66:69], v[138:141], v[114:117], v[66:69]
	v_mfma_f32_16x16x32_bf16 v[162:165], v[166:169], v[122:125], v[90:93]
	v_mfma_f32_16x16x32_bf16 v[166:169], v[174:177], v[122:125], v[82:85]
	v_mfma_f32_16x16x32_bf16 v[170:173], v[142:145], v[102:105], v[70:73]
	v_mfma_f32_16x16x32_bf16 v[136:139], v[142:145], v[122:125], v[66:69]
	s_setprio 0
	s_barrier
	s_nop 1
	ds_read_b128 v[66:69], v0 offset:16384
	ds_read_b128 v[70:73], v0 offset:17408
	ds_read_b128 v[82:85], v190 offset:16384
	ds_read_b128 v[90:93], v190 offset:17408
	ds_read_b128 v[140:143], v191 offset:16384
	ds_read_b128 v[174:177], v191 offset:17408
	ds_read_b128 v[178:181], v246 offset:16384
	ds_read_b128 v[194:197], v246 offset:17408
	s_waitcnt vmcnt(4)
	s_barrier
	s_waitcnt lgkmcnt(0)
	s_setprio 1
	v_mfma_f32_16x16x32_bf16 v[62:65], v[66:69], v[146:149], v[62:65]
	v_mfma_f32_16x16x32_bf16 v[54:57], v[82:85], v[146:149], v[54:57]
	v_mfma_f32_16x16x32_bf16 v[46:49], v[140:143], v[146:149], v[46:49]
	v_mfma_f32_16x16x32_bf16 v[42:45], v[140:143], v[154:157], v[42:45]
	v_mfma_f32_16x16x32_bf16 v[62:65], v[70:73], v[150:153], v[62:65]
	v_mfma_f32_16x16x32_bf16 v[58:61], v[66:69], v[154:157], v[58:61]
	v_mfma_f32_16x16x32_bf16 v[54:57], v[90:93], v[150:153], v[54:57]
	v_mfma_f32_16x16x32_bf16 v[50:53], v[82:85], v[154:157], v[50:53]
	v_mfma_f32_16x16x32_bf16 v[46:49], v[174:177], v[150:153], v[46:49]
	v_mfma_f32_16x16x32_bf16 v[42:45], v[174:177], v[158:161], v[42:45]
	v_mfma_f32_16x16x32_bf16 v[38:41], v[178:181], v[146:149], v[38:41]
	v_mfma_f32_16x16x32_bf16 v[34:37], v[178:181], v[154:157], v[34:37]
	v_mfma_f32_16x16x32_bf16 v[214:217], v[70:73], v[158:161], v[58:61]
	v_mfma_f32_16x16x32_bf16 v[218:221], v[90:93], v[158:161], v[50:53]
	v_mfma_f32_16x16x32_bf16 v[144:147], v[194:197], v[150:153], v[38:41]
	v_mfma_f32_16x16x32_bf16 v[148:151], v[194:197], v[158:161], v[34:37]
	s_setprio 0
	s_setprio 1
	v_mfma_f32_16x16x32_bf16 v[30:33], v[66:69], v[98:101], v[30:33]
	v_mfma_f32_16x16x32_bf16 v[22:25], v[82:85], v[98:101], v[22:25]
	v_mfma_f32_16x16x32_bf16 v[14:17], v[140:143], v[98:101], v[14:17]
	v_mfma_f32_16x16x32_bf16 v[6:9], v[178:181], v[98:101], v[6:9]
	v_mfma_f32_16x16x32_bf16 v[30:33], v[70:73], v[102:105], v[30:33]
	v_mfma_f32_16x16x32_bf16 v[26:29], v[66:69], v[114:117], v[26:29]
	v_mfma_f32_16x16x32_bf16 v[22:25], v[90:93], v[102:105], v[22:25]
	v_mfma_f32_16x16x32_bf16 v[18:21], v[82:85], v[114:117], v[18:21]
	v_mfma_f32_16x16x32_bf16 v[14:17], v[174:177], v[102:105], v[14:17]
	v_mfma_f32_16x16x32_bf16 v[10:13], v[140:143], v[114:117], v[10:13]
	v_mfma_f32_16x16x32_bf16 v[6:9], v[194:197], v[102:105], v[6:9]
	v_mfma_f32_16x16x32_bf16 v[2:5], v[178:181], v[114:117], v[2:5]
	v_mfma_f32_16x16x32_bf16 v[152:155], v[70:73], v[122:125], v[26:29]
	v_mfma_f32_16x16x32_bf16 v[156:159], v[90:93], v[122:125], v[18:21]
	v_mfma_f32_16x16x32_bf16 v[140:143], v[174:177], v[122:125], v[10:13]
	v_mfma_f32_16x16x32_bf16 v[174:177], v[194:197], v[122:125], v[2:5]
	s_setprio 0
	s_nop 2
	v_add_u32_e32 v2, v134, v132
	s_barrier
	ds_read_b128 v[178:181], v2
	ds_read_b128 v[194:197], v2 offset:1024
	ds_read_b128 v[222:225], v2 offset:2048
	ds_read_b128 v[226:229], v2 offset:3072
	ds_read_b128 v[2:5], v0 offset:32768
	ds_read_b128 v[10:13], v0 offset:33792
	ds_read_b128 v[18:21], v190 offset:32768
	ds_read_b128 v[34:37], v190 offset:33792
	ds_read_b128 v[230:233], v191 offset:32768
	ds_read_b128 v[234:237], v191 offset:33792
	ds_read_b128 v[238:241], v246 offset:32768
	ds_read_b128 v[242:245], v246 offset:33792
	s_waitcnt vmcnt(2)
	s_barrier
; #define LDA(dst, b, h) for (int m = 0; m < 4; ++m) for (int k = 0; k < 2; ++k) \
;     dst[m][k] = *reinterpret_cast<const bf16x8*>((char*)SA(b, h) + lds_byte(wr * 64 + m * 16 + fr, k * 32 + fq * 8))
; #define LDB(dst, b, h) for (int n = 0; n < 2; ++n) for (int k = 0; k < 2; ++k) \
;     dst[n][k] = *reinterpret_cast<const bf16x8*>((char*)SB(b, h) + lds_byte(wc * 32 + n * 16 + fr, k * 32 + fq * 8))
; #define MMA(ai, bj, At, Bt_) do { __builtin_amdgcn_s_setprio(1); \
;     for (int m = 0; m < 4; ++m) for (int n = 0; n < 2; ++n) for (int k = 0; k < 2; ++k) \
;       acc[ai][bj][m][n] = __builtin_amdgcn_mfma_f32_16x16x32_bf16(At[m][k], Bt_[n][k], acc[ai][bj][m][n], 0, 0, 0); \
;     __builtin_amdgcn_s_setprio(0); } while (0)
; #define WAIT_V(n) asm volatile("s_waitcnt vmcnt(" #n ")" ::: "memory")
; #define WAIT_L(n) asm volatile("s_waitcnt lgkmcnt(" #n ")" ::: "memory")
; #define BAR __builtin_amdgcn_s_barrier()
; __device__ __forceinline__ void gemm_main(acc_t& acc, const u16* A, int lda, const u16* Bt, int ldb, int nt, const int tidx) {
;     ...
;     { LDB(B0, 1, 0); LDA(At, 1, 0); WAIT_V(2); BAR; WAIT_L(0); MMA(0, 0, At, B0); BAR;
;       LDB(B1, 1, 1); WAIT_V(0); BAR; WAIT_L(0); MMA(0, 1, At, B1); BAR;
;       LDA(At, 1, 1); BAR; WAIT_L(0); MMA(1, 0, At, B0); MMA(1, 1, At, B1); BAR; }
;     if (wr == 0) BAR;
	s_waitcnt lgkmcnt(0)
	s_setprio 1
	v_mfma_f32_16x16x32_bf16 v[26:29], v[2:5], v[178:181], v[126:129]
	v_mfma_f32_16x16x32_bf16 v[122:125], v[10:13], v[194:197], v[26:29]
	v_mfma_f32_16x16x32_bf16 v[26:29], v[2:5], v[222:225], v[198:201]
	v_mfma_f32_16x16x32_bf16 v[90:93], v[10:13], v[226:229], v[26:29]
	v_mfma_f32_16x16x32_bf16 v[26:29], v[18:21], v[178:181], v[118:121]
	v_mfma_f32_16x16x32_bf16 v[114:117], v[34:37], v[194:197], v[26:29]
	v_mfma_f32_16x16x32_bf16 v[26:29], v[18:21], v[222:225], v[202:205]
	v_mfma_f32_16x16x32_bf16 v[82:85], v[34:37], v[226:229], v[26:29]
	v_mfma_f32_16x16x32_bf16 v[26:29], v[230:233], v[178:181], v[110:113]
	v_mfma_f32_16x16x32_bf16 v[102:105], v[234:237], v[194:197], v[26:29]
	v_mfma_f32_16x16x32_bf16 v[26:29], v[230:233], v[222:225], v[106:109]
	v_mfma_f32_16x16x32_bf16 v[70:73], v[234:237], v[226:229], v[26:29]
	v_mfma_f32_16x16x32_bf16 v[26:29], v[238:241], v[178:181], v[206:209]
	v_mfma_f32_16x16x32_bf16 v[98:101], v[242:245], v[194:197], v[26:29]
	v_mfma_f32_16x16x32_bf16 v[26:29], v[238:241], v[222:225], v[210:213]
	v_mfma_f32_16x16x32_bf16 v[66:69], v[242:245], v[226:229], v[26:29]
	s_setprio 0
	s_nop 5
	v_add_u32_e32 v26, v133, v132
	s_barrier
	ds_read_b128 v[130:133], v26
	ds_read_b128 v[198:201], v26 offset:1024
	ds_read_b128 v[202:205], v26 offset:2048
	ds_read_b128 v[206:209], v26 offset:3072
	s_waitcnt vmcnt(0)
	s_barrier
	s_waitcnt lgkmcnt(0)
	s_setprio 1
	v_mfma_f32_16x16x32_bf16 v[26:29], v[2:5], v[130:133], v[94:97]
	v_mfma_f32_16x16x32_bf16 v[2:5], v[2:5], v[202:205], v[162:165]
	v_mfma_f32_16x16x32_bf16 v[58:61], v[10:13], v[198:201], v[26:29]
	v_mfma_f32_16x16x32_bf16 v[26:29], v[10:13], v[206:209], v[2:5]
	v_mfma_f32_16x16x32_bf16 v[2:5], v[18:21], v[130:133], v[86:89]
	v_mfma_f32_16x16x32_bf16 v[50:53], v[34:37], v[198:201], v[2:5]
	v_mfma_f32_16x16x32_bf16 v[2:5], v[18:21], v[202:205], v[166:169]
	v_mfma_f32_16x16x32_bf16 v[18:21], v[34:37], v[206:209], v[2:5]
	v_mfma_f32_16x16x32_bf16 v[2:5], v[230:233], v[130:133], v[78:81]
	v_mfma_f32_16x16x32_bf16 v[38:41], v[234:237], v[198:201], v[2:5]
	v_mfma_f32_16x16x32_bf16 v[2:5], v[230:233], v[202:205], v[74:77]
	v_mfma_f32_16x16x32_bf16 v[10:13], v[234:237], v[206:209], v[2:5]
	v_mfma_f32_16x16x32_bf16 v[2:5], v[238:241], v[130:133], v[170:173]
	v_mfma_f32_16x16x32_bf16 v[34:37], v[242:245], v[198:201], v[2:5]
	v_mfma_f32_16x16x32_bf16 v[2:5], v[238:241], v[202:205], v[136:139]
	v_mfma_f32_16x16x32_bf16 v[2:5], v[242:245], v[206:209], v[2:5]
	s_setprio 0
	s_barrier
	ds_read_b128 v[134:137], v0 offset:49152
	ds_read_b128 v[160:163], v0 offset:50176
	ds_read_b128 v[164:167], v190 offset:49152
	ds_read_b128 v[168:171], v190 offset:50176
	ds_read_b128 v[210:213], v191 offset:49152
	ds_read_b128 v[230:233], v191 offset:50176
	ds_read_b128 v[234:237], v246 offset:49152
	ds_read_b128 v[238:241], v246 offset:50176
	s_barrier
	s_waitcnt lgkmcnt(0)
	s_setprio 1
	v_mfma_f32_16x16x32_bf16 v[42:45], v[210:213], v[222:225], v[42:45]
	v_mfma_f32_16x16x32_bf16 v[62:65], v[134:137], v[178:181], v[62:65]
	v_mfma_f32_16x16x32_bf16 v[54:57], v[164:167], v[178:181], v[54:57]
	v_mfma_f32_16x16x32_bf16 v[78:81], v[230:233], v[226:229], v[42:45]
	v_mfma_f32_16x16x32_bf16 v[42:45], v[234:237], v[178:181], v[144:147]
	v_mfma_f32_16x16x32_bf16 v[126:129], v[160:163], v[194:197], v[62:65]
	v_mfma_f32_16x16x32_bf16 v[62:65], v[134:137], v[222:225], v[214:217]
	v_mfma_f32_16x16x32_bf16 v[118:121], v[168:171], v[194:197], v[54:57]
	v_mfma_f32_16x16x32_bf16 v[54:57], v[164:167], v[222:225], v[218:221]
	v_mfma_f32_16x16x32_bf16 v[46:49], v[210:213], v[178:181], v[46:49]
	v_mfma_f32_16x16x32_bf16 v[106:109], v[238:241], v[194:197], v[42:45]
	v_mfma_f32_16x16x32_bf16 v[42:45], v[234:237], v[222:225], v[148:151]
	v_mfma_f32_16x16x32_bf16 v[94:97], v[160:163], v[226:229], v[62:65]
	v_mfma_f32_16x16x32_bf16 v[86:89], v[168:171], v[226:229], v[54:57]
	v_mfma_f32_16x16x32_bf16 v[110:113], v[230:233], v[194:197], v[46:49]
	v_mfma_f32_16x16x32_bf16 v[74:77], v[238:241], v[226:229], v[42:45]
	s_setprio 0
	s_setprio 1
	v_mfma_f32_16x16x32_bf16 v[30:33], v[134:137], v[130:133], v[30:33]
	v_mfma_f32_16x16x32_bf16 v[22:25], v[164:167], v[130:133], v[22:25]
	v_mfma_f32_16x16x32_bf16 v[14:17], v[210:213], v[130:133], v[14:17]
	v_mfma_f32_16x16x32_bf16 v[6:9], v[234:237], v[130:133], v[6:9]
	v_mfma_f32_16x16x32_bf16 v[62:65], v[160:163], v[198:201], v[30:33]
	v_mfma_f32_16x16x32_bf16 v[30:33], v[134:137], v[202:205], v[152:155]
	v_mfma_f32_16x16x32_bf16 v[54:57], v[168:171], v[198:201], v[22:25]
	v_mfma_f32_16x16x32_bf16 v[22:25], v[164:167], v[202:205], v[156:159]
	v_mfma_f32_16x16x32_bf16 v[46:49], v[230:233], v[198:201], v[14:17]
	v_mfma_f32_16x16x32_bf16 v[14:17], v[210:213], v[202:205], v[140:143]
	v_mfma_f32_16x16x32_bf16 v[42:45], v[238:241], v[198:201], v[6:9]
	v_mfma_f32_16x16x32_bf16 v[6:9], v[234:237], v[202:205], v[174:177]
	v_mfma_f32_16x16x32_bf16 v[30:33], v[160:163], v[206:209], v[30:33]
	v_mfma_f32_16x16x32_bf16 v[22:25], v[168:171], v[206:209], v[22:25]
	v_mfma_f32_16x16x32_bf16 v[14:17], v[230:233], v[206:209], v[14:17]
	v_mfma_f32_16x16x32_bf16 v[6:9], v[238:241], v[206:209], v[6:9]
	s_setprio 0
	s_barrier
	s_and_saveexec_b64 s[2:3], vcc
	s_cbranch_execz .LBB0_719
	s_barrier
